# GEMM epilogue dwordx4 stores marked nt (non-temporal) to keep operand tiles in L2; on top of v62
# baseline (speedup 1.0000x reference)
; __device__ __forceinline__ unsigned pk2(float lo, float hi) { f32x2_t v = {lo, hi}; bf16x2_t b = __builtin_convertvector(v, bf16x2_t); return __builtin_bit_cast(unsigned, b); }
; __device__ __forceinline__ float siluf_(float x) { return x * sigmoidf_(x); }
;     __device__ __forceinline__ void operator()(Acc& acc, const Unit& u, int wr, int wc, int fr, int fq, const float (&rsa)[2][4]) const {
;         const int row0 = u.pm * BM + wr * 64 + fr, col0 = u.pn * HALF + wc * 32 + 8 * fq;
; #pragma unroll
;         for (int ai = 0; ai < 2; ++ai)
; #pragma unroll
;             for (int m = 0; m < 4; ++m) {
;                 const int row = row0 + ai * HALF + m * 16; const float rs = rsa[ai][m];
;                 float o[8];
; #pragma unroll
;                 for (int n = 0; n < 2; ++n)
; #pragma unroll
;                     for (int j = 0; j < 4; ++j) { const float g = acc[ai][0][m][n][j] * rs, up = acc[ai][1][m][n][j] * rs; o[n * 4 + j] = siluf_(g) * up; }
;                 u32x4 w; w.x = pk2(o[0], o[1]); w.y = pk2(o[2], o[3]); w.z = pk2(o[4], o[5]); w.w = pk2(o[6], o[7]);
;                 const int rr = row & (BM - 1);
;                 *(u32x4*)((char*)O + ((size_t)(u.pm * (FF / BK) + (col0 >> 6))) * (2 * HTB) + (rr >> 7) * HTB + lds_byte(rr & 127, col0 & 63)) = w;
;             }
.LBB0_409:
	v_pk_mul_f32 v[140:141], v[126:127], v[134:135] op_sel_hi:[1,0]
	v_mov_b64_e32 v[126:127], 0
	v_pk_mul_f32 v[144:145], v[94:95], v[134:135] op_sel_hi:[1,0]
	v_mov_b64_e32 v[94:95], 0
	v_mul_f32_e32 v131, 0xbfb8aa3b, v140
	v_exp_f32_e32 v131, v131
	v_pk_mul_f32 v[186:187], v[96:97], v[134:135] op_sel_hi:[1,0]
	v_mov_b64_e32 v[96:97], 0
	v_pk_mul_f32 v[188:189], v[90:91], v[134:135] op_sel_hi:[1,0]
	v_mov_b64_e32 v[90:91], 0
	s_lshl_b32 s39, s10, 7
	v_add_f32_e32 v131, 1.0, v131
	v_rcp_f32_e32 v142, v131
	v_mul_f32_e32 v131, 0xbfb8aa3b, v141
	v_exp_f32_e32 v131, v131
	s_or_b32 s39, s39, s17
	s_ashr_i32 s39, s39, 6
	s_mul_i32 s41, s8, 44
	v_add_f32_e32 v131, 1.0, v131
	v_rcp_f32_e32 v143, v131
	s_add_i32 s46, s39, s41
	s_ashr_i32 s47, s46, 31
	s_lshl_b64 s[46:47], s[46:47], 15
	v_pk_mul_f32 v[140:141], v[140:141], v[142:143]
	v_pk_mul_f32 v[142:143], v[128:129], v[134:135] op_sel_hi:[1,0]
	v_mov_b64_e32 v[128:129], 0
	v_pk_mul_f32 v[140:141], v[144:145], v[140:141]
	v_mul_f32_e32 v131, 0xbfb8aa3b, v142
	v_exp_f32_e32 v131, v131
	s_add_u32 s39, s14, s46
	s_addc_u32 s41, s15, s47
	s_add_u32 s46, s39, s62
	v_add_f32_e32 v131, 1.0, v131
	v_rcp_f32_e32 v144, v131
	v_mul_f32_e32 v131, 0xbfb8aa3b, v143
	v_exp_f32_e32 v131, v131
	s_addc_u32 s47, s41, 0
	v_cvt_pk_bf16_f32 v140, v140, v141
	v_add_f32_e32 v131, 1.0, v131
	v_rcp_f32_e32 v145, v131
	s_nop 0
	v_pk_mul_f32 v[142:143], v[142:143], v[144:145]
	v_pk_mul_f32 v[144:145], v[122:123], v[134:135] op_sel_hi:[1,0]
	v_mov_b64_e32 v[122:123], 0
	v_pk_mul_f32 v[142:143], v[186:187], v[142:143]
	v_mul_f32_e32 v131, 0xbfb8aa3b, v144
	v_exp_f32_e32 v131, v131
	v_cvt_pk_bf16_f32 v141, v142, v143
	v_add_f32_e32 v131, 1.0, v131
	v_rcp_f32_e32 v186, v131
	v_mul_f32_e32 v131, 0xbfb8aa3b, v145
	v_exp_f32_e32 v131, v131
	s_nop 0
	v_add_f32_e32 v131, 1.0, v131
	v_rcp_f32_e32 v187, v131
	s_nop 0
	v_pk_mul_f32 v[144:145], v[144:145], v[186:187]
	v_pk_mul_f32 v[186:187], v[124:125], v[134:135] op_sel_hi:[1,0]
	v_mov_b64_e32 v[124:125], 0
	v_pk_mul_f32 v[144:145], v[188:189], v[144:145]
	v_mul_f32_e32 v131, 0xbfb8aa3b, v186
	v_exp_f32_e32 v131, v131
	v_pk_mul_f32 v[134:135], v[92:93], v[134:135] op_sel_hi:[1,0]
	v_mov_b64_e32 v[92:93], 0
	v_cvt_pk_bf16_f32 v142, v144, v145
	v_pk_mul_f32 v[144:145], v[88:89], v[170:171] op_sel_hi:[1,0]
	v_mov_b64_e32 v[88:89], 0
	v_add_f32_e32 v131, 1.0, v131
	v_rcp_f32_e32 v188, v131
	v_mul_f32_e32 v131, 0xbfb8aa3b, v187
	v_exp_f32_e32 v131, v131
	s_nop 0
	v_add_f32_e32 v131, 1.0, v131
	v_rcp_f32_e32 v189, v131
	s_nop 0
	v_pk_mul_f32 v[186:187], v[186:187], v[188:189]
	s_nop 0
	v_pk_mul_f32 v[134:135], v[134:135], v[186:187]
	v_pk_mul_f32 v[186:187], v[82:83], v[170:171] op_sel_hi:[1,0]
	v_mov_b64_e32 v[82:83], 0
	v_cvt_pk_bf16_f32 v143, v134, v135
	v_lshl_add_u64 v[134:135], s[46:47], 0, v[152:153]
	global_store_dwordx4 v[134:135], v[140:143], off nt
	v_pk_mul_f32 v[134:135], v[118:119], v[170:171] op_sel_hi:[1,0]
	v_mov_b64_e32 v[118:119], 0
	v_pk_mul_f32 v[188:189], v[84:85], v[170:171] op_sel_hi:[1,0]
	v_mov_b64_e32 v[84:85], 0
	v_mul_f32_e32 v131, 0xbfb8aa3b, v134
	v_exp_f32_e32 v131, v131
	v_pk_mul_f32 v[142:143], v[86:87], v[170:171] op_sel_hi:[1,0]
	v_mov_b64_e32 v[86:87], 0
	v_add_f32_e32 v131, 1.0, v131
	v_rcp_f32_e32 v140, v131
	v_mul_f32_e32 v131, 0xbfb8aa3b, v135
	v_exp_f32_e32 v131, v131
	s_nop 0
	v_add_f32_e32 v131, 1.0, v131
	v_rcp_f32_e32 v141, v131
	s_nop 0
	v_pk_mul_f32 v[134:135], v[134:135], v[140:141]
	v_pk_mul_f32 v[140:141], v[120:121], v[170:171] op_sel_hi:[1,0]
	v_mov_b64_e32 v[120:121], 0
	v_pk_mul_f32 v[134:135], v[142:143], v[134:135]
	v_mul_f32_e32 v131, 0xbfb8aa3b, v140
	v_exp_f32_e32 v131, v131
	s_nop 0
	v_add_f32_e32 v131, 1.0, v131
	v_rcp_f32_e32 v142, v131
	v_mul_f32_e32 v131, 0xbfb8aa3b, v141
	v_exp_f32_e32 v131, v131
	s_nop 0
	v_add_f32_e32 v131, 1.0, v131
	v_rcp_f32_e32 v143, v131
	s_nop 0
	v_pk_mul_f32 v[140:141], v[140:141], v[142:143]
	s_nop 0
	v_pk_mul_f32 v[142:143], v[144:145], v[140:141]
	v_pk_mul_f32 v[140:141], v[114:115], v[170:171] op_sel_hi:[1,0]
	v_mov_b64_e32 v[114:115], 0
	s_nop 0
	v_mul_f32_e32 v131, 0xbfb8aa3b, v140
	v_exp_f32_e32 v131, v131
	s_nop 0
	v_add_f32_e32 v131, 1.0, v131
	v_rcp_f32_e32 v144, v131
	v_mul_f32_e32 v131, 0xbfb8aa3b, v141
	v_exp_f32_e32 v131, v131
	s_nop 0
	v_add_f32_e32 v131, 1.0, v131
	v_rcp_f32_e32 v145, v131
	s_nop 0
	v_pk_mul_f32 v[140:141], v[140:141], v[144:145]
	s_nop 0
	v_pk_mul_f32 v[144:145], v[186:187], v[140:141]
	v_pk_mul_f32 v[140:141], v[116:117], v[170:171] op_sel_hi:[1,0]
	v_mov_b64_e32 v[116:117], 0
	s_nop 0
	v_mul_f32_e32 v131, 0xbfb8aa3b, v140
	v_exp_f32_e32 v131, v131
	s_nop 0
	v_add_f32_e32 v131, 1.0, v131
	v_rcp_f32_e32 v186, v131
	v_mul_f32_e32 v131, 0xbfb8aa3b, v141
	v_exp_f32_e32 v131, v131
	s_nop 0
	v_add_f32_e32 v131, 1.0, v131
	v_rcp_f32_e32 v187, v131
	s_nop 0
	v_pk_mul_f32 v[140:141], v[140:141], v[186:187]
	s_nop 0
	v_pk_mul_f32 v[186:187], v[188:189], v[140:141]
	v_cvt_pk_bf16_f32 v140, v134, v135
	v_cvt_pk_bf16_f32 v141, v142, v143
	v_cvt_pk_bf16_f32 v142, v144, v145
	v_cvt_pk_bf16_f32 v143, v186, v187
	v_lshl_add_u64 v[134:135], s[46:47], 0, v[156:157]
	global_store_dwordx4 v[134:135], v[140:143], off nt
	v_pk_mul_f32 v[134:135], v[110:111], v[136:137] op_sel_hi:[1,0]
	v_mov_b64_e32 v[110:111], 0
	v_pk_mul_f32 v[144:145], v[80:81], v[136:137] op_sel_hi:[1,0]
	v_mov_b64_e32 v[80:81], 0
	v_mul_f32_e32 v131, 0xbfb8aa3b, v134
	v_exp_f32_e32 v131, v131
	v_pk_mul_f32 v[142:143], v[78:79], v[136:137] op_sel_hi:[1,0]
	v_mov_b64_e32 v[78:79], 0
	v_pk_mul_f32 v[186:187], v[74:75], v[136:137] op_sel_hi:[1,0]
	v_mov_b64_e32 v[74:75], 0
	v_add_f32_e32 v131, 1.0, v131
; __device__ __forceinline__ unsigned pk2(float lo, float hi) { f32x2_t v = {lo, hi}; bf16x2_t b = __builtin_convertvector(v, bf16x2_t); return __builtin_bit_cast(unsigned, b); }
; __device__ __forceinline__ float siluf_(float x) { return x * sigmoidf_(x); }
;     __device__ __forceinline__ void operator()(Acc& acc, const Unit& u, int wr, int wc, int fr, int fq, const float (&rsa)[2][4]) const {
;         const int row0 = u.pm * BM + wr * 64 + fr, col0 = u.pn * HALF + wc * 32 + 8 * fq;
; #pragma unroll
;         for (int ai = 0; ai < 2; ++ai)
; #pragma unroll
;             for (int m = 0; m < 4; ++m) {
;                 const int row = row0 + ai * HALF + m * 16; const float rs = rsa[ai][m];
;                 float o[8];
; #pragma unroll
;                 for (int n = 0; n < 2; ++n)
; #pragma unroll
;                     for (int j = 0; j < 4; ++j) { const float g = acc[ai][0][m][n][j] * rs, up = acc[ai][1][m][n][j] * rs; o[n * 4 + j] = siluf_(g) * up; }
;                 u32x4 w; w.x = pk2(o[0], o[1]); w.y = pk2(o[2], o[3]); w.z = pk2(o[4], o[5]); w.w = pk2(o[6], o[7]);
;                 const int rr = row & (BM - 1);
;                 *(u32x4*)((char*)O + ((size_t)(u.pm * (FF / BK) + (col0 >> 6))) * (2 * HTB) + (rr >> 7) * HTB + lds_byte(rr & 127, col0 & 63)) = w;
;             }
	v_rcp_f32_e32 v140, v131
	v_mul_f32_e32 v131, 0xbfb8aa3b, v135
	v_exp_f32_e32 v131, v131
	s_nop 0
	v_add_f32_e32 v131, 1.0, v131
	v_rcp_f32_e32 v141, v131
	s_nop 0
	v_pk_mul_f32 v[134:135], v[134:135], v[140:141]
	v_pk_mul_f32 v[140:141], v[112:113], v[136:137] op_sel_hi:[1,0]
	v_mov_b64_e32 v[112:113], 0
	v_pk_mul_f32 v[134:135], v[142:143], v[134:135]
	v_mul_f32_e32 v131, 0xbfb8aa3b, v140
	v_exp_f32_e32 v131, v131
	v_cvt_pk_bf16_f32 v134, v134, v135
	v_add_f32_e32 v131, 1.0, v131
	v_rcp_f32_e32 v142, v131
	v_mul_f32_e32 v131, 0xbfb8aa3b, v141
	v_exp_f32_e32 v131, v131
	s_nop 0
	v_add_f32_e32 v131, 1.0, v131
	v_rcp_f32_e32 v143, v131
	s_nop 0
	v_pk_mul_f32 v[140:141], v[140:141], v[142:143]
	v_pk_mul_f32 v[142:143], v[106:107], v[136:137] op_sel_hi:[1,0]
	v_mov_b64_e32 v[106:107], 0
	v_pk_mul_f32 v[140:141], v[144:145], v[140:141]
	v_mul_f32_e32 v131, 0xbfb8aa3b, v142
	v_exp_f32_e32 v131, v131
	v_cvt_pk_bf16_f32 v135, v140, v141
	v_lshl_add_u64 v[140:141], s[46:47], 0, v[158:159]
	v_add_f32_e32 v131, 1.0, v131
	v_rcp_f32_e32 v144, v131
	v_mul_f32_e32 v131, 0xbfb8aa3b, v143
	v_exp_f32_e32 v131, v131
	s_nop 0
	v_add_f32_e32 v131, 1.0, v131
	v_rcp_f32_e32 v145, v131
	s_nop 0
	v_pk_mul_f32 v[142:143], v[142:143], v[144:145]
	v_pk_mul_f32 v[144:145], v[108:109], v[136:137] op_sel_hi:[1,0]
	v_mov_b64_e32 v[108:109], 0
	v_pk_mul_f32 v[142:143], v[186:187], v[142:143]
	v_mul_f32_e32 v131, 0xbfb8aa3b, v144
	v_exp_f32_e32 v131, v131
	v_pk_mul_f32 v[136:137], v[76:77], v[136:137] op_sel_hi:[1,0]
	v_mov_b64_e32 v[76:77], 0
	v_add_f32_e32 v131, 1.0, v131
	v_rcp_f32_e32 v186, v131
	v_mul_f32_e32 v131, 0xbfb8aa3b, v145
	v_exp_f32_e32 v131, v131
	s_nop 0
	v_add_f32_e32 v131, 1.0, v131
	v_rcp_f32_e32 v187, v131
	s_nop 0
	v_pk_mul_f32 v[144:145], v[144:145], v[186:187]
	s_nop 0
	v_pk_mul_f32 v[144:145], v[136:137], v[144:145]
	v_cvt_pk_bf16_f32 v136, v142, v143
	v_cvt_pk_bf16_f32 v137, v144, v145
	global_store_dwordx4 v[140:141], v[134:137], off nt
	v_pk_mul_f32 v[140:141], v[70:71], v[168:169] op_sel_hi:[1,0]
	v_mov_b64_e32 v[70:71], 0
	v_pk_mul_f32 v[142:143], v[72:73], v[168:169] op_sel_hi:[1,0]
	v_mov_b64_e32 v[72:73], 0
	v_pk_mul_f32 v[134:135], v[102:103], v[168:169] op_sel_hi:[1,0]
	v_mov_b64_e32 v[102:103], 0
	v_pk_mul_f32 v[144:145], v[66:67], v[168:169] op_sel_hi:[1,0]
	v_mov_b64_e32 v[66:67], 0
	v_mul_f32_e32 v131, 0xbfb8aa3b, v134
	v_exp_f32_e32 v131, v131
	v_pk_mul_f32 v[186:187], v[68:69], v[168:169] op_sel_hi:[1,0]
	v_mov_b64_e32 v[68:69], 0
	v_add_f32_e32 v131, 1.0, v131
	v_rcp_f32_e32 v136, v131
	v_mul_f32_e32 v131, 0xbfb8aa3b, v135
	v_exp_f32_e32 v131, v131
	s_nop 0
	v_add_f32_e32 v131, 1.0, v131
	v_rcp_f32_e32 v137, v131
	s_nop 0
	v_pk_mul_f32 v[134:135], v[134:135], v[136:137]
	v_pk_mul_f32 v[136:137], v[104:105], v[168:169] op_sel_hi:[1,0]
	v_mov_b64_e32 v[104:105], 0
	v_pk_mul_f32 v[134:135], v[140:141], v[134:135]
	v_mul_f32_e32 v131, 0xbfb8aa3b, v136
	v_exp_f32_e32 v131, v131
	v_cvt_pk_bf16_f32 v134, v134, v135
	v_add_f32_e32 v131, 1.0, v131
	v_rcp_f32_e32 v140, v131
	v_mul_f32_e32 v131, 0xbfb8aa3b, v137
	v_exp_f32_e32 v131, v131
	s_nop 0
	v_add_f32_e32 v131, 1.0, v131
	v_rcp_f32_e32 v141, v131
	s_nop 0
	v_pk_mul_f32 v[136:137], v[136:137], v[140:141]
	v_pk_mul_f32 v[140:141], v[98:99], v[168:169] op_sel_hi:[1,0]
	v_mov_b64_e32 v[98:99], 0
	v_pk_mul_f32 v[136:137], v[142:143], v[136:137]
	v_mul_f32_e32 v131, 0xbfb8aa3b, v140
	v_exp_f32_e32 v131, v131
	v_cvt_pk_bf16_f32 v135, v136, v137
	v_add_f32_e32 v131, 1.0, v131
	v_rcp_f32_e32 v142, v131
	v_mul_f32_e32 v131, 0xbfb8aa3b, v141
	v_exp_f32_e32 v131, v131
	s_nop 0
	v_add_f32_e32 v131, 1.0, v131
	v_rcp_f32_e32 v143, v131
	s_nop 0
	v_pk_mul_f32 v[140:141], v[140:141], v[142:143]
	v_pk_mul_f32 v[142:143], v[100:101], v[168:169] op_sel_hi:[1,0]
	v_mov_b64_e32 v[100:101], 0
	v_pk_mul_f32 v[140:141], v[144:145], v[140:141]
	v_mul_f32_e32 v131, 0xbfb8aa3b, v142
	v_exp_f32_e32 v131, v131
	v_cvt_pk_bf16_f32 v136, v140, v141
	v_lshl_add_u64 v[140:141], s[46:47], 0, v[160:161]
	s_add_u32 s46, s39, s63
	v_add_f32_e32 v131, 1.0, v131
	v_rcp_f32_e32 v144, v131
	v_mul_f32_e32 v131, 0xbfb8aa3b, v143
	v_exp_f32_e32 v131, v131
	s_addc_u32 s47, s41, 0
	s_andn2_b64 vcc, exec, s[6:7]
	v_add_f32_e32 v131, 1.0, v131
	v_rcp_f32_e32 v145, v131
	s_nop 0
	v_pk_mul_f32 v[142:143], v[142:143], v[144:145]
	s_nop 0
	v_pk_mul_f32 v[142:143], v[186:187], v[142:143]
	s_nop 0
	v_cvt_pk_bf16_f32 v137, v142, v143
	global_store_dwordx4 v[140:141], v[134:137], off nt
	s_nop 1
	v_pk_mul_f32 v[134:135], v[62:63], v[130:131] op_sel_hi:[1,0]
	v_mov_b64_e32 v[62:63], 0
	s_nop 0
	v_mul_f32_e32 v131, 0xbfb8aa3b, v134
	v_exp_f32_e32 v131, v131
	s_nop 0
	v_add_f32_e32 v131, 1.0, v131
	v_rcp_f32_e32 v136, v131
	v_pk_mul_f32 v[140:141], v[30:31], v[130:131] op_sel_hi:[1,0]
	v_mov_b64_e32 v[30:31], 0
	v_mul_f32_e32 v131, 0xbfb8aa3b, v135
	v_exp_f32_e32 v131, v131
	s_nop 0
	v_add_f32_e32 v131, 1.0, v131
	v_rcp_f32_e32 v137, v131
	s_nop 0
	v_pk_mul_f32 v[134:135], v[134:135], v[136:137]
	v_pk_mul_f32 v[136:137], v[64:65], v[130:131] op_sel_hi:[1,0]
	v_mov_b64_e32 v[64:65], 0
	v_pk_mul_f32 v[134:135], v[140:141], v[134:135]
	v_mul_f32_e32 v131, 0xbfb8aa3b, v136
	v_exp_f32_e32 v131, v131
	v_cvt_pk_bf16_f32 v134, v134, v135
	v_add_f32_e32 v131, 1.0, v131
	v_rcp_f32_e32 v140, v131
	v_pk_mul_f32 v[142:143], v[32:33], v[130:131] op_sel_hi:[1,0]
	v_mov_b64_e32 v[32:33], 0
	v_mul_f32_e32 v131, 0xbfb8aa3b, v137
	v_exp_f32_e32 v131, v131
	s_nop 0
	v_add_f32_e32 v131, 1.0, v131
	v_rcp_f32_e32 v141, v131
	s_nop 0
	v_pk_mul_f32 v[136:137], v[136:137], v[140:141]
	v_pk_mul_f32 v[140:141], v[58:59], v[130:131] op_sel_hi:[1,0]
	v_mov_b64_e32 v[58:59], 0
; __device__ __forceinline__ unsigned pk2(float lo, float hi) { f32x2_t v = {lo, hi}; bf16x2_t b = __builtin_convertvector(v, bf16x2_t); return __builtin_bit_cast(unsigned, b); }
; __device__ __forceinline__ float siluf_(float x) { return x * sigmoidf_(x); }
;     __device__ __forceinline__ void operator()(Acc& acc, const Unit& u, int wr, int wc, int fr, int fq, const float (&rsa)[2][4]) const {
;         const int row0 = u.pm * BM + wr * 64 + fr, col0 = u.pn * HALF + wc * 32 + 8 * fq;
; #pragma unroll
;         for (int ai = 0; ai < 2; ++ai)
; #pragma unroll
;             for (int m = 0; m < 4; ++m) {
;                 const int row = row0 + ai * HALF + m * 16; const float rs = rsa[ai][m];
;                 float o[8];
; #pragma unroll
;                 for (int n = 0; n < 2; ++n)
; #pragma unroll
;                     for (int j = 0; j < 4; ++j) { const float g = acc[ai][0][m][n][j] * rs, up = acc[ai][1][m][n][j] * rs; o[n * 4 + j] = siluf_(g) * up; }
;                 u32x4 w; w.x = pk2(o[0], o[1]); w.y = pk2(o[2], o[3]); w.z = pk2(o[4], o[5]); w.w = pk2(o[6], o[7]);
;                 const int rr = row & (BM - 1);
;                 *(u32x4*)((char*)O + ((size_t)(u.pm * (FF / BK) + (col0 >> 6))) * (2 * HTB) + (rr >> 7) * HTB + lds_byte(rr & 127, col0 & 63)) = w;
;             }
	v_pk_mul_f32 v[136:137], v[142:143], v[136:137]
	v_mul_f32_e32 v131, 0xbfb8aa3b, v140
	v_exp_f32_e32 v131, v131
	v_cvt_pk_bf16_f32 v135, v136, v137
	v_add_f32_e32 v131, 1.0, v131
	v_rcp_f32_e32 v142, v131
	v_pk_mul_f32 v[144:145], v[26:27], v[130:131] op_sel_hi:[1,0]
	v_mov_b64_e32 v[26:27], 0
	v_mul_f32_e32 v131, 0xbfb8aa3b, v141
	v_exp_f32_e32 v131, v131
	s_nop 0
	v_add_f32_e32 v131, 1.0, v131
	v_rcp_f32_e32 v143, v131
	s_nop 0
	v_pk_mul_f32 v[140:141], v[140:141], v[142:143]
	v_pk_mul_f32 v[142:143], v[60:61], v[130:131] op_sel_hi:[1,0]
	v_mov_b64_e32 v[60:61], 0
	v_pk_mul_f32 v[140:141], v[144:145], v[140:141]
	v_mul_f32_e32 v131, 0xbfb8aa3b, v142
	v_mul_f32_e32 v133, 0xbfb8aa3b, v143
	v_exp_f32_e32 v131, v131
	v_exp_f32_e32 v133, v133
	v_cvt_pk_bf16_f32 v136, v140, v141
	v_pk_mul_f32 v[140:141], v[24:25], v[166:167] op_sel_hi:[1,0]
	v_mov_b64_e32 v[24:25], 0
	v_add_f32_e32 v131, 1.0, v131
	v_add_f32_e32 v133, 1.0, v133
	v_rcp_f32_e32 v144, v131
	v_rcp_f32_e32 v145, v133
	v_pk_mul_f32 v[130:131], v[28:29], v[130:131] op_sel_hi:[1,0]
	v_mov_b64_e32 v[28:29], 0
	v_pk_mul_f32 v[142:143], v[142:143], v[144:145]
	s_nop 0
	v_pk_mul_f32 v[130:131], v[130:131], v[142:143]
	v_pk_mul_f32 v[142:143], v[18:19], v[166:167] op_sel_hi:[1,0]
	v_mov_b64_e32 v[18:19], 0
	v_cvt_pk_bf16_f32 v137, v130, v131
	v_lshl_add_u64 v[130:131], s[46:47], 0, v[152:153]
	global_store_dwordx4 v[130:131], v[134:137], off nt
	v_pk_mul_f32 v[130:131], v[54:55], v[166:167] op_sel_hi:[1,0]
	v_mov_b64_e32 v[54:55], 0
	v_pk_mul_f32 v[144:145], v[20:21], v[166:167] op_sel_hi:[1,0]
	v_mov_b64_e32 v[20:21], 0
	v_mul_f32_e32 v133, 0xbfb8aa3b, v130
	v_exp_f32_e32 v133, v133
	v_pk_mul_f32 v[136:137], v[22:23], v[166:167] op_sel_hi:[1,0]
	v_mov_b64_e32 v[22:23], 0
	v_add_f32_e32 v133, 1.0, v133
	v_rcp_f32_e32 v134, v133
	v_mul_f32_e32 v133, 0xbfb8aa3b, v131
	v_exp_f32_e32 v133, v133
	s_nop 0
	v_add_f32_e32 v133, 1.0, v133
	v_rcp_f32_e32 v135, v133
	s_nop 0
	v_pk_mul_f32 v[130:131], v[130:131], v[134:135]
	v_pk_mul_f32 v[134:135], v[56:57], v[166:167] op_sel_hi:[1,0]
	v_mov_b64_e32 v[56:57], 0
	v_pk_mul_f32 v[130:131], v[136:137], v[130:131]
	v_mul_f32_e32 v133, 0xbfb8aa3b, v134
	v_exp_f32_e32 v133, v133
	s_nop 0
	v_add_f32_e32 v133, 1.0, v133
	v_rcp_f32_e32 v136, v133
	v_mul_f32_e32 v133, 0xbfb8aa3b, v135
	v_exp_f32_e32 v133, v133
	s_nop 0
	v_add_f32_e32 v133, 1.0, v133
	v_rcp_f32_e32 v137, v133
	s_nop 0
	v_pk_mul_f32 v[134:135], v[134:135], v[136:137]
	s_nop 0
	v_pk_mul_f32 v[136:137], v[140:141], v[134:135]
	v_pk_mul_f32 v[134:135], v[50:51], v[166:167] op_sel_hi:[1,0]
	v_mov_b64_e32 v[50:51], 0
	s_nop 0
	v_mul_f32_e32 v133, 0xbfb8aa3b, v134
	v_exp_f32_e32 v133, v133
	s_nop 0
	v_add_f32_e32 v133, 1.0, v133
	v_rcp_f32_e32 v140, v133
	v_mul_f32_e32 v133, 0xbfb8aa3b, v135
	v_exp_f32_e32 v133, v133
	s_nop 0
	v_add_f32_e32 v133, 1.0, v133
	v_rcp_f32_e32 v141, v133
	s_nop 0
	v_pk_mul_f32 v[134:135], v[134:135], v[140:141]
	s_nop 0
	v_pk_mul_f32 v[140:141], v[142:143], v[134:135]
	v_pk_mul_f32 v[134:135], v[52:53], v[166:167] op_sel_hi:[1,0]
	v_mov_b64_e32 v[52:53], 0
	s_nop 0
	v_mul_f32_e32 v133, 0xbfb8aa3b, v134
	v_exp_f32_e32 v133, v133
	s_nop 0
	v_add_f32_e32 v133, 1.0, v133
	v_rcp_f32_e32 v142, v133
	v_mul_f32_e32 v133, 0xbfb8aa3b, v135
	v_exp_f32_e32 v133, v133
	s_nop 0
	v_add_f32_e32 v133, 1.0, v133
	v_rcp_f32_e32 v143, v133
	s_nop 0
	v_pk_mul_f32 v[134:135], v[134:135], v[142:143]
	s_nop 0
	v_pk_mul_f32 v[142:143], v[144:145], v[134:135]
	v_cvt_pk_bf16_f32 v134, v130, v131
	v_cvt_pk_bf16_f32 v135, v136, v137
	v_cvt_pk_bf16_f32 v136, v140, v141
	v_cvt_pk_bf16_f32 v137, v142, v143
	v_lshl_add_u64 v[130:131], s[46:47], 0, v[156:157]
	global_store_dwordx4 v[130:131], v[134:137], off nt
	v_pk_mul_f32 v[130:131], v[46:47], v[132:133] op_sel_hi:[1,0]
	v_mov_b64_e32 v[46:47], 0
	s_nop 0
	v_mul_f32_e32 v133, 0xbfb8aa3b, v130
	v_exp_f32_e32 v133, v133
	s_nop 0
	v_add_f32_e32 v133, 1.0, v133
	v_rcp_f32_e32 v134, v133
	v_pk_mul_f32 v[136:137], v[14:15], v[132:133] op_sel_hi:[1,0]
	v_mov_b64_e32 v[14:15], 0
	v_mul_f32_e32 v133, 0xbfb8aa3b, v131
	v_exp_f32_e32 v133, v133
	s_nop 0
	v_add_f32_e32 v133, 1.0, v133
	v_rcp_f32_e32 v135, v133
	s_nop 0
	v_pk_mul_f32 v[130:131], v[130:131], v[134:135]
	v_pk_mul_f32 v[134:135], v[48:49], v[132:133] op_sel_hi:[1,0]
; __device__ __forceinline__ unsigned pk2(float lo, float hi) { f32x2_t v = {lo, hi}; bf16x2_t b = __builtin_convertvector(v, bf16x2_t); return __builtin_bit_cast(unsigned, b); }
; __device__ __forceinline__ float siluf_(float x) { return x * sigmoidf_(x); }
;     __device__ __forceinline__ void operator()(Acc& acc, const Unit& u, int wr, int wc, int fr, int fq, const float (&rsa)[2][4]) const {
;         const int row0 = u.pm * BM + wr * 64 + fr, col0 = u.pn * HALF + wc * 32 + 8 * fq;
; #pragma unroll
;         for (int ai = 0; ai < 2; ++ai)
; #pragma unroll
;             for (int m = 0; m < 4; ++m) {
;                 const int row = row0 + ai * HALF + m * 16; const float rs = rsa[ai][m];
;                 float o[8];
; #pragma unroll
;                 for (int n = 0; n < 2; ++n)
; #pragma unroll
;                     for (int j = 0; j < 4; ++j) { const float g = acc[ai][0][m][n][j] * rs, up = acc[ai][1][m][n][j] * rs; o[n * 4 + j] = siluf_(g) * up; }
;                 u32x4 w; w.x = pk2(o[0], o[1]); w.y = pk2(o[2], o[3]); w.z = pk2(o[4], o[5]); w.w = pk2(o[6], o[7]);
;                 const int rr = row & (BM - 1);
;                 *(u32x4*)((char*)O + ((size_t)(u.pm * (FF / BK) + (col0 >> 6))) * (2 * HTB) + (rr >> 7) * HTB + lds_byte(rr & 127, col0 & 63)) = w;
;             }
	v_mov_b64_e32 v[48:49], 0
	v_pk_mul_f32 v[130:131], v[136:137], v[130:131]
	v_mul_f32_e32 v133, 0xbfb8aa3b, v134
	v_exp_f32_e32 v133, v133
	v_cvt_pk_bf16_f32 v130, v130, v131
	v_add_f32_e32 v133, 1.0, v133
	v_rcp_f32_e32 v136, v133
	v_pk_mul_f32 v[140:141], v[16:17], v[132:133] op_sel_hi:[1,0]
	v_mov_b64_e32 v[16:17], 0
	v_mul_f32_e32 v133, 0xbfb8aa3b, v135
	v_exp_f32_e32 v133, v133
	s_nop 0
	v_add_f32_e32 v133, 1.0, v133
	v_rcp_f32_e32 v137, v133
	s_nop 0
	v_pk_mul_f32 v[134:135], v[134:135], v[136:137]
	v_pk_mul_f32 v[136:137], v[42:43], v[132:133] op_sel_hi:[1,0]
	v_mov_b64_e32 v[42:43], 0
	v_pk_mul_f32 v[134:135], v[140:141], v[134:135]
	v_mul_f32_e32 v133, 0xbfb8aa3b, v136
	v_exp_f32_e32 v133, v133
	v_cvt_pk_bf16_f32 v131, v134, v135
	v_lshl_add_u64 v[134:135], s[46:47], 0, v[158:159]
	v_add_f32_e32 v133, 1.0, v133
	v_rcp_f32_e32 v140, v133
	v_pk_mul_f32 v[142:143], v[10:11], v[132:133] op_sel_hi:[1,0]
	v_mov_b64_e32 v[10:11], 0
	v_mul_f32_e32 v133, 0xbfb8aa3b, v137
	v_exp_f32_e32 v133, v133
	s_nop 0
	v_add_f32_e32 v133, 1.0, v133
	v_rcp_f32_e32 v141, v133
	s_nop 0
	v_pk_mul_f32 v[136:137], v[136:137], v[140:141]
	v_pk_mul_f32 v[140:141], v[44:45], v[132:133] op_sel_hi:[1,0]
	v_mov_b64_e32 v[44:45], 0
	v_pk_mul_f32 v[136:137], v[142:143], v[136:137]
	v_mul_f32_e32 v133, 0xbfb8aa3b, v140
	v_mul_f32_e32 v139, 0xbfb8aa3b, v141
	v_exp_f32_e32 v133, v133
	v_exp_f32_e32 v139, v139
	v_add_f32_e32 v133, 1.0, v133
	v_add_f32_e32 v139, 1.0, v139
	v_rcp_f32_e32 v142, v133
	v_rcp_f32_e32 v143, v139
	v_pk_mul_f32 v[132:133], v[12:13], v[132:133] op_sel_hi:[1,0]
	v_mov_b64_e32 v[12:13], 0
	v_pk_mul_f32 v[140:141], v[140:141], v[142:143]
	s_nop 0
	v_pk_mul_f32 v[140:141], v[132:133], v[140:141]
	v_cvt_pk_bf16_f32 v132, v136, v137
	v_cvt_pk_bf16_f32 v133, v140, v141
	global_store_dwordx4 v[134:135], v[130:133], off nt
	v_pk_mul_f32 v[134:135], v[6:7], v[138:139] op_sel_hi:[1,0]
	v_mov_b64_e32 v[6:7], 0
	v_pk_mul_f32 v[136:137], v[8:9], v[138:139] op_sel_hi:[1,0]
	v_mov_b64_e32 v[8:9], 0
	v_pk_mul_f32 v[130:131], v[38:39], v[138:139] op_sel_hi:[1,0]
	v_mov_b64_e32 v[38:39], 0
	v_pk_mul_f32 v[140:141], v[2:3], v[138:139] op_sel_hi:[1,0]
	v_mov_b64_e32 v[2:3], 0
	v_mul_f32_e32 v132, 0xbfb8aa3b, v130
	v_mul_f32_e32 v133, 0xbfb8aa3b, v131
	v_exp_f32_e32 v132, v132
	v_exp_f32_e32 v133, v133
	v_add_f32_e32 v132, 1.0, v132
	v_add_f32_e32 v133, 1.0, v133
	v_rcp_f32_e32 v132, v132
	v_rcp_f32_e32 v133, v133
	s_nop 0
	v_pk_mul_f32 v[130:131], v[130:131], v[132:133]
	v_pk_mul_f32 v[132:133], v[40:41], v[138:139] op_sel_hi:[1,0]
	v_mov_b64_e32 v[40:41], 0
	v_pk_mul_f32 v[130:131], v[134:135], v[130:131]
	v_mul_f32_e32 v134, 0xbfb8aa3b, v132
	v_mul_f32_e32 v135, 0xbfb8aa3b, v133
	v_exp_f32_e32 v134, v134
	v_exp_f32_e32 v135, v135
	v_cvt_pk_bf16_f32 v130, v130, v131
	v_add_f32_e32 v134, 1.0, v134
	v_add_f32_e32 v135, 1.0, v135
	v_rcp_f32_e32 v134, v134
	v_rcp_f32_e32 v135, v135
	s_nop 0
	v_pk_mul_f32 v[132:133], v[132:133], v[134:135]
	v_pk_mul_f32 v[134:135], v[34:35], v[138:139] op_sel_hi:[1,0]
	v_mov_b64_e32 v[34:35], 0
	v_pk_mul_f32 v[132:133], v[136:137], v[132:133]
	v_mul_f32_e32 v136, 0xbfb8aa3b, v134
	v_mul_f32_e32 v137, 0xbfb8aa3b, v135
	v_exp_f32_e32 v136, v136
	v_exp_f32_e32 v137, v137
	v_cvt_pk_bf16_f32 v131, v132, v133
	v_add_f32_e32 v136, 1.0, v136
	v_add_f32_e32 v137, 1.0, v137
	v_rcp_f32_e32 v136, v136
	v_rcp_f32_e32 v137, v137
	s_nop 0
	v_pk_mul_f32 v[134:135], v[134:135], v[136:137]
	v_pk_mul_f32 v[136:137], v[36:37], v[138:139] op_sel_hi:[1,0]
	v_mov_b64_e32 v[36:37], 0
	v_pk_mul_f32 v[134:135], v[140:141], v[134:135]
	v_mul_f32_e32 v139, 0xbfb8aa3b, v136
	v_mul_f32_e32 v141, 0xbfb8aa3b, v137
	v_exp_f32_e32 v139, v139
	v_exp_f32_e32 v141, v141
	v_cvt_pk_bf16_f32 v132, v134, v135
	v_lshl_add_u64 v[134:135], s[46:47], 0, v[160:161]
	v_add_f32_e32 v139, 1.0, v139
	v_add_f32_e32 v141, 1.0, v141
	v_rcp_f32_e32 v140, v139
	v_rcp_f32_e32 v141, v141
	v_pk_mul_f32 v[138:139], v[4:5], v[138:139] op_sel_hi:[1,0]
	v_mov_b64_e32 v[4:5], 0
	v_pk_mul_f32 v[136:137], v[136:137], v[140:141]
	s_nop 0
	v_pk_mul_f32 v[136:137], v[138:139], v[136:137]
	s_nop 0
	v_cvt_pk_bf16_f32 v133, v136, v137
	global_store_dwordx4 v[134:135], v[130:133], off nt
	s_cbranch_vccnz .LBB0_398
	s_andn2_b64 vcc, exec, s[26:27]
	s_cbranch_vccnz .Lp1_nz
	s_barrier

; __device__ __forceinline__ unsigned pk2(float lo, float hi) { f32x2_t v = {lo, hi}; bf16x2_t b = __builtin_convertvector(v, bf16x2_t); return __builtin_bit_cast(unsigned, b); }
; __device__ __forceinline__ float bflo(unsigned w) { return __uint_as_float(w << 16); }
; __device__ __forceinline__ float bfhi(unsigned w) { return __uint_as_float(w & 0xffff0000u); }
;     __device__ __forceinline__ void operator()(Acc& acc, const Unit& u, int wr, int wc, int fr, int fq) const {
;     ...
;         u32x4 rb[2][4][2];
;         if (RES_BF16) {
; #pragma unroll
;             for (int ai = 0; ai < 2; ++ai)
; #pragma unroll
;                 for (int m = 0; m < 4; ++m)
; #pragma unroll
;                     for (int bj = 0; bj < 2; ++bj) rb[ai][m][bj] = *(const u32x4*)((const char*)XBo + xb_piece(u.pm, u.pn, wr, wc, ai, m, bj) + xlo);
;         }
; #pragma unroll
;         for (int ai = 0; ai < 2; ++ai)
; #pragma unroll
;             for (int m = 0; m < 4; ++m) {
;                 const int row = u.pm * BM + ai * HALF + wr * 64 + m * 16 + fr;
;                 float ss = 0.f;
; #pragma unroll
;                 for (int bj = 0; bj < 2; ++bj) {
;                     const size_t off = (size_t)row * D + col0 + bj * HALF;
;                     f32x4 r0, r1;
;                     if (RES_BF16) { const u32x4 q = rb[ai][m][bj]; r0 = (f32x4){bflo(q.x), bfhi(q.x), bflo(q.y), bfhi(q.y)}; r1 = (f32x4){bflo(q.z), bfhi(q.z), bflo(q.w), bfhi(q.w)}; }
;                     else { r0 = *(const f32x4*)(res_f32 + off); r1 = *(const f32x4*)(res_f32 + off + 4); }
;                     const f32x4 v0 = r0 + acc[ai][bj][m][0] * alpha, v1 = r1 + acc[ai][bj][m][1] * alpha;
;                     u32x4 w; w.x = pk2(v0[0], v0[1]); w.y = pk2(v0[2], v0[3]); w.z = pk2(v1[0], v1[1]); w.w = pk2(v1[2], v1[3]);
;                     *(u32x4*)((char*)XBo + xb_piece(u.pm, u.pn, wr, wc, ai, m, bj) + xlo) = w;
;                     ss += (v0[0] * v0[0] + v0[1] * v0[1]) + (v0[2] * v0[2] + v0[3] * v0[3]) + (v1[0] * v1[0] + v1[1] * v1[1]) + (v1[2] * v1[2] + v1[3] * v1[3]);
;                 }
;                 ss += __shfl_xor(ss, 16); ss += __shfl_xor(ss, 32);
;                 if (ssqp && fq == 0) ssqp[(size_t)row * 16 + u.pn * 4 + wc] = ss;
;                 if (!RES_BF16 && (m & 1)) asm volatile("" ::: "memory");
.LBB0_543:
	s_lshl_b32 s51, s60, 4
	s_lshl_b32 s50, s26, 2
	s_add_i32 s51, s51, s50
	s_or_b32 s52, s51, s69
	s_ashr_i32 s53, s52, 31
	s_lshl_b64 s[54:55], s[52:53], 15
	v_lshl_add_u64 v[98:99], v[202:203], 0, s[54:55]
	global_load_dwordx4 v[190:193], v[98:99], off
	s_or_b32 s52, s52, 2
	s_ashr_i32 s53, s52, 31
	s_lshl_b64 s[52:53], s[52:53], 15
	v_lshl_add_u64 v[100:101], v[202:203], 0, s[52:53]
	global_load_dwordx4 v[186:189], v[100:101], off
	global_load_dwordx4 v[182:185], v[98:99], off offset:2048
	global_load_dwordx4 v[178:181], v[100:101], off offset:2048
	v_lshl_add_u64 v[98:99], v[204:205], 0, s[54:55]
	global_load_dwordx4 v[174:177], v[98:99], off
	v_lshl_add_u64 v[98:99], v[204:205], 0, s[52:53]
	global_load_dwordx4 v[170:173], v[98:99], off
	v_lshl_add_u64 v[98:99], v[206:207], 0, s[54:55]
	global_load_dwordx4 v[166:169], v[98:99], off
	v_lshl_add_u64 v[98:99], v[206:207], 0, s[52:53]
	global_load_dwordx4 v[154:157], v[98:99], off
	v_lshl_add_u64 v[98:99], v[208:209], 0, s[54:55]
	global_load_dwordx4 v[150:153], v[98:99], off
	v_lshl_add_u64 v[98:99], v[208:209], 0, s[52:53]
	global_load_dwordx4 v[146:149], v[98:99], off
	v_lshl_add_u64 v[98:99], v[210:211], 0, s[54:55]
	global_load_dwordx4 v[142:145], v[98:99], off
	v_lshl_add_u64 v[98:99], v[210:211], 0, s[52:53]
	global_load_dwordx4 v[134:137], v[98:99], off
	v_lshl_add_u64 v[98:99], v[212:213], 0, s[54:55]
	global_load_dwordx4 v[126:129], v[98:99], off
	v_lshl_add_u64 v[98:99], v[212:213], 0, s[52:53]
	global_load_dwordx4 v[122:125], v[98:99], off
	v_lshl_add_u64 v[98:99], v[214:215], 0, s[54:55]
	global_load_dwordx4 v[110:113], v[98:99], off
	v_lshl_add_u64 v[98:99], v[214:215], 0, s[52:53]
	global_load_dwordx4 v[98:101], v[98:99], off
	v_and_b32_e32 v243, 64, v241
	v_xor_b32_e32 v242, 16, v241
	v_add_u32_e32 v243, 64, v243
	v_cmp_lt_i32_e32 vcc, v242, v243
	v_xor_b32_e32 v244, 32, v241
	s_add_u32 s54, s14, s54
	v_cndmask_b32_e32 v242, v241, v242, vcc
	v_cmp_lt_i32_e32 vcc, v244, v243
	s_addc_u32 s55, s15, s55
	s_add_u32 s78, s54, s42
	v_cndmask_b32_e32 v243, v241, v244, vcc
	s_addc_u32 s79, s55, s43
	v_lshlrev_b32_e32 v242, 2, v242
	v_lshlrev_b32_e32 v243, 2, v243
	s_waitcnt vmcnt(15)
	v_lshlrev_b32_e32 v244, 16, v190
	v_and_b32_e32 v245, 0xffff0000, v190
	v_lshlrev_b32_e32 v190, 16, v191
	v_and_b32_e32 v191, 0xffff0000, v191
	v_lshlrev_b32_e32 v246, 16, v192
	v_and_b32_e32 v247, 0xffff0000, v192
	v_lshlrev_b32_e32 v192, 16, v193
	v_and_b32_e32 v193, 0xffff0000, v193
	v_pk_fma_f32 v[164:165], v[164:165], 0.5, v[190:191] op_sel_hi:[1,0,1]
	v_pk_fma_f32 v[190:191], v[162:163], 0.5, v[244:245] op_sel_hi:[1,0,1]
	v_pk_fma_f32 v[192:193], v[160:161], 0.5, v[192:193] op_sel_hi:[1,0,1]
	v_pk_fma_f32 v[244:245], v[158:159], 0.5, v[246:247] op_sel_hi:[1,0,1]
	v_cvt_pk_bf16_f32 v160, v190, v191
	v_cvt_pk_bf16_f32 v161, v164, v165
	v_cvt_pk_bf16_f32 v162, v244, v245
	v_cvt_pk_bf16_f32 v163, v192, v193
	v_lshl_add_u64 v[158:159], s[78:79], 0, v[200:201]
	global_store_dwordx4 v[158:159], v[160:163], off nt
	s_add_u32 s78, s14, s52
	s_addc_u32 s79, s15, s53
	v_mul_f32_e32 v160, v191, v191
	v_mul_f32_e32 v161, v165, v165
	v_fmac_f32_e32 v160, v190, v190
	v_fmac_f32_e32 v161, v164, v164
	v_add_f32_e32 v160, v160, v161
	v_mul_f32_e32 v161, v245, v245
	v_fmac_f32_e32 v161, v244, v244
	v_add_f32_e32 v160, v161, v160
	v_mul_f32_e32 v161, v193, v193
	v_fmac_f32_e32 v161, v192, v192
	v_add_f32_e32 v190, v161, v160
	s_waitcnt vmcnt(15)
	v_lshlrev_b32_e32 v160, 16, v186
	v_and_b32_e32 v161, 0xffff0000, v186
	v_lshlrev_b32_e32 v162, 16, v187
	v_and_b32_e32 v163, 0xffff0000, v187
	v_lshlrev_b32_e32 v164, 16, v188
	v_and_b32_e32 v165, 0xffff0000, v188
	v_lshlrev_b32_e32 v186, 16, v189
	v_and_b32_e32 v187, 0xffff0000, v189
	s_add_u32 s52, s78, s42
	v_pk_fma_f32 v[162:163], v[140:141], 0.5, v[162:163] op_sel_hi:[1,0,1]
	v_pk_fma_f32 v[160:161], v[138:139], 0.5, v[160:161] op_sel_hi:[1,0,1]
	v_pk_fma_f32 v[132:133], v[132:133], 0.5, v[186:187] op_sel_hi:[1,0,1]
	v_pk_fma_f32 v[164:165], v[130:131], 0.5, v[164:165] op_sel_hi:[1,0,1]
	s_addc_u32 s53, s79, s43
	v_cvt_pk_bf16_f32 v138, v160, v161
	v_cvt_pk_bf16_f32 v139, v162, v163
	v_cvt_pk_bf16_f32 v140, v164, v165
	v_cvt_pk_bf16_f32 v141, v132, v133
	v_lshl_add_u64 v[130:131], s[52:53], 0, v[200:201]
	global_store_dwordx4 v[130:131], v[138:141], off nt
	v_mul_f32_e32 v133, v133, v133
	v_fmac_f32_e32 v133, v132, v132
	v_mul_f32_e32 v138, v161, v161
	v_mul_f32_e32 v139, v163, v163
	v_fmac_f32_e32 v138, v160, v160
	v_fmac_f32_e32 v139, v162, v162
	v_add_f32_e32 v138, v138, v139
	v_mul_f32_e32 v139, v165, v165
	v_fmac_f32_e32 v139, v164, v164
	v_add_f32_e32 v138, v139, v138
	v_add_f32_e32 v132, v133, v138
	v_add_f32_e32 v132, v190, v132
	ds_bpermute_b32 v133, v242, v132
	s_waitcnt lgkmcnt(0)
	v_add_f32_e32 v132, v132, v133
	ds_bpermute_b32 v133, v243, v132
	s_and_saveexec_b64 s[52:53], s[4:5]
	s_cbranch_execz .LBB0_545
	v_lshl_add_u32 v138, s60, 8, v229
	v_ashrrev_i32_e32 v139, 31, v138
	s_waitcnt lgkmcnt(0)
	v_add_f32_e32 v140, v132, v133
	v_lshlrev_b64 v[132:133], 6, v[138:139]
	s_ashr_i32 s51, s50, 31
	v_lshl_add_u64 v[132:133], s[30:31], 0, v[132:133]
	v_lshl_add_u64 v[132:133], s[50:51], 2, v[132:133]
	s_lshl_b32 s26, s66, 2
	v_lshl_add_u64 v[132:133], v[132:133], 0, s[26:27]
	global_store_dword v[132:133], v140, off
; __device__ __forceinline__ unsigned pk2(float lo, float hi) { f32x2_t v = {lo, hi}; bf16x2_t b = __builtin_convertvector(v, bf16x2_t); return __builtin_bit_cast(unsigned, b); }
; __device__ __forceinline__ float bflo(unsigned w) { return __uint_as_float(w << 16); }
; __device__ __forceinline__ float bfhi(unsigned w) { return __uint_as_float(w & 0xffff0000u); }
;     __device__ __forceinline__ void operator()(Acc& acc, const Unit& u, int wr, int wc, int fr, int fq) const {
;     ...
; #pragma unroll
;         for (int ai = 0; ai < 2; ++ai)
; #pragma unroll
;             for (int m = 0; m < 4; ++m) {
;                 const int row = u.pm * BM + ai * HALF + wr * 64 + m * 16 + fr;
;                 float ss = 0.f;
; #pragma unroll
;                 for (int bj = 0; bj < 2; ++bj) {
;                     const size_t off = (size_t)row * D + col0 + bj * HALF;
;                     f32x4 r0, r1;
;                     if (RES_BF16) { const u32x4 q = rb[ai][m][bj]; r0 = (f32x4){bflo(q.x), bfhi(q.x), bflo(q.y), bfhi(q.y)}; r1 = (f32x4){bflo(q.z), bfhi(q.z), bflo(q.w), bfhi(q.w)}; }
;                     else { r0 = *(const f32x4*)(res_f32 + off); r1 = *(const f32x4*)(res_f32 + off + 4); }
;                     const f32x4 v0 = r0 + acc[ai][bj][m][0] * alpha, v1 = r1 + acc[ai][bj][m][1] * alpha;
;                     u32x4 w; w.x = pk2(v0[0], v0[1]); w.y = pk2(v0[2], v0[3]); w.z = pk2(v1[0], v1[1]); w.w = pk2(v1[2], v1[3]);
;                     *(u32x4*)((char*)XBo + xb_piece(u.pm, u.pn, wr, wc, ai, m, bj) + xlo) = w;
;                     ss += (v0[0] * v0[0] + v0[1] * v0[1]) + (v0[2] * v0[2] + v0[3] * v0[3]) + (v1[0] * v1[0] + v1[1] * v1[1]) + (v1[2] * v1[2] + v1[3] * v1[3]);
;                 }
;                 ss += __shfl_xor(ss, 16); ss += __shfl_xor(ss, 32);
;                 if (ssqp && fq == 0) ssqp[(size_t)row * 16 + u.pn * 4 + wc] = ss;
;                 if (!RES_BF16 && (m & 1)) asm volatile("" ::: "memory");
.LBB0_545:
	s_or_b64 exec, exec, s[52:53]
	s_waitcnt vmcnt(15)
	v_lshlrev_b32_e32 v132, 16, v182
	s_waitcnt lgkmcnt(0)
	v_and_b32_e32 v133, 0xffff0000, v182
	v_lshlrev_b32_e32 v138, 16, v183
	v_and_b32_e32 v139, 0xffff0000, v183
	v_lshlrev_b32_e32 v140, 16, v184
	v_and_b32_e32 v141, 0xffff0000, v184
	v_lshlrev_b32_e32 v160, 16, v185
	v_and_b32_e32 v161, 0xffff0000, v185
	v_pk_fma_f32 v[118:119], v[118:119], 0.5, v[132:133] op_sel_hi:[1,0,1]
	v_pk_fma_f32 v[120:121], v[120:121], 0.5, v[138:139] op_sel_hi:[1,0,1]
	v_pk_fma_f32 v[132:133], v[116:117], 0.5, v[160:161] op_sel_hi:[1,0,1]
	v_pk_fma_f32 v[116:117], v[114:115], 0.5, v[140:141] op_sel_hi:[1,0,1]
	v_cvt_pk_bf16_f32 v114, v118, v119
	v_mul_f32_e32 v119, v119, v119
	v_fmac_f32_e32 v119, v118, v118
	v_mul_f32_e32 v118, v121, v121
	v_fmac_f32_e32 v118, v120, v120
	v_add_f32_e32 v118, v119, v118
	v_mul_f32_e32 v119, v117, v117
	v_fmac_f32_e32 v119, v116, v116
	v_add_f32_e32 v118, v119, v118
	v_mul_f32_e32 v119, v133, v133
	v_fmac_f32_e32 v119, v132, v132
	v_cvt_pk_bf16_f32 v115, v120, v121
	v_add_f32_e32 v160, v119, v118
	s_waitcnt vmcnt(14)
	v_lshlrev_b32_e32 v118, 16, v178
	v_and_b32_e32 v119, 0xffff0000, v178
	v_lshlrev_b32_e32 v120, 16, v179
	v_and_b32_e32 v121, 0xffff0000, v179
	v_lshlrev_b32_e32 v138, 16, v180
	v_and_b32_e32 v139, 0xffff0000, v180
	v_pk_fma_f32 v[108:109], v[108:109], 0.5, v[120:121] op_sel_hi:[1,0,1]
	v_pk_fma_f32 v[106:107], v[106:107], 0.5, v[118:119] op_sel_hi:[1,0,1]
	v_pk_fma_f32 v[120:121], v[102:103], 0.5, v[138:139] op_sel_hi:[1,0,1]
	v_mul_f32_e32 v102, v107, v107
	v_mul_f32_e32 v103, v109, v109
	v_fmac_f32_e32 v102, v106, v106
	v_fmac_f32_e32 v103, v108, v108
	v_lshlrev_b32_e32 v140, 16, v181
	v_and_b32_e32 v141, 0xffff0000, v181
	v_add_f32_e32 v102, v102, v103
	v_mul_f32_e32 v103, v121, v121
	v_pk_fma_f32 v[118:119], v[104:105], 0.5, v[140:141] op_sel_hi:[1,0,1]
	v_fmac_f32_e32 v103, v120, v120
	v_add_f32_e32 v102, v103, v102
	v_mul_f32_e32 v103, v119, v119
	v_fmac_f32_e32 v103, v118, v118
	v_add_f32_e32 v102, v103, v102
	v_add_f32_e32 v102, v160, v102
	ds_bpermute_b32 v103, v242, v102
	v_cvt_pk_bf16_f32 v116, v116, v117
	v_cvt_pk_bf16_f32 v117, v132, v133
	v_cvt_pk_bf16_f32 v104, v106, v107
	v_cvt_pk_bf16_f32 v105, v108, v109
	s_waitcnt lgkmcnt(0)
	v_add_f32_e32 v102, v102, v103
	ds_bpermute_b32 v103, v243, v102
	v_cvt_pk_bf16_f32 v106, v120, v121
	v_cvt_pk_bf16_f32 v107, v118, v119
	global_store_dwordx4 v[158:159], v[114:117], off offset:2048 nt
	global_store_dwordx4 v[130:131], v[104:107], off offset:2048 nt
	s_and_saveexec_b64 s[52:53], s[4:5]
	s_cbranch_execz .LBB0_547
	v_lshl_add_u32 v104, s60, 8, v231
	v_ashrrev_i32_e32 v105, 31, v104
	s_waitcnt lgkmcnt(0)
	v_add_f32_e32 v106, v102, v103
	v_lshlrev_b64 v[102:103], 6, v[104:105]
	s_ashr_i32 s51, s50, 31
	v_lshl_add_u64 v[102:103], s[30:31], 0, v[102:103]
	v_lshl_add_u64 v[102:103], s[50:51], 2, v[102:103]
	s_lshl_b32 s26, s66, 2
	v_lshl_add_u64 v[102:103], v[102:103], 0, s[26:27]
	global_store_dword v[102:103], v106, off
.LBB0_547:
	s_or_b64 exec, exec, s[52:53]
	s_waitcnt vmcnt(15)
	v_lshlrev_b32_e32 v102, 16, v174
	s_waitcnt lgkmcnt(0)
	v_and_b32_e32 v103, 0xffff0000, v174
	v_lshlrev_b32_e32 v104, 16, v175
	v_and_b32_e32 v105, 0xffff0000, v175
	v_lshlrev_b32_e32 v106, 16, v176
	v_and_b32_e32 v107, 0xffff0000, v176
	v_lshlrev_b32_e32 v108, 16, v177
	v_and_b32_e32 v109, 0xffff0000, v177
	s_add_u32 s52, s54, s46
	v_pk_fma_f32 v[96:97], v[96:97], 0.5, v[104:105] op_sel_hi:[1,0,1]
	v_pk_fma_f32 v[94:95], v[94:95], 0.5, v[102:103] op_sel_hi:[1,0,1]
	v_pk_fma_f32 v[102:103], v[92:93], 0.5, v[108:109] op_sel_hi:[1,0,1]
	v_pk_fma_f32 v[104:105], v[90:91], 0.5, v[106:107] op_sel_hi:[1,0,1]
	s_addc_u32 s53, s55, s47
	v_cvt_pk_bf16_f32 v90, v94, v95
	v_cvt_pk_bf16_f32 v91, v96, v97
	v_cvt_pk_bf16_f32 v92, v104, v105
	v_cvt_pk_bf16_f32 v93, v102, v103
	v_lshl_add_u64 v[106:107], s[52:53], 0, v[200:201]
	global_store_dwordx4 v[106:107], v[90:93], off nt
	s_add_u32 s52, s78, s46
	s_addc_u32 s53, s79, s47
	v_mul_f32_e32 v90, v95, v95
	v_mul_f32_e32 v91, v97, v97
	v_fmac_f32_e32 v90, v94, v94
	v_fmac_f32_e32 v91, v96, v96
	v_add_f32_e32 v90, v90, v91
	v_mul_f32_e32 v91, v105, v105
	v_fmac_f32_e32 v91, v104, v104
	v_add_f32_e32 v90, v91, v90
	v_mul_f32_e32 v91, v103, v103
	v_fmac_f32_e32 v91, v102, v102
	v_add_f32_e32 v102, v91, v90
	s_waitcnt vmcnt(15)
	v_lshlrev_b32_e32 v90, 16, v170
	v_and_b32_e32 v91, 0xffff0000, v170
	v_lshlrev_b32_e32 v92, 16, v171
	v_and_b32_e32 v93, 0xffff0000, v171
	v_lshlrev_b32_e32 v96, 16, v173
	v_and_b32_e32 v97, 0xffff0000, v173
	v_pk_fma_f32 v[88:89], v[88:89], 0.5, v[92:93] op_sel_hi:[1,0,1]
	v_pk_fma_f32 v[86:87], v[86:87], 0.5, v[90:91] op_sel_hi:[1,0,1]
	v_lshlrev_b32_e32 v94, 16, v172
	v_and_b32_e32 v95, 0xffff0000, v172
	v_pk_fma_f32 v[90:91], v[84:85], 0.5, v[96:97] op_sel_hi:[1,0,1]
	v_mul_f32_e32 v84, v87, v87
	v_mul_f32_e32 v85, v89, v89
	v_pk_fma_f32 v[82:83], v[82:83], 0.5, v[94:95] op_sel_hi:[1,0,1]
	v_fmac_f32_e32 v84, v86, v86
	v_fmac_f32_e32 v85, v88, v88
	v_add_f32_e32 v84, v84, v85
	v_mul_f32_e32 v85, v83, v83
	v_fmac_f32_e32 v85, v82, v82
	v_add_f32_e32 v84, v85, v84
	v_mul_f32_e32 v85, v91, v91
	v_fmac_f32_e32 v85, v90, v90
	v_add_f32_e32 v84, v85, v84
	v_add_f32_e32 v92, v102, v84
	ds_bpermute_b32 v93, v242, v92
	v_cvt_pk_bf16_f32 v84, v86, v87
	v_cvt_pk_bf16_f32 v86, v82, v83
	v_cvt_pk_bf16_f32 v85, v88, v89
	v_cvt_pk_bf16_f32 v87, v90, v91
	s_waitcnt lgkmcnt(0)
	v_add_f32_e32 v82, v92, v93
	ds_bpermute_b32 v83, v243, v82
	v_lshl_add_u64 v[88:89], s[52:53], 0, v[200:201]
	global_store_dwordx4 v[88:89], v[84:87], off nt
	s_and_saveexec_b64 s[52:53], s[4:5]
	s_cbranch_execz .LBB0_549
	v_lshl_add_u32 v84, s60, 8, v232
	v_ashrrev_i32_e32 v85, 31, v84
	s_waitcnt lgkmcnt(0)
	v_add_f32_e32 v86, v82, v83
	v_lshlrev_b64 v[82:83], 6, v[84:85]
	s_ashr_i32 s51, s50, 31
	v_lshl_add_u64 v[82:83], s[30:31], 0, v[82:83]
	v_lshl_add_u64 v[82:83], s[50:51], 2, v[82:83]
	s_lshl_b32 s26, s66, 2
	v_lshl_add_u64 v[82:83], v[82:83], 0, s[26:27]
	global_store_dword v[82:83], v86, off
; __device__ __forceinline__ unsigned pk2(float lo, float hi) { f32x2_t v = {lo, hi}; bf16x2_t b = __builtin_convertvector(v, bf16x2_t); return __builtin_bit_cast(unsigned, b); }
; __device__ __forceinline__ float bflo(unsigned w) { return __uint_as_float(w << 16); }
; __device__ __forceinline__ float bfhi(unsigned w) { return __uint_as_float(w & 0xffff0000u); }
;     __device__ __forceinline__ void operator()(Acc& acc, const Unit& u, int wr, int wc, int fr, int fq) const {
;     ...
; #pragma unroll
;         for (int ai = 0; ai < 2; ++ai)
; #pragma unroll
;             for (int m = 0; m < 4; ++m) {
;                 const int row = u.pm * BM + ai * HALF + wr * 64 + m * 16 + fr;
;                 float ss = 0.f;
; #pragma unroll
;                 for (int bj = 0; bj < 2; ++bj) {
;                     const size_t off = (size_t)row * D + col0 + bj * HALF;
;                     f32x4 r0, r1;
;                     if (RES_BF16) { const u32x4 q = rb[ai][m][bj]; r0 = (f32x4){bflo(q.x), bfhi(q.x), bflo(q.y), bfhi(q.y)}; r1 = (f32x4){bflo(q.z), bfhi(q.z), bflo(q.w), bfhi(q.w)}; }
;                     else { r0 = *(const f32x4*)(res_f32 + off); r1 = *(const f32x4*)(res_f32 + off + 4); }
;                     const f32x4 v0 = r0 + acc[ai][bj][m][0] * alpha, v1 = r1 + acc[ai][bj][m][1] * alpha;
;                     u32x4 w; w.x = pk2(v0[0], v0[1]); w.y = pk2(v0[2], v0[3]); w.z = pk2(v1[0], v1[1]); w.w = pk2(v1[2], v1[3]);
;                     *(u32x4*)((char*)XBo + xb_piece(u.pm, u.pn, wr, wc, ai, m, bj) + xlo) = w;
;                     ss += (v0[0] * v0[0] + v0[1] * v0[1]) + (v0[2] * v0[2] + v0[3] * v0[3]) + (v1[0] * v1[0] + v1[1] * v1[1]) + (v1[2] * v1[2] + v1[3] * v1[3]);
;                 }
;                 ss += __shfl_xor(ss, 16); ss += __shfl_xor(ss, 32);
;                 if (ssqp && fq == 0) ssqp[(size_t)row * 16 + u.pn * 4 + wc] = ss;
;                 if (!RES_BF16 && (m & 1)) asm volatile("" ::: "memory");
.LBB0_549:
	s_or_b64 exec, exec, s[52:53]
	s_waitcnt vmcnt(15)
	v_lshlrev_b32_e32 v82, 16, v166
	s_waitcnt lgkmcnt(0)
	v_and_b32_e32 v83, 0xffff0000, v166
	v_lshlrev_b32_e32 v84, 16, v167
	v_and_b32_e32 v85, 0xffff0000, v167
	v_lshlrev_b32_e32 v86, 16, v168
	v_and_b32_e32 v87, 0xffff0000, v168
	v_lshlrev_b32_e32 v88, 16, v169
	v_and_b32_e32 v89, 0xffff0000, v169
	s_add_u32 s52, s54, s44
	v_pk_fma_f32 v[80:81], v[80:81], 0.5, v[84:85] op_sel_hi:[1,0,1]
	v_pk_fma_f32 v[78:79], v[78:79], 0.5, v[82:83] op_sel_hi:[1,0,1]
	v_pk_fma_f32 v[82:83], v[76:77], 0.5, v[88:89] op_sel_hi:[1,0,1]
	v_pk_fma_f32 v[84:85], v[74:75], 0.5, v[86:87] op_sel_hi:[1,0,1]
	s_addc_u32 s53, s55, s45
	v_cvt_pk_bf16_f32 v74, v78, v79
	v_cvt_pk_bf16_f32 v75, v80, v81
	v_cvt_pk_bf16_f32 v76, v84, v85
	v_cvt_pk_bf16_f32 v77, v82, v83
	v_lshl_add_u64 v[86:87], s[52:53], 0, v[200:201]
	global_store_dwordx4 v[86:87], v[74:77], off nt
	s_add_u32 s52, s78, s44
	s_addc_u32 s53, s79, s45
	v_mul_f32_e32 v74, v79, v79
	v_mul_f32_e32 v75, v81, v81
	v_fmac_f32_e32 v74, v78, v78
	v_fmac_f32_e32 v75, v80, v80
	v_add_f32_e32 v74, v74, v75
	v_mul_f32_e32 v75, v85, v85
	v_fmac_f32_e32 v75, v84, v84
	v_add_f32_e32 v74, v75, v74
	v_mul_f32_e32 v75, v83, v83
	v_fmac_f32_e32 v75, v82, v82
	v_add_f32_e32 v82, v75, v74
	s_waitcnt vmcnt(15)
	v_lshlrev_b32_e32 v74, 16, v154
	v_and_b32_e32 v75, 0xffff0000, v154
	v_lshlrev_b32_e32 v76, 16, v155
	v_and_b32_e32 v77, 0xffff0000, v155
	v_lshlrev_b32_e32 v80, 16, v157
	v_and_b32_e32 v81, 0xffff0000, v157
	v_pk_fma_f32 v[72:73], v[72:73], 0.5, v[76:77] op_sel_hi:[1,0,1]
	v_pk_fma_f32 v[70:71], v[70:71], 0.5, v[74:75] op_sel_hi:[1,0,1]
	v_lshlrev_b32_e32 v78, 16, v156
	v_and_b32_e32 v79, 0xffff0000, v156
	v_pk_fma_f32 v[74:75], v[68:69], 0.5, v[80:81] op_sel_hi:[1,0,1]
	v_mul_f32_e32 v68, v71, v71
	v_mul_f32_e32 v69, v73, v73
	v_pk_fma_f32 v[66:67], v[66:67], 0.5, v[78:79] op_sel_hi:[1,0,1]
	v_fmac_f32_e32 v68, v70, v70
	v_fmac_f32_e32 v69, v72, v72
	v_add_f32_e32 v68, v68, v69
	v_mul_f32_e32 v69, v67, v67
	v_fmac_f32_e32 v69, v66, v66
	v_add_f32_e32 v68, v69, v68
	v_mul_f32_e32 v69, v75, v75
	v_fmac_f32_e32 v69, v74, v74
	v_add_f32_e32 v68, v69, v68
	v_add_f32_e32 v76, v82, v68
	ds_bpermute_b32 v77, v242, v76
	v_cvt_pk_bf16_f32 v68, v70, v71
	v_cvt_pk_bf16_f32 v70, v66, v67
	v_cvt_pk_bf16_f32 v69, v72, v73
	v_cvt_pk_bf16_f32 v71, v74, v75
	s_waitcnt lgkmcnt(0)
	v_add_f32_e32 v66, v76, v77
	ds_bpermute_b32 v67, v243, v66
	v_lshl_add_u64 v[72:73], s[52:53], 0, v[200:201]
	global_store_dwordx4 v[72:73], v[68:71], off nt
	s_and_saveexec_b64 s[52:53], s[4:5]
	s_cbranch_execz .LBB0_551
	v_lshl_add_u32 v68, s60, 8, v233
	v_ashrrev_i32_e32 v69, 31, v68
	s_waitcnt lgkmcnt(0)
	v_add_f32_e32 v70, v66, v67
	v_lshlrev_b64 v[66:67], 6, v[68:69]
	s_ashr_i32 s51, s50, 31
	v_lshl_add_u64 v[66:67], s[30:31], 0, v[66:67]
	v_lshl_add_u64 v[66:67], s[50:51], 2, v[66:67]
	s_lshl_b32 s26, s66, 2
	v_lshl_add_u64 v[66:67], v[66:67], 0, s[26:27]
	global_store_dword v[66:67], v70, off
.LBB0_551:
	s_or_b64 exec, exec, s[52:53]
	s_waitcnt vmcnt(15)
	v_lshlrev_b32_e32 v66, 16, v150
	s_waitcnt lgkmcnt(0)
	v_and_b32_e32 v67, 0xffff0000, v150
	v_lshlrev_b32_e32 v68, 16, v151
	v_and_b32_e32 v69, 0xffff0000, v151
	v_lshlrev_b32_e32 v70, 16, v152
	v_and_b32_e32 v71, 0xffff0000, v152
	v_lshlrev_b32_e32 v72, 16, v153
	v_and_b32_e32 v73, 0xffff0000, v153
	v_pk_fma_f32 v[64:65], v[64:65], 0.5, v[68:69] op_sel_hi:[1,0,1]
	v_pk_fma_f32 v[66:67], v[62:63], 0.5, v[66:67] op_sel_hi:[1,0,1]
	v_pk_fma_f32 v[68:69], v[60:61], 0.5, v[72:73] op_sel_hi:[1,0,1]
	v_pk_fma_f32 v[70:71], v[58:59], 0.5, v[70:71] op_sel_hi:[1,0,1]
	v_add_co_u32_e32 v58, vcc, s65, v158
	v_cvt_pk_bf16_f32 v60, v66, v67
	v_cvt_pk_bf16_f32 v61, v64, v65
	v_cvt_pk_bf16_f32 v62, v70, v71
	v_cvt_pk_bf16_f32 v63, v68, v69
	v_addc_co_u32_e32 v59, vcc, 0, v159, vcc
	global_store_dwordx4 v[58:59], v[60:63], off nt
	s_nop 1
	v_mul_f32_e32 v60, v67, v67
	v_mul_f32_e32 v61, v65, v65
	v_fmac_f32_e32 v60, v66, v66
	v_fmac_f32_e32 v61, v64, v64
	v_add_f32_e32 v60, v60, v61
	v_mul_f32_e32 v61, v71, v71
	v_fmac_f32_e32 v61, v70, v70
	v_add_f32_e32 v60, v61, v60
	v_mul_f32_e32 v61, v69, v69
	v_fmac_f32_e32 v61, v68, v68
	v_add_f32_e32 v68, v61, v60
	s_waitcnt vmcnt(15)
	v_lshlrev_b32_e32 v60, 16, v146
	v_and_b32_e32 v61, 0xffff0000, v146
	v_lshlrev_b32_e32 v62, 16, v147
	v_and_b32_e32 v63, 0xffff0000, v147
	v_pk_fma_f32 v[56:57], v[56:57], 0.5, v[62:63] op_sel_hi:[1,0,1]
	v_pk_fma_f32 v[54:55], v[54:55], 0.5, v[60:61] op_sel_hi:[1,0,1]
	v_lshlrev_b32_e32 v64, 16, v148
	v_and_b32_e32 v65, 0xffff0000, v148
	v_mul_f32_e32 v60, v55, v55
	v_mul_f32_e32 v61, v57, v57
	v_pk_fma_f32 v[50:51], v[50:51], 0.5, v[64:65] op_sel_hi:[1,0,1]
	v_fmac_f32_e32 v60, v54, v54
	v_fmac_f32_e32 v61, v56, v56
	v_lshlrev_b32_e32 v66, 16, v149
	v_and_b32_e32 v67, 0xffff0000, v149
	v_add_f32_e32 v60, v60, v61
	v_mul_f32_e32 v61, v51, v51
	v_pk_fma_f32 v[52:53], v[52:53], 0.5, v[66:67] op_sel_hi:[1,0,1]
	v_fmac_f32_e32 v61, v50, v50
	v_add_f32_e32 v60, v61, v60
	v_mul_f32_e32 v61, v53, v53
	v_fmac_f32_e32 v61, v52, v52
	v_add_f32_e32 v60, v61, v60
	v_add_f32_e32 v60, v68, v60
	ds_bpermute_b32 v61, v242, v60
	v_cvt_pk_bf16_f32 v54, v54, v55
	v_cvt_pk_bf16_f32 v55, v56, v57
	v_cvt_pk_bf16_f32 v57, v52, v53
	v_cvt_pk_bf16_f32 v56, v50, v51
	s_waitcnt lgkmcnt(0)
	v_add_f32_e32 v52, v60, v61
	ds_bpermute_b32 v53, v243, v52
	v_add_co_u32_e32 v50, vcc, s65, v130
	s_nop 1
	v_addc_co_u32_e32 v51, vcc, 0, v131, vcc
	global_store_dwordx4 v[50:51], v[54:57], off nt
	s_and_saveexec_b64 s[52:53], s[4:5]
	s_cbranch_execz .LBB0_553
	v_lshl_add_u32 v54, s60, 8, v234
	v_ashrrev_i32_e32 v55, 31, v54
	s_waitcnt lgkmcnt(0)
	v_add_f32_e32 v56, v52, v53
	v_lshlrev_b64 v[52:53], 6, v[54:55]
	s_ashr_i32 s51, s50, 31
	v_lshl_add_u64 v[52:53], s[30:31], 0, v[52:53]
	v_lshl_add_u64 v[52:53], s[50:51], 2, v[52:53]
	s_lshl_b32 s26, s66, 2
	v_lshl_add_u64 v[52:53], v[52:53], 0, s[26:27]
	global_store_dword v[52:53], v56, off
; __device__ __forceinline__ unsigned pk2(float lo, float hi) { f32x2_t v = {lo, hi}; bf16x2_t b = __builtin_convertvector(v, bf16x2_t); return __builtin_bit_cast(unsigned, b); }
; __device__ __forceinline__ float bflo(unsigned w) { return __uint_as_float(w << 16); }
; __device__ __forceinline__ float bfhi(unsigned w) { return __uint_as_float(w & 0xffff0000u); }
;     __device__ __forceinline__ void operator()(Acc& acc, const Unit& u, int wr, int wc, int fr, int fq) const {
;     ...
; #pragma unroll
;         for (int ai = 0; ai < 2; ++ai)
; #pragma unroll
;             for (int m = 0; m < 4; ++m) {
;                 const int row = u.pm * BM + ai * HALF + wr * 64 + m * 16 + fr;
;                 float ss = 0.f;
; #pragma unroll
;                 for (int bj = 0; bj < 2; ++bj) {
;                     const size_t off = (size_t)row * D + col0 + bj * HALF;
;                     f32x4 r0, r1;
;                     if (RES_BF16) { const u32x4 q = rb[ai][m][bj]; r0 = (f32x4){bflo(q.x), bfhi(q.x), bflo(q.y), bfhi(q.y)}; r1 = (f32x4){bflo(q.z), bfhi(q.z), bflo(q.w), bfhi(q.w)}; }
;                     else { r0 = *(const f32x4*)(res_f32 + off); r1 = *(const f32x4*)(res_f32 + off + 4); }
;                     const f32x4 v0 = r0 + acc[ai][bj][m][0] * alpha, v1 = r1 + acc[ai][bj][m][1] * alpha;
;                     u32x4 w; w.x = pk2(v0[0], v0[1]); w.y = pk2(v0[2], v0[3]); w.z = pk2(v1[0], v1[1]); w.w = pk2(v1[2], v1[3]);
;                     *(u32x4*)((char*)XBo + xb_piece(u.pm, u.pn, wr, wc, ai, m, bj) + xlo) = w;
;                     ss += (v0[0] * v0[0] + v0[1] * v0[1]) + (v0[2] * v0[2] + v0[3] * v0[3]) + (v1[0] * v1[0] + v1[1] * v1[1]) + (v1[2] * v1[2] + v1[3] * v1[3]);
;                 }
;                 ss += __shfl_xor(ss, 16); ss += __shfl_xor(ss, 32);
;                 if (ssqp && fq == 0) ssqp[(size_t)row * 16 + u.pn * 4 + wc] = ss;
;                 if (!RES_BF16 && (m & 1)) asm volatile("" ::: "memory");
.LBB0_553:
	s_or_b64 exec, exec, s[52:53]
	s_waitcnt vmcnt(15)
	v_lshlrev_b32_e32 v52, 16, v142
	s_waitcnt lgkmcnt(0)
	v_and_b32_e32 v53, 0xffff0000, v142
	v_lshlrev_b32_e32 v54, 16, v143
	v_and_b32_e32 v55, 0xffff0000, v143
	v_lshlrev_b32_e32 v56, 16, v144
	v_and_b32_e32 v57, 0xffff0000, v144
	v_lshlrev_b32_e32 v60, 16, v145
	v_and_b32_e32 v61, 0xffff0000, v145
	v_pk_fma_f32 v[46:47], v[46:47], 0.5, v[52:53] op_sel_hi:[1,0,1]
	v_pk_fma_f32 v[48:49], v[48:49], 0.5, v[54:55] op_sel_hi:[1,0,1]
	v_pk_fma_f32 v[52:53], v[44:45], 0.5, v[60:61] op_sel_hi:[1,0,1]
	v_pk_fma_f32 v[44:45], v[42:43], 0.5, v[56:57] op_sel_hi:[1,0,1]
	v_cvt_pk_bf16_f32 v42, v46, v47
	v_mul_f32_e32 v47, v47, v47
	v_fmac_f32_e32 v47, v46, v46
	v_mul_f32_e32 v46, v49, v49
	v_fmac_f32_e32 v46, v48, v48
	v_add_f32_e32 v46, v47, v46
	v_mul_f32_e32 v47, v45, v45
	v_fmac_f32_e32 v47, v44, v44
	v_add_f32_e32 v46, v47, v46
	v_mul_f32_e32 v47, v53, v53
	v_fmac_f32_e32 v47, v52, v52
	v_cvt_pk_bf16_f32 v43, v48, v49
	v_add_f32_e32 v60, v47, v46
	s_waitcnt vmcnt(14)
	v_lshlrev_b32_e32 v46, 16, v134
	v_and_b32_e32 v47, 0xffff0000, v134
	v_lshlrev_b32_e32 v48, 16, v135
	v_and_b32_e32 v49, 0xffff0000, v135
	v_lshlrev_b32_e32 v54, 16, v136
	v_and_b32_e32 v55, 0xffff0000, v136
	v_pk_fma_f32 v[40:41], v[40:41], 0.5, v[48:49] op_sel_hi:[1,0,1]
	v_pk_fma_f32 v[38:39], v[38:39], 0.5, v[46:47] op_sel_hi:[1,0,1]
	v_pk_fma_f32 v[48:49], v[34:35], 0.5, v[54:55] op_sel_hi:[1,0,1]
	v_mul_f32_e32 v34, v39, v39
	v_mul_f32_e32 v35, v41, v41
	v_fmac_f32_e32 v34, v38, v38
	v_fmac_f32_e32 v35, v40, v40
	v_lshlrev_b32_e32 v56, 16, v137
	v_and_b32_e32 v57, 0xffff0000, v137
	v_add_f32_e32 v34, v34, v35
	v_mul_f32_e32 v35, v49, v49
	v_pk_fma_f32 v[46:47], v[36:37], 0.5, v[56:57] op_sel_hi:[1,0,1]
	v_fmac_f32_e32 v35, v48, v48
	v_add_f32_e32 v34, v35, v34
	v_mul_f32_e32 v35, v47, v47
	v_fmac_f32_e32 v35, v46, v46
	v_add_f32_e32 v34, v35, v34
	v_add_f32_e32 v34, v60, v34
	ds_bpermute_b32 v35, v242, v34
	v_cvt_pk_bf16_f32 v44, v44, v45
	v_cvt_pk_bf16_f32 v45, v52, v53
	v_cvt_pk_bf16_f32 v36, v38, v39
	v_cvt_pk_bf16_f32 v37, v40, v41
	s_waitcnt lgkmcnt(0)
	v_add_f32_e32 v34, v34, v35
	ds_bpermute_b32 v35, v243, v34
	v_cvt_pk_bf16_f32 v38, v48, v49
	v_cvt_pk_bf16_f32 v39, v46, v47
	global_store_dwordx4 v[58:59], v[42:45], off offset:2048 nt
	global_store_dwordx4 v[50:51], v[36:39], off offset:2048 nt
	s_and_saveexec_b64 s[52:53], s[4:5]
	s_cbranch_execz .LBB0_555
	v_lshl_add_u32 v36, s60, 8, v235
	v_ashrrev_i32_e32 v37, 31, v36
	s_waitcnt lgkmcnt(0)
	v_add_f32_e32 v38, v34, v35
	v_lshlrev_b64 v[34:35], 6, v[36:37]
	s_ashr_i32 s51, s50, 31
	v_lshl_add_u64 v[34:35], s[30:31], 0, v[34:35]
	v_lshl_add_u64 v[34:35], s[50:51], 2, v[34:35]
	s_lshl_b32 s26, s66, 2
	v_lshl_add_u64 v[34:35], v[34:35], 0, s[26:27]
	global_store_dword v[34:35], v38, off
; __device__ __forceinline__ unsigned pk2(float lo, float hi) { f32x2_t v = {lo, hi}; bf16x2_t b = __builtin_convertvector(v, bf16x2_t); return __builtin_bit_cast(unsigned, b); }
; __device__ __forceinline__ float bflo(unsigned w) { return __uint_as_float(w << 16); }
; __device__ __forceinline__ float bfhi(unsigned w) { return __uint_as_float(w & 0xffff0000u); }
;     __device__ __forceinline__ void operator()(Acc& acc, const Unit& u, int wr, int wc, int fr, int fq) const {
;     ...
; #pragma unroll
;         for (int ai = 0; ai < 2; ++ai)
; #pragma unroll
;             for (int m = 0; m < 4; ++m) {
;                 const int row = u.pm * BM + ai * HALF + wr * 64 + m * 16 + fr;
;                 float ss = 0.f;
; #pragma unroll
;                 for (int bj = 0; bj < 2; ++bj) {
;                     const size_t off = (size_t)row * D + col0 + bj * HALF;
;                     f32x4 r0, r1;
;                     if (RES_BF16) { const u32x4 q = rb[ai][m][bj]; r0 = (f32x4){bflo(q.x), bfhi(q.x), bflo(q.y), bfhi(q.y)}; r1 = (f32x4){bflo(q.z), bfhi(q.z), bflo(q.w), bfhi(q.w)}; }
;                     else { r0 = *(const f32x4*)(res_f32 + off); r1 = *(const f32x4*)(res_f32 + off + 4); }
;                     const f32x4 v0 = r0 + acc[ai][bj][m][0] * alpha, v1 = r1 + acc[ai][bj][m][1] * alpha;
;                     u32x4 w; w.x = pk2(v0[0], v0[1]); w.y = pk2(v0[2], v0[3]); w.z = pk2(v1[0], v1[1]); w.w = pk2(v1[2], v1[3]);
;                     *(u32x4*)((char*)XBo + xb_piece(u.pm, u.pn, wr, wc, ai, m, bj) + xlo) = w;
;                     ss += (v0[0] * v0[0] + v0[1] * v0[1]) + (v0[2] * v0[2] + v0[3] * v0[3]) + (v1[0] * v1[0] + v1[1] * v1[1]) + (v1[2] * v1[2] + v1[3] * v1[3]);
;                 }
;                 ss += __shfl_xor(ss, 16); ss += __shfl_xor(ss, 32);
;                 if (ssqp && fq == 0) ssqp[(size_t)row * 16 + u.pn * 4 + wc] = ss;
;                 if (!RES_BF16 && (m & 1)) asm volatile("" ::: "memory");
.LBB0_555:
	s_or_b64 exec, exec, s[52:53]
	s_waitcnt vmcnt(15)
	v_lshlrev_b32_e32 v34, 16, v126
	s_waitcnt lgkmcnt(0)
	v_and_b32_e32 v35, 0xffff0000, v126
	v_lshlrev_b32_e32 v36, 16, v127
	v_and_b32_e32 v37, 0xffff0000, v127
	v_lshlrev_b32_e32 v38, 16, v128
	v_and_b32_e32 v39, 0xffff0000, v128
	v_lshlrev_b32_e32 v40, 16, v129
	v_and_b32_e32 v41, 0xffff0000, v129
	v_pk_fma_f32 v[32:33], v[32:33], 0.5, v[36:37] op_sel_hi:[1,0,1]
	v_pk_fma_f32 v[34:35], v[30:31], 0.5, v[34:35] op_sel_hi:[1,0,1]
	v_pk_fma_f32 v[36:37], v[28:29], 0.5, v[40:41] op_sel_hi:[1,0,1]
	v_pk_fma_f32 v[38:39], v[26:27], 0.5, v[38:39] op_sel_hi:[1,0,1]
	v_add_co_u32_e32 v26, vcc, s70, v158
	v_cvt_pk_bf16_f32 v28, v34, v35
	v_cvt_pk_bf16_f32 v29, v32, v33
	v_cvt_pk_bf16_f32 v30, v38, v39
	v_cvt_pk_bf16_f32 v31, v36, v37
	v_addc_co_u32_e32 v27, vcc, 0, v159, vcc
	global_store_dwordx4 v[26:27], v[28:31], off nt
	s_nop 1
	v_mul_f32_e32 v28, v35, v35
	v_mul_f32_e32 v29, v33, v33
	v_fmac_f32_e32 v28, v34, v34
	v_fmac_f32_e32 v29, v32, v32
	v_add_f32_e32 v28, v28, v29
	v_mul_f32_e32 v29, v39, v39
	v_fmac_f32_e32 v29, v38, v38
	v_add_f32_e32 v28, v29, v28
	v_mul_f32_e32 v29, v37, v37
	v_fmac_f32_e32 v29, v36, v36
	v_add_f32_e32 v36, v29, v28
	s_waitcnt vmcnt(15)
	v_lshlrev_b32_e32 v28, 16, v122
	v_and_b32_e32 v29, 0xffff0000, v122
	v_lshlrev_b32_e32 v30, 16, v123
	v_and_b32_e32 v31, 0xffff0000, v123
	v_pk_fma_f32 v[24:25], v[24:25], 0.5, v[30:31] op_sel_hi:[1,0,1]
	v_pk_fma_f32 v[22:23], v[22:23], 0.5, v[28:29] op_sel_hi:[1,0,1]
	v_lshlrev_b32_e32 v32, 16, v124
	v_and_b32_e32 v33, 0xffff0000, v124
	v_mul_f32_e32 v28, v23, v23
	v_mul_f32_e32 v29, v25, v25
	v_pk_fma_f32 v[18:19], v[18:19], 0.5, v[32:33] op_sel_hi:[1,0,1]
	v_fmac_f32_e32 v28, v22, v22
	v_fmac_f32_e32 v29, v24, v24
	v_lshlrev_b32_e32 v34, 16, v125
	v_and_b32_e32 v35, 0xffff0000, v125
	v_add_f32_e32 v28, v28, v29
	v_mul_f32_e32 v29, v19, v19
	v_pk_fma_f32 v[20:21], v[20:21], 0.5, v[34:35] op_sel_hi:[1,0,1]
	v_fmac_f32_e32 v29, v18, v18
	v_add_f32_e32 v28, v29, v28
	v_mul_f32_e32 v29, v21, v21
	v_fmac_f32_e32 v29, v20, v20
	v_add_f32_e32 v28, v29, v28
	v_add_f32_e32 v28, v36, v28
	ds_bpermute_b32 v29, v242, v28
	v_cvt_pk_bf16_f32 v22, v22, v23
	v_cvt_pk_bf16_f32 v23, v24, v25
	v_cvt_pk_bf16_f32 v25, v20, v21
	v_cvt_pk_bf16_f32 v24, v18, v19
	s_waitcnt lgkmcnt(0)
	v_add_f32_e32 v20, v28, v29
	ds_bpermute_b32 v21, v243, v20
	v_add_co_u32_e32 v18, vcc, s70, v130
	s_nop 1
	v_addc_co_u32_e32 v19, vcc, 0, v131, vcc
	global_store_dwordx4 v[18:19], v[22:25], off nt
	s_and_saveexec_b64 s[52:53], s[4:5]
	s_cbranch_execz .LBB0_557
	v_lshl_add_u32 v22, s60, 8, v236
	v_ashrrev_i32_e32 v23, 31, v22
	s_waitcnt lgkmcnt(0)
	v_add_f32_e32 v24, v20, v21
	v_lshlrev_b64 v[20:21], 6, v[22:23]
	s_ashr_i32 s51, s50, 31
	v_lshl_add_u64 v[20:21], s[30:31], 0, v[20:21]
	v_lshl_add_u64 v[20:21], s[50:51], 2, v[20:21]
	s_lshl_b32 s26, s66, 2
	v_lshl_add_u64 v[20:21], v[20:21], 0, s[26:27]
	global_store_dword v[20:21], v24, off
.LBB0_557:
	s_or_b64 exec, exec, s[52:53]
	s_waitcnt vmcnt(15)
	v_lshlrev_b32_e32 v20, 16, v110
	s_waitcnt lgkmcnt(0)
	v_and_b32_e32 v21, 0xffff0000, v110
	v_lshlrev_b32_e32 v22, 16, v111
	v_and_b32_e32 v23, 0xffff0000, v111
	v_lshlrev_b32_e32 v24, 16, v112
	v_and_b32_e32 v25, 0xffff0000, v112
	v_lshlrev_b32_e32 v28, 16, v113
	v_and_b32_e32 v29, 0xffff0000, v113
	v_pk_fma_f32 v[14:15], v[14:15], 0.5, v[20:21] op_sel_hi:[1,0,1]
	v_pk_fma_f32 v[16:17], v[16:17], 0.5, v[22:23] op_sel_hi:[1,0,1]
	v_pk_fma_f32 v[20:21], v[12:13], 0.5, v[28:29] op_sel_hi:[1,0,1]
	v_pk_fma_f32 v[12:13], v[10:11], 0.5, v[24:25] op_sel_hi:[1,0,1]
	v_cvt_pk_bf16_f32 v10, v14, v15
	v_mul_f32_e32 v15, v15, v15
	v_fmac_f32_e32 v15, v14, v14
	v_mul_f32_e32 v14, v17, v17
	v_fmac_f32_e32 v14, v16, v16
	v_add_f32_e32 v14, v15, v14
	v_mul_f32_e32 v15, v13, v13
	v_fmac_f32_e32 v15, v12, v12
	v_add_f32_e32 v14, v15, v14
	v_mul_f32_e32 v15, v21, v21
	v_fmac_f32_e32 v15, v20, v20
	v_cvt_pk_bf16_f32 v11, v16, v17
	v_add_f32_e32 v28, v15, v14
	s_waitcnt vmcnt(14)
	v_lshlrev_b32_e32 v14, 16, v98
	v_and_b32_e32 v15, 0xffff0000, v98
	v_lshlrev_b32_e32 v16, 16, v99
	v_and_b32_e32 v17, 0xffff0000, v99
	v_lshlrev_b32_e32 v22, 16, v100
	v_and_b32_e32 v23, 0xffff0000, v100
	v_pk_fma_f32 v[8:9], v[8:9], 0.5, v[16:17] op_sel_hi:[1,0,1]
	v_pk_fma_f32 v[6:7], v[6:7], 0.5, v[14:15] op_sel_hi:[1,0,1]
	v_pk_fma_f32 v[16:17], v[2:3], 0.5, v[22:23] op_sel_hi:[1,0,1]
	v_mul_f32_e32 v2, v7, v7
	v_mul_f32_e32 v3, v9, v9
	v_fmac_f32_e32 v2, v6, v6
	v_fmac_f32_e32 v3, v8, v8
	v_lshlrev_b32_e32 v24, 16, v101
	v_and_b32_e32 v25, 0xffff0000, v101
	v_add_f32_e32 v2, v2, v3
	v_mul_f32_e32 v3, v17, v17
	v_pk_fma_f32 v[14:15], v[4:5], 0.5, v[24:25] op_sel_hi:[1,0,1]
	v_fmac_f32_e32 v3, v16, v16
	v_add_f32_e32 v2, v3, v2
	v_mul_f32_e32 v3, v15, v15
	v_fmac_f32_e32 v3, v14, v14
	v_add_f32_e32 v2, v3, v2
	v_add_f32_e32 v2, v28, v2
	ds_bpermute_b32 v3, v242, v2
	v_cvt_pk_bf16_f32 v12, v12, v13
	v_cvt_pk_bf16_f32 v13, v20, v21
	v_cvt_pk_bf16_f32 v4, v6, v7
	v_cvt_pk_bf16_f32 v5, v8, v9
	s_waitcnt lgkmcnt(0)
	v_add_f32_e32 v2, v2, v3
	ds_bpermute_b32 v3, v243, v2
	v_cvt_pk_bf16_f32 v6, v16, v17
	v_cvt_pk_bf16_f32 v7, v14, v15
	global_store_dwordx4 v[26:27], v[10:13], off offset:2048 nt
	global_store_dwordx4 v[18:19], v[4:7], off offset:2048 nt
	s_and_saveexec_b64 s[52:53], s[4:5]
	s_cbranch_execz .LBB0_559
	v_lshl_add_u32 v4, s60, 8, v237
	v_ashrrev_i32_e32 v5, 31, v4
	s_waitcnt lgkmcnt(0)
	v_add_f32_e32 v6, v2, v3
	v_lshlrev_b64 v[2:3], 6, v[4:5]
	s_ashr_i32 s51, s50, 31
	v_lshl_add_u64 v[2:3], s[30:31], 0, v[2:3]
	v_lshl_add_u64 v[2:3], s[50:51], 2, v[2:3]
	s_lshl_b32 s26, s66, 2
	v_lshl_add_u64 v[2:3], v[2:3], 0, s[26:27]
	global_store_dword v[2:3], v6, off

; __device__ __forceinline__ unsigned pk2(float lo, float hi) { f32x2_t v = {lo, hi}; bf16x2_t b = __builtin_convertvector(v, bf16x2_t); return __builtin_bit_cast(unsigned, b); }
; __device__ __forceinline__ void sg_proj(const Args& a, Frame& F, int part) {
;     ...
;                 } else if (n0 >= 4096) {
;                     v2u w; w.x = pk2(v[0], v[1]); w.y = pk2(v[2], v[3]);
;                     *(v2u*)((bf16*)(ws + WS_SKV) + (size_t)m * 256 + (nq - 4096)) = w;
;                     const int bs = lr >> 5, t = lr & 31;
;                     *(f32x4*)(a.out + (nq < 4224 ? O_CKS : O_CVS) + ((size_t)(bs * WINDOW + 96 + t)) * 128 + ((nq - 4096) & 127)) = v;
.LBB0_673:
	s_and_b64 vcc, exec, s[38:39]
	s_cbranch_vccz .LBB0_675
	v_lshl_add_u64 v[20:21], v[34:35], 1, v[24:25]
	v_add_co_u32_e32 v20, vcc, 0x1bf3e000, v20
	v_cvt_pk_bf16_f32 v18, v14, v15
	s_nop 0
	v_addc_co_u32_e32 v21, vcc, 0, v21, vcc
	v_cvt_pk_bf16_f32 v19, v16, v17
	v_cmp_gt_i32_e32 vcc, s19, v34
	global_store_dwordx2 v[20:21], v[18:19], off
	v_mov_b32_e32 v19, v35
	v_cndmask_b32_e32 v18, v73, v74, vcc
	v_lshl_add_u64 v[18:19], s[94:95], 0, v[18:19]
	v_and_b32_e32 v20, 0x6c, v34
	v_lshl_add_u64 v[18:19], v[18:19], 0, v[22:23]
	v_lshlrev_b32_e32 v20, 2, v20
	v_mov_b32_e32 v21, v35
	v_lshl_add_u64 v[18:19], v[18:19], 0, v[20:21]
	global_store_dwordx4 v[18:19], v[14:17], off nt

; __device__ __forceinline__ void sg_proj(const Args& a, Frame& F, int part) {
;     ...
;                 if (n0 >= 4352) {
;                     *(f32x4*)((float*)(ws + WS_GLR) + (size_t)m * 16 + 4 * fq) = v;
.LBB0_676:
	s_andn2_b64 vcc, exec, s[38:39]
	s_cbranch_vccnz .LBB0_678
	v_lshlrev_b64 v[18:19], 6, v[30:31]
	v_lshl_add_u64 v[18:19], v[38:39], 0, v[18:19]
	global_store_dwordx4 v[18:19], v[14:17], off nt

; __device__ __forceinline__ unsigned pk2(float lo, float hi) { f32x2_t v = {lo, hi}; bf16x2_t b = __builtin_convertvector(v, bf16x2_t); return __builtin_bit_cast(unsigned, b); }
; __device__ __forceinline__ void sg_proj(const Args& a, Frame& F, int part) {
;     ...
;                 } else if (n0 >= 4096) {
;                     v2u w; w.x = pk2(v[0], v[1]); w.y = pk2(v[2], v[3]);
;                     *(v2u*)((bf16*)(ws + WS_SKV) + (size_t)m * 256 + (nq - 4096)) = w;
;                     const int bs = lr >> 5, t = lr & 31;
;                     *(f32x4*)(a.out + (nq < 4224 ? O_CKS : O_CVS) + ((size_t)(bs * WINDOW + 96 + t)) * 128 + ((nq - 4096) & 127)) = v;
.LBB0_695:
	s_and_b64 vcc, exec, s[40:41]
	s_cbranch_vccz .LBB0_697
	v_mov_b32_e32 v19, v35
	v_lshl_add_u64 v[16:17], v[18:19], 1, v[24:25]
	v_add_co_u32_e32 v16, vcc, 0x1bf3e000, v16
	v_cvt_pk_bf16_f32 v14, v10, v11
	s_nop 0
	v_addc_co_u32_e32 v17, vcc, 0, v17, vcc
	v_cvt_pk_bf16_f32 v15, v12, v13
	v_cmp_gt_i32_e32 vcc, s19, v18
	global_store_dwordx2 v[16:17], v[14:15], off
	v_mov_b32_e32 v15, v35
	v_cndmask_b32_e32 v14, v73, v74, vcc
	v_lshl_add_u64 v[14:15], s[94:95], 0, v[14:15]
	v_and_b32_e32 v16, 0x7c, v18
	v_lshl_add_u64 v[14:15], v[14:15], 0, v[22:23]
	v_lshlrev_b32_e32 v16, 2, v16
	v_mov_b32_e32 v17, v35
	v_lshl_add_u64 v[14:15], v[14:15], 0, v[16:17]
	global_store_dwordx4 v[14:15], v[10:13], off nt

; __device__ __forceinline__ unsigned pk2(float lo, float hi) { f32x2_t v = {lo, hi}; bf16x2_t b = __builtin_convertvector(v, bf16x2_t); return __builtin_bit_cast(unsigned, b); }
; __device__ __forceinline__ void sg_proj(const Args& a, Frame& F, int part) {
;     ...
;                 } else if (n0 >= 4096) {
;                     v2u w; w.x = pk2(v[0], v[1]); w.y = pk2(v[2], v[3]);
;                     *(v2u*)((bf16*)(ws + WS_SKV) + (size_t)m * 256 + (nq - 4096)) = w;
;                     const int bs = lr >> 5, t = lr & 31;
;                     *(f32x4*)(a.out + (nq < 4224 ? O_CKS : O_CVS) + ((size_t)(bs * WINDOW + 96 + t)) * 128 + ((nq - 4096) & 127)) = v;
.LBB0_715:
	s_and_b64 vcc, exec, s[10:11]
	s_cbranch_vccz .LBB0_717
	v_lshl_add_u64 v[12:13], v[34:35], 1, v[16:17]
	v_add_co_u32_e32 v12, vcc, 0x1bf3e000, v12
	v_cvt_pk_bf16_f32 v10, v6, v7
	s_nop 0
	v_addc_co_u32_e32 v13, vcc, 0, v13, vcc
	v_cvt_pk_bf16_f32 v11, v8, v9
	v_cmp_gt_i32_e32 vcc, s19, v34
	global_store_dwordx2 v[12:13], v[10:11], off
	v_mov_b32_e32 v11, v35
	v_cndmask_b32_e32 v10, v73, v74, vcc
	v_lshl_add_u64 v[10:11], s[94:95], 0, v[10:11]
	v_and_b32_e32 v12, 0x6c, v34
	v_lshl_add_u64 v[10:11], v[10:11], 0, v[14:15]
	v_lshlrev_b32_e32 v34, 2, v12
	v_lshl_add_u64 v[10:11], v[10:11], 0, v[34:35]
	global_store_dwordx4 v[10:11], v[6:9], off nt

; __device__ __forceinline__ void sg_proj(const Args& a, Frame& F, int part) {
;     ...
;                 if (n0 >= 4352) {
;                     *(f32x4*)((float*)(ws + WS_GLR) + (size_t)m * 16 + 4 * fq) = v;
.LBB0_718:
	s_andn2_b64 vcc, exec, s[10:11]
	s_cbranch_vccnz .LBB0_720
	v_lshlrev_b64 v[10:11], 6, v[24:25]
	v_lshl_add_u64 v[10:11], v[38:39], 0, v[10:11]
	global_store_dwordx4 v[10:11], v[6:9], off nt

; __device__ __forceinline__ unsigned pk2(float lo, float hi) { f32x2_t v = {lo, hi}; bf16x2_t b = __builtin_convertvector(v, bf16x2_t); return __builtin_bit_cast(unsigned, b); }
; __device__ __forceinline__ void sg_proj(const Args& a, Frame& F, int part) {
;     ...
;                 } else if (n0 >= 4096) {
;                     v2u w; w.x = pk2(v[0], v[1]); w.y = pk2(v[2], v[3]);
;                     *(v2u*)((bf16*)(ws + WS_SKV) + (size_t)m * 256 + (nq - 4096)) = w;
;                     const int bs = lr >> 5, t = lr & 31;
;                     *(f32x4*)(a.out + (nq < 4224 ? O_CKS : O_CVS) + ((size_t)(bs * WINDOW + 96 + t)) * 128 + ((nq - 4096) & 127)) = v;
.LBB0_737:
	s_and_b64 vcc, exec, s[10:11]
	s_cbranch_vccz .LBB0_642
	v_mov_b32_e32 v19, v35
	v_lshl_add_u64 v[8:9], v[18:19], 1, v[16:17]
	v_add_co_u32_e32 v8, vcc, 0x1bf3e000, v8
	v_cvt_pk_bf16_f32 v6, v2, v3
	s_nop 0
	v_addc_co_u32_e32 v9, vcc, 0, v9, vcc
	v_cmp_gt_i32_e32 vcc, s19, v18
	v_cvt_pk_bf16_f32 v7, v4, v5
	global_store_dwordx2 v[8:9], v[6:7], off
	v_cndmask_b32_e32 v34, v73, v74, vcc
	v_lshl_add_u64 v[6:7], s[94:95], 0, v[34:35]
	v_and_b32_e32 v8, 0x7c, v18
	v_lshl_add_u64 v[6:7], v[6:7], 0, v[14:15]
	v_lshlrev_b32_e32 v34, 2, v8
	v_lshl_add_u64 v[6:7], v[6:7], 0, v[34:35]
	global_store_dwordx4 v[6:7], v[2:5], off nt
	s_branch .LBB0_642

; __device__ __forceinline__ unsigned pk2(float lo, float hi) { f32x2_t v = {lo, hi}; bf16x2_t b = __builtin_convertvector(v, bf16x2_t); return __builtin_bit_cast(unsigned, b); }
;     __device__ __forceinline__ void operator()(Acc& acc, const Unit& u, int wr, int wc, int fr, int fq, const float (&rsa)[2][4]) const {
;     ...
;                     u32x4 w; w.x = pk2(v0[0], v0[1]); w.y = pk2(v0[2], v0[3]); w.z = pk2(v1[0], v1[1]); w.w = pk2(v1[2], v1[3]);
;                     *(u32x4*)(dst + (size_t)row * ld + cbase + within) = w;
;                     if (mode == 2) {
;                         float* cp = nullptr;
;                         if (u.pm >= MP / BM) { const int rs_ = row - MP, bs = rs_ >> 5, t = rs_ & 31; cp = out + (bj == 0 ? O_CKS : O_CVS) + ((size_t)(bs * WINDOW + 96 + t)) * 128 + (within & 127); }
;                         else if ((u.pm & 15) == 15 && ai == 1) { const int b = row >> 12, t = row & 4095; cp = out + (bj == 0 ? O_CKP : O_CVP) + ((size_t)(b * WINDOW + (t - (SEQ - WINDOW)))) * 128 + (within & 127); }
;                         if (cp) { *(f32x4*)cp = v0; *(f32x4*)(cp + 4) = v1; }
.LBB0_843:
	s_cmpk_gt_i32 s30, 0x7f
	s_cselect_b64 s[12:13], -1, 0
	v_lshlrev_b32_e32 v162, 1, v160
	s_and_b64 s[12:13], s[62:63], s[12:13]
	v_cvt_pk_bf16_f32 v214, v146, v147
	v_cvt_pk_bf16_f32 v215, v148, v149
	v_cvt_pk_bf16_f32 v216, v150, v151
	v_cvt_pk_bf16_f32 v217, v152, v153
	v_lshl_add_u64 v[218:219], v[180:181], 0, v[162:163]
	s_andn2_b64 vcc, exec, s[12:13]
	global_store_dwordx4 v[218:219], v[214:217], off nt
	s_cbranch_vccnz .LBB0_845
	s_nop 0
	v_lshl_add_u64 v[214:215], v[168:169], 0, v[178:179]
	global_store_dwordx4 v[214:215], v[146:149], off nt
	global_store_dwordx4 v[214:215], v[150:153], off offset:16 nt

;     __device__ __forceinline__ void operator()(Acc& acc, const Unit& u, int wr, int wc, int fr, int fq, const float (&rsa)[2][4]) const {
;     ...
;                     if (mode == 3) { if (within < GRANK) { *(f32x4*)(GLR + (size_t)row * 16 + within) = v0; *(f32x4*)(GLR + (size_t)row * 16 + within + 4) = v1; } continue; }
.LBB0_847:
	s_and_b64 vcc, exec, s[70:71]
	s_cbranch_vccz .LBB0_846
	s_and_saveexec_b64 s[12:13], s[4:5]
	s_cbranch_execz .LBB0_850
	v_lshlrev_b64 v[146:147], 6, v[184:185]
	v_lshl_add_u64 v[146:147], v[164:165], 0, v[146:147]
	global_store_dwordx4 v[146:147], v[138:141], off nt
	global_store_dwordx4 v[146:147], v[142:145], off offset:16 nt

; __device__ __forceinline__ unsigned pk2(float lo, float hi) { f32x2_t v = {lo, hi}; bf16x2_t b = __builtin_convertvector(v, bf16x2_t); return __builtin_bit_cast(unsigned, b); }
;     __device__ __forceinline__ void operator()(Acc& acc, const Unit& u, int wr, int wc, int fr, int fq, const float (&rsa)[2][4]) const {
;     ...
;                     u32x4 w; w.x = pk2(v0[0], v0[1]); w.y = pk2(v0[2], v0[3]); w.z = pk2(v1[0], v1[1]); w.w = pk2(v1[2], v1[3]);
;                     *(u32x4*)(dst + (size_t)row * ld + cbase + within) = w;
;                     if (mode == 2) {
;                         float* cp = nullptr;
;                         if (u.pm >= MP / BM) { const int rs_ = row - MP, bs = rs_ >> 5, t = rs_ & 31; cp = out + (bj == 0 ? O_CKS : O_CVS) + ((size_t)(bs * WINDOW + 96 + t)) * 128 + (within & 127); }
;                         else if ((u.pm & 15) == 15 && ai == 1) { const int b = row >> 12, t = row & 4095; cp = out + (bj == 0 ? O_CKP : O_CVP) + ((size_t)(b * WINDOW + (t - (SEQ - WINDOW)))) * 128 + (within & 127); }
;                         if (cp) { *(f32x4*)cp = v0; *(f32x4*)(cp + 4) = v1; }
.LBB0_853:
	s_cmpk_gt_i32 s30, 0x7f
	s_cselect_b64 s[68:69], -1, 0
	v_lshlrev_b32_e32 v162, 1, v160
	s_and_b64 s[68:69], s[62:63], s[68:69]
	v_cvt_pk_bf16_f32 v146, v138, v139
	v_cvt_pk_bf16_f32 v147, v140, v141
	v_cvt_pk_bf16_f32 v148, v142, v143
	v_cvt_pk_bf16_f32 v149, v144, v145
	v_lshl_add_u64 v[150:151], v[180:181], 0, v[162:163]
	s_andn2_b64 vcc, exec, s[68:69]
	global_store_dwordx4 v[150:151], v[146:149], off offset:256 nt
	s_cbranch_vccnz .LBB0_855
	s_nop 0
	v_lshl_add_u64 v[146:147], v[170:171], 0, v[178:179]
	global_store_dwordx4 v[146:147], v[138:141], off nt
	global_store_dwordx4 v[146:147], v[142:145], off offset:16 nt

; __device__ __forceinline__ unsigned pk2(float lo, float hi) { f32x2_t v = {lo, hi}; bf16x2_t b = __builtin_convertvector(v, bf16x2_t); return __builtin_bit_cast(unsigned, b); }
;     __device__ __forceinline__ void operator()(Acc& acc, const Unit& u, int wr, int wc, int fr, int fq, const float (&rsa)[2][4]) const {
;     ...
;                     u32x4 w; w.x = pk2(v0[0], v0[1]); w.y = pk2(v0[2], v0[3]); w.z = pk2(v1[0], v1[1]); w.w = pk2(v1[2], v1[3]);
;                     *(u32x4*)(dst + (size_t)row * ld + cbase + within) = w;
;                     if (mode == 2) {
;                         float* cp = nullptr;
;                         if (u.pm >= MP / BM) { const int rs_ = row - MP, bs = rs_ >> 5, t = rs_ & 31; cp = out + (bj == 0 ? O_CKS : O_CVS) + ((size_t)(bs * WINDOW + 96 + t)) * 128 + (within & 127); }
;                         else if ((u.pm & 15) == 15 && ai == 1) { const int b = row >> 12, t = row & 4095; cp = out + (bj == 0 ? O_CKP : O_CVP) + ((size_t)(b * WINDOW + (t - (SEQ - WINDOW)))) * 128 + (within & 127); }
;                         if (cp) { *(f32x4*)cp = v0; *(f32x4*)(cp + 4) = v1; }
.LBB0_858:
	s_cmpk_gt_i32 s30, 0x7f
	s_cselect_b64 s[68:69], -1, 0
	v_lshlrev_b32_e32 v162, 1, v160
	s_and_b64 s[68:69], s[62:63], s[68:69]
	v_cvt_pk_bf16_f32 v214, v146, v147
	v_cvt_pk_bf16_f32 v215, v148, v149
	v_cvt_pk_bf16_f32 v216, v150, v151
	v_cvt_pk_bf16_f32 v217, v152, v153
	v_lshl_add_u64 v[184:185], v[178:179], 0, v[162:163]
	s_andn2_b64 vcc, exec, s[68:69]
	global_store_dwordx4 v[184:185], v[214:217], off nt
	s_cbranch_vccnz .LBB0_860
	v_lshl_add_u64 v[184:185], v[168:169], 0, v[134:135]
	global_store_dwordx4 v[184:185], v[146:149], off nt
	global_store_dwordx4 v[184:185], v[150:153], off offset:16 nt

;     __device__ __forceinline__ void operator()(Acc& acc, const Unit& u, int wr, int wc, int fr, int fq, const float (&rsa)[2][4]) const {
;     ...
;                     if (mode == 3) { if (within < GRANK) { *(f32x4*)(GLR + (size_t)row * 16 + within) = v0; *(f32x4*)(GLR + (size_t)row * 16 + within + 4) = v1; } continue; }
.LBB0_862:
	s_and_b64 vcc, exec, s[68:69]
	s_cbranch_vccz .LBB0_861
	s_and_saveexec_b64 s[68:69], s[4:5]
	s_cbranch_execz .LBB0_865
	v_lshlrev_b64 v[146:147], 6, v[182:183]
	v_lshl_add_u64 v[146:147], v[164:165], 0, v[146:147]
	global_store_dwordx4 v[146:147], v[138:141], off nt
	global_store_dwordx4 v[146:147], v[142:145], off offset:16 nt

; __device__ __forceinline__ unsigned pk2(float lo, float hi) { f32x2_t v = {lo, hi}; bf16x2_t b = __builtin_convertvector(v, bf16x2_t); return __builtin_bit_cast(unsigned, b); }
;     __device__ __forceinline__ void operator()(Acc& acc, const Unit& u, int wr, int wc, int fr, int fq, const float (&rsa)[2][4]) const {
;     ...
;                     u32x4 w; w.x = pk2(v0[0], v0[1]); w.y = pk2(v0[2], v0[3]); w.z = pk2(v1[0], v1[1]); w.w = pk2(v1[2], v1[3]);
;                     *(u32x4*)(dst + (size_t)row * ld + cbase + within) = w;
;                     if (mode == 2) {
;                         float* cp = nullptr;
;                         if (u.pm >= MP / BM) { const int rs_ = row - MP, bs = rs_ >> 5, t = rs_ & 31; cp = out + (bj == 0 ? O_CKS : O_CVS) + ((size_t)(bs * WINDOW + 96 + t)) * 128 + (within & 127); }
;                         else if ((u.pm & 15) == 15 && ai == 1) { const int b = row >> 12, t = row & 4095; cp = out + (bj == 0 ? O_CKP : O_CVP) + ((size_t)(b * WINDOW + (t - (SEQ - WINDOW)))) * 128 + (within & 127); }
;                         if (cp) { *(f32x4*)cp = v0; *(f32x4*)(cp + 4) = v1; }
.LBB0_868:
	s_cmpk_gt_i32 s30, 0x7f
	s_cselect_b64 s[68:69], -1, 0
	v_lshlrev_b32_e32 v162, 1, v160
	s_and_b64 s[68:69], s[62:63], s[68:69]
	v_cvt_pk_bf16_f32 v146, v138, v139
	v_cvt_pk_bf16_f32 v147, v140, v141
	v_cvt_pk_bf16_f32 v148, v142, v143
	v_cvt_pk_bf16_f32 v149, v144, v145
	v_lshl_add_u64 v[150:151], v[178:179], 0, v[162:163]
	s_andn2_b64 vcc, exec, s[68:69]
	global_store_dwordx4 v[150:151], v[146:149], off offset:256 nt
	s_cbranch_vccnz .LBB0_870
	v_lshl_add_u64 v[134:135], v[170:171], 0, v[134:135]
	global_store_dwordx4 v[134:135], v[138:141], off nt
	global_store_dwordx4 v[134:135], v[142:145], off offset:16 nt

; __device__ __forceinline__ unsigned pk2(float lo, float hi) { f32x2_t v = {lo, hi}; bf16x2_t b = __builtin_convertvector(v, bf16x2_t); return __builtin_bit_cast(unsigned, b); }
;     __device__ __forceinline__ void operator()(Acc& acc, const Unit& u, int wr, int wc, int fr, int fq, const float (&rsa)[2][4]) const {
;     ...
;                     u32x4 w; w.x = pk2(v0[0], v0[1]); w.y = pk2(v0[2], v0[3]); w.z = pk2(v1[0], v1[1]); w.w = pk2(v1[2], v1[3]);
;                     *(u32x4*)(dst + (size_t)row * ld + cbase + within) = w;
;                     if (mode == 2) {
;                         float* cp = nullptr;
;                         if (u.pm >= MP / BM) { const int rs_ = row - MP, bs = rs_ >> 5, t = rs_ & 31; cp = out + (bj == 0 ? O_CKS : O_CVS) + ((size_t)(bs * WINDOW + 96 + t)) * 128 + (within & 127); }
;                         else if ((u.pm & 15) == 15 && ai == 1) { const int b = row >> 12, t = row & 4095; cp = out + (bj == 0 ? O_CKP : O_CVP) + ((size_t)(b * WINDOW + (t - (SEQ - WINDOW)))) * 128 + (within & 127); }
;                         if (cp) { *(f32x4*)cp = v0; *(f32x4*)(cp + 4) = v1; }
.LBB0_888:
	s_cmpk_gt_i32 s30, 0x7f
	s_cselect_b64 s[68:69], -1, 0
	v_lshlrev_b32_e32 v162, 1, v160
	s_and_b64 s[68:69], s[62:63], s[68:69]
	v_cvt_pk_bf16_f32 v182, v142, v143
	v_cvt_pk_bf16_f32 v183, v144, v145
	v_cvt_pk_bf16_f32 v184, v146, v147
	v_cvt_pk_bf16_f32 v185, v148, v149
	v_lshl_add_u64 v[214:215], v[152:153], 0, v[162:163]
	s_andn2_b64 vcc, exec, s[68:69]
	global_store_dwordx4 v[214:215], v[182:185], off nt
	s_cbranch_vccnz .LBB0_890
	s_nop 0
	v_lshl_add_u64 v[182:183], v[168:169], 0, v[150:151]
	global_store_dwordx4 v[182:183], v[142:145], off nt
	global_store_dwordx4 v[182:183], v[146:149], off offset:16 nt

;     __device__ __forceinline__ void operator()(Acc& acc, const Unit& u, int wr, int wc, int fr, int fq, const float (&rsa)[2][4]) const {
;     ...
;                     if (mode == 3) { if (within < GRANK) { *(f32x4*)(GLR + (size_t)row * 16 + within) = v0; *(f32x4*)(GLR + (size_t)row * 16 + within + 4) = v1; } continue; }
.LBB0_892:
	s_and_b64 vcc, exec, s[68:69]
	s_cbranch_vccz .LBB0_891
	s_and_saveexec_b64 s[68:69], s[4:5]
	s_cbranch_execz .LBB0_895
	v_lshlrev_b64 v[142:143], 6, v[180:181]
	v_lshl_add_u64 v[142:143], v[164:165], 0, v[142:143]
	global_store_dwordx4 v[142:143], v[134:137], off nt
	global_store_dwordx4 v[142:143], v[138:141], off offset:16 nt

; __device__ __forceinline__ unsigned pk2(float lo, float hi) { f32x2_t v = {lo, hi}; bf16x2_t b = __builtin_convertvector(v, bf16x2_t); return __builtin_bit_cast(unsigned, b); }
;     __device__ __forceinline__ void operator()(Acc& acc, const Unit& u, int wr, int wc, int fr, int fq, const float (&rsa)[2][4]) const {
;     ...
;                     u32x4 w; w.x = pk2(v0[0], v0[1]); w.y = pk2(v0[2], v0[3]); w.z = pk2(v1[0], v1[1]); w.w = pk2(v1[2], v1[3]);
;                     *(u32x4*)(dst + (size_t)row * ld + cbase + within) = w;
;                     if (mode == 2) {
;                         float* cp = nullptr;
;                         if (u.pm >= MP / BM) { const int rs_ = row - MP, bs = rs_ >> 5, t = rs_ & 31; cp = out + (bj == 0 ? O_CKS : O_CVS) + ((size_t)(bs * WINDOW + 96 + t)) * 128 + (within & 127); }
;                         else if ((u.pm & 15) == 15 && ai == 1) { const int b = row >> 12, t = row & 4095; cp = out + (bj == 0 ? O_CKP : O_CVP) + ((size_t)(b * WINDOW + (t - (SEQ - WINDOW)))) * 128 + (within & 127); }
;                         if (cp) { *(f32x4*)cp = v0; *(f32x4*)(cp + 4) = v1; }
.LBB0_898:
	s_cmpk_gt_i32 s30, 0x7f
	s_cselect_b64 s[68:69], -1, 0
	v_lshlrev_b32_e32 v162, 1, v160
	s_and_b64 s[68:69], s[62:63], s[68:69]
	v_cvt_pk_bf16_f32 v142, v134, v135
	v_cvt_pk_bf16_f32 v143, v136, v137
	v_cvt_pk_bf16_f32 v144, v138, v139
	v_cvt_pk_bf16_f32 v145, v140, v141
	v_lshl_add_u64 v[146:147], v[152:153], 0, v[162:163]
	s_andn2_b64 vcc, exec, s[68:69]
	global_store_dwordx4 v[146:147], v[142:145], off offset:256 nt
	s_cbranch_vccnz .LBB0_900
	s_nop 0
	v_lshl_add_u64 v[142:143], v[170:171], 0, v[150:151]
	global_store_dwordx4 v[142:143], v[134:137], off nt
	global_store_dwordx4 v[142:143], v[138:141], off offset:16 nt

; __device__ __forceinline__ unsigned pk2(float lo, float hi) { f32x2_t v = {lo, hi}; bf16x2_t b = __builtin_convertvector(v, bf16x2_t); return __builtin_bit_cast(unsigned, b); }
;     __device__ __forceinline__ void operator()(Acc& acc, const Unit& u, int wr, int wc, int fr, int fq, const float (&rsa)[2][4]) const {
;     ...
;                     u32x4 w; w.x = pk2(v0[0], v0[1]); w.y = pk2(v0[2], v0[3]); w.z = pk2(v1[0], v1[1]); w.w = pk2(v1[2], v1[3]);
;                     *(u32x4*)(dst + (size_t)row * ld + cbase + within) = w;
;                     if (mode == 2) {
;                         float* cp = nullptr;
;                         if (u.pm >= MP / BM) { const int rs_ = row - MP, bs = rs_ >> 5, t = rs_ & 31; cp = out + (bj == 0 ? O_CKS : O_CVS) + ((size_t)(bs * WINDOW + 96 + t)) * 128 + (within & 127); }
;                         else if ((u.pm & 15) == 15 && ai == 1) { const int b = row >> 12, t = row & 4095; cp = out + (bj == 0 ? O_CKP : O_CVP) + ((size_t)(b * WINDOW + (t - (SEQ - WINDOW)))) * 128 + (within & 127); }
;                         if (cp) { *(f32x4*)cp = v0; *(f32x4*)(cp + 4) = v1; }
.LBB0_903:
	v_lshlrev_b32_e32 v162, 1, v160
	v_cvt_pk_bf16_f32 v214, v142, v143
	v_cvt_pk_bf16_f32 v215, v144, v145
	v_cvt_pk_bf16_f32 v216, v146, v147
	v_cvt_pk_bf16_f32 v217, v148, v149
	v_lshl_add_u64 v[184:185], v[178:179], 0, v[162:163]
	s_andn2_b64 vcc, exec, s[62:63]
	global_store_dwordx4 v[184:185], v[214:217], off nt
	s_cbranch_vccnz .LBB0_909
	s_cmpk_gt_i32 s30, 0x7f
	s_cbranch_scc1 .LBB0_995
	s_and_b32 s68, s30, 15
	s_cmp_eq_u32 s68, 15
	v_lshl_add_u64 v[184:185], v[172:173], 0, v[152:153]
	s_cselect_b64 vcc, -1, 0
	v_cndmask_b32_e32 v185, 0, v185, vcc
	v_cndmask_b32_e32 v184, 0, v184, vcc
	s_cbranch_execz .LBB0_996

;     __device__ __forceinline__ void operator()(Acc& acc, const Unit& u, int wr, int wc, int fr, int fq, const float (&rsa)[2][4]) const {
;     ...
;                         if (u.pm >= MP / BM) { const int rs_ = row - MP, bs = rs_ >> 5, t = rs_ & 31; cp = out + (bj == 0 ? O_CKS : O_CVS) + ((size_t)(bs * WINDOW + 96 + t)) * 128 + (within & 127); }
;                         else if ((u.pm & 15) == 15 && ai == 1) { const int b = row >> 12, t = row & 4095; cp = out + (bj == 0 ? O_CKP : O_CVP) + ((size_t)(b * WINDOW + (t - (SEQ - WINDOW)))) * 128 + (within & 127); }
;                         if (cp) { *(f32x4*)cp = v0; *(f32x4*)(cp + 4) = v1; }
.LBB0_907:
	global_store_dwordx4 v[184:185], v[142:145], off nt
	global_store_dwordx4 v[184:185], v[146:149], off offset:16 nt

;     __device__ __forceinline__ void operator()(Acc& acc, const Unit& u, int wr, int wc, int fr, int fq, const float (&rsa)[2][4]) const {
;     ...
;                     if (mode == 3) { if (within < GRANK) { *(f32x4*)(GLR + (size_t)row * 16 + within) = v0; *(f32x4*)(GLR + (size_t)row * 16 + within + 4) = v1; } continue; }
.LBB0_911:
	s_and_b64 vcc, exec, s[68:69]
	s_cbranch_vccz .LBB0_910
	s_and_saveexec_b64 s[68:69], s[4:5]
	s_cbranch_execz .LBB0_914
	v_lshlrev_b64 v[142:143], 6, v[182:183]
	v_lshl_add_u64 v[142:143], v[164:165], 0, v[142:143]
	global_store_dwordx4 v[142:143], v[134:137], off nt
	global_store_dwordx4 v[142:143], v[138:141], off offset:16 nt

; __device__ __forceinline__ unsigned pk2(float lo, float hi) { f32x2_t v = {lo, hi}; bf16x2_t b = __builtin_convertvector(v, bf16x2_t); return __builtin_bit_cast(unsigned, b); }
;     __device__ __forceinline__ void operator()(Acc& acc, const Unit& u, int wr, int wc, int fr, int fq, const float (&rsa)[2][4]) const {
;     ...
;                     u32x4 w; w.x = pk2(v0[0], v0[1]); w.y = pk2(v0[2], v0[3]); w.z = pk2(v1[0], v1[1]); w.w = pk2(v1[2], v1[3]);
;                     *(u32x4*)(dst + (size_t)row * ld + cbase + within) = w;
;                     if (mode == 2) {
;                         float* cp = nullptr;
;                         if (u.pm >= MP / BM) { const int rs_ = row - MP, bs = rs_ >> 5, t = rs_ & 31; cp = out + (bj == 0 ? O_CKS : O_CVS) + ((size_t)(bs * WINDOW + 96 + t)) * 128 + (within & 127); }
;                         else if ((u.pm & 15) == 15 && ai == 1) { const int b = row >> 12, t = row & 4095; cp = out + (bj == 0 ? O_CKP : O_CVP) + ((size_t)(b * WINDOW + (t - (SEQ - WINDOW)))) * 128 + (within & 127); }
.LBB0_917:
	v_lshlrev_b32_e32 v162, 1, v160
	v_cvt_pk_bf16_f32 v142, v134, v135
	v_cvt_pk_bf16_f32 v143, v136, v137
	v_cvt_pk_bf16_f32 v144, v138, v139
	v_cvt_pk_bf16_f32 v145, v140, v141
	v_lshl_add_u64 v[146:147], v[178:179], 0, v[162:163]
	s_andn2_b64 vcc, exec, s[62:63]
	global_store_dwordx4 v[146:147], v[142:145], off offset:256 nt
	s_cbranch_vccnz .LBB0_923
	s_cmpk_gt_i32 s30, 0x7f
	s_mov_b64 s[68:69], -1
	s_cbranch_scc1 .LBB0_997
	s_and_b32 s68, s30, 15
	s_cmp_eq_u32 s68, 15
	v_lshl_add_u64 v[142:143], v[174:175], 0, v[152:153]
	s_cselect_b64 vcc, -1, 0
	v_cndmask_b32_e32 v143, 0, v143, vcc
	v_cndmask_b32_e32 v142, 0, v142, vcc
	s_cbranch_execz .LBB0_998

;     __device__ __forceinline__ void operator()(Acc& acc, const Unit& u, int wr, int wc, int fr, int fq, const float (&rsa)[2][4]) const {
;     ...
;                         if (cp) { *(f32x4*)cp = v0; *(f32x4*)(cp + 4) = v1; }
.LBB0_921:
	global_store_dwordx4 v[142:143], v[134:137], off nt
	global_store_dwordx4 v[142:143], v[138:141], off offset:16 nt

; __device__ __forceinline__ unsigned pk2(float lo, float hi) { f32x2_t v = {lo, hi}; bf16x2_t b = __builtin_convertvector(v, bf16x2_t); return __builtin_bit_cast(unsigned, b); }
;     __device__ __forceinline__ void operator()(Acc& acc, const Unit& u, int wr, int wc, int fr, int fq, const float (&rsa)[2][4]) const {
;     ...
;                     u32x4 w; w.x = pk2(v0[0], v0[1]); w.y = pk2(v0[2], v0[3]); w.z = pk2(v1[0], v1[1]); w.w = pk2(v1[2], v1[3]);
;                     *(u32x4*)(dst + (size_t)row * ld + cbase + within) = w;
;                     if (mode == 2) {
;                         float* cp = nullptr;
;                         if (u.pm >= MP / BM) { const int rs_ = row - MP, bs = rs_ >> 5, t = rs_ & 31; cp = out + (bj == 0 ? O_CKS : O_CVS) + ((size_t)(bs * WINDOW + 96 + t)) * 128 + (within & 127); }
;                         else if ((u.pm & 15) == 15 && ai == 1) { const int b = row >> 12, t = row & 4095; cp = out + (bj == 0 ? O_CKP : O_CVP) + ((size_t)(b * WINDOW + (t - (SEQ - WINDOW)))) * 128 + (within & 127); }
.LBB0_926:
	v_lshlrev_b32_e32 v162, 1, v160
	v_cvt_pk_bf16_f32 v182, v142, v143
	v_cvt_pk_bf16_f32 v183, v144, v145
	v_cvt_pk_bf16_f32 v184, v146, v147
	v_cvt_pk_bf16_f32 v185, v148, v149
	v_lshl_add_u64 v[214:215], v[152:153], 0, v[162:163]
	s_andn2_b64 vcc, exec, s[62:63]
	global_store_dwordx4 v[214:215], v[182:185], off nt
	s_cbranch_vccnz .LBB0_932
	s_cmpk_gt_i32 s30, 0x7f
	s_cbranch_scc1 .LBB0_999
	s_and_b32 s57, s30, 15
	s_cmp_eq_u32 s57, 15
	v_lshl_add_u64 v[182:183], v[172:173], 0, v[150:151]
	s_cselect_b64 vcc, -1, 0
	v_cndmask_b32_e32 v183, 0, v183, vcc
	v_cndmask_b32_e32 v182, 0, v182, vcc
	s_cbranch_execz .LBB0_1000

;     __device__ __forceinline__ void operator()(Acc& acc, const Unit& u, int wr, int wc, int fr, int fq, const float (&rsa)[2][4]) const {
;     ...
;                         if (cp) { *(f32x4*)cp = v0; *(f32x4*)(cp + 4) = v1; }
.LBB0_930:
	global_store_dwordx4 v[182:183], v[142:145], off nt
	global_store_dwordx4 v[182:183], v[146:149], off offset:16 nt

; __device__ __forceinline__ unsigned pk2(float lo, float hi) { f32x2_t v = {lo, hi}; bf16x2_t b = __builtin_convertvector(v, bf16x2_t); return __builtin_bit_cast(unsigned, b); }
;     __device__ __forceinline__ void operator()(Acc& acc, const Unit& u, int wr, int wc, int fr, int fq, const float (&rsa)[2][4]) const {
;     ...
;                     u32x4 w; w.x = pk2(v0[0], v0[1]); w.y = pk2(v0[2], v0[3]); w.z = pk2(v1[0], v1[1]); w.w = pk2(v1[2], v1[3]);
;                     *(u32x4*)(dst + (size_t)row * ld + cbase + within) = w;
;                     if (mode == 2) {
;                         float* cp = nullptr;
;                         if (u.pm >= MP / BM) { const int rs_ = row - MP, bs = rs_ >> 5, t = rs_ & 31; cp = out + (bj == 0 ? O_CKS : O_CVS) + ((size_t)(bs * WINDOW + 96 + t)) * 128 + (within & 127); }
;                         else if ((u.pm & 15) == 15 && ai == 1) { const int b = row >> 12, t = row & 4095; cp = out + (bj == 0 ? O_CKP : O_CVP) + ((size_t)(b * WINDOW + (t - (SEQ - WINDOW)))) * 128 + (within & 127); }
.LBB0_940:
	v_lshlrev_b32_e32 v162, 1, v160
	v_cvt_pk_bf16_f32 v142, v134, v135
	v_cvt_pk_bf16_f32 v143, v136, v137
	v_cvt_pk_bf16_f32 v144, v138, v139
	v_cvt_pk_bf16_f32 v145, v140, v141
	v_lshl_add_u64 v[146:147], v[152:153], 0, v[162:163]
	s_andn2_b64 vcc, exec, s[62:63]
	global_store_dwordx4 v[146:147], v[142:145], off offset:256 nt
	s_cbranch_vccnz .LBB0_946
	s_cmpk_gt_i32 s30, 0x7f
	s_mov_b64 s[68:69], -1
	s_cbranch_scc1 .LBB0_1001
	s_and_b32 s57, s30, 15
	s_cmp_eq_u32 s57, 15
	v_lshl_add_u64 v[142:143], v[174:175], 0, v[150:151]
	s_cselect_b64 vcc, -1, 0
	v_cndmask_b32_e32 v143, 0, v143, vcc
	v_cndmask_b32_e32 v142, 0, v142, vcc
	s_cbranch_execz .LBB0_1002

; __device__ __forceinline__ unsigned pk2(float lo, float hi) { f32x2_t v = {lo, hi}; bf16x2_t b = __builtin_convertvector(v, bf16x2_t); return __builtin_bit_cast(unsigned, b); }
;     __device__ __forceinline__ void operator()(Acc& acc, const Unit& u, int wr, int wc, int fr, int fq, const float (&rsa)[2][4]) const {
;     ...
;                     u32x4 w; w.x = pk2(v0[0], v0[1]); w.y = pk2(v0[2], v0[3]); w.z = pk2(v1[0], v1[1]); w.w = pk2(v1[2], v1[3]);
;                     *(u32x4*)(dst + (size_t)row * ld + cbase + within) = w;
;                     if (mode == 2) {
;                         float* cp = nullptr;
;                         if (u.pm >= MP / BM) { const int rs_ = row - MP, bs = rs_ >> 5, t = rs_ & 31; cp = out + (bj == 0 ? O_CKS : O_CVS) + ((size_t)(bs * WINDOW + 96 + t)) * 128 + (within & 127); }
;                         else if ((u.pm & 15) == 15 && ai == 1) { const int b = row >> 12, t = row & 4095; cp = out + (bj == 0 ? O_CKP : O_CVP) + ((size_t)(b * WINDOW + (t - (SEQ - WINDOW)))) * 128 + (within & 127); }
.LBB0_972:
	v_lshlrev_b32_e32 v162, 1, v160
	v_cvt_pk_bf16_f32 v180, v138, v139
	v_cvt_pk_bf16_f32 v181, v140, v141
	v_cvt_pk_bf16_f32 v182, v142, v143
	v_cvt_pk_bf16_f32 v183, v144, v145
	v_lshl_add_u64 v[184:185], v[150:151], 0, v[162:163]
	s_andn2_b64 vcc, exec, s[62:63]
	global_store_dwordx4 v[184:185], v[180:183], off nt
	s_cbranch_vccnz .LBB0_978
	s_cmpk_gt_i32 s30, 0x7f
	s_cbranch_scc1 .LBB0_1007
	s_and_b32 s33, s30, 15
	s_cmp_eq_u32 s33, 15
	v_lshl_add_u64 v[180:181], v[172:173], 0, v[148:149]
	s_cselect_b64 vcc, -1, 0
	v_cndmask_b32_e32 v181, 0, v181, vcc
	v_cndmask_b32_e32 v180, 0, v180, vcc
	s_cbranch_execz .LBB0_1008

;     __device__ __forceinline__ void operator()(Acc& acc, const Unit& u, int wr, int wc, int fr, int fq, const float (&rsa)[2][4]) const {
;     ...
;                         if (cp) { *(f32x4*)cp = v0; *(f32x4*)(cp + 4) = v1; }
.LBB0_976:
	global_store_dwordx4 v[180:181], v[138:141], off nt
	global_store_dwordx4 v[180:181], v[142:145], off offset:16 nt

;     __device__ __forceinline__ void operator()(Acc& acc, const Unit& u, int wr, int wc, int fr, int fq, const float (&rsa)[2][4]) const {
;     ...
;                     if (mode == 3) { if (within < GRANK) { *(f32x4*)(GLR + (size_t)row * 16 + within) = v0; *(f32x4*)(GLR + (size_t)row * 16 + within + 4) = v1; } continue; }
.LBB0_980:
	s_and_b64 vcc, exec, s[64:65]
	s_cbranch_vccz .LBB0_979
	s_and_saveexec_b64 s[64:65], s[4:5]
	s_cbranch_execz .LBB0_983
	v_lshlrev_b64 v[138:139], 6, v[178:179]
	v_lshl_add_u64 v[138:139], v[164:165], 0, v[138:139]
	global_store_dwordx4 v[138:139], v[130:133], off nt
	global_store_dwordx4 v[138:139], v[134:137], off offset:16 nt

; __device__ __forceinline__ unsigned pk2(float lo, float hi) { f32x2_t v = {lo, hi}; bf16x2_t b = __builtin_convertvector(v, bf16x2_t); return __builtin_bit_cast(unsigned, b); }
;     __device__ __forceinline__ void operator()(Acc& acc, const Unit& u, int wr, int wc, int fr, int fq, const float (&rsa)[2][4]) const {
;     ...
;                     u32x4 w; w.x = pk2(v0[0], v0[1]); w.y = pk2(v0[2], v0[3]); w.z = pk2(v1[0], v1[1]); w.w = pk2(v1[2], v1[3]);
;                     *(u32x4*)(dst + (size_t)row * ld + cbase + within) = w;
;                     if (mode == 2) {
;                         float* cp = nullptr;
;                         if (u.pm >= MP / BM) { const int rs_ = row - MP, bs = rs_ >> 5, t = rs_ & 31; cp = out + (bj == 0 ? O_CKS : O_CVS) + ((size_t)(bs * WINDOW + 96 + t)) * 128 + (within & 127); }
;                         else if ((u.pm & 15) == 15 && ai == 1) { const int b = row >> 12, t = row & 4095; cp = out + (bj == 0 ? O_CKP : O_CVP) + ((size_t)(b * WINDOW + (t - (SEQ - WINDOW)))) * 128 + (within & 127); }
.LBB0_986:
	v_lshlrev_b32_e32 v162, 1, v160
	v_cvt_pk_bf16_f32 v138, v130, v131
	v_cvt_pk_bf16_f32 v139, v132, v133
	v_cvt_pk_bf16_f32 v140, v134, v135
	v_cvt_pk_bf16_f32 v141, v136, v137
	v_lshl_add_u64 v[142:143], v[150:151], 0, v[162:163]
	s_andn2_b64 vcc, exec, s[62:63]
	global_store_dwordx4 v[142:143], v[138:141], off offset:256 nt
	s_cbranch_vccnz .LBB0_992
	s_cmpk_gt_i32 s30, 0x7f
	s_mov_b64 s[10:11], -1
	s_cbranch_scc1 .LBB0_1009
	s_and_b32 s10, s30, 15
	s_cmp_eq_u32 s10, 15
	v_lshl_add_u64 v[138:139], v[174:175], 0, v[148:149]
	s_cselect_b64 vcc, -1, 0
	v_cndmask_b32_e32 v139, 0, v139, vcc
	v_cndmask_b32_e32 v138, 0, v138, vcc
	s_cbranch_execz .LBB0_1010

;     __device__ __forceinline__ void operator()(Acc& acc, const Unit& u, int wr, int wc, int fr, int fq, const float (&rsa)[2][4]) const {
;     ...
;                         if (cp) { *(f32x4*)cp = v0; *(f32x4*)(cp + 4) = v1; }
.LBB0_990:
	global_store_dwordx4 v[138:139], v[130:133], off nt
	global_store_dwordx4 v[138:139], v[134:137], off offset:16 nt

; __device__ __forceinline__ unsigned pk2(float lo, float hi) { f32x2_t v = {lo, hi}; bf16x2_t b = __builtin_convertvector(v, bf16x2_t); return __builtin_bit_cast(unsigned, b); }
; __device__ __forceinline__ float siluf_(float x) { return x * sigmoidf_(x); }
;     __device__ __forceinline__ void operator()(Acc& acc, const Unit& u, int wr, int wc, int fr, int fq, const float (&rsa)[2][4]) const {
;         const int pn = u.pn;
;         bf16_t* dst; int ld = D, cbase; float scale = 1.f; int mode = 0;
;         if (pn < 4) { dst = QK; cbase = pn * BM; if (pn < 2) scale = 0.08838834764831845f; }
;         else if (pn < 8) { dst = V; cbase = (pn - 4) * BM; }
;         else if (pn < 12) { dst = SQ; cbase = (pn - 8) * BM; scale = 0.125f * LOG2E; }
;         else if (pn < 16) { dst = GR; cbase = (pn - 12) * BM; mode = 1; }
;         else if (pn == 16) { dst = SKVb; ld = 256; cbase = 0; mode = 2; }
;         else { dst = SKVb; cbase = 0; mode = 3; }
; #pragma unroll
;         for (int ai = 0; ai < 2; ++ai)
; #pragma unroll
;             for (int m = 0; m < 4; ++m) {
;                 const int row = u.pm * BM + ai * HALF + wr * 64 + m * 16 + fr; const float rs = rsa[ai][m] * scale;
; #pragma unroll
;                 for (int bj = 0; bj < 2; ++bj) {
;                     const int within = bj * HALF + wc * 32 + 8 * fq;
;                     f32x4 v0 = acc[ai][bj][m][0] * rs, v1 = acc[ai][bj][m][1] * rs;
;                     if (mode == 3) { if (within < GRANK) { *(f32x4*)(GLR + (size_t)row * 16 + within) = v0; *(f32x4*)(GLR + (size_t)row * 16 + within + 4) = v1; } continue; }
;                     if (mode == 1) {
; #pragma unroll
;                         for (int j = 0; j < 4; ++j) { v0[j] = siluf_(v0[j]); v1[j] = siluf_(v1[j]); }
;                     }
;                     u32x4 w; w.x = pk2(v0[0], v0[1]); w.y = pk2(v0[2], v0[3]); w.z = pk2(v1[0], v1[1]); w.w = pk2(v1[2], v1[3]);
;                     *(u32x4*)(dst + (size_t)row * ld + cbase + within) = w;
.Lp3f_ns1:
	v_cvt_pk_bf16_f32 v240, v222, v223
	v_cvt_pk_bf16_f32 v241, v224, v225
	v_cvt_pk_bf16_f32 v242, v226, v227
	v_cvt_pk_bf16_f32 v243, v228, v229
	ds_bpermute_b32 v248, v221, v240
	ds_bpermute_b32 v249, v221, v241
	ds_bpermute_b32 v250, v221, v242
	ds_bpermute_b32 v251, v221, v243
	s_waitcnt lgkmcnt(4)
	s_add_u32 s100, s98, 0x0
	s_addc_u32 s101, s99, 0
	global_store_dwordx4 v220, v[244:247], s[100:101] offset:0 nt
	v_mul_f32_e32 v238, s88, v135
	v_pk_mul_f32 v[222:223], v[118:119], v[238:239] op_sel_hi:[1,0]
	v_mov_b64_e32 v[118:119], 0
	v_pk_mul_f32 v[224:225], v[120:121], v[238:239] op_sel_hi:[1,0]
	v_mov_b64_e32 v[120:121], 0
	v_pk_mul_f32 v[226:227], v[114:115], v[238:239] op_sel_hi:[1,0]
	v_mov_b64_e32 v[114:115], 0
	v_pk_mul_f32 v[228:229], v[116:117], v[238:239] op_sel_hi:[1,0]
	v_mov_b64_e32 v[116:117], 0
	s_cmp_lg_u32 s79, 3
	s_cbranch_scc1 .Lp3f_ns2
	v_mul_f32_e32 v230, 0xbfb8aa3b, v222
	v_mul_f32_e32 v231, 0xbfb8aa3b, v223
	v_mul_f32_e32 v232, 0xbfb8aa3b, v224
	v_mul_f32_e32 v233, 0xbfb8aa3b, v225
	v_mul_f32_e32 v234, 0xbfb8aa3b, v226
	v_mul_f32_e32 v235, 0xbfb8aa3b, v227
	v_mul_f32_e32 v236, 0xbfb8aa3b, v228
	v_mul_f32_e32 v237, 0xbfb8aa3b, v229
	v_exp_f32_e32 v230, v230
	v_exp_f32_e32 v231, v231
	v_exp_f32_e32 v232, v232
	v_exp_f32_e32 v233, v233
	v_exp_f32_e32 v234, v234
	v_exp_f32_e32 v235, v235
	v_exp_f32_e32 v236, v236
	v_exp_f32_e32 v237, v237
	v_add_f32_e32 v230, 1.0, v230
	v_add_f32_e32 v231, 1.0, v231
	v_add_f32_e32 v232, 1.0, v232
	v_add_f32_e32 v233, 1.0, v233
	v_add_f32_e32 v234, 1.0, v234
	v_add_f32_e32 v235, 1.0, v235
	v_add_f32_e32 v236, 1.0, v236
	v_add_f32_e32 v237, 1.0, v237
	v_rcp_f32_e32 v230, v230
	v_rcp_f32_e32 v231, v231
	v_rcp_f32_e32 v232, v232
	v_rcp_f32_e32 v233, v233
	v_rcp_f32_e32 v234, v234
	v_rcp_f32_e32 v235, v235
	v_rcp_f32_e32 v236, v236
	v_rcp_f32_e32 v237, v237
	v_pk_mul_f32 v[222:223], v[222:223], v[230:231]
	v_pk_mul_f32 v[224:225], v[224:225], v[232:233]
	v_pk_mul_f32 v[226:227], v[226:227], v[234:235]
	v_pk_mul_f32 v[228:229], v[228:229], v[236:237]
.Lp3f_ns2:
	v_cvt_pk_bf16_f32 v240, v222, v223
	v_cvt_pk_bf16_f32 v241, v224, v225
	v_cvt_pk_bf16_f32 v242, v226, v227
	v_cvt_pk_bf16_f32 v243, v228, v229
	ds_bpermute_b32 v244, v221, v240
	ds_bpermute_b32 v245, v221, v241
	ds_bpermute_b32 v246, v221, v242
	ds_bpermute_b32 v247, v221, v243
	s_waitcnt lgkmcnt(4)
	s_add_u32 s100, s98, 0x0
	s_addc_u32 s101, s99, 0
	global_store_dwordx4 v220, v[248:251], s[100:101] offset:256 nt
	v_pk_mul_f32 v[222:223], v[86:87], v[238:239] op_sel_hi:[1,0]
	v_mov_b64_e32 v[86:87], 0
	v_pk_mul_f32 v[224:225], v[88:89], v[238:239] op_sel_hi:[1,0]
	v_mov_b64_e32 v[88:89], 0
	v_pk_mul_f32 v[226:227], v[82:83], v[238:239] op_sel_hi:[1,0]
	v_mov_b64_e32 v[82:83], 0
	v_pk_mul_f32 v[228:229], v[84:85], v[238:239] op_sel_hi:[1,0]
	v_mov_b64_e32 v[84:85], 0
	s_cmp_lg_u32 s79, 3
	s_cbranch_scc1 .Lp3f_ns3
	v_mul_f32_e32 v230, 0xbfb8aa3b, v222
	v_mul_f32_e32 v231, 0xbfb8aa3b, v223
	v_mul_f32_e32 v232, 0xbfb8aa3b, v224
	v_mul_f32_e32 v233, 0xbfb8aa3b, v225
	v_mul_f32_e32 v234, 0xbfb8aa3b, v226
	v_mul_f32_e32 v235, 0xbfb8aa3b, v227
	v_mul_f32_e32 v236, 0xbfb8aa3b, v228
	v_mul_f32_e32 v237, 0xbfb8aa3b, v229
	v_exp_f32_e32 v230, v230
	v_exp_f32_e32 v231, v231
	v_exp_f32_e32 v232, v232
	v_exp_f32_e32 v233, v233
	v_exp_f32_e32 v234, v234
	v_exp_f32_e32 v235, v235
	v_exp_f32_e32 v236, v236
	v_exp_f32_e32 v237, v237
	v_add_f32_e32 v230, 1.0, v230
	v_add_f32_e32 v231, 1.0, v231
	v_add_f32_e32 v232, 1.0, v232
	v_add_f32_e32 v233, 1.0, v233
	v_add_f32_e32 v234, 1.0, v234
	v_add_f32_e32 v235, 1.0, v235
	v_add_f32_e32 v236, 1.0, v236
	v_add_f32_e32 v237, 1.0, v237
	v_rcp_f32_e32 v230, v230
	v_rcp_f32_e32 v231, v231
	v_rcp_f32_e32 v232, v232
	v_rcp_f32_e32 v233, v233
	v_rcp_f32_e32 v234, v234
	v_rcp_f32_e32 v235, v235
	v_rcp_f32_e32 v236, v236
	v_rcp_f32_e32 v237, v237
	v_pk_mul_f32 v[222:223], v[222:223], v[230:231]
	v_pk_mul_f32 v[224:225], v[224:225], v[232:233]
	v_pk_mul_f32 v[226:227], v[226:227], v[234:235]
	v_pk_mul_f32 v[228:229], v[228:229], v[236:237]
.Lp3f_ns3:
	v_cvt_pk_bf16_f32 v240, v222, v223
	v_cvt_pk_bf16_f32 v241, v224, v225
	v_cvt_pk_bf16_f32 v242, v226, v227
	v_cvt_pk_bf16_f32 v243, v228, v229
	ds_bpermute_b32 v248, v221, v240
	ds_bpermute_b32 v249, v221, v241
	ds_bpermute_b32 v250, v221, v242
	ds_bpermute_b32 v251, v221, v243
	s_waitcnt lgkmcnt(4)
	s_add_u32 s100, s98, 0x8000
	s_addc_u32 s101, s99, 0
	global_store_dwordx4 v220, v[244:247], s[100:101] offset:0 nt
	v_mul_f32_e32 v238, s88, v136
	v_pk_mul_f32 v[222:223], v[110:111], v[238:239] op_sel_hi:[1,0]
	v_mov_b64_e32 v[110:111], 0
	v_pk_mul_f32 v[224:225], v[112:113], v[238:239] op_sel_hi:[1,0]
	v_mov_b64_e32 v[112:113], 0
	v_pk_mul_f32 v[226:227], v[106:107], v[238:239] op_sel_hi:[1,0]
	v_mov_b64_e32 v[106:107], 0
	v_pk_mul_f32 v[228:229], v[108:109], v[238:239] op_sel_hi:[1,0]
	v_mov_b64_e32 v[108:109], 0
	s_cmp_lg_u32 s79, 3
	s_cbranch_scc1 .Lp3f_ns4
	v_mul_f32_e32 v230, 0xbfb8aa3b, v222
	v_mul_f32_e32 v231, 0xbfb8aa3b, v223
	v_mul_f32_e32 v232, 0xbfb8aa3b, v224
	v_mul_f32_e32 v233, 0xbfb8aa3b, v225
	v_mul_f32_e32 v234, 0xbfb8aa3b, v226
	v_mul_f32_e32 v235, 0xbfb8aa3b, v227
	v_mul_f32_e32 v236, 0xbfb8aa3b, v228
	v_mul_f32_e32 v237, 0xbfb8aa3b, v229
	v_exp_f32_e32 v230, v230
	v_exp_f32_e32 v231, v231
	v_exp_f32_e32 v232, v232
	v_exp_f32_e32 v233, v233
	v_exp_f32_e32 v234, v234
	v_exp_f32_e32 v235, v235
	v_exp_f32_e32 v236, v236
	v_exp_f32_e32 v237, v237
	v_add_f32_e32 v230, 1.0, v230
	v_add_f32_e32 v231, 1.0, v231
	v_add_f32_e32 v232, 1.0, v232
	v_add_f32_e32 v233, 1.0, v233
	v_add_f32_e32 v234, 1.0, v234
	v_add_f32_e32 v235, 1.0, v235
	v_add_f32_e32 v236, 1.0, v236
	v_add_f32_e32 v237, 1.0, v237
	v_rcp_f32_e32 v230, v230
	v_rcp_f32_e32 v231, v231
	v_rcp_f32_e32 v232, v232
	v_rcp_f32_e32 v233, v233
	v_rcp_f32_e32 v234, v234
	v_rcp_f32_e32 v235, v235
	v_rcp_f32_e32 v236, v236
	v_rcp_f32_e32 v237, v237
	v_pk_mul_f32 v[222:223], v[222:223], v[230:231]
	v_pk_mul_f32 v[224:225], v[224:225], v[232:233]
	v_pk_mul_f32 v[226:227], v[226:227], v[234:235]
	v_pk_mul_f32 v[228:229], v[228:229], v[236:237]
; __device__ __forceinline__ unsigned pk2(float lo, float hi) { f32x2_t v = {lo, hi}; bf16x2_t b = __builtin_convertvector(v, bf16x2_t); return __builtin_bit_cast(unsigned, b); }
; __device__ __forceinline__ float siluf_(float x) { return x * sigmoidf_(x); }
;     __device__ __forceinline__ void operator()(Acc& acc, const Unit& u, int wr, int wc, int fr, int fq, const float (&rsa)[2][4]) const {
;         const int pn = u.pn;
;         bf16_t* dst; int ld = D, cbase; float scale = 1.f; int mode = 0;
;         if (pn < 4) { dst = QK; cbase = pn * BM; if (pn < 2) scale = 0.08838834764831845f; }
;         else if (pn < 8) { dst = V; cbase = (pn - 4) * BM; }
;         else if (pn < 12) { dst = SQ; cbase = (pn - 8) * BM; scale = 0.125f * LOG2E; }
;         else if (pn < 16) { dst = GR; cbase = (pn - 12) * BM; mode = 1; }
;         else if (pn == 16) { dst = SKVb; ld = 256; cbase = 0; mode = 2; }
;         else { dst = SKVb; cbase = 0; mode = 3; }
; #pragma unroll
;         for (int ai = 0; ai < 2; ++ai)
; #pragma unroll
;             for (int m = 0; m < 4; ++m) {
;                 const int row = u.pm * BM + ai * HALF + wr * 64 + m * 16 + fr; const float rs = rsa[ai][m] * scale;
; #pragma unroll
;                 for (int bj = 0; bj < 2; ++bj) {
;                     const int within = bj * HALF + wc * 32 + 8 * fq;
;                     f32x4 v0 = acc[ai][bj][m][0] * rs, v1 = acc[ai][bj][m][1] * rs;
;                     if (mode == 3) { if (within < GRANK) { *(f32x4*)(GLR + (size_t)row * 16 + within) = v0; *(f32x4*)(GLR + (size_t)row * 16 + within + 4) = v1; } continue; }
;                     if (mode == 1) {
; #pragma unroll
;                         for (int j = 0; j < 4; ++j) { v0[j] = siluf_(v0[j]); v1[j] = siluf_(v1[j]); }
;                     }
;                     u32x4 w; w.x = pk2(v0[0], v0[1]); w.y = pk2(v0[2], v0[3]); w.z = pk2(v1[0], v1[1]); w.w = pk2(v1[2], v1[3]);
;                     *(u32x4*)(dst + (size_t)row * ld + cbase + within) = w;
.Lp3f_ns4:
	v_cvt_pk_bf16_f32 v240, v222, v223
	v_cvt_pk_bf16_f32 v241, v224, v225
	v_cvt_pk_bf16_f32 v242, v226, v227
	v_cvt_pk_bf16_f32 v243, v228, v229
	ds_bpermute_b32 v244, v221, v240
	ds_bpermute_b32 v245, v221, v241
	ds_bpermute_b32 v246, v221, v242
	ds_bpermute_b32 v247, v221, v243
	s_waitcnt lgkmcnt(4)
	s_add_u32 s100, s98, 0x8000
	s_addc_u32 s101, s99, 0
	global_store_dwordx4 v220, v[248:251], s[100:101] offset:256 nt
	v_pk_mul_f32 v[222:223], v[78:79], v[238:239] op_sel_hi:[1,0]
	v_mov_b64_e32 v[78:79], 0
	v_pk_mul_f32 v[224:225], v[80:81], v[238:239] op_sel_hi:[1,0]
	v_mov_b64_e32 v[80:81], 0
	v_pk_mul_f32 v[226:227], v[74:75], v[238:239] op_sel_hi:[1,0]
	v_mov_b64_e32 v[74:75], 0
	v_pk_mul_f32 v[228:229], v[76:77], v[238:239] op_sel_hi:[1,0]
	v_mov_b64_e32 v[76:77], 0
	s_cmp_lg_u32 s79, 3
	s_cbranch_scc1 .Lp3f_ns5
	v_mul_f32_e32 v230, 0xbfb8aa3b, v222
	v_mul_f32_e32 v231, 0xbfb8aa3b, v223
	v_mul_f32_e32 v232, 0xbfb8aa3b, v224
	v_mul_f32_e32 v233, 0xbfb8aa3b, v225
	v_mul_f32_e32 v234, 0xbfb8aa3b, v226
	v_mul_f32_e32 v235, 0xbfb8aa3b, v227
	v_mul_f32_e32 v236, 0xbfb8aa3b, v228
	v_mul_f32_e32 v237, 0xbfb8aa3b, v229
	v_exp_f32_e32 v230, v230
	v_exp_f32_e32 v231, v231
	v_exp_f32_e32 v232, v232
	v_exp_f32_e32 v233, v233
	v_exp_f32_e32 v234, v234
	v_exp_f32_e32 v235, v235
	v_exp_f32_e32 v236, v236
	v_exp_f32_e32 v237, v237
	v_add_f32_e32 v230, 1.0, v230
	v_add_f32_e32 v231, 1.0, v231
	v_add_f32_e32 v232, 1.0, v232
	v_add_f32_e32 v233, 1.0, v233
	v_add_f32_e32 v234, 1.0, v234
	v_add_f32_e32 v235, 1.0, v235
	v_add_f32_e32 v236, 1.0, v236
	v_add_f32_e32 v237, 1.0, v237
	v_rcp_f32_e32 v230, v230
	v_rcp_f32_e32 v231, v231
	v_rcp_f32_e32 v232, v232
	v_rcp_f32_e32 v233, v233
	v_rcp_f32_e32 v234, v234
	v_rcp_f32_e32 v235, v235
	v_rcp_f32_e32 v236, v236
	v_rcp_f32_e32 v237, v237
	v_pk_mul_f32 v[222:223], v[222:223], v[230:231]
	v_pk_mul_f32 v[224:225], v[224:225], v[232:233]
	v_pk_mul_f32 v[226:227], v[226:227], v[234:235]
	v_pk_mul_f32 v[228:229], v[228:229], v[236:237]
.Lp3f_ns5:
	v_cvt_pk_bf16_f32 v240, v222, v223
	v_cvt_pk_bf16_f32 v241, v224, v225
	v_cvt_pk_bf16_f32 v242, v226, v227
	v_cvt_pk_bf16_f32 v243, v228, v229
	ds_bpermute_b32 v248, v221, v240
	ds_bpermute_b32 v249, v221, v241
	ds_bpermute_b32 v250, v221, v242
	ds_bpermute_b32 v251, v221, v243
	s_waitcnt lgkmcnt(4)
	s_add_u32 s100, s98, 0x10000
	s_addc_u32 s101, s99, 0
	global_store_dwordx4 v220, v[244:247], s[100:101] offset:0 nt
	v_mul_f32_e32 v238, s88, v137
	v_pk_mul_f32 v[222:223], v[102:103], v[238:239] op_sel_hi:[1,0]
	v_mov_b64_e32 v[102:103], 0
	v_pk_mul_f32 v[224:225], v[104:105], v[238:239] op_sel_hi:[1,0]
	v_mov_b64_e32 v[104:105], 0
	v_pk_mul_f32 v[226:227], v[98:99], v[238:239] op_sel_hi:[1,0]
	v_mov_b64_e32 v[98:99], 0
	v_pk_mul_f32 v[228:229], v[100:101], v[238:239] op_sel_hi:[1,0]
	v_mov_b64_e32 v[100:101], 0
	s_cmp_lg_u32 s79, 3
	s_cbranch_scc1 .Lp3f_ns6
	v_mul_f32_e32 v230, 0xbfb8aa3b, v222
	v_mul_f32_e32 v231, 0xbfb8aa3b, v223
	v_mul_f32_e32 v232, 0xbfb8aa3b, v224
	v_mul_f32_e32 v233, 0xbfb8aa3b, v225
	v_mul_f32_e32 v234, 0xbfb8aa3b, v226
	v_mul_f32_e32 v235, 0xbfb8aa3b, v227
	v_mul_f32_e32 v236, 0xbfb8aa3b, v228
	v_mul_f32_e32 v237, 0xbfb8aa3b, v229
	v_exp_f32_e32 v230, v230
	v_exp_f32_e32 v231, v231
	v_exp_f32_e32 v232, v232
	v_exp_f32_e32 v233, v233
	v_exp_f32_e32 v234, v234
	v_exp_f32_e32 v235, v235
	v_exp_f32_e32 v236, v236
	v_exp_f32_e32 v237, v237
	v_add_f32_e32 v230, 1.0, v230
	v_add_f32_e32 v231, 1.0, v231
	v_add_f32_e32 v232, 1.0, v232
	v_add_f32_e32 v233, 1.0, v233
	v_add_f32_e32 v234, 1.0, v234
	v_add_f32_e32 v235, 1.0, v235
	v_add_f32_e32 v236, 1.0, v236
	v_add_f32_e32 v237, 1.0, v237
	v_rcp_f32_e32 v230, v230
	v_rcp_f32_e32 v231, v231
	v_rcp_f32_e32 v232, v232
	v_rcp_f32_e32 v233, v233
	v_rcp_f32_e32 v234, v234
	v_rcp_f32_e32 v235, v235
	v_rcp_f32_e32 v236, v236
	v_rcp_f32_e32 v237, v237
	v_pk_mul_f32 v[222:223], v[222:223], v[230:231]
	v_pk_mul_f32 v[224:225], v[224:225], v[232:233]
	v_pk_mul_f32 v[226:227], v[226:227], v[234:235]
	v_pk_mul_f32 v[228:229], v[228:229], v[236:237]
.Lp3f_ns6:
	v_cvt_pk_bf16_f32 v240, v222, v223
	v_cvt_pk_bf16_f32 v241, v224, v225
	v_cvt_pk_bf16_f32 v242, v226, v227
	v_cvt_pk_bf16_f32 v243, v228, v229
	ds_bpermute_b32 v244, v221, v240
	ds_bpermute_b32 v245, v221, v241
	ds_bpermute_b32 v246, v221, v242
	ds_bpermute_b32 v247, v221, v243
	s_waitcnt lgkmcnt(4)
	s_add_u32 s100, s98, 0x10000
	s_addc_u32 s101, s99, 0
	global_store_dwordx4 v220, v[248:251], s[100:101] offset:256 nt
	v_pk_mul_f32 v[222:223], v[70:71], v[238:239] op_sel_hi:[1,0]
	v_mov_b64_e32 v[70:71], 0
	v_pk_mul_f32 v[224:225], v[72:73], v[238:239] op_sel_hi:[1,0]
	v_mov_b64_e32 v[72:73], 0
	v_pk_mul_f32 v[226:227], v[66:67], v[238:239] op_sel_hi:[1,0]
	v_mov_b64_e32 v[66:67], 0
	v_pk_mul_f32 v[228:229], v[68:69], v[238:239] op_sel_hi:[1,0]
	v_mov_b64_e32 v[68:69], 0
	s_cmp_lg_u32 s79, 3
	s_cbranch_scc1 .Lp3f_ns7
	v_mul_f32_e32 v230, 0xbfb8aa3b, v222
	v_mul_f32_e32 v231, 0xbfb8aa3b, v223
	v_mul_f32_e32 v232, 0xbfb8aa3b, v224
	v_mul_f32_e32 v233, 0xbfb8aa3b, v225
	v_mul_f32_e32 v234, 0xbfb8aa3b, v226
	v_mul_f32_e32 v235, 0xbfb8aa3b, v227
	v_mul_f32_e32 v236, 0xbfb8aa3b, v228
	v_mul_f32_e32 v237, 0xbfb8aa3b, v229
	v_exp_f32_e32 v230, v230
	v_exp_f32_e32 v231, v231
	v_exp_f32_e32 v232, v232
	v_exp_f32_e32 v233, v233
	v_exp_f32_e32 v234, v234
	v_exp_f32_e32 v235, v235
	v_exp_f32_e32 v236, v236
	v_exp_f32_e32 v237, v237
	v_add_f32_e32 v230, 1.0, v230
	v_add_f32_e32 v231, 1.0, v231
	v_add_f32_e32 v232, 1.0, v232
	v_add_f32_e32 v233, 1.0, v233
	v_add_f32_e32 v234, 1.0, v234
	v_add_f32_e32 v235, 1.0, v235
	v_add_f32_e32 v236, 1.0, v236
	v_add_f32_e32 v237, 1.0, v237
	v_rcp_f32_e32 v230, v230
	v_rcp_f32_e32 v231, v231
	v_rcp_f32_e32 v232, v232
	v_rcp_f32_e32 v233, v233
	v_rcp_f32_e32 v234, v234
	v_rcp_f32_e32 v235, v235
	v_rcp_f32_e32 v236, v236
	v_rcp_f32_e32 v237, v237
	v_pk_mul_f32 v[222:223], v[222:223], v[230:231]
	v_pk_mul_f32 v[224:225], v[224:225], v[232:233]
	v_pk_mul_f32 v[226:227], v[226:227], v[234:235]
	v_pk_mul_f32 v[228:229], v[228:229], v[236:237]
; __device__ __forceinline__ unsigned pk2(float lo, float hi) { f32x2_t v = {lo, hi}; bf16x2_t b = __builtin_convertvector(v, bf16x2_t); return __builtin_bit_cast(unsigned, b); }
; __device__ __forceinline__ float siluf_(float x) { return x * sigmoidf_(x); }
;     __device__ __forceinline__ void operator()(Acc& acc, const Unit& u, int wr, int wc, int fr, int fq, const float (&rsa)[2][4]) const {
;         const int pn = u.pn;
;         bf16_t* dst; int ld = D, cbase; float scale = 1.f; int mode = 0;
;         if (pn < 4) { dst = QK; cbase = pn * BM; if (pn < 2) scale = 0.08838834764831845f; }
;         else if (pn < 8) { dst = V; cbase = (pn - 4) * BM; }
;         else if (pn < 12) { dst = SQ; cbase = (pn - 8) * BM; scale = 0.125f * LOG2E; }
;         else if (pn < 16) { dst = GR; cbase = (pn - 12) * BM; mode = 1; }
;         else if (pn == 16) { dst = SKVb; ld = 256; cbase = 0; mode = 2; }
;         else { dst = SKVb; cbase = 0; mode = 3; }
; #pragma unroll
;         for (int ai = 0; ai < 2; ++ai)
; #pragma unroll
;             for (int m = 0; m < 4; ++m) {
;                 const int row = u.pm * BM + ai * HALF + wr * 64 + m * 16 + fr; const float rs = rsa[ai][m] * scale;
; #pragma unroll
;                 for (int bj = 0; bj < 2; ++bj) {
;                     const int within = bj * HALF + wc * 32 + 8 * fq;
;                     f32x4 v0 = acc[ai][bj][m][0] * rs, v1 = acc[ai][bj][m][1] * rs;
;                     if (mode == 3) { if (within < GRANK) { *(f32x4*)(GLR + (size_t)row * 16 + within) = v0; *(f32x4*)(GLR + (size_t)row * 16 + within + 4) = v1; } continue; }
;                     if (mode == 1) {
; #pragma unroll
;                         for (int j = 0; j < 4; ++j) { v0[j] = siluf_(v0[j]); v1[j] = siluf_(v1[j]); }
;                     }
;                     u32x4 w; w.x = pk2(v0[0], v0[1]); w.y = pk2(v0[2], v0[3]); w.z = pk2(v1[0], v1[1]); w.w = pk2(v1[2], v1[3]);
;                     *(u32x4*)(dst + (size_t)row * ld + cbase + within) = w;
.Lp3f_ns7:
	v_cvt_pk_bf16_f32 v240, v222, v223
	v_cvt_pk_bf16_f32 v241, v224, v225
	v_cvt_pk_bf16_f32 v242, v226, v227
	v_cvt_pk_bf16_f32 v243, v228, v229
	ds_bpermute_b32 v248, v221, v240
	ds_bpermute_b32 v249, v221, v241
	ds_bpermute_b32 v250, v221, v242
	ds_bpermute_b32 v251, v221, v243
	s_waitcnt lgkmcnt(4)
	s_add_u32 s100, s98, 0x18000
	s_addc_u32 s101, s99, 0
	global_store_dwordx4 v220, v[244:247], s[100:101] offset:0 nt
	v_mul_f32_e32 v238, s88, v130
	v_pk_mul_f32 v[222:223], v[62:63], v[238:239] op_sel_hi:[1,0]
	v_mov_b64_e32 v[62:63], 0
	v_pk_mul_f32 v[224:225], v[64:65], v[238:239] op_sel_hi:[1,0]
	v_mov_b64_e32 v[64:65], 0
	v_pk_mul_f32 v[226:227], v[58:59], v[238:239] op_sel_hi:[1,0]
	v_mov_b64_e32 v[58:59], 0
	v_pk_mul_f32 v[228:229], v[60:61], v[238:239] op_sel_hi:[1,0]
	v_mov_b64_e32 v[60:61], 0
	s_cmp_lg_u32 s79, 3
	s_cbranch_scc1 .Lp3f_ns8
	v_mul_f32_e32 v230, 0xbfb8aa3b, v222
	v_mul_f32_e32 v231, 0xbfb8aa3b, v223
	v_mul_f32_e32 v232, 0xbfb8aa3b, v224
	v_mul_f32_e32 v233, 0xbfb8aa3b, v225
	v_mul_f32_e32 v234, 0xbfb8aa3b, v226
	v_mul_f32_e32 v235, 0xbfb8aa3b, v227
	v_mul_f32_e32 v236, 0xbfb8aa3b, v228
	v_mul_f32_e32 v237, 0xbfb8aa3b, v229
	v_exp_f32_e32 v230, v230
	v_exp_f32_e32 v231, v231
	v_exp_f32_e32 v232, v232
	v_exp_f32_e32 v233, v233
	v_exp_f32_e32 v234, v234
	v_exp_f32_e32 v235, v235
	v_exp_f32_e32 v236, v236
	v_exp_f32_e32 v237, v237
	v_add_f32_e32 v230, 1.0, v230
	v_add_f32_e32 v231, 1.0, v231
	v_add_f32_e32 v232, 1.0, v232
	v_add_f32_e32 v233, 1.0, v233
	v_add_f32_e32 v234, 1.0, v234
	v_add_f32_e32 v235, 1.0, v235
	v_add_f32_e32 v236, 1.0, v236
	v_add_f32_e32 v237, 1.0, v237
	v_rcp_f32_e32 v230, v230
	v_rcp_f32_e32 v231, v231
	v_rcp_f32_e32 v232, v232
	v_rcp_f32_e32 v233, v233
	v_rcp_f32_e32 v234, v234
	v_rcp_f32_e32 v235, v235
	v_rcp_f32_e32 v236, v236
	v_rcp_f32_e32 v237, v237
	v_pk_mul_f32 v[222:223], v[222:223], v[230:231]
	v_pk_mul_f32 v[224:225], v[224:225], v[232:233]
	v_pk_mul_f32 v[226:227], v[226:227], v[234:235]
	v_pk_mul_f32 v[228:229], v[228:229], v[236:237]
.Lp3f_ns8:
	v_cvt_pk_bf16_f32 v240, v222, v223
	v_cvt_pk_bf16_f32 v241, v224, v225
	v_cvt_pk_bf16_f32 v242, v226, v227
	v_cvt_pk_bf16_f32 v243, v228, v229
	ds_bpermute_b32 v244, v221, v240
	ds_bpermute_b32 v245, v221, v241
	ds_bpermute_b32 v246, v221, v242
	ds_bpermute_b32 v247, v221, v243
	s_waitcnt lgkmcnt(4)
	s_add_u32 s100, s98, 0x18000
	s_addc_u32 s101, s99, 0
	global_store_dwordx4 v220, v[248:251], s[100:101] offset:256 nt
	v_pk_mul_f32 v[222:223], v[30:31], v[238:239] op_sel_hi:[1,0]
	v_mov_b64_e32 v[30:31], 0
	v_pk_mul_f32 v[224:225], v[32:33], v[238:239] op_sel_hi:[1,0]
	v_mov_b64_e32 v[32:33], 0
	v_pk_mul_f32 v[226:227], v[26:27], v[238:239] op_sel_hi:[1,0]
	v_mov_b64_e32 v[26:27], 0
	v_pk_mul_f32 v[228:229], v[28:29], v[238:239] op_sel_hi:[1,0]
	v_mov_b64_e32 v[28:29], 0
	s_cmp_lg_u32 s79, 3
	s_cbranch_scc1 .Lp3f_ns9
	v_mul_f32_e32 v230, 0xbfb8aa3b, v222
	v_mul_f32_e32 v231, 0xbfb8aa3b, v223
	v_mul_f32_e32 v232, 0xbfb8aa3b, v224
	v_mul_f32_e32 v233, 0xbfb8aa3b, v225
	v_mul_f32_e32 v234, 0xbfb8aa3b, v226
	v_mul_f32_e32 v235, 0xbfb8aa3b, v227
	v_mul_f32_e32 v236, 0xbfb8aa3b, v228
	v_mul_f32_e32 v237, 0xbfb8aa3b, v229
	v_exp_f32_e32 v230, v230
	v_exp_f32_e32 v231, v231
	v_exp_f32_e32 v232, v232
	v_exp_f32_e32 v233, v233
	v_exp_f32_e32 v234, v234
	v_exp_f32_e32 v235, v235
	v_exp_f32_e32 v236, v236
	v_exp_f32_e32 v237, v237
	v_add_f32_e32 v230, 1.0, v230
	v_add_f32_e32 v231, 1.0, v231
	v_add_f32_e32 v232, 1.0, v232
	v_add_f32_e32 v233, 1.0, v233
	v_add_f32_e32 v234, 1.0, v234
	v_add_f32_e32 v235, 1.0, v235
	v_add_f32_e32 v236, 1.0, v236
	v_add_f32_e32 v237, 1.0, v237
	v_rcp_f32_e32 v230, v230
	v_rcp_f32_e32 v231, v231
	v_rcp_f32_e32 v232, v232
	v_rcp_f32_e32 v233, v233
	v_rcp_f32_e32 v234, v234
	v_rcp_f32_e32 v235, v235
	v_rcp_f32_e32 v236, v236
	v_rcp_f32_e32 v237, v237
	v_pk_mul_f32 v[222:223], v[222:223], v[230:231]
	v_pk_mul_f32 v[224:225], v[224:225], v[232:233]
	v_pk_mul_f32 v[226:227], v[226:227], v[234:235]
	v_pk_mul_f32 v[228:229], v[228:229], v[236:237]
.Lp3f_ns9:
	v_cvt_pk_bf16_f32 v240, v222, v223
	v_cvt_pk_bf16_f32 v241, v224, v225
	v_cvt_pk_bf16_f32 v242, v226, v227
	v_cvt_pk_bf16_f32 v243, v228, v229
	ds_bpermute_b32 v248, v221, v240
	ds_bpermute_b32 v249, v221, v241
	ds_bpermute_b32 v250, v221, v242
	ds_bpermute_b32 v251, v221, v243
	s_waitcnt lgkmcnt(4)
	s_add_u32 s100, s98, 0x40000
	s_addc_u32 s101, s99, 0
	global_store_dwordx4 v220, v[244:247], s[100:101] offset:0 nt
	v_mul_f32_e32 v238, s88, v131
	v_pk_mul_f32 v[222:223], v[54:55], v[238:239] op_sel_hi:[1,0]
	v_mov_b64_e32 v[54:55], 0
	v_pk_mul_f32 v[224:225], v[56:57], v[238:239] op_sel_hi:[1,0]
	v_mov_b64_e32 v[56:57], 0
	v_pk_mul_f32 v[226:227], v[50:51], v[238:239] op_sel_hi:[1,0]
	v_mov_b64_e32 v[50:51], 0
	v_pk_mul_f32 v[228:229], v[52:53], v[238:239] op_sel_hi:[1,0]
	v_mov_b64_e32 v[52:53], 0
	s_cmp_lg_u32 s79, 3
	s_cbranch_scc1 .Lp3f_ns10
	v_mul_f32_e32 v230, 0xbfb8aa3b, v222
	v_mul_f32_e32 v231, 0xbfb8aa3b, v223
	v_mul_f32_e32 v232, 0xbfb8aa3b, v224
	v_mul_f32_e32 v233, 0xbfb8aa3b, v225
	v_mul_f32_e32 v234, 0xbfb8aa3b, v226
	v_mul_f32_e32 v235, 0xbfb8aa3b, v227
	v_mul_f32_e32 v236, 0xbfb8aa3b, v228
	v_mul_f32_e32 v237, 0xbfb8aa3b, v229
	v_exp_f32_e32 v230, v230
	v_exp_f32_e32 v231, v231
	v_exp_f32_e32 v232, v232
	v_exp_f32_e32 v233, v233
	v_exp_f32_e32 v234, v234
	v_exp_f32_e32 v235, v235
	v_exp_f32_e32 v236, v236
	v_exp_f32_e32 v237, v237
	v_add_f32_e32 v230, 1.0, v230
	v_add_f32_e32 v231, 1.0, v231
	v_add_f32_e32 v232, 1.0, v232
	v_add_f32_e32 v233, 1.0, v233
	v_add_f32_e32 v234, 1.0, v234
	v_add_f32_e32 v235, 1.0, v235
	v_add_f32_e32 v236, 1.0, v236
	v_add_f32_e32 v237, 1.0, v237
	v_rcp_f32_e32 v230, v230
	v_rcp_f32_e32 v231, v231
	v_rcp_f32_e32 v232, v232
	v_rcp_f32_e32 v233, v233
	v_rcp_f32_e32 v234, v234
	v_rcp_f32_e32 v235, v235
	v_rcp_f32_e32 v236, v236
	v_rcp_f32_e32 v237, v237
	v_pk_mul_f32 v[222:223], v[222:223], v[230:231]
	v_pk_mul_f32 v[224:225], v[224:225], v[232:233]
	v_pk_mul_f32 v[226:227], v[226:227], v[234:235]
	v_pk_mul_f32 v[228:229], v[228:229], v[236:237]
; __device__ __forceinline__ unsigned pk2(float lo, float hi) { f32x2_t v = {lo, hi}; bf16x2_t b = __builtin_convertvector(v, bf16x2_t); return __builtin_bit_cast(unsigned, b); }
; __device__ __forceinline__ float siluf_(float x) { return x * sigmoidf_(x); }
;     __device__ __forceinline__ void operator()(Acc& acc, const Unit& u, int wr, int wc, int fr, int fq, const float (&rsa)[2][4]) const {
;         const int pn = u.pn;
;         bf16_t* dst; int ld = D, cbase; float scale = 1.f; int mode = 0;
;         if (pn < 4) { dst = QK; cbase = pn * BM; if (pn < 2) scale = 0.08838834764831845f; }
;         else if (pn < 8) { dst = V; cbase = (pn - 4) * BM; }
;         else if (pn < 12) { dst = SQ; cbase = (pn - 8) * BM; scale = 0.125f * LOG2E; }
;         else if (pn < 16) { dst = GR; cbase = (pn - 12) * BM; mode = 1; }
;         else if (pn == 16) { dst = SKVb; ld = 256; cbase = 0; mode = 2; }
;         else { dst = SKVb; cbase = 0; mode = 3; }
; #pragma unroll
;         for (int ai = 0; ai < 2; ++ai)
; #pragma unroll
;             for (int m = 0; m < 4; ++m) {
;                 const int row = u.pm * BM + ai * HALF + wr * 64 + m * 16 + fr; const float rs = rsa[ai][m] * scale;
; #pragma unroll
;                 for (int bj = 0; bj < 2; ++bj) {
;                     const int within = bj * HALF + wc * 32 + 8 * fq;
;                     f32x4 v0 = acc[ai][bj][m][0] * rs, v1 = acc[ai][bj][m][1] * rs;
;                     if (mode == 3) { if (within < GRANK) { *(f32x4*)(GLR + (size_t)row * 16 + within) = v0; *(f32x4*)(GLR + (size_t)row * 16 + within + 4) = v1; } continue; }
;                     if (mode == 1) {
; #pragma unroll
;                         for (int j = 0; j < 4; ++j) { v0[j] = siluf_(v0[j]); v1[j] = siluf_(v1[j]); }
;                     }
;                     u32x4 w; w.x = pk2(v0[0], v0[1]); w.y = pk2(v0[2], v0[3]); w.z = pk2(v1[0], v1[1]); w.w = pk2(v1[2], v1[3]);
;                     *(u32x4*)(dst + (size_t)row * ld + cbase + within) = w;
.Lp3f_ns10:
	v_cvt_pk_bf16_f32 v240, v222, v223
	v_cvt_pk_bf16_f32 v241, v224, v225
	v_cvt_pk_bf16_f32 v242, v226, v227
	v_cvt_pk_bf16_f32 v243, v228, v229
	ds_bpermute_b32 v244, v221, v240
	ds_bpermute_b32 v245, v221, v241
	ds_bpermute_b32 v246, v221, v242
	ds_bpermute_b32 v247, v221, v243
	s_waitcnt lgkmcnt(4)
	s_add_u32 s100, s98, 0x40000
	s_addc_u32 s101, s99, 0
	global_store_dwordx4 v220, v[248:251], s[100:101] offset:256 nt
	v_pk_mul_f32 v[222:223], v[22:23], v[238:239] op_sel_hi:[1,0]
	v_mov_b64_e32 v[22:23], 0
	v_pk_mul_f32 v[224:225], v[24:25], v[238:239] op_sel_hi:[1,0]
	v_mov_b64_e32 v[24:25], 0
	v_pk_mul_f32 v[226:227], v[18:19], v[238:239] op_sel_hi:[1,0]
	v_mov_b64_e32 v[18:19], 0
	v_pk_mul_f32 v[228:229], v[20:21], v[238:239] op_sel_hi:[1,0]
	v_mov_b64_e32 v[20:21], 0
	s_cmp_lg_u32 s79, 3
	s_cbranch_scc1 .Lp3f_ns11
	v_mul_f32_e32 v230, 0xbfb8aa3b, v222
	v_mul_f32_e32 v231, 0xbfb8aa3b, v223
	v_mul_f32_e32 v232, 0xbfb8aa3b, v224
	v_mul_f32_e32 v233, 0xbfb8aa3b, v225
	v_mul_f32_e32 v234, 0xbfb8aa3b, v226
	v_mul_f32_e32 v235, 0xbfb8aa3b, v227
	v_mul_f32_e32 v236, 0xbfb8aa3b, v228
	v_mul_f32_e32 v237, 0xbfb8aa3b, v229
	v_exp_f32_e32 v230, v230
	v_exp_f32_e32 v231, v231
	v_exp_f32_e32 v232, v232
	v_exp_f32_e32 v233, v233
	v_exp_f32_e32 v234, v234
	v_exp_f32_e32 v235, v235
	v_exp_f32_e32 v236, v236
	v_exp_f32_e32 v237, v237
	v_add_f32_e32 v230, 1.0, v230
	v_add_f32_e32 v231, 1.0, v231
	v_add_f32_e32 v232, 1.0, v232
	v_add_f32_e32 v233, 1.0, v233
	v_add_f32_e32 v234, 1.0, v234
	v_add_f32_e32 v235, 1.0, v235
	v_add_f32_e32 v236, 1.0, v236
	v_add_f32_e32 v237, 1.0, v237
	v_rcp_f32_e32 v230, v230
	v_rcp_f32_e32 v231, v231
	v_rcp_f32_e32 v232, v232
	v_rcp_f32_e32 v233, v233
	v_rcp_f32_e32 v234, v234
	v_rcp_f32_e32 v235, v235
	v_rcp_f32_e32 v236, v236
	v_rcp_f32_e32 v237, v237
	v_pk_mul_f32 v[222:223], v[222:223], v[230:231]
	v_pk_mul_f32 v[224:225], v[224:225], v[232:233]
	v_pk_mul_f32 v[226:227], v[226:227], v[234:235]
	v_pk_mul_f32 v[228:229], v[228:229], v[236:237]
.Lp3f_ns11:
	v_cvt_pk_bf16_f32 v240, v222, v223
	v_cvt_pk_bf16_f32 v241, v224, v225
	v_cvt_pk_bf16_f32 v242, v226, v227
	v_cvt_pk_bf16_f32 v243, v228, v229
	ds_bpermute_b32 v248, v221, v240
	ds_bpermute_b32 v249, v221, v241
	ds_bpermute_b32 v250, v221, v242
	ds_bpermute_b32 v251, v221, v243
	s_waitcnt lgkmcnt(4)
	s_add_u32 s100, s98, 0x48000
	s_addc_u32 s101, s99, 0
	global_store_dwordx4 v220, v[244:247], s[100:101] offset:0 nt
	v_mul_f32_e32 v238, s88, v132
	v_pk_mul_f32 v[222:223], v[46:47], v[238:239] op_sel_hi:[1,0]
	v_mov_b64_e32 v[46:47], 0
	v_pk_mul_f32 v[224:225], v[48:49], v[238:239] op_sel_hi:[1,0]
	v_mov_b64_e32 v[48:49], 0
	v_pk_mul_f32 v[226:227], v[42:43], v[238:239] op_sel_hi:[1,0]
	v_mov_b64_e32 v[42:43], 0
	v_pk_mul_f32 v[228:229], v[44:45], v[238:239] op_sel_hi:[1,0]
	v_mov_b64_e32 v[44:45], 0
	s_cmp_lg_u32 s79, 3
	s_cbranch_scc1 .Lp3f_ns12
	v_mul_f32_e32 v230, 0xbfb8aa3b, v222
	v_mul_f32_e32 v231, 0xbfb8aa3b, v223
	v_mul_f32_e32 v232, 0xbfb8aa3b, v224
	v_mul_f32_e32 v233, 0xbfb8aa3b, v225
	v_mul_f32_e32 v234, 0xbfb8aa3b, v226
	v_mul_f32_e32 v235, 0xbfb8aa3b, v227
	v_mul_f32_e32 v236, 0xbfb8aa3b, v228
	v_mul_f32_e32 v237, 0xbfb8aa3b, v229
	v_exp_f32_e32 v230, v230
	v_exp_f32_e32 v231, v231
	v_exp_f32_e32 v232, v232
	v_exp_f32_e32 v233, v233
	v_exp_f32_e32 v234, v234
	v_exp_f32_e32 v235, v235
	v_exp_f32_e32 v236, v236
	v_exp_f32_e32 v237, v237
	v_add_f32_e32 v230, 1.0, v230
	v_add_f32_e32 v231, 1.0, v231
	v_add_f32_e32 v232, 1.0, v232
	v_add_f32_e32 v233, 1.0, v233
	v_add_f32_e32 v234, 1.0, v234
	v_add_f32_e32 v235, 1.0, v235
	v_add_f32_e32 v236, 1.0, v236
	v_add_f32_e32 v237, 1.0, v237
	v_rcp_f32_e32 v230, v230
	v_rcp_f32_e32 v231, v231
	v_rcp_f32_e32 v232, v232
	v_rcp_f32_e32 v233, v233
	v_rcp_f32_e32 v234, v234
	v_rcp_f32_e32 v235, v235
	v_rcp_f32_e32 v236, v236
	v_rcp_f32_e32 v237, v237
	v_pk_mul_f32 v[222:223], v[222:223], v[230:231]
	v_pk_mul_f32 v[224:225], v[224:225], v[232:233]
	v_pk_mul_f32 v[226:227], v[226:227], v[234:235]
	v_pk_mul_f32 v[228:229], v[228:229], v[236:237]
.Lp3f_ns12:
	v_cvt_pk_bf16_f32 v240, v222, v223
	v_cvt_pk_bf16_f32 v241, v224, v225
	v_cvt_pk_bf16_f32 v242, v226, v227
	v_cvt_pk_bf16_f32 v243, v228, v229
	ds_bpermute_b32 v244, v221, v240
	ds_bpermute_b32 v245, v221, v241
	ds_bpermute_b32 v246, v221, v242
	ds_bpermute_b32 v247, v221, v243
	s_waitcnt lgkmcnt(4)
	s_add_u32 s100, s98, 0x48000
	s_addc_u32 s101, s99, 0
	global_store_dwordx4 v220, v[248:251], s[100:101] offset:256 nt
	v_pk_mul_f32 v[222:223], v[14:15], v[238:239] op_sel_hi:[1,0]
	v_mov_b64_e32 v[14:15], 0
	v_pk_mul_f32 v[224:225], v[16:17], v[238:239] op_sel_hi:[1,0]
	v_mov_b64_e32 v[16:17], 0
	v_pk_mul_f32 v[226:227], v[10:11], v[238:239] op_sel_hi:[1,0]
	v_mov_b64_e32 v[10:11], 0
	v_pk_mul_f32 v[228:229], v[12:13], v[238:239] op_sel_hi:[1,0]
	v_mov_b64_e32 v[12:13], 0
	s_cmp_lg_u32 s79, 3
	s_cbranch_scc1 .Lp3f_ns13
	v_mul_f32_e32 v230, 0xbfb8aa3b, v222
	v_mul_f32_e32 v231, 0xbfb8aa3b, v223
	v_mul_f32_e32 v232, 0xbfb8aa3b, v224
	v_mul_f32_e32 v233, 0xbfb8aa3b, v225
	v_mul_f32_e32 v234, 0xbfb8aa3b, v226
	v_mul_f32_e32 v235, 0xbfb8aa3b, v227
	v_mul_f32_e32 v236, 0xbfb8aa3b, v228
	v_mul_f32_e32 v237, 0xbfb8aa3b, v229
	v_exp_f32_e32 v230, v230
	v_exp_f32_e32 v231, v231
	v_exp_f32_e32 v232, v232
	v_exp_f32_e32 v233, v233
	v_exp_f32_e32 v234, v234
	v_exp_f32_e32 v235, v235
	v_exp_f32_e32 v236, v236
	v_exp_f32_e32 v237, v237
	v_add_f32_e32 v230, 1.0, v230
	v_add_f32_e32 v231, 1.0, v231
	v_add_f32_e32 v232, 1.0, v232
	v_add_f32_e32 v233, 1.0, v233
	v_add_f32_e32 v234, 1.0, v234
	v_add_f32_e32 v235, 1.0, v235
	v_add_f32_e32 v236, 1.0, v236
	v_add_f32_e32 v237, 1.0, v237
	v_rcp_f32_e32 v230, v230
	v_rcp_f32_e32 v231, v231
	v_rcp_f32_e32 v232, v232
	v_rcp_f32_e32 v233, v233
	v_rcp_f32_e32 v234, v234
	v_rcp_f32_e32 v235, v235
	v_rcp_f32_e32 v236, v236
	v_rcp_f32_e32 v237, v237
	v_pk_mul_f32 v[222:223], v[222:223], v[230:231]
	v_pk_mul_f32 v[224:225], v[224:225], v[232:233]
	v_pk_mul_f32 v[226:227], v[226:227], v[234:235]
	v_pk_mul_f32 v[228:229], v[228:229], v[236:237]
; #define PG8_LAS __attribute__((address_space(3)))
;     __device__ __forceinline__ void operator()(Acc& acc, const Unit& u, int wr, int wc, int fr, int fq, const float (&rsa)[2][4]) const {
;         const int pn = u.pn;
;         bf16_t* dst; int ld = D, cbase; float scale = 1.f; int mode = 0;
;         if (pn < 4) { dst = QK; cbase = pn * BM; if (pn < 2) scale = 0.08838834764831845f; }
;         else if (pn < 8) { dst = V; cbase = (pn - 4) * BM; }
;         else if (pn < 12) { dst = SQ; cbase = (pn - 8) * BM; scale = 0.125f * LOG2E; }
;         else if (pn < 16) { dst = GR; cbase = (pn - 12) * BM; mode = 1; }
;         else if (pn == 16) { dst = SKVb; ld = 256; cbase = 0; mode = 2; }
;         else { dst = SKVb; cbase = 0; mode = 3; }
; #pragma unroll
;         for (int ai = 0; ai < 2; ++ai)
; #pragma unroll
;             for (int m = 0; m < 4; ++m) {
;                 const int row = u.pm * BM + ai * HALF + wr * 64 + m * 16 + fr; const float rs = rsa[ai][m] * scale;
; #pragma unroll
;                 for (int bj = 0; bj < 2; ++bj) {
;                     const int within = bj * HALF + wc * 32 + 8 * fq;
;                     f32x4 v0 = acc[ai][bj][m][0] * rs, v1 = acc[ai][bj][m][1] * rs;
;                     if (mode == 3) { if (within < GRANK) { *(f32x4*)(GLR + (size_t)row * 16 + within) = v0; *(f32x4*)(GLR + (size_t)row * 16 + within + 4) = v1; } continue; }
;                     if (mode == 1) {
; #pragma unroll
;                         for (int j = 0; j < 4; ++j) { v0[j] = siluf_(v0[j]); v1[j] = siluf_(v1[j]); }
;                     }
;                     u32x4 w; w.x = pk2(v0[0], v0[1]); w.y = pk2(v0[2], v0[3]); w.z = pk2(v1[0], v1[1]); w.w = pk2(v1[2], v1[3]);
;                     *(u32x4*)(dst + (size_t)row * ld + cbase + within) = w;
; template <class Epi, bool ALIGN_EPI, bool ABLK = false>
; __device__ __forceinline__ void gemm_phase(PG8_LAS unsigned char* lds, const Gemm g, const StaticOrder& S, const Epi& E) {
;     ...
;         if constexpr (ALIGN_EPI) { if (wr == 0) PG8_BAR; }
;         if constexpr (Epi::FUSED) E.fused(acc, cur, wr, wc, fr, fq, lds, wid, lane);
;         else if constexpr (Epi::RSTD_LDS) {
;             float rsa[2][4];
;             if (ui < RS_MAXT) { const f32x4 r0 = *(const PG8_LAS f32x4*)(RS + ui * 256 + (wr * 16 + fr) * 8), r1 = *(const PG8_LAS f32x4*)(RS + ui * 256 + (wr * 16 + fr) * 8 + 4);
; #pragma unroll
.Lp3f_ns13:
	v_cvt_pk_bf16_f32 v240, v222, v223
	v_cvt_pk_bf16_f32 v241, v224, v225
	v_cvt_pk_bf16_f32 v242, v226, v227
	v_cvt_pk_bf16_f32 v243, v228, v229
	ds_bpermute_b32 v248, v221, v240
	ds_bpermute_b32 v249, v221, v241
	ds_bpermute_b32 v250, v221, v242
	ds_bpermute_b32 v251, v221, v243
	s_waitcnt lgkmcnt(4)
	s_add_u32 s100, s98, 0x50000
	s_addc_u32 s101, s99, 0
	global_store_dwordx4 v220, v[244:247], s[100:101] offset:0 nt
	v_mul_f32_e32 v238, s88, v133
	v_pk_mul_f32 v[222:223], v[38:39], v[238:239] op_sel_hi:[1,0]
	v_mov_b64_e32 v[38:39], 0
	v_pk_mul_f32 v[224:225], v[40:41], v[238:239] op_sel_hi:[1,0]
	v_mov_b64_e32 v[40:41], 0
	v_pk_mul_f32 v[226:227], v[34:35], v[238:239] op_sel_hi:[1,0]
	v_mov_b64_e32 v[34:35], 0
	v_pk_mul_f32 v[228:229], v[36:37], v[238:239] op_sel_hi:[1,0]
	v_mov_b64_e32 v[36:37], 0
	s_cmp_lg_u32 s79, 3
	s_cbranch_scc1 .Lp3f_ns14
	v_mul_f32_e32 v230, 0xbfb8aa3b, v222
	v_mul_f32_e32 v231, 0xbfb8aa3b, v223
	v_mul_f32_e32 v232, 0xbfb8aa3b, v224
	v_mul_f32_e32 v233, 0xbfb8aa3b, v225
	v_mul_f32_e32 v234, 0xbfb8aa3b, v226
	v_mul_f32_e32 v235, 0xbfb8aa3b, v227
	v_mul_f32_e32 v236, 0xbfb8aa3b, v228
	v_mul_f32_e32 v237, 0xbfb8aa3b, v229
	v_exp_f32_e32 v230, v230
	v_exp_f32_e32 v231, v231
	v_exp_f32_e32 v232, v232
	v_exp_f32_e32 v233, v233
	v_exp_f32_e32 v234, v234
	v_exp_f32_e32 v235, v235
	v_exp_f32_e32 v236, v236
	v_exp_f32_e32 v237, v237
	v_add_f32_e32 v230, 1.0, v230
	v_add_f32_e32 v231, 1.0, v231
	v_add_f32_e32 v232, 1.0, v232
	v_add_f32_e32 v233, 1.0, v233
	v_add_f32_e32 v234, 1.0, v234
	v_add_f32_e32 v235, 1.0, v235
	v_add_f32_e32 v236, 1.0, v236
	v_add_f32_e32 v237, 1.0, v237
	v_rcp_f32_e32 v230, v230
	v_rcp_f32_e32 v231, v231
	v_rcp_f32_e32 v232, v232
	v_rcp_f32_e32 v233, v233
	v_rcp_f32_e32 v234, v234
	v_rcp_f32_e32 v235, v235
	v_rcp_f32_e32 v236, v236
	v_rcp_f32_e32 v237, v237
	v_pk_mul_f32 v[222:223], v[222:223], v[230:231]
	v_pk_mul_f32 v[224:225], v[224:225], v[232:233]
	v_pk_mul_f32 v[226:227], v[226:227], v[234:235]
	v_pk_mul_f32 v[228:229], v[228:229], v[236:237]
.Lp3f_ns14:
	v_cvt_pk_bf16_f32 v240, v222, v223
	v_cvt_pk_bf16_f32 v241, v224, v225
	v_cvt_pk_bf16_f32 v242, v226, v227
	v_cvt_pk_bf16_f32 v243, v228, v229
	ds_bpermute_b32 v244, v221, v240
	ds_bpermute_b32 v245, v221, v241
	ds_bpermute_b32 v246, v221, v242
	ds_bpermute_b32 v247, v221, v243
	s_waitcnt lgkmcnt(4)
	s_add_u32 s100, s98, 0x50000
	s_addc_u32 s101, s99, 0
	global_store_dwordx4 v220, v[248:251], s[100:101] offset:256 nt
	v_pk_mul_f32 v[222:223], v[6:7], v[238:239] op_sel_hi:[1,0]
	v_mov_b64_e32 v[6:7], 0
	v_pk_mul_f32 v[224:225], v[8:9], v[238:239] op_sel_hi:[1,0]
	v_mov_b64_e32 v[8:9], 0
	v_pk_mul_f32 v[226:227], v[2:3], v[238:239] op_sel_hi:[1,0]
	v_mov_b64_e32 v[2:3], 0
	v_pk_mul_f32 v[228:229], v[4:5], v[238:239] op_sel_hi:[1,0]
	v_mov_b64_e32 v[4:5], 0
	s_cmp_lg_u32 s79, 3
	s_cbranch_scc1 .Lp3f_ns15
	v_mul_f32_e32 v230, 0xbfb8aa3b, v222
	v_mul_f32_e32 v231, 0xbfb8aa3b, v223
	v_mul_f32_e32 v232, 0xbfb8aa3b, v224
	v_mul_f32_e32 v233, 0xbfb8aa3b, v225
	v_mul_f32_e32 v234, 0xbfb8aa3b, v226
	v_mul_f32_e32 v235, 0xbfb8aa3b, v227
	v_mul_f32_e32 v236, 0xbfb8aa3b, v228
	v_mul_f32_e32 v237, 0xbfb8aa3b, v229
	v_exp_f32_e32 v230, v230
	v_exp_f32_e32 v231, v231
	v_exp_f32_e32 v232, v232
	v_exp_f32_e32 v233, v233
	v_exp_f32_e32 v234, v234
	v_exp_f32_e32 v235, v235
	v_exp_f32_e32 v236, v236
	v_exp_f32_e32 v237, v237
	v_add_f32_e32 v230, 1.0, v230
	v_add_f32_e32 v231, 1.0, v231
	v_add_f32_e32 v232, 1.0, v232
	v_add_f32_e32 v233, 1.0, v233
	v_add_f32_e32 v234, 1.0, v234
	v_add_f32_e32 v235, 1.0, v235
	v_add_f32_e32 v236, 1.0, v236
	v_add_f32_e32 v237, 1.0, v237
	v_rcp_f32_e32 v230, v230
	v_rcp_f32_e32 v231, v231
	v_rcp_f32_e32 v232, v232
	v_rcp_f32_e32 v233, v233
	v_rcp_f32_e32 v234, v234
	v_rcp_f32_e32 v235, v235
	v_rcp_f32_e32 v236, v236
	v_rcp_f32_e32 v237, v237
	v_pk_mul_f32 v[222:223], v[222:223], v[230:231]
	v_pk_mul_f32 v[224:225], v[224:225], v[232:233]
	v_pk_mul_f32 v[226:227], v[226:227], v[234:235]
	v_pk_mul_f32 v[228:229], v[228:229], v[236:237]
.Lp3f_ns15:
	v_cvt_pk_bf16_f32 v240, v222, v223
	v_cvt_pk_bf16_f32 v241, v224, v225
	v_cvt_pk_bf16_f32 v242, v226, v227
	v_cvt_pk_bf16_f32 v243, v228, v229
	ds_bpermute_b32 v248, v221, v240
	ds_bpermute_b32 v249, v221, v241
	ds_bpermute_b32 v250, v221, v242
	ds_bpermute_b32 v251, v221, v243
	s_waitcnt lgkmcnt(4)
	s_add_u32 s100, s98, 0x58000
	s_addc_u32 s101, s99, 0
	global_store_dwordx4 v220, v[244:247], s[100:101] offset:0 nt
	s_waitcnt lgkmcnt(0)
	s_add_u32 s100, s98, 0x58000
	s_addc_u32 s101, s99, 0
	global_store_dwordx4 v220, v[248:251], s[100:101] offset:256 nt
	s_andn2_b64 vcc, exec, s[8:9]
	s_cbranch_vccnz .LBB0_814
	s_andn2_b64 vcc, exec, s[40:41]
	s_cbranch_vccnz .Lp3_nz
	s_barrier

; __device__ __forceinline__ unsigned pk2(float lo, float hi) { f32x2_t v = {lo, hi}; bf16x2_t b = __builtin_convertvector(v, bf16x2_t); return __builtin_bit_cast(unsigned, b); }
; __device__ __forceinline__ void sg_proj(const Args& a, Frame& F, int part) {
;     ...
;                 f32x4 v = c[r][n] * rs;
;                 if (n0 >= 4352) {
;                     *(f32x4*)((float*)(ws + WS_GLR) + (size_t)m * 16 + 4 * fq) = v;
;                 } else if (n0 >= 4096) {
;                     v2u w; w.x = pk2(v[0], v[1]); w.y = pk2(v[2], v[3]);
;                     *(v2u*)((bf16*)(ws + WS_SKV) + (size_t)m * 256 + (nq - 4096)) = w;
;                     const int bs = lr >> 5, t = lr & 31;
;                     *(f32x4*)(a.out + (nq < 4224 ? O_CKS : O_CVS) + ((size_t)(bs * WINDOW + 96 + t)) * 128 + ((nq - 4096) & 127)) = v;
.LBB0_1045:
	s_and_b64 vcc, exec, s[30:31]
	s_cbranch_vccz .LBB0_1047
	v_lshl_add_u64 v[20:21], v[34:35], 1, v[24:25]
	v_add_co_u32_e32 v20, vcc, 0x1bf3e000, v20
	v_cvt_pk_bf16_f32 v18, v14, v15
	s_nop 0
	v_addc_co_u32_e32 v21, vcc, 0, v21, vcc
	v_cvt_pk_bf16_f32 v19, v16, v17
	v_cmp_gt_i32_e32 vcc, s33, v34
	global_store_dwordx2 v[20:21], v[18:19], off
	v_mov_b32_e32 v19, v35
	v_cndmask_b32_e32 v18, v73, v74, vcc
	v_lshl_add_u64 v[18:19], s[94:95], 0, v[18:19]
	v_and_b32_e32 v20, 0x6c, v34
	v_lshl_add_u64 v[18:19], v[18:19], 0, v[22:23]
	v_lshlrev_b32_e32 v20, 2, v20
	v_mov_b32_e32 v21, v35
	v_lshl_add_u64 v[18:19], v[18:19], 0, v[20:21]
	global_store_dwordx4 v[18:19], v[14:17], off nt

; __device__ __forceinline__ void sg_proj(const Args& a, Frame& F, int part) {
;     ...
;                 if (n0 >= 4352) {
;                     *(f32x4*)((float*)(ws + WS_GLR) + (size_t)m * 16 + 4 * fq) = v;
.LBB0_1048:
	s_andn2_b64 vcc, exec, s[30:31]
	s_cbranch_vccnz .LBB0_1050
	v_lshlrev_b64 v[18:19], 6, v[30:31]
	v_lshl_add_u64 v[18:19], v[38:39], 0, v[18:19]
	global_store_dwordx4 v[18:19], v[14:17], off nt

; __device__ __forceinline__ unsigned pk2(float lo, float hi) { f32x2_t v = {lo, hi}; bf16x2_t b = __builtin_convertvector(v, bf16x2_t); return __builtin_bit_cast(unsigned, b); }
; __device__ __forceinline__ void sg_proj(const Args& a, Frame& F, int part) {
;     ...
;                 } else if (n0 >= 4096) {
;                     v2u w; w.x = pk2(v[0], v[1]); w.y = pk2(v[2], v[3]);
;                     *(v2u*)((bf16*)(ws + WS_SKV) + (size_t)m * 256 + (nq - 4096)) = w;
;                     const int bs = lr >> 5, t = lr & 31;
;                     *(f32x4*)(a.out + (nq < 4224 ? O_CKS : O_CVS) + ((size_t)(bs * WINDOW + 96 + t)) * 128 + ((nq - 4096) & 127)) = v;
.LBB0_1067:
	s_and_b64 vcc, exec, s[34:35]
	s_cbranch_vccz .LBB0_1069
	v_mov_b32_e32 v19, v35
	v_lshl_add_u64 v[16:17], v[18:19], 1, v[24:25]
	v_add_co_u32_e32 v16, vcc, 0x1bf3e000, v16
	v_cvt_pk_bf16_f32 v14, v10, v11
	s_nop 0
	v_addc_co_u32_e32 v17, vcc, 0, v17, vcc
	v_cvt_pk_bf16_f32 v15, v12, v13
	v_cmp_gt_i32_e32 vcc, s33, v18
	global_store_dwordx2 v[16:17], v[14:15], off
	v_mov_b32_e32 v15, v35
	v_cndmask_b32_e32 v14, v73, v74, vcc
	v_lshl_add_u64 v[14:15], s[94:95], 0, v[14:15]
	v_and_b32_e32 v16, 0x7c, v18
	v_lshl_add_u64 v[14:15], v[14:15], 0, v[22:23]
	v_lshlrev_b32_e32 v16, 2, v16
	v_mov_b32_e32 v17, v35
	v_lshl_add_u64 v[14:15], v[14:15], 0, v[16:17]
	global_store_dwordx4 v[14:15], v[10:13], off nt

; __device__ __forceinline__ unsigned pk2(float lo, float hi) { f32x2_t v = {lo, hi}; bf16x2_t b = __builtin_convertvector(v, bf16x2_t); return __builtin_bit_cast(unsigned, b); }
; __device__ __forceinline__ void sg_proj(const Args& a, Frame& F, int part) {
;     ...
;                 } else if (n0 >= 4096) {
;                     v2u w; w.x = pk2(v[0], v[1]); w.y = pk2(v[2], v[3]);
;                     *(v2u*)((bf16*)(ws + WS_SKV) + (size_t)m * 256 + (nq - 4096)) = w;
;                     const int bs = lr >> 5, t = lr & 31;
;                     *(f32x4*)(a.out + (nq < 4224 ? O_CKS : O_CVS) + ((size_t)(bs * WINDOW + 96 + t)) * 128 + ((nq - 4096) & 127)) = v;
.LBB0_1087:
	s_and_b64 vcc, exec, s[10:11]
	s_cbranch_vccz .LBB0_1089
	v_lshl_add_u64 v[12:13], v[34:35], 1, v[16:17]
	v_add_co_u32_e32 v12, vcc, 0x1bf3e000, v12
	v_cvt_pk_bf16_f32 v10, v6, v7
	s_nop 0
	v_addc_co_u32_e32 v13, vcc, 0, v13, vcc
	v_cvt_pk_bf16_f32 v11, v8, v9
	v_cmp_gt_i32_e32 vcc, s33, v34
	global_store_dwordx2 v[12:13], v[10:11], off
	v_mov_b32_e32 v11, v35
	v_cndmask_b32_e32 v10, v73, v74, vcc
	v_lshl_add_u64 v[10:11], s[94:95], 0, v[10:11]
	v_and_b32_e32 v12, 0x6c, v34
	v_lshl_add_u64 v[10:11], v[10:11], 0, v[14:15]
	v_lshlrev_b32_e32 v34, 2, v12
	v_lshl_add_u64 v[10:11], v[10:11], 0, v[34:35]
	global_store_dwordx4 v[10:11], v[6:9], off nt

; __device__ __forceinline__ unsigned pk2(float lo, float hi) { f32x2_t v = {lo, hi}; bf16x2_t b = __builtin_convertvector(v, bf16x2_t); return __builtin_bit_cast(unsigned, b); }
; __device__ __forceinline__ void sg_proj(const Args& a, Frame& F, int part) {
;     ...
;                 } else if (n0 >= 4096) {
;                     v2u w; w.x = pk2(v[0], v[1]); w.y = pk2(v[2], v[3]);
;                     *(v2u*)((bf16*)(ws + WS_SKV) + (size_t)m * 256 + (nq - 4096)) = w;
;                     const int bs = lr >> 5, t = lr & 31;
;                     *(f32x4*)(a.out + (nq < 4224 ? O_CKS : O_CVS) + ((size_t)(bs * WINDOW + 96 + t)) * 128 + ((nq - 4096) & 127)) = v;
.LBB0_1109:
	s_and_b64 vcc, exec, s[10:11]
	s_cbranch_vccz .LBB0_1014
	v_mov_b32_e32 v19, v35
	v_lshl_add_u64 v[8:9], v[18:19], 1, v[16:17]
	v_add_co_u32_e32 v8, vcc, 0x1bf3e000, v8
	v_cvt_pk_bf16_f32 v6, v2, v3
	s_nop 0
	v_addc_co_u32_e32 v9, vcc, 0, v9, vcc
	v_cmp_gt_i32_e32 vcc, s33, v18
	v_cvt_pk_bf16_f32 v7, v4, v5
	global_store_dwordx2 v[8:9], v[6:7], off
	v_cndmask_b32_e32 v34, v73, v74, vcc
	v_lshl_add_u64 v[6:7], s[94:95], 0, v[34:35]
	v_and_b32_e32 v8, 0x7c, v18
	v_lshl_add_u64 v[6:7], v[6:7], 0, v[14:15]
	v_lshlrev_b32_e32 v34, 2, v8
	v_lshl_add_u64 v[6:7], v[6:7], 0, v[34:35]
	global_store_dwordx4 v[6:7], v[2:5], off nt
	s_branch .LBB0_1014

; __device__ __forceinline__ unsigned pk2(float lo, float hi) { f32x2_t v = {lo, hi}; bf16x2_t b = __builtin_convertvector(v, bf16x2_t); return __builtin_bit_cast(unsigned, b); }
; __device__ __forceinline__ float fast_exp(float x) { return __builtin_amdgcn_exp2f(x * LOG2E); }
; __device__ __forceinline__ float fast_rcp(float x) { return __builtin_amdgcn_rcpf(x); }
;     __device__ __forceinline__ void operator()(Acc& acc, const Unit& u, int wr, int wc, int fr, int fq, const float (&rsa)[2][4]) const {
;         const int row0 = u.pm * BM + wr * 64 + fr, col0 = u.pn * HALF + wc * 32 + 8 * fq;
; #pragma unroll
;         for (int ai = 0; ai < 2; ++ai)
; #pragma unroll
;             for (int m = 0; m < 4; ++m) {
;                 const int row = row0 + ai * HALF + m * 16; const float rs = rsa[ai][m];
;                 float r[8], ss[8];
; #pragma unroll
;                 for (int n = 0; n < 2; ++n)
; #pragma unroll
;                     for (int j = 0; j < 4; ++j) { const float eg = fast_exp(-acc[ai][0][m][n][j] * rs), es = fast_exp(-acc[ai][1][m][n][j] * rs);
;                         ss[n * 4 + j] = fast_rcp(1.0f + es); r[n * 4 + j] = (1.0f + es) * fast_rcp(1.0f + eg); }
;                 const size_t po = ((size_t)(u.pm * 8 + u.pn) << 16) + (size_t)((((wr * 4 + wc) * 8 + ai * 4 + m) << 10) + (fq * 16 + fr) * 16);
;                 u32x4 w; w.x = pk2(r[0], r[1]); w.y = pk2(r[2], r[3]); w.z = pk2(r[4], r[5]); w.w = pk2(r[6], r[7]);
;                 *(u32x4*)((char*)R + po) = w;
;                 w.x = pk2(ss[0], ss[1]); w.y = pk2(ss[2], ss[3]); w.z = pk2(ss[4], ss[5]); w.w = pk2(ss[6], ss[7]);
;                 *(u32x4*)((char*)SS + po) = w;
.LBB0_1990:
	s_waitcnt lgkmcnt(0)
	v_mul_f32_e64 v184, v134, -v126
	v_mul_f32_e32 v184, 0x3fb8aa3b, v184
	v_exp_f32_e32 v185, v184
	v_mul_f32_e64 v184, v134, -v94
	v_mul_f32_e32 v184, 0x3fb8aa3b, v184
	v_exp_f32_e32 v184, v184
	v_add_f32_e32 v185, 1.0, v185
	v_rcp_f32_e32 v186, v185
	v_mul_f32_e64 v185, v134, -v127
	v_mul_f32_e32 v185, 0x3fb8aa3b, v185
	v_exp_f32_e32 v187, v185
	v_mul_f32_e64 v185, v134, -v95
	v_mul_f32_e32 v185, 0x3fb8aa3b, v185
	v_exp_f32_e32 v185, v185
	v_add_f32_e32 v187, 1.0, v187
	v_rcp_f32_e32 v187, v187
	v_mul_f32_e64 v188, v134, -v96
	v_pk_add_f32 v[184:185], v[184:185], 1.0 op_sel_hi:[1,0]
	v_mul_f32_e64 v189, v134, -v97
	v_rcp_f32_e32 v196, v184
	v_pk_mul_f32 v[186:187], v[184:185], v[186:187]
	v_mul_f32_e64 v184, v134, -v128
	v_mul_f32_e32 v184, 0x3fb8aa3b, v184
	v_exp_f32_e32 v184, v184
	v_mul_f32_e32 v188, 0x3fb8aa3b, v188
	v_mul_f32_e32 v189, 0x3fb8aa3b, v189
	v_exp_f32_e32 v188, v188
	v_add_f32_e32 v184, 1.0, v184
	v_rcp_f32_e32 v190, v184
	v_mul_f32_e64 v184, v134, -v129
	v_mul_f32_e32 v184, 0x3fb8aa3b, v184
	v_exp_f32_e32 v184, v184
	v_exp_f32_e32 v189, v189
	v_rcp_f32_e32 v197, v185
	s_lshl_b32 s53, s20, 3
	v_add_f32_e32 v184, 1.0, v184
	v_rcp_f32_e32 v191, v184
	v_pk_add_f32 v[184:185], v[188:189], 1.0 op_sel_hi:[1,0]
	s_add_i32 s60, s53, s22
	v_rcp_f32_e32 v198, v184
	v_pk_mul_f32 v[188:189], v[184:185], v[190:191]
	v_mul_f32_e64 v184, v134, -v122
	v_mul_f32_e32 v184, 0x3fb8aa3b, v184
	v_exp_f32_e32 v184, v184
	v_mul_f32_e64 v190, v134, -v90
	v_mul_f32_e64 v191, v134, -v91
	v_mul_f32_e32 v190, 0x3fb8aa3b, v190
	v_add_f32_e32 v184, 1.0, v184
	v_rcp_f32_e32 v192, v184
	v_mul_f32_e64 v184, v134, -v123
	v_mul_f32_e32 v184, 0x3fb8aa3b, v184
	v_exp_f32_e32 v184, v184
	v_mul_f32_e32 v191, 0x3fb8aa3b, v191
	v_exp_f32_e32 v190, v190
	v_exp_f32_e32 v191, v191
	v_add_f32_e32 v184, 1.0, v184
	v_rcp_f32_e32 v193, v184
	v_rcp_f32_e32 v199, v185
	v_pk_add_f32 v[184:185], v[190:191], 1.0 op_sel_hi:[1,0]
	s_ashr_i32 s61, s60, 31
	v_rcp_f32_e32 v200, v184
	v_pk_mul_f32 v[190:191], v[184:185], v[192:193]
	v_mul_f32_e64 v184, v134, -v124
	v_mul_f32_e32 v184, 0x3fb8aa3b, v184
	v_exp_f32_e32 v184, v184
	v_mul_f32_e64 v192, v134, -v92
	v_mul_f32_e32 v192, 0x3fb8aa3b, v192
	v_exp_f32_e32 v192, v192
	v_add_f32_e32 v184, 1.0, v184
	v_rcp_f32_e32 v194, v184
	v_mul_f32_e64 v184, v134, -v125
	v_mul_f32_e32 v184, 0x3fb8aa3b, v184
	v_exp_f32_e32 v184, v184
	v_mul_f32_e64 v134, v134, -v93
	v_mul_f32_e32 v134, 0x3fb8aa3b, v134
	v_exp_f32_e32 v193, v134
	v_add_f32_e32 v134, 1.0, v184
	v_rcp_f32_e32 v195, v134
	v_rcp_f32_e32 v134, v185
	v_pk_add_f32 v[184:185], v[192:193], 1.0 op_sel_hi:[1,0]
	s_lshl_b64 s[60:61], s[60:61], 16
	v_pk_mul_f32 v[192:193], v[184:185], v[194:195]
	v_lshl_add_u64 v[194:195], s[60:61], 0, v[144:145]
	v_rcp_f32_e32 v201, v184
	v_rcp_f32_e32 v202, v185
	v_cvt_pk_bf16_f32 v184, v186, v187
	v_cvt_pk_bf16_f32 v185, v188, v189
	v_cvt_pk_bf16_f32 v186, v190, v191
	v_cvt_pk_bf16_f32 v187, v192, v193
	v_lshl_add_u64 v[188:189], s[10:11], 0, v[194:195]
	global_store_dwordx4 v[188:189], v[184:187], off nt
	v_mul_f32_e64 v190, v135, -v86
	v_mul_f32_e64 v191, v135, -v87
	v_cvt_pk_bf16_f32 v186, v200, v134
	v_mul_f32_e64 v134, v135, -v118
	v_mul_f32_e32 v134, 0x3fb8aa3b, v134
	v_exp_f32_e32 v134, v134
	v_mul_f32_e32 v190, 0x3fb8aa3b, v190
	v_mul_f32_e32 v191, 0x3fb8aa3b, v191
	v_exp_f32_e32 v190, v190
	v_add_f32_e32 v134, 1.0, v134
	v_rcp_f32_e32 v192, v134
	v_mul_f32_e64 v134, v135, -v119
	v_mul_f32_e32 v134, 0x3fb8aa3b, v134
	v_exp_f32_e32 v134, v134
	v_exp_f32_e32 v191, v191
	v_cvt_pk_bf16_f32 v184, v196, v197
	v_cvt_pk_bf16_f32 v185, v198, v199
	v_add_f32_e32 v134, 1.0, v134
	v_rcp_f32_e32 v193, v134
	v_mul_f32_e64 v134, v135, -v120
	v_mul_f32_e32 v134, 0x3fb8aa3b, v134
	v_exp_f32_e32 v134, v134
	v_cvt_pk_bf16_f32 v187, v201, v202
	v_lshl_add_u64 v[188:189], s[12:13], 0, v[194:195]
	global_store_dwordx4 v[188:189], v[184:187], off nt
	v_add_f32_e32 v134, 1.0, v134
	s_andn2_b64 vcc, exec, s[6:7]
	v_pk_add_f32 v[184:185], v[190:191], 1.0 op_sel_hi:[1,0]
	v_rcp_f32_e32 v190, v134
	v_mul_f32_e64 v134, v135, -v121
	v_mul_f32_e32 v134, 0x3fb8aa3b, v134
	v_exp_f32_e32 v134, v134
	v_rcp_f32_e32 v194, v184
	v_pk_mul_f32 v[186:187], v[184:185], v[192:193]
	v_mul_f32_e64 v184, v135, -v88
	v_add_f32_e32 v134, 1.0, v134
	v_rcp_f32_e32 v191, v134
	v_mul_f32_e64 v134, v135, -v114
	v_mul_f32_e32 v184, 0x3fb8aa3b, v184
	v_mul_f32_e32 v134, 0x3fb8aa3b, v134
	v_exp_f32_e32 v188, v184
	v_mul_f32_e64 v184, v135, -v89
	v_exp_f32_e32 v134, v134
	v_mul_f32_e32 v184, 0x3fb8aa3b, v184
	v_exp_f32_e32 v189, v184
	v_rcp_f32_e32 v195, v185
	v_add_f32_e32 v134, 1.0, v134
	v_rcp_f32_e32 v192, v134
	v_mul_f32_e64 v134, v135, -v115
	v_pk_add_f32 v[184:185], v[188:189], 1.0 op_sel_hi:[1,0]
	v_mul_f32_e32 v134, 0x3fb8aa3b, v134
	v_rcp_f32_e32 v196, v184
	v_pk_mul_f32 v[188:189], v[184:185], v[190:191]
	v_mul_f32_e64 v184, v135, -v82
	v_exp_f32_e32 v134, v134
	v_mul_f32_e32 v184, 0x3fb8aa3b, v184
	v_exp_f32_e32 v190, v184
	v_mul_f32_e64 v184, v135, -v83
	v_mul_f32_e32 v184, 0x3fb8aa3b, v184
	v_exp_f32_e32 v191, v184
	v_add_f32_e32 v134, 1.0, v134
	v_rcp_f32_e32 v193, v134
	v_mul_f32_e64 v134, v135, -v116
	v_rcp_f32_e32 v197, v185
	v_pk_add_f32 v[184:185], v[190:191], 1.0 op_sel_hi:[1,0]
	v_mul_f32_e32 v134, 0x3fb8aa3b, v134
	v_rcp_f32_e32 v198, v184
	v_pk_mul_f32 v[190:191], v[184:185], v[192:193]
	v_exp_f32_e32 v184, v134
	v_mul_f32_e64 v134, v135, -v84
	v_mul_f32_e32 v134, 0x3fb8aa3b, v134
	v_exp_f32_e32 v134, v134
	v_add_f32_e32 v184, 1.0, v184
	v_rcp_f32_e32 v192, v184
	v_mul_f32_e64 v184, v135, -v117
	v_mul_f32_e32 v184, 0x3fb8aa3b, v184
; __device__ __forceinline__ unsigned pk2(float lo, float hi) { f32x2_t v = {lo, hi}; bf16x2_t b = __builtin_convertvector(v, bf16x2_t); return __builtin_bit_cast(unsigned, b); }
; __device__ __forceinline__ float fast_exp(float x) { return __builtin_amdgcn_exp2f(x * LOG2E); }
; __device__ __forceinline__ float fast_rcp(float x) { return __builtin_amdgcn_rcpf(x); }
;     __device__ __forceinline__ void operator()(Acc& acc, const Unit& u, int wr, int wc, int fr, int fq, const float (&rsa)[2][4]) const {
;     ...
;                 const int row = row0 + ai * HALF + m * 16; const float rs = rsa[ai][m];
;                 float r[8], ss[8];
; #pragma unroll
;                 for (int n = 0; n < 2; ++n)
; #pragma unroll
;                     for (int j = 0; j < 4; ++j) { const float eg = fast_exp(-acc[ai][0][m][n][j] * rs), es = fast_exp(-acc[ai][1][m][n][j] * rs);
;                         ss[n * 4 + j] = fast_rcp(1.0f + es); r[n * 4 + j] = (1.0f + es) * fast_rcp(1.0f + eg); }
;                 const size_t po = ((size_t)(u.pm * 8 + u.pn) << 16) + (size_t)((((wr * 4 + wc) * 8 + ai * 4 + m) << 10) + (fq * 16 + fr) * 16);
;                 u32x4 w; w.x = pk2(r[0], r[1]); w.y = pk2(r[2], r[3]); w.z = pk2(r[4], r[5]); w.w = pk2(r[6], r[7]);
;                 *(u32x4*)((char*)R + po) = w;
;                 w.x = pk2(ss[0], ss[1]); w.y = pk2(ss[2], ss[3]); w.z = pk2(ss[4], ss[5]); w.w = pk2(ss[6], ss[7]);
;                 *(u32x4*)((char*)SS + po) = w;
	v_exp_f32_e32 v184, v184
	v_mul_f32_e64 v135, v135, -v85
	v_mul_f32_e32 v135, 0x3fb8aa3b, v135
	v_exp_f32_e32 v135, v135
	v_add_f32_e32 v184, 1.0, v184
	v_rcp_f32_e32 v193, v184
	v_rcp_f32_e32 v199, v185
	v_pk_add_f32 v[134:135], v[134:135], 1.0 op_sel_hi:[1,0]
	v_cvt_pk_bf16_f32 v184, v186, v187
	v_rcp_f32_e32 v200, v134
	v_pk_mul_f32 v[192:193], v[134:135], v[192:193]
	v_rcp_f32_e32 v201, v135
	v_lshl_add_u64 v[134:135], s[60:61], 0, v[146:147]
	v_cvt_pk_bf16_f32 v185, v188, v189
	v_cvt_pk_bf16_f32 v186, v190, v191
	v_cvt_pk_bf16_f32 v187, v192, v193
	v_lshl_add_u64 v[188:189], s[10:11], 0, v[134:135]
	global_store_dwordx4 v[188:189], v[184:187], off nt
	v_mul_f32_e64 v188, v136, -v110
	v_mul_f32_e32 v188, 0x3fb8aa3b, v188
	v_exp_f32_e32 v189, v188
	v_mul_f32_e64 v188, v136, -v78
	v_mul_f32_e32 v188, 0x3fb8aa3b, v188
	v_exp_f32_e32 v188, v188
	v_add_f32_e32 v189, 1.0, v189
	v_rcp_f32_e32 v190, v189
	v_mul_f32_e64 v189, v136, -v111
	v_mul_f32_e32 v189, 0x3fb8aa3b, v189
	v_exp_f32_e32 v191, v189
	v_mul_f32_e64 v189, v136, -v79
	v_mul_f32_e32 v189, 0x3fb8aa3b, v189
	v_exp_f32_e32 v189, v189
	v_add_f32_e32 v191, 1.0, v191
	v_rcp_f32_e32 v191, v191
	v_cvt_pk_bf16_f32 v184, v194, v195
	v_cvt_pk_bf16_f32 v185, v196, v197
	v_cvt_pk_bf16_f32 v186, v198, v199
	v_cvt_pk_bf16_f32 v187, v200, v201
	v_lshl_add_u64 v[134:135], s[12:13], 0, v[134:135]
	global_store_dwordx4 v[134:135], v[184:187], off nt
	v_pk_add_f32 v[134:135], v[188:189], 1.0 op_sel_hi:[1,0]
	s_nop 0
	v_rcp_f32_e32 v194, v134
	v_pk_mul_f32 v[184:185], v[134:135], v[190:191]
	v_mul_f32_e64 v134, v136, -v112
	v_mul_f32_e32 v134, 0x3fb8aa3b, v134
	v_exp_f32_e32 v134, v134
	v_mul_f32_e64 v186, v136, -v80
	v_mul_f32_e64 v187, v136, -v81
	v_mul_f32_e32 v186, 0x3fb8aa3b, v186
	v_add_f32_e32 v134, 1.0, v134
	v_rcp_f32_e32 v188, v134
	v_mul_f32_e64 v134, v136, -v113
	v_mul_f32_e32 v134, 0x3fb8aa3b, v134
	v_exp_f32_e32 v134, v134
	v_mul_f32_e32 v187, 0x3fb8aa3b, v187
	v_exp_f32_e32 v186, v186
	v_exp_f32_e32 v187, v187
	v_add_f32_e32 v134, 1.0, v134
	v_rcp_f32_e32 v189, v134
	v_rcp_f32_e32 v195, v135
	v_pk_add_f32 v[134:135], v[186:187], 1.0 op_sel_hi:[1,0]
	v_cvt_pk_bf16_f32 v184, v184, v185
	v_rcp_f32_e32 v196, v134
	v_pk_mul_f32 v[186:187], v[134:135], v[188:189]
	v_mul_f32_e64 v134, v136, -v106
	v_mul_f32_e32 v134, 0x3fb8aa3b, v134
	v_exp_f32_e32 v134, v134
	v_mul_f32_e64 v188, v136, -v74
	v_mul_f32_e64 v189, v136, -v75
	v_mul_f32_e32 v188, 0x3fb8aa3b, v188
	v_add_f32_e32 v134, 1.0, v134
	v_rcp_f32_e32 v190, v134
	v_mul_f32_e64 v134, v136, -v107
	v_mul_f32_e32 v134, 0x3fb8aa3b, v134
	v_exp_f32_e32 v134, v134
	v_mul_f32_e32 v189, 0x3fb8aa3b, v189
	v_exp_f32_e32 v188, v188
	v_exp_f32_e32 v189, v189
	v_add_f32_e32 v134, 1.0, v134
	v_rcp_f32_e32 v191, v134
	v_rcp_f32_e32 v197, v135
	v_pk_add_f32 v[134:135], v[188:189], 1.0 op_sel_hi:[1,0]
	v_cvt_pk_bf16_f32 v185, v186, v187
	v_rcp_f32_e32 v198, v134
	v_pk_mul_f32 v[188:189], v[134:135], v[190:191]
	v_mul_f32_e64 v134, v136, -v108
	v_mul_f32_e32 v134, 0x3fb8aa3b, v134
	v_exp_f32_e32 v134, v134
	v_mul_f32_e64 v190, v136, -v76
	v_mul_f32_e32 v190, 0x3fb8aa3b, v190
	v_exp_f32_e32 v190, v190
	v_add_f32_e32 v134, 1.0, v134
	v_rcp_f32_e32 v192, v134
	v_mul_f32_e64 v134, v136, -v109
	v_mul_f32_e32 v134, 0x3fb8aa3b, v134
	v_exp_f32_e32 v134, v134
	v_mul_f32_e64 v136, v136, -v77
	v_mul_f32_e32 v136, 0x3fb8aa3b, v136
	v_exp_f32_e32 v191, v136
	v_add_f32_e32 v134, 1.0, v134
	v_rcp_f32_e32 v193, v134
	v_rcp_f32_e32 v136, v135
	v_pk_add_f32 v[134:135], v[190:191], 1.0 op_sel_hi:[1,0]
	v_cvt_pk_bf16_f32 v186, v188, v189
	v_rcp_f32_e32 v199, v134
	v_pk_mul_f32 v[190:191], v[134:135], v[192:193]
	v_rcp_f32_e32 v192, v135
	v_lshl_add_u64 v[134:135], s[60:61], 0, v[148:149]
	v_cvt_pk_bf16_f32 v187, v190, v191
	v_lshl_add_u64 v[188:189], s[10:11], 0, v[134:135]
	global_store_dwordx4 v[188:189], v[184:187], off nt
	v_mul_f32_e64 v188, v137, -v70
	v_mul_f32_e64 v189, v137, -v71
	v_cvt_pk_bf16_f32 v186, v198, v136
	v_mul_f32_e64 v136, v137, -v102
	v_mul_f32_e32 v136, 0x3fb8aa3b, v136
	v_exp_f32_e32 v136, v136
	v_mul_f32_e32 v188, 0x3fb8aa3b, v188
	v_mul_f32_e32 v189, 0x3fb8aa3b, v189
	v_exp_f32_e32 v188, v188
	v_add_f32_e32 v136, 1.0, v136
	v_rcp_f32_e32 v190, v136
	v_mul_f32_e64 v136, v137, -v103
	v_mul_f32_e32 v136, 0x3fb8aa3b, v136
	v_exp_f32_e32 v136, v136
	v_exp_f32_e32 v189, v189
	v_cvt_pk_bf16_f32 v184, v194, v195
	v_cvt_pk_bf16_f32 v185, v196, v197
	v_add_f32_e32 v136, 1.0, v136
	v_rcp_f32_e32 v191, v136
	v_cvt_pk_bf16_f32 v187, v199, v192
	v_lshl_add_u64 v[134:135], s[12:13], 0, v[134:135]
	global_store_dwordx4 v[134:135], v[184:187], off nt
	v_pk_add_f32 v[134:135], v[188:189], 1.0 op_sel_hi:[1,0]
	v_mul_f32_e64 v136, v137, -v72
	v_rcp_f32_e32 v194, v134
	v_pk_mul_f32 v[184:185], v[134:135], v[190:191]
	v_mul_f32_e64 v134, v137, -v104
	v_mul_f32_e32 v134, 0x3fb8aa3b, v134
	v_exp_f32_e32 v134, v134
	v_mul_f32_e32 v136, 0x3fb8aa3b, v136
	v_exp_f32_e32 v186, v136
	v_mul_f32_e64 v136, v137, -v73
	v_add_f32_e32 v134, 1.0, v134
	v_rcp_f32_e32 v188, v134
	v_mul_f32_e64 v134, v137, -v105
	v_mul_f32_e32 v134, 0x3fb8aa3b, v134
	v_exp_f32_e32 v134, v134
	v_mul_f32_e32 v136, 0x3fb8aa3b, v136
	v_exp_f32_e32 v187, v136
	v_rcp_f32_e32 v195, v135
	v_add_f32_e32 v134, 1.0, v134
	v_rcp_f32_e32 v189, v134
	v_pk_add_f32 v[134:135], v[186:187], 1.0 op_sel_hi:[1,0]
	v_mul_f32_e64 v136, v137, -v66
	v_rcp_f32_e32 v196, v134
	v_pk_mul_f32 v[186:187], v[134:135], v[188:189]
	v_mul_f32_e64 v134, v137, -v98
	v_mul_f32_e32 v134, 0x3fb8aa3b, v134
	v_exp_f32_e32 v134, v134
	v_mul_f32_e32 v136, 0x3fb8aa3b, v136
	v_exp_f32_e32 v188, v136
	v_mul_f32_e64 v136, v137, -v67
; __device__ __forceinline__ unsigned pk2(float lo, float hi) { f32x2_t v = {lo, hi}; bf16x2_t b = __builtin_convertvector(v, bf16x2_t); return __builtin_bit_cast(unsigned, b); }
; __device__ __forceinline__ float fast_exp(float x) { return __builtin_amdgcn_exp2f(x * LOG2E); }
; __device__ __forceinline__ float fast_rcp(float x) { return __builtin_amdgcn_rcpf(x); }
;     __device__ __forceinline__ void operator()(Acc& acc, const Unit& u, int wr, int wc, int fr, int fq, const float (&rsa)[2][4]) const {
;     ...
;                 const int row = row0 + ai * HALF + m * 16; const float rs = rsa[ai][m];
;                 float r[8], ss[8];
; #pragma unroll
;                 for (int n = 0; n < 2; ++n)
; #pragma unroll
;                     for (int j = 0; j < 4; ++j) { const float eg = fast_exp(-acc[ai][0][m][n][j] * rs), es = fast_exp(-acc[ai][1][m][n][j] * rs);
;                         ss[n * 4 + j] = fast_rcp(1.0f + es); r[n * 4 + j] = (1.0f + es) * fast_rcp(1.0f + eg); }
;                 const size_t po = ((size_t)(u.pm * 8 + u.pn) << 16) + (size_t)((((wr * 4 + wc) * 8 + ai * 4 + m) << 10) + (fq * 16 + fr) * 16);
;                 u32x4 w; w.x = pk2(r[0], r[1]); w.y = pk2(r[2], r[3]); w.z = pk2(r[4], r[5]); w.w = pk2(r[6], r[7]);
;                 *(u32x4*)((char*)R + po) = w;
;                 w.x = pk2(ss[0], ss[1]); w.y = pk2(ss[2], ss[3]); w.z = pk2(ss[4], ss[5]); w.w = pk2(ss[6], ss[7]);
;                 *(u32x4*)((char*)SS + po) = w;
	v_add_f32_e32 v134, 1.0, v134
	v_rcp_f32_e32 v190, v134
	v_mul_f32_e64 v134, v137, -v99
	v_mul_f32_e32 v134, 0x3fb8aa3b, v134
	v_exp_f32_e32 v134, v134
	v_mul_f32_e32 v136, 0x3fb8aa3b, v136
	v_exp_f32_e32 v189, v136
	v_rcp_f32_e32 v197, v135
	v_add_f32_e32 v134, 1.0, v134
	v_rcp_f32_e32 v191, v134
	v_pk_add_f32 v[134:135], v[188:189], 1.0 op_sel_hi:[1,0]
	v_mul_f32_e64 v136, v137, -v68
	v_rcp_f32_e32 v198, v134
	v_pk_mul_f32 v[188:189], v[134:135], v[190:191]
	v_mul_f32_e64 v134, v137, -v100
	v_mul_f32_e32 v134, 0x3fb8aa3b, v134
	v_exp_f32_e32 v134, v134
	v_mul_f32_e32 v136, 0x3fb8aa3b, v136
	v_exp_f32_e32 v136, v136
	v_rcp_f32_e32 v199, v135
	v_add_f32_e32 v134, 1.0, v134
	v_rcp_f32_e32 v190, v134
	v_mul_f32_e64 v134, v137, -v101
	v_mul_f32_e32 v134, 0x3fb8aa3b, v134
	v_exp_f32_e32 v134, v134
	v_mul_f32_e64 v137, v137, -v69
	v_mul_f32_e32 v137, 0x3fb8aa3b, v137
	v_exp_f32_e32 v137, v137
	v_add_f32_e32 v134, 1.0, v134
	v_rcp_f32_e32 v191, v134
	v_lshl_add_u64 v[192:193], s[60:61], 0, v[150:151]
	v_pk_add_f32 v[134:135], v[136:137], 1.0 op_sel_hi:[1,0]
	v_cvt_pk_bf16_f32 v136, v188, v189
	v_pk_mul_f32 v[190:191], v[134:135], v[190:191]
	v_rcp_f32_e32 v201, v135
	v_cvt_pk_bf16_f32 v135, v186, v187
	v_mul_f32_e64 v186, v130, -v62
	v_mul_f32_e32 v186, 0x3fb8aa3b, v186
	v_exp_f32_e32 v187, v186
	v_mul_f32_e64 v186, v130, -v30
	v_rcp_f32_e32 v200, v134
	v_mul_f32_e32 v186, 0x3fb8aa3b, v186
	v_add_f32_e32 v187, 1.0, v187
	v_rcp_f32_e32 v188, v187
	v_mul_f32_e64 v187, v130, -v63
	v_mul_f32_e32 v187, 0x3fb8aa3b, v187
	v_exp_f32_e32 v189, v187
	v_mul_f32_e64 v187, v130, -v31
	v_mul_f32_e32 v187, 0x3fb8aa3b, v187
	v_exp_f32_e32 v186, v186
	v_exp_f32_e32 v187, v187
	v_add_f32_e32 v189, 1.0, v189
	v_rcp_f32_e32 v189, v189
	v_cvt_pk_bf16_f32 v134, v184, v185
	v_cvt_pk_bf16_f32 v137, v190, v191
	v_lshl_add_u64 v[184:185], s[10:11], 0, v[192:193]
	global_store_dwordx4 v[184:185], v[134:137], off nt
	v_lshl_add_u64 v[184:185], s[12:13], 0, v[192:193]
	s_nop 0
	v_cvt_pk_bf16_f32 v134, v194, v195
	v_cvt_pk_bf16_f32 v135, v196, v197
	v_cvt_pk_bf16_f32 v136, v198, v199
	v_cvt_pk_bf16_f32 v137, v200, v201
	global_store_dwordx4 v[184:185], v[134:137], off nt
	v_mul_f32_e64 v184, v130, -v32
	v_mul_f32_e64 v185, v130, -v33
	v_pk_add_f32 v[134:135], v[186:187], 1.0 op_sel_hi:[1,0]
	v_mul_f32_e32 v184, 0x3fb8aa3b, v184
	v_rcp_f32_e32 v192, v134
	v_pk_mul_f32 v[136:137], v[134:135], v[188:189]
	v_mul_f32_e64 v134, v130, -v64
	v_mul_f32_e32 v134, 0x3fb8aa3b, v134
	v_exp_f32_e32 v134, v134
	v_mul_f32_e32 v185, 0x3fb8aa3b, v185
	v_exp_f32_e32 v184, v184
	v_exp_f32_e32 v185, v185
	v_add_f32_e32 v134, 1.0, v134
	v_rcp_f32_e32 v186, v134
	v_mul_f32_e64 v134, v130, -v65
	v_mul_f32_e32 v134, 0x3fb8aa3b, v134
	v_exp_f32_e32 v134, v134
	v_rcp_f32_e32 v193, v135
	v_add_f32_e32 v134, 1.0, v134
	v_rcp_f32_e32 v187, v134
	v_pk_add_f32 v[134:135], v[184:185], 1.0 op_sel_hi:[1,0]
	s_nop 0
	v_rcp_f32_e32 v194, v134
	v_pk_mul_f32 v[184:185], v[134:135], v[186:187]
	v_mul_f32_e64 v134, v130, -v58
	v_mul_f32_e32 v134, 0x3fb8aa3b, v134
	v_exp_f32_e32 v134, v134
	v_mul_f32_e64 v186, v130, -v26
	v_mul_f32_e64 v187, v130, -v27
	v_mul_f32_e32 v186, 0x3fb8aa3b, v186
	v_add_f32_e32 v134, 1.0, v134
	v_rcp_f32_e32 v188, v134
	v_mul_f32_e64 v134, v130, -v59
	v_mul_f32_e32 v134, 0x3fb8aa3b, v134
	v_exp_f32_e32 v134, v134
	v_mul_f32_e32 v187, 0x3fb8aa3b, v187
	v_exp_f32_e32 v186, v186
	v_exp_f32_e32 v187, v187
	v_add_f32_e32 v134, 1.0, v134
	v_rcp_f32_e32 v189, v134
	v_rcp_f32_e32 v195, v135
	v_pk_add_f32 v[134:135], v[186:187], 1.0 op_sel_hi:[1,0]
	s_nop 0
	v_rcp_f32_e32 v196, v134
	v_pk_mul_f32 v[186:187], v[134:135], v[188:189]
	v_mul_f32_e64 v134, v130, -v60
	v_mul_f32_e32 v134, 0x3fb8aa3b, v134
	v_exp_f32_e32 v134, v134
	v_mul_f32_e64 v188, v130, -v28
	v_mul_f32_e32 v188, 0x3fb8aa3b, v188
	v_exp_f32_e32 v188, v188
	v_add_f32_e32 v134, 1.0, v134
	v_rcp_f32_e32 v190, v134
	v_mul_f32_e64 v134, v130, -v61
	v_mul_f32_e32 v134, 0x3fb8aa3b, v134
	v_exp_f32_e32 v134, v134
	v_mul_f32_e64 v130, v130, -v29
	v_mul_f32_e32 v130, 0x3fb8aa3b, v130
	v_exp_f32_e32 v189, v130
	v_add_f32_e32 v130, 1.0, v134
	v_rcp_f32_e32 v191, v130
	v_rcp_f32_e32 v130, v135
	v_pk_add_f32 v[134:135], v[188:189], 1.0 op_sel_hi:[1,0]
	s_nop 0
	v_pk_mul_f32 v[188:189], v[134:135], v[190:191]
	v_lshl_add_u64 v[190:191], s[60:61], 0, v[152:153]
	v_rcp_f32_e32 v197, v134
	v_rcp_f32_e32 v198, v135
	v_cvt_pk_bf16_f32 v134, v136, v137
	v_cvt_pk_bf16_f32 v135, v184, v185
	v_cvt_pk_bf16_f32 v136, v186, v187
	v_cvt_pk_bf16_f32 v137, v188, v189
	v_lshl_add_u64 v[184:185], s[10:11], 0, v[190:191]
	global_store_dwordx4 v[184:185], v[134:137], off nt
	v_mul_f32_e64 v186, v131, -v22
	v_mul_f32_e64 v187, v131, -v23
	v_cvt_pk_bf16_f32 v136, v196, v130
	v_mul_f32_e64 v130, v131, -v54
	v_mul_f32_e32 v130, 0x3fb8aa3b, v130
	v_exp_f32_e32 v130, v130
	v_mul_f32_e32 v186, 0x3fb8aa3b, v186
	v_mul_f32_e32 v187, 0x3fb8aa3b, v187
	v_exp_f32_e32 v186, v186
	v_add_f32_e32 v130, 1.0, v130
	v_rcp_f32_e32 v188, v130
	v_mul_f32_e64 v130, v131, -v55
	v_mul_f32_e32 v130, 0x3fb8aa3b, v130
	v_exp_f32_e32 v130, v130
	v_exp_f32_e32 v187, v187
	v_cvt_pk_bf16_f32 v134, v192, v193
	v_cvt_pk_bf16_f32 v135, v194, v195
	v_add_f32_e32 v130, 1.0, v130
	v_rcp_f32_e32 v189, v130
	v_mul_f32_e64 v130, v131, -v56
	v_mul_f32_e32 v130, 0x3fb8aa3b, v130
	v_exp_f32_e32 v130, v130
	v_cvt_pk_bf16_f32 v137, v197, v198
	v_lshl_add_u64 v[184:185], s[12:13], 0, v[190:191]
	global_store_dwordx4 v[184:185], v[134:137], off nt
	v_add_f32_e32 v130, 1.0, v130
	s_nop 0
	v_pk_add_f32 v[134:135], v[186:187], 1.0 op_sel_hi:[1,0]
	v_rcp_f32_e32 v186, v130
	v_mul_f32_e64 v130, v131, -v57
; __device__ __forceinline__ unsigned pk2(float lo, float hi) { f32x2_t v = {lo, hi}; bf16x2_t b = __builtin_convertvector(v, bf16x2_t); return __builtin_bit_cast(unsigned, b); }
; __device__ __forceinline__ float fast_exp(float x) { return __builtin_amdgcn_exp2f(x * LOG2E); }
; __device__ __forceinline__ float fast_rcp(float x) { return __builtin_amdgcn_rcpf(x); }
;     __device__ __forceinline__ void operator()(Acc& acc, const Unit& u, int wr, int wc, int fr, int fq, const float (&rsa)[2][4]) const {
;     ...
;                 const int row = row0 + ai * HALF + m * 16; const float rs = rsa[ai][m];
;                 float r[8], ss[8];
; #pragma unroll
;                 for (int n = 0; n < 2; ++n)
; #pragma unroll
;                     for (int j = 0; j < 4; ++j) { const float eg = fast_exp(-acc[ai][0][m][n][j] * rs), es = fast_exp(-acc[ai][1][m][n][j] * rs);
;                         ss[n * 4 + j] = fast_rcp(1.0f + es); r[n * 4 + j] = (1.0f + es) * fast_rcp(1.0f + eg); }
;                 const size_t po = ((size_t)(u.pm * 8 + u.pn) << 16) + (size_t)((((wr * 4 + wc) * 8 + ai * 4 + m) << 10) + (fq * 16 + fr) * 16);
;                 u32x4 w; w.x = pk2(r[0], r[1]); w.y = pk2(r[2], r[3]); w.z = pk2(r[4], r[5]); w.w = pk2(r[6], r[7]);
;                 *(u32x4*)((char*)R + po) = w;
;                 w.x = pk2(ss[0], ss[1]); w.y = pk2(ss[2], ss[3]); w.z = pk2(ss[4], ss[5]); w.w = pk2(ss[6], ss[7]);
;                 *(u32x4*)((char*)SS + po) = w;
	v_mul_f32_e32 v130, 0x3fb8aa3b, v130
	v_exp_f32_e32 v130, v130
	v_rcp_f32_e32 v190, v134
	v_pk_mul_f32 v[136:137], v[134:135], v[188:189]
	v_mul_f32_e64 v134, v131, -v24
	v_add_f32_e32 v130, 1.0, v130
	v_rcp_f32_e32 v187, v130
	v_mul_f32_e64 v130, v131, -v50
	v_mul_f32_e32 v134, 0x3fb8aa3b, v134
	v_mul_f32_e32 v130, 0x3fb8aa3b, v130
	v_exp_f32_e32 v184, v134
	v_mul_f32_e64 v134, v131, -v25
	v_exp_f32_e32 v130, v130
	v_mul_f32_e32 v134, 0x3fb8aa3b, v134
	v_exp_f32_e32 v185, v134
	v_rcp_f32_e32 v191, v135
	v_add_f32_e32 v130, 1.0, v130
	v_rcp_f32_e32 v188, v130
	v_mul_f32_e64 v130, v131, -v51
	v_pk_add_f32 v[134:135], v[184:185], 1.0 op_sel_hi:[1,0]
	v_mul_f32_e32 v130, 0x3fb8aa3b, v130
	v_rcp_f32_e32 v192, v134
	v_pk_mul_f32 v[184:185], v[134:135], v[186:187]
	v_mul_f32_e64 v134, v131, -v18
	v_exp_f32_e32 v130, v130
	v_mul_f32_e32 v134, 0x3fb8aa3b, v134
	v_exp_f32_e32 v186, v134
	v_mul_f32_e64 v134, v131, -v19
	v_mul_f32_e32 v134, 0x3fb8aa3b, v134
	v_exp_f32_e32 v187, v134
	v_add_f32_e32 v130, 1.0, v130
	v_rcp_f32_e32 v189, v130
	v_mul_f32_e64 v130, v131, -v52
	v_rcp_f32_e32 v193, v135
	v_pk_add_f32 v[134:135], v[186:187], 1.0 op_sel_hi:[1,0]
	v_mul_f32_e32 v130, 0x3fb8aa3b, v130
	v_rcp_f32_e32 v194, v134
	v_pk_mul_f32 v[186:187], v[134:135], v[188:189]
	v_exp_f32_e32 v134, v130
	v_mul_f32_e64 v130, v131, -v20
	v_mul_f32_e32 v130, 0x3fb8aa3b, v130
	v_exp_f32_e32 v130, v130
	v_add_f32_e32 v134, 1.0, v134
	v_rcp_f32_e32 v188, v134
	v_mul_f32_e64 v134, v131, -v53
	v_mul_f32_e32 v134, 0x3fb8aa3b, v134
	v_exp_f32_e32 v134, v134
	v_mul_f32_e64 v131, v131, -v21
	v_mul_f32_e32 v131, 0x3fb8aa3b, v131
	v_exp_f32_e32 v131, v131
	v_add_f32_e32 v134, 1.0, v134
	v_rcp_f32_e32 v189, v134
	v_rcp_f32_e32 v195, v135
	v_pk_add_f32 v[130:131], v[130:131], 1.0 op_sel_hi:[1,0]
	v_cvt_pk_bf16_f32 v134, v136, v137
	v_rcp_f32_e32 v196, v130
	v_pk_mul_f32 v[188:189], v[130:131], v[188:189]
	v_rcp_f32_e32 v197, v131
	v_lshl_add_u64 v[130:131], s[60:61], 0, v[154:155]
	v_cvt_pk_bf16_f32 v135, v184, v185
	v_cvt_pk_bf16_f32 v136, v186, v187
	v_cvt_pk_bf16_f32 v137, v188, v189
	v_lshl_add_u64 v[184:185], s[10:11], 0, v[130:131]
	global_store_dwordx4 v[184:185], v[134:137], off nt
	v_mul_f32_e64 v184, v132, -v46
	v_mul_f32_e32 v184, 0x3fb8aa3b, v184
	v_exp_f32_e32 v185, v184
	v_mul_f32_e64 v184, v132, -v14
	v_mul_f32_e32 v184, 0x3fb8aa3b, v184
	v_exp_f32_e32 v184, v184
	v_add_f32_e32 v185, 1.0, v185
	v_rcp_f32_e32 v186, v185
	v_mul_f32_e64 v185, v132, -v47
	v_mul_f32_e32 v185, 0x3fb8aa3b, v185
	v_exp_f32_e32 v187, v185
	v_mul_f32_e64 v185, v132, -v15
	v_mul_f32_e32 v185, 0x3fb8aa3b, v185
	v_exp_f32_e32 v185, v185
	v_add_f32_e32 v187, 1.0, v187
	v_rcp_f32_e32 v187, v187
	v_cvt_pk_bf16_f32 v134, v190, v191
	v_cvt_pk_bf16_f32 v135, v192, v193
	v_cvt_pk_bf16_f32 v136, v194, v195
	v_cvt_pk_bf16_f32 v137, v196, v197
	v_lshl_add_u64 v[130:131], s[12:13], 0, v[130:131]
	global_store_dwordx4 v[130:131], v[134:137], off nt
	v_pk_add_f32 v[130:131], v[184:185], 1.0 op_sel_hi:[1,0]
	s_nop 0
	v_rcp_f32_e32 v190, v130
	v_pk_mul_f32 v[134:135], v[130:131], v[186:187]
	v_mul_f32_e64 v130, v132, -v48
	v_mul_f32_e32 v130, 0x3fb8aa3b, v130
	v_exp_f32_e32 v130, v130
	v_mul_f32_e64 v136, v132, -v16
	v_mul_f32_e64 v137, v132, -v17
	v_mul_f32_e32 v136, 0x3fb8aa3b, v136
	v_add_f32_e32 v130, 1.0, v130
	v_rcp_f32_e32 v184, v130
	v_mul_f32_e64 v130, v132, -v49
	v_mul_f32_e32 v130, 0x3fb8aa3b, v130
	v_exp_f32_e32 v130, v130
	v_mul_f32_e32 v137, 0x3fb8aa3b, v137
	v_exp_f32_e32 v136, v136
	v_exp_f32_e32 v137, v137
	v_add_f32_e32 v130, 1.0, v130
	v_rcp_f32_e32 v185, v130
	v_rcp_f32_e32 v191, v131
	v_pk_add_f32 v[130:131], v[136:137], 1.0 op_sel_hi:[1,0]
	v_cvt_pk_bf16_f32 v134, v134, v135
	v_rcp_f32_e32 v192, v130
	v_pk_mul_f32 v[136:137], v[130:131], v[184:185]
	v_mul_f32_e64 v130, v132, -v42
	v_mul_f32_e32 v130, 0x3fb8aa3b, v130
	v_exp_f32_e32 v130, v130
	v_mul_f32_e64 v184, v132, -v10
	v_mul_f32_e64 v185, v132, -v11
	v_mul_f32_e32 v184, 0x3fb8aa3b, v184
	v_add_f32_e32 v130, 1.0, v130
	v_rcp_f32_e32 v186, v130
	v_mul_f32_e64 v130, v132, -v43
	v_mul_f32_e32 v130, 0x3fb8aa3b, v130
	v_exp_f32_e32 v130, v130
	v_mul_f32_e32 v185, 0x3fb8aa3b, v185
	v_exp_f32_e32 v184, v184
	v_exp_f32_e32 v185, v185
	v_add_f32_e32 v130, 1.0, v130
	v_rcp_f32_e32 v187, v130
	v_rcp_f32_e32 v193, v131
	v_pk_add_f32 v[130:131], v[184:185], 1.0 op_sel_hi:[1,0]
	v_cvt_pk_bf16_f32 v135, v136, v137
	v_rcp_f32_e32 v194, v130
	v_pk_mul_f32 v[184:185], v[130:131], v[186:187]
; __device__ __forceinline__ unsigned pk2(float lo, float hi) { f32x2_t v = {lo, hi}; bf16x2_t b = __builtin_convertvector(v, bf16x2_t); return __builtin_bit_cast(unsigned, b); }
; __device__ __forceinline__ float fast_exp(float x) { return __builtin_amdgcn_exp2f(x * LOG2E); }
; __device__ __forceinline__ float fast_rcp(float x) { return __builtin_amdgcn_rcpf(x); }
;     __device__ __forceinline__ void operator()(Acc& acc, const Unit& u, int wr, int wc, int fr, int fq, const float (&rsa)[2][4]) const {
;     ...
;                 const int row = row0 + ai * HALF + m * 16; const float rs = rsa[ai][m];
;                 float r[8], ss[8];
; #pragma unroll
;                 for (int n = 0; n < 2; ++n)
; #pragma unroll
;                     for (int j = 0; j < 4; ++j) { const float eg = fast_exp(-acc[ai][0][m][n][j] * rs), es = fast_exp(-acc[ai][1][m][n][j] * rs);
;                         ss[n * 4 + j] = fast_rcp(1.0f + es); r[n * 4 + j] = (1.0f + es) * fast_rcp(1.0f + eg); }
;                 const size_t po = ((size_t)(u.pm * 8 + u.pn) << 16) + (size_t)((((wr * 4 + wc) * 8 + ai * 4 + m) << 10) + (fq * 16 + fr) * 16);
;                 u32x4 w; w.x = pk2(r[0], r[1]); w.y = pk2(r[2], r[3]); w.z = pk2(r[4], r[5]); w.w = pk2(r[6], r[7]);
;                 *(u32x4*)((char*)R + po) = w;
;                 w.x = pk2(ss[0], ss[1]); w.y = pk2(ss[2], ss[3]); w.z = pk2(ss[4], ss[5]); w.w = pk2(ss[6], ss[7]);
;                 *(u32x4*)((char*)SS + po) = w;
	v_mul_f32_e64 v130, v132, -v44
	v_mul_f32_e32 v130, 0x3fb8aa3b, v130
	v_exp_f32_e32 v130, v130
	v_mul_f32_e64 v186, v132, -v12
	v_mul_f32_e32 v186, 0x3fb8aa3b, v186
	v_exp_f32_e32 v186, v186
	v_add_f32_e32 v130, 1.0, v130
	v_rcp_f32_e32 v188, v130
	v_mul_f32_e64 v130, v132, -v45
	v_mul_f32_e32 v130, 0x3fb8aa3b, v130
	v_exp_f32_e32 v130, v130
	v_mul_f32_e64 v132, v132, -v13
	v_mul_f32_e32 v132, 0x3fb8aa3b, v132
	v_exp_f32_e32 v187, v132
	v_add_f32_e32 v130, 1.0, v130
	v_rcp_f32_e32 v189, v130
	v_rcp_f32_e32 v132, v131
	v_pk_add_f32 v[130:131], v[186:187], 1.0 op_sel_hi:[1,0]
	v_cvt_pk_bf16_f32 v136, v184, v185
	v_rcp_f32_e32 v195, v130
	v_pk_mul_f32 v[186:187], v[130:131], v[188:189]
	v_rcp_f32_e32 v188, v131
	v_lshl_add_u64 v[130:131], s[60:61], 0, v[156:157]
	v_cvt_pk_bf16_f32 v137, v186, v187
	v_lshl_add_u64 v[184:185], s[10:11], 0, v[130:131]
	global_store_dwordx4 v[184:185], v[134:137], off nt
	v_mul_f32_e64 v184, v133, -v6
	v_mul_f32_e64 v185, v133, -v7
	v_cvt_pk_bf16_f32 v136, v194, v132
	v_mul_f32_e64 v132, v133, -v38
	v_mul_f32_e32 v132, 0x3fb8aa3b, v132
	v_exp_f32_e32 v132, v132
	v_mul_f32_e32 v184, 0x3fb8aa3b, v184
	v_mul_f32_e32 v185, 0x3fb8aa3b, v185
	v_exp_f32_e32 v184, v184
	v_add_f32_e32 v132, 1.0, v132
	v_rcp_f32_e32 v186, v132
	v_mul_f32_e64 v132, v133, -v39
	v_mul_f32_e32 v132, 0x3fb8aa3b, v132
	v_exp_f32_e32 v132, v132
	v_exp_f32_e32 v185, v185
	v_cvt_pk_bf16_f32 v134, v190, v191
	v_cvt_pk_bf16_f32 v135, v192, v193
	v_add_f32_e32 v132, 1.0, v132
	v_rcp_f32_e32 v187, v132
	v_cvt_pk_bf16_f32 v137, v195, v188
	v_lshl_add_u64 v[130:131], s[12:13], 0, v[130:131]
	global_store_dwordx4 v[130:131], v[134:137], off nt
	v_pk_add_f32 v[130:131], v[184:185], 1.0 op_sel_hi:[1,0]
	v_mul_f32_e64 v132, v133, -v8
	v_rcp_f32_e32 v190, v130
	v_pk_mul_f32 v[134:135], v[130:131], v[186:187]
	v_mul_f32_e64 v130, v133, -v40
	v_mul_f32_e32 v130, 0x3fb8aa3b, v130
	v_exp_f32_e32 v130, v130
	v_mul_f32_e32 v132, 0x3fb8aa3b, v132
	v_exp_f32_e32 v136, v132
	v_mul_f32_e64 v132, v133, -v9
	v_add_f32_e32 v130, 1.0, v130
	v_rcp_f32_e32 v184, v130
	v_mul_f32_e64 v130, v133, -v41
	v_mul_f32_e32 v130, 0x3fb8aa3b, v130
	v_exp_f32_e32 v130, v130
	v_mul_f32_e32 v132, 0x3fb8aa3b, v132
	v_exp_f32_e32 v137, v132
	v_rcp_f32_e32 v191, v131
	v_add_f32_e32 v130, 1.0, v130
	v_rcp_f32_e32 v185, v130
	v_pk_add_f32 v[130:131], v[136:137], 1.0 op_sel_hi:[1,0]
	v_mul_f32_e64 v132, v133, -v2
	v_rcp_f32_e32 v192, v130
	v_pk_mul_f32 v[136:137], v[130:131], v[184:185]
	v_mul_f32_e64 v130, v133, -v34
	v_mul_f32_e32 v130, 0x3fb8aa3b, v130
	v_exp_f32_e32 v130, v130
	v_mul_f32_e32 v132, 0x3fb8aa3b, v132
	v_exp_f32_e32 v184, v132
	v_mul_f32_e64 v132, v133, -v3
	v_add_f32_e32 v130, 1.0, v130
	v_rcp_f32_e32 v186, v130
	v_mul_f32_e64 v130, v133, -v35
	v_mul_f32_e32 v130, 0x3fb8aa3b, v130
	v_exp_f32_e32 v130, v130
	v_mul_f32_e32 v132, 0x3fb8aa3b, v132
	v_exp_f32_e32 v185, v132
	v_rcp_f32_e32 v193, v131
	v_add_f32_e32 v130, 1.0, v130
	v_rcp_f32_e32 v187, v130
	v_pk_add_f32 v[130:131], v[184:185], 1.0 op_sel_hi:[1,0]
	v_mul_f32_e64 v132, v133, -v4
	v_rcp_f32_e32 v194, v130
	v_pk_mul_f32 v[184:185], v[130:131], v[186:187]
	v_mul_f32_e64 v130, v133, -v36
	v_mul_f32_e32 v130, 0x3fb8aa3b, v130
	v_exp_f32_e32 v130, v130
	v_mul_f32_e32 v132, 0x3fb8aa3b, v132
	v_exp_f32_e32 v132, v132
	v_rcp_f32_e32 v195, v131
	v_add_f32_e32 v130, 1.0, v130
	v_rcp_f32_e32 v186, v130
	v_mul_f32_e64 v130, v133, -v37
	v_mul_f32_e32 v130, 0x3fb8aa3b, v130
	v_exp_f32_e32 v130, v130
	v_mul_f32_e64 v133, v133, -v5
	v_mul_f32_e32 v133, 0x3fb8aa3b, v133
	v_exp_f32_e32 v133, v133
	v_add_f32_e32 v130, 1.0, v130
	v_rcp_f32_e32 v187, v130
	v_lshl_add_u64 v[188:189], s[60:61], 0, v[158:159]
	v_pk_add_f32 v[130:131], v[132:133], 1.0 op_sel_hi:[1,0]
	v_cvt_pk_bf16_f32 v132, v184, v185
	v_rcp_f32_e32 v196, v130
	v_rcp_f32_e32 v197, v131
	v_pk_mul_f32 v[186:187], v[130:131], v[186:187]
	v_cvt_pk_bf16_f32 v130, v134, v135
	v_cvt_pk_bf16_f32 v131, v136, v137
	v_cvt_pk_bf16_f32 v133, v186, v187
	v_lshl_add_u64 v[134:135], s[10:11], 0, v[188:189]
	global_store_dwordx4 v[134:135], v[130:133], off nt
	v_lshl_add_u64 v[134:135], s[12:13], 0, v[188:189]
	s_nop 0
	v_cvt_pk_bf16_f32 v130, v190, v191
	v_cvt_pk_bf16_f32 v131, v192, v193
	v_cvt_pk_bf16_f32 v132, v194, v195
	v_cvt_pk_bf16_f32 v133, v196, v197
	global_store_dwordx4 v[134:135], v[130:133], off nt
	s_cbranch_vccnz .LBB0_1975
	s_andn2_b64 vcc, exec, s[28:29]
	s_cbranch_vccnz .LBB0_1974
	s_barrier
	s_branch .LBB0_1974

; __device__ __forceinline__ unsigned pk2(float lo, float hi) { f32x2_t v = {lo, hi}; bf16x2_t b = __builtin_convertvector(v, bf16x2_t); return __builtin_bit_cast(unsigned, b); }
; __device__ __forceinline__ float bflo(unsigned w) { return __uint_as_float(w << 16); }
; __device__ __forceinline__ float bfhi(unsigned w) { return __uint_as_float(w & 0xffff0000u); }
;     __device__ __forceinline__ void operator()(Acc& acc, const Unit& u, int wr, int wc, int fr, int fq) const {
;         const int col0 = u.pn * BM + wc * 32 + 8 * fq;
;         const bf16_t* G = u.sub == 0 ? R : SS;
;         const unsigned xlo = (unsigned)lds_byte(fr, 8 * fq);
;         const size_t tbase = (size_t)u.pm * BM * D * 2; const unsigned loff = (unsigned)((wr * 64 + fr) * D + col0) * 2u;
;         const char* gbase = (const char*)G + tbase; char* obase = (char*)O + tbase;
;         u32x4 gq[2][4][2];
; #pragma unroll
;         for (int ai = 0; ai < 2; ++ai)
; #pragma unroll
;             for (int m = 0; m < 4; ++m)
; #pragma unroll
;                 for (int bj = 0; bj < 2; ++bj) gq[ai][m][bj] = *(const u32x4*)((const char*)G + ((size_t)(u.pm * 8 + 2 * u.pn + bj) << 16) + (size_t)((((wr * 4 + wc) * 8 + ai * 4 + m) << 10) + (fq * 16 + fr) * 16));
; #pragma unroll
;         for (int ai = 0; ai < 2; ++ai)
; #pragma unroll
;             for (int m = 0; m < 4; ++m) {
; #pragma unroll
;                 for (int bj = 0; bj < 2; ++bj) {
;                     const u32x4 s = gq[ai][m][bj];
;                     const float gv[8] = {bflo(s.x), bfhi(s.x), bflo(s.y), bfhi(s.y), bflo(s.z), bfhi(s.z), bflo(s.w), bfhi(s.w)};
;                     if (u.sub == 0) {
; #pragma unroll
;                         for (int j = 0; j < 4; ++j) { acc[ai][bj][m][0][j] *= gv[j]; acc[ai][bj][m][1][j] *= gv[4 + j]; }
;                     } else {
;                         float o[8];
; #pragma unroll
;                         for (int j = 0; j < 4; ++j) { o[j] = acc[ai][bj][m][0][j] * gv[j]; o[4 + j] = acc[ai][bj][m][1][j] * gv[4 + j]; }
;                         u32x4 w; w.x = pk2(o[0], o[1]); w.y = pk2(o[2], o[3]); w.z = pk2(o[4], o[5]); w.w = pk2(o[6], o[7]);
;                         *(u32x4*)((char*)O + xb_piece(u.pm, u.pn, wr, wc, ai, m, bj) + xlo) = w;
.LBB0_2108:
	s_cmp_lg_u32 s68, 0
	s_cselect_b64 s[48:49], -1, 0
	s_cmp_eq_u32 s68, 0
	s_cselect_b64 s[6:7], -1, 0
	s_and_b64 vcc, s[6:7], exec
	s_cselect_b32 s7, s9, s11
	s_cselect_b32 s6, s8, s10
	s_lshl_b32 s41, s36, 3
	s_lshl_b32 s43, s38, 1
	s_add_i32 s50, s41, s43
	s_ashr_i32 s51, s50, 31
	v_lshl_add_u64 v[4:5], s[6:7], 0, v[202:203]
	s_or_b32 s6, s50, 1
	s_lshl_b64 s[68:69], s[50:51], 16
	s_ashr_i32 s7, s6, 31
	v_lshl_add_u64 v[134:135], v[4:5], 0, s[68:69]
	s_lshl_b64 s[6:7], s[6:7], 16
	v_lshl_add_u64 v[136:137], v[4:5], 0, s[6:7]
	global_load_dwordx4 v[242:245], v[134:135], off
	global_load_dwordx4 v[186:189], v[134:135], off offset:1024
	global_load_dwordx4 v[190:193], v[136:137], off
	global_load_dwordx4 v[182:185], v[136:137], off offset:1024
	global_load_dwordx4 v[178:181], v[134:135], off offset:2048
	global_load_dwordx4 v[170:173], v[134:135], off offset:3072
	global_load_dwordx4 v[174:177], v[136:137], off offset:2048
	global_load_dwordx4 v[166:169], v[136:137], off offset:3072
	v_lshl_add_u64 v[134:135], v[4:5], 0, s[26:27]
	v_lshl_add_u64 v[136:137], v[134:135], 0, s[68:69]
	v_lshl_add_u64 v[134:135], v[134:135], 0, s[6:7]
	global_load_dwordx4 v[162:165], v[136:137], off
	global_load_dwordx4 v[158:161], v[134:135], off
	v_lshl_add_u64 v[134:135], v[4:5], 0, s[30:31]
	v_lshl_add_u64 v[136:137], v[134:135], 0, s[68:69]
	v_lshl_add_u64 v[134:135], v[134:135], 0, s[6:7]
	global_load_dwordx4 v[154:157], v[136:137], off
	global_load_dwordx4 v[150:153], v[134:135], off
	v_lshl_add_u64 v[134:135], v[4:5], 0, s[28:29]
	v_lshl_add_u64 v[136:137], v[134:135], 0, s[68:69]
	v_lshl_add_u64 v[134:135], v[134:135], 0, s[6:7]
	v_lshl_add_u64 v[4:5], v[4:5], 0, s[34:35]
	global_load_dwordx4 v[146:149], v[136:137], off
	global_load_dwordx4 v[142:145], v[134:135], off
	v_lshl_add_u64 v[134:135], v[4:5], 0, s[68:69]
	v_lshl_add_u64 v[4:5], v[4:5], 0, s[6:7]
	global_load_dwordx4 v[138:141], v[134:135], off
	s_nop 0
	global_load_dwordx4 v[134:137], v[4:5], off
	s_mov_b64 s[6:7], -1
	s_waitcnt vmcnt(15)
	v_lshlrev_b32_e32 v230, 16, v242
	v_and_b32_e32 v231, 0xffff0000, v242
	v_lshlrev_b32_e32 v228, 16, v243
	v_and_b32_e32 v229, 0xffff0000, v243
	v_lshlrev_b32_e32 v226, 16, v244
	v_and_b32_e32 v227, 0xffff0000, v244
	v_lshlrev_b32_e32 v4, 16, v245
	v_and_b32_e32 v5, 0xffff0000, v245
	s_cbranch_vccnz .LBB0_2110
	s_lshl_b32 s6, s36, 4
	s_lshl_b32 s7, s38, 2
	s_add_i32 s6, s6, s7
	s_or_b32 s6, s6, s61
	s_ashr_i32 s7, s6, 31
	v_pk_mul_f32 v[242:243], v[130:131], v[230:231]
	v_pk_mul_f32 v[244:245], v[126:127], v[226:227]
	v_pk_mul_f32 v[246:247], v[132:133], v[228:229]
	v_pk_mul_f32 v[248:249], v[128:129], v[4:5]
	s_lshl_b64 s[6:7], s[6:7], 15
	v_cvt_pk_bf16_f32 v242, v242, v243
	v_cvt_pk_bf16_f32 v243, v246, v247
	v_cvt_pk_bf16_f32 v244, v244, v245
	v_cvt_pk_bf16_f32 v245, v248, v249
	v_lshl_add_u64 v[246:247], v[204:205], 0, s[6:7]
	s_mov_b64 s[6:7], 0
	global_store_dwordx4 v[246:247], v[242:245], off nt

; __device__ __forceinline__ unsigned pk2(float lo, float hi) { f32x2_t v = {lo, hi}; bf16x2_t b = __builtin_convertvector(v, bf16x2_t); return __builtin_bit_cast(unsigned, b); }
; __device__ __forceinline__ float bflo(unsigned w) { return __uint_as_float(w << 16); }
; __device__ __forceinline__ float bfhi(unsigned w) { return __uint_as_float(w & 0xffff0000u); }
;     __device__ __forceinline__ void operator()(Acc& acc, const Unit& u, int wr, int wc, int fr, int fq) const {
;     ...
;                     const u32x4 s = gq[ai][m][bj];
;                     const float gv[8] = {bflo(s.x), bfhi(s.x), bflo(s.y), bfhi(s.y), bflo(s.z), bfhi(s.z), bflo(s.w), bfhi(s.w)};
;                     if (u.sub == 0) {
; #pragma unroll
;                         for (int j = 0; j < 4; ++j) { acc[ai][bj][m][0][j] *= gv[j]; acc[ai][bj][m][1][j] *= gv[4 + j]; }
;                     } else {
;                         float o[8];
; #pragma unroll
;                         for (int j = 0; j < 4; ++j) { o[j] = acc[ai][bj][m][0][j] * gv[j]; o[4 + j] = acc[ai][bj][m][1][j] * gv[4 + j]; }
;                         u32x4 w; w.x = pk2(o[0], o[1]); w.y = pk2(o[2], o[3]); w.z = pk2(o[4], o[5]); w.w = pk2(o[6], o[7]);
;                         *(u32x4*)((char*)O + xb_piece(u.pm, u.pn, wr, wc, ai, m, bj) + xlo) = w;
.LBB0_2112:
	v_cndmask_b32_e64 v3, 0, 1, s[48:49]
	s_waitcnt vmcnt(13)
	v_lshlrev_b32_e32 v228, 16, v190
	v_and_b32_e32 v229, 0xffff0000, v190
	v_lshlrev_b32_e32 v226, 16, v191
	v_and_b32_e32 v227, 0xffff0000, v191
	v_lshlrev_b32_e32 v190, 16, v192
	v_and_b32_e32 v191, 0xffff0000, v192
	v_lshlrev_b32_e32 v4, 16, v193
	v_and_b32_e32 v5, 0xffff0000, v193
	v_cmp_ne_u32_e64 s[6:7], 1, v3
	s_andn2_b64 vcc, exec, s[48:49]
	s_mov_b64 s[48:49], -1
	s_cbranch_vccnz .LBB0_2114
	s_lshl_b32 s41, s36, 4
	s_lshl_b32 s43, s38, 2
	s_add_i32 s41, s41, s43
	s_or_b32 s48, s41, s62
	s_ashr_i32 s49, s48, 31
	v_pk_mul_f32 v[192:193], v[98:99], v[228:229]
	v_pk_mul_f32 v[230:231], v[94:95], v[190:191]
	v_pk_mul_f32 v[244:245], v[100:101], v[226:227]
	v_pk_mul_f32 v[246:247], v[96:97], v[4:5]
	s_lshl_b64 s[48:49], s[48:49], 15
	v_cvt_pk_bf16_f32 v242, v192, v193
	v_cvt_pk_bf16_f32 v243, v244, v245
	v_cvt_pk_bf16_f32 v244, v230, v231
	v_cvt_pk_bf16_f32 v245, v246, v247
	v_lshl_add_u64 v[192:193], v[204:205], 0, s[48:49]
	s_mov_b64 s[48:49], 0
	global_store_dwordx4 v[192:193], v[242:245], off nt

; __device__ __forceinline__ unsigned pk2(float lo, float hi) { f32x2_t v = {lo, hi}; bf16x2_t b = __builtin_convertvector(v, bf16x2_t); return __builtin_bit_cast(unsigned, b); }
; __device__ __forceinline__ float bflo(unsigned w) { return __uint_as_float(w << 16); }
; __device__ __forceinline__ float bfhi(unsigned w) { return __uint_as_float(w & 0xffff0000u); }
;     __device__ __forceinline__ void operator()(Acc& acc, const Unit& u, int wr, int wc, int fr, int fq) const {
;     ...
;                     const u32x4 s = gq[ai][m][bj];
;                     const float gv[8] = {bflo(s.x), bfhi(s.x), bflo(s.y), bfhi(s.y), bflo(s.z), bfhi(s.z), bflo(s.w), bfhi(s.w)};
;                     if (u.sub == 0) {
; #pragma unroll
;                         for (int j = 0; j < 4; ++j) { acc[ai][bj][m][0][j] *= gv[j]; acc[ai][bj][m][1][j] *= gv[4 + j]; }
;                     } else {
;                         float o[8];
; #pragma unroll
;                         for (int j = 0; j < 4; ++j) { o[j] = acc[ai][bj][m][0][j] * gv[j]; o[4 + j] = acc[ai][bj][m][1][j] * gv[4 + j]; }
;                         u32x4 w; w.x = pk2(o[0], o[1]); w.y = pk2(o[2], o[3]); w.z = pk2(o[4], o[5]); w.w = pk2(o[6], o[7]);
;                         *(u32x4*)((char*)O + xb_piece(u.pm, u.pn, wr, wc, ai, m, bj) + xlo) = w;
.LBB0_2116:
	v_lshlrev_b32_e32 v192, 16, v186
	v_and_b32_e32 v193, 0xffff0000, v186
	v_lshlrev_b32_e32 v190, 16, v187
	v_and_b32_e32 v191, 0xffff0000, v187
	v_lshlrev_b32_e32 v186, 16, v188
	v_and_b32_e32 v187, 0xffff0000, v188
	v_lshlrev_b32_e32 v4, 16, v189
	v_and_b32_e32 v5, 0xffff0000, v189
	s_and_b64 vcc, exec, s[6:7]
	s_mov_b64 s[48:49], -1
	s_cbranch_vccnz .LBB0_2118
	s_lshl_b32 s41, s36, 4
	s_lshl_b32 s43, s38, 2
	s_add_i32 s41, s41, s43
	s_or_b32 s48, s41, s61
	s_ashr_i32 s49, s48, 31
	v_pk_mul_f32 v[188:189], v[122:123], v[192:193]
	v_pk_mul_f32 v[228:229], v[118:119], v[186:187]
	v_pk_mul_f32 v[230:231], v[124:125], v[190:191]
	v_pk_mul_f32 v[242:243], v[120:121], v[4:5]
	s_lshl_b64 s[48:49], s[48:49], 15
	v_cvt_pk_bf16_f32 v226, v188, v189
	v_cvt_pk_bf16_f32 v227, v230, v231
	v_cvt_pk_bf16_f32 v228, v228, v229
	v_cvt_pk_bf16_f32 v229, v242, v243
	v_lshl_add_u64 v[188:189], v[204:205], 0, s[48:49]
	s_mov_b64 s[48:49], 0
	global_store_dwordx4 v[188:189], v[226:229], off offset:2048 nt

; __device__ __forceinline__ unsigned pk2(float lo, float hi) { f32x2_t v = {lo, hi}; bf16x2_t b = __builtin_convertvector(v, bf16x2_t); return __builtin_bit_cast(unsigned, b); }
; __device__ __forceinline__ float bflo(unsigned w) { return __uint_as_float(w << 16); }
; __device__ __forceinline__ float bfhi(unsigned w) { return __uint_as_float(w & 0xffff0000u); }
;     __device__ __forceinline__ void operator()(Acc& acc, const Unit& u, int wr, int wc, int fr, int fq) const {
;     ...
;                     const u32x4 s = gq[ai][m][bj];
;                     const float gv[8] = {bflo(s.x), bfhi(s.x), bflo(s.y), bfhi(s.y), bflo(s.z), bfhi(s.z), bflo(s.w), bfhi(s.w)};
;                     if (u.sub == 0) {
; #pragma unroll
;                         for (int j = 0; j < 4; ++j) { acc[ai][bj][m][0][j] *= gv[j]; acc[ai][bj][m][1][j] *= gv[4 + j]; }
;                     } else {
;                         float o[8];
; #pragma unroll
;                         for (int j = 0; j < 4; ++j) { o[j] = acc[ai][bj][m][0][j] * gv[j]; o[4 + j] = acc[ai][bj][m][1][j] * gv[4 + j]; }
;                         u32x4 w; w.x = pk2(o[0], o[1]); w.y = pk2(o[2], o[3]); w.z = pk2(o[4], o[5]); w.w = pk2(o[6], o[7]);
;                         *(u32x4*)((char*)O + xb_piece(u.pm, u.pn, wr, wc, ai, m, bj) + xlo) = w;
.LBB0_2120:
	s_waitcnt vmcnt(12)
	v_lshlrev_b32_e32 v188, 16, v182
	v_and_b32_e32 v189, 0xffff0000, v182
	v_lshlrev_b32_e32 v186, 16, v183
	v_and_b32_e32 v187, 0xffff0000, v183
	v_lshlrev_b32_e32 v182, 16, v184
	v_and_b32_e32 v183, 0xffff0000, v184
	v_lshlrev_b32_e32 v4, 16, v185
	v_and_b32_e32 v5, 0xffff0000, v185
	s_and_b64 vcc, exec, s[6:7]
	s_mov_b64 s[48:49], -1
	s_cbranch_vccnz .LBB0_2122
	s_lshl_b32 s41, s36, 4
	s_lshl_b32 s43, s38, 2
	s_add_i32 s41, s41, s43
	s_or_b32 s48, s41, s62
	s_ashr_i32 s49, s48, 31
	v_pk_mul_f32 v[184:185], v[90:91], v[188:189]
	v_pk_mul_f32 v[192:193], v[86:87], v[182:183]
	v_pk_mul_f32 v[226:227], v[92:93], v[186:187]
	v_pk_mul_f32 v[228:229], v[88:89], v[4:5]
	s_lshl_b64 s[48:49], s[48:49], 15
	v_cvt_pk_bf16_f32 v190, v184, v185
	v_cvt_pk_bf16_f32 v191, v226, v227
	v_cvt_pk_bf16_f32 v192, v192, v193
	v_cvt_pk_bf16_f32 v193, v228, v229
	v_lshl_add_u64 v[184:185], v[204:205], 0, s[48:49]
	s_mov_b64 s[48:49], 0
	global_store_dwordx4 v[184:185], v[190:193], off offset:2048 nt

; __device__ __forceinline__ unsigned pk2(float lo, float hi) { f32x2_t v = {lo, hi}; bf16x2_t b = __builtin_convertvector(v, bf16x2_t); return __builtin_bit_cast(unsigned, b); }
; __device__ __forceinline__ float bflo(unsigned w) { return __uint_as_float(w << 16); }
; __device__ __forceinline__ float bfhi(unsigned w) { return __uint_as_float(w & 0xffff0000u); }
;     __device__ __forceinline__ void operator()(Acc& acc, const Unit& u, int wr, int wc, int fr, int fq) const {
;     ...
;                     const u32x4 s = gq[ai][m][bj];
;                     const float gv[8] = {bflo(s.x), bfhi(s.x), bflo(s.y), bfhi(s.y), bflo(s.z), bfhi(s.z), bflo(s.w), bfhi(s.w)};
;                     if (u.sub == 0) {
; #pragma unroll
;                         for (int j = 0; j < 4; ++j) { acc[ai][bj][m][0][j] *= gv[j]; acc[ai][bj][m][1][j] *= gv[4 + j]; }
;                     } else {
;                         float o[8];
; #pragma unroll
;                         for (int j = 0; j < 4; ++j) { o[j] = acc[ai][bj][m][0][j] * gv[j]; o[4 + j] = acc[ai][bj][m][1][j] * gv[4 + j]; }
;                         u32x4 w; w.x = pk2(o[0], o[1]); w.y = pk2(o[2], o[3]); w.z = pk2(o[4], o[5]); w.w = pk2(o[6], o[7]);
;                         *(u32x4*)((char*)O + xb_piece(u.pm, u.pn, wr, wc, ai, m, bj) + xlo) = w;
.LBB0_2124:
	s_waitcnt vmcnt(11)
	v_lshlrev_b32_e32 v184, 16, v178
	v_and_b32_e32 v185, 0xffff0000, v178
	v_lshlrev_b32_e32 v182, 16, v179
	v_and_b32_e32 v183, 0xffff0000, v179
	v_lshlrev_b32_e32 v178, 16, v180
	v_and_b32_e32 v179, 0xffff0000, v180
	v_lshlrev_b32_e32 v4, 16, v181
	v_and_b32_e32 v5, 0xffff0000, v181
	s_and_b64 vcc, exec, s[6:7]
	s_mov_b64 s[48:49], -1
	s_cbranch_vccnz .LBB0_2126
	s_lshl_b32 s41, s36, 4
	s_lshl_b32 s43, s38, 2
	s_add_i32 s41, s41, s43
	s_or_b32 s48, s41, s61
	s_ashr_i32 s49, s48, 31
	v_pk_mul_f32 v[180:181], v[114:115], v[184:185]
	v_pk_mul_f32 v[188:189], v[110:111], v[178:179]
	v_pk_mul_f32 v[190:191], v[116:117], v[182:183]
	v_pk_mul_f32 v[192:193], v[112:113], v[4:5]
	s_lshl_b64 s[48:49], s[48:49], 15
	v_cvt_pk_bf16_f32 v186, v180, v181
	v_cvt_pk_bf16_f32 v187, v190, v191
	v_cvt_pk_bf16_f32 v188, v188, v189
	v_cvt_pk_bf16_f32 v189, v192, v193
	v_lshl_add_u64 v[180:181], v[206:207], 0, s[48:49]
	s_mov_b64 s[48:49], 0
	global_store_dwordx4 v[180:181], v[186:189], off nt

; __device__ __forceinline__ unsigned pk2(float lo, float hi) { f32x2_t v = {lo, hi}; bf16x2_t b = __builtin_convertvector(v, bf16x2_t); return __builtin_bit_cast(unsigned, b); }
; __device__ __forceinline__ float bflo(unsigned w) { return __uint_as_float(w << 16); }
; __device__ __forceinline__ float bfhi(unsigned w) { return __uint_as_float(w & 0xffff0000u); }
;     __device__ __forceinline__ void operator()(Acc& acc, const Unit& u, int wr, int wc, int fr, int fq) const {
;     ...
;                     const u32x4 s = gq[ai][m][bj];
;                     const float gv[8] = {bflo(s.x), bfhi(s.x), bflo(s.y), bfhi(s.y), bflo(s.z), bfhi(s.z), bflo(s.w), bfhi(s.w)};
;                     if (u.sub == 0) {
; #pragma unroll
;                         for (int j = 0; j < 4; ++j) { acc[ai][bj][m][0][j] *= gv[j]; acc[ai][bj][m][1][j] *= gv[4 + j]; }
;                     } else {
;                         float o[8];
; #pragma unroll
;                         for (int j = 0; j < 4; ++j) { o[j] = acc[ai][bj][m][0][j] * gv[j]; o[4 + j] = acc[ai][bj][m][1][j] * gv[4 + j]; }
;                         u32x4 w; w.x = pk2(o[0], o[1]); w.y = pk2(o[2], o[3]); w.z = pk2(o[4], o[5]); w.w = pk2(o[6], o[7]);
;                         *(u32x4*)((char*)O + xb_piece(u.pm, u.pn, wr, wc, ai, m, bj) + xlo) = w;
.LBB0_2128:
	s_waitcnt vmcnt(9)
	v_lshlrev_b32_e32 v180, 16, v174
	v_and_b32_e32 v181, 0xffff0000, v174
	v_lshlrev_b32_e32 v178, 16, v175
	v_and_b32_e32 v179, 0xffff0000, v175
	v_lshlrev_b32_e32 v174, 16, v176
	v_and_b32_e32 v175, 0xffff0000, v176
	v_lshlrev_b32_e32 v4, 16, v177
	v_and_b32_e32 v5, 0xffff0000, v177
	s_and_b64 vcc, exec, s[6:7]
	s_mov_b64 s[48:49], -1
	s_cbranch_vccnz .LBB0_2130
	s_lshl_b32 s41, s36, 4
	s_lshl_b32 s43, s38, 2
	s_add_i32 s41, s41, s43
	s_or_b32 s48, s41, s62
	s_ashr_i32 s49, s48, 31
	v_pk_mul_f32 v[176:177], v[82:83], v[180:181]
	v_pk_mul_f32 v[184:185], v[78:79], v[174:175]
	v_pk_mul_f32 v[186:187], v[84:85], v[178:179]
	v_pk_mul_f32 v[188:189], v[80:81], v[4:5]
	s_lshl_b64 s[48:49], s[48:49], 15
	v_cvt_pk_bf16_f32 v182, v176, v177
	v_cvt_pk_bf16_f32 v183, v186, v187
	v_cvt_pk_bf16_f32 v184, v184, v185
	v_cvt_pk_bf16_f32 v185, v188, v189
	v_lshl_add_u64 v[176:177], v[206:207], 0, s[48:49]
	s_mov_b64 s[48:49], 0
	global_store_dwordx4 v[176:177], v[182:185], off nt

; __device__ __forceinline__ unsigned pk2(float lo, float hi) { f32x2_t v = {lo, hi}; bf16x2_t b = __builtin_convertvector(v, bf16x2_t); return __builtin_bit_cast(unsigned, b); }
; __device__ __forceinline__ float bflo(unsigned w) { return __uint_as_float(w << 16); }
; __device__ __forceinline__ float bfhi(unsigned w) { return __uint_as_float(w & 0xffff0000u); }
;     __device__ __forceinline__ void operator()(Acc& acc, const Unit& u, int wr, int wc, int fr, int fq) const {
;     ...
;                     const u32x4 s = gq[ai][m][bj];
;                     const float gv[8] = {bflo(s.x), bfhi(s.x), bflo(s.y), bfhi(s.y), bflo(s.z), bfhi(s.z), bflo(s.w), bfhi(s.w)};
;                     if (u.sub == 0) {
; #pragma unroll
;                         for (int j = 0; j < 4; ++j) { acc[ai][bj][m][0][j] *= gv[j]; acc[ai][bj][m][1][j] *= gv[4 + j]; }
;                     } else {
;                         float o[8];
; #pragma unroll
;                         for (int j = 0; j < 4; ++j) { o[j] = acc[ai][bj][m][0][j] * gv[j]; o[4 + j] = acc[ai][bj][m][1][j] * gv[4 + j]; }
;                         u32x4 w; w.x = pk2(o[0], o[1]); w.y = pk2(o[2], o[3]); w.z = pk2(o[4], o[5]); w.w = pk2(o[6], o[7]);
;                         *(u32x4*)((char*)O + xb_piece(u.pm, u.pn, wr, wc, ai, m, bj) + xlo) = w;
.LBB0_2132:
	v_lshlrev_b32_e32 v176, 16, v170
	v_and_b32_e32 v177, 0xffff0000, v170
	v_lshlrev_b32_e32 v174, 16, v171
	v_and_b32_e32 v175, 0xffff0000, v171
	v_lshlrev_b32_e32 v170, 16, v172
	v_and_b32_e32 v171, 0xffff0000, v172
	v_lshlrev_b32_e32 v4, 16, v173
	v_and_b32_e32 v5, 0xffff0000, v173
	s_and_b64 vcc, exec, s[6:7]
	s_mov_b64 s[48:49], -1
	s_cbranch_vccnz .LBB0_2134
	s_lshl_b32 s41, s36, 4
	s_lshl_b32 s43, s38, 2
	s_add_i32 s41, s41, s43
	s_or_b32 s48, s41, s61
	s_ashr_i32 s49, s48, 31
	v_pk_mul_f32 v[172:173], v[106:107], v[176:177]
	v_pk_mul_f32 v[180:181], v[102:103], v[170:171]
	v_pk_mul_f32 v[182:183], v[108:109], v[174:175]
	v_pk_mul_f32 v[184:185], v[104:105], v[4:5]
	s_lshl_b64 s[48:49], s[48:49], 15
	v_cvt_pk_bf16_f32 v178, v172, v173
	v_cvt_pk_bf16_f32 v179, v182, v183
	v_cvt_pk_bf16_f32 v180, v180, v181
	v_cvt_pk_bf16_f32 v181, v184, v185
	v_lshl_add_u64 v[172:173], v[208:209], 0, s[48:49]
	s_mov_b64 s[48:49], 0
	global_store_dwordx4 v[172:173], v[178:181], off nt

; __device__ __forceinline__ unsigned pk2(float lo, float hi) { f32x2_t v = {lo, hi}; bf16x2_t b = __builtin_convertvector(v, bf16x2_t); return __builtin_bit_cast(unsigned, b); }
; __device__ __forceinline__ float bflo(unsigned w) { return __uint_as_float(w << 16); }
; __device__ __forceinline__ float bfhi(unsigned w) { return __uint_as_float(w & 0xffff0000u); }
;     __device__ __forceinline__ void operator()(Acc& acc, const Unit& u, int wr, int wc, int fr, int fq) const {
;     ...
;                     const u32x4 s = gq[ai][m][bj];
;                     const float gv[8] = {bflo(s.x), bfhi(s.x), bflo(s.y), bfhi(s.y), bflo(s.z), bfhi(s.z), bflo(s.w), bfhi(s.w)};
;                     if (u.sub == 0) {
; #pragma unroll
;                         for (int j = 0; j < 4; ++j) { acc[ai][bj][m][0][j] *= gv[j]; acc[ai][bj][m][1][j] *= gv[4 + j]; }
;                     } else {
;                         float o[8];
; #pragma unroll
;                         for (int j = 0; j < 4; ++j) { o[j] = acc[ai][bj][m][0][j] * gv[j]; o[4 + j] = acc[ai][bj][m][1][j] * gv[4 + j]; }
;                         u32x4 w; w.x = pk2(o[0], o[1]); w.y = pk2(o[2], o[3]); w.z = pk2(o[4], o[5]); w.w = pk2(o[6], o[7]);
;                         *(u32x4*)((char*)O + xb_piece(u.pm, u.pn, wr, wc, ai, m, bj) + xlo) = w;
.LBB0_2136:
	s_waitcnt vmcnt(8)
	v_lshlrev_b32_e32 v172, 16, v166
	v_and_b32_e32 v173, 0xffff0000, v166
	v_lshlrev_b32_e32 v170, 16, v167
	v_and_b32_e32 v171, 0xffff0000, v167
	v_lshlrev_b32_e32 v166, 16, v168
	v_and_b32_e32 v167, 0xffff0000, v168
	v_lshlrev_b32_e32 v4, 16, v169
	v_and_b32_e32 v5, 0xffff0000, v169
	s_and_b64 vcc, exec, s[6:7]
	s_mov_b64 s[48:49], -1
	s_cbranch_vccnz .LBB0_2138
	s_lshl_b32 s41, s36, 4
	s_lshl_b32 s43, s38, 2
	s_add_i32 s41, s41, s43
	s_or_b32 s48, s41, s62
	s_ashr_i32 s49, s48, 31
	v_pk_mul_f32 v[168:169], v[74:75], v[172:173]
	v_pk_mul_f32 v[176:177], v[70:71], v[166:167]
	v_pk_mul_f32 v[178:179], v[76:77], v[170:171]
	v_pk_mul_f32 v[180:181], v[72:73], v[4:5]
	s_lshl_b64 s[48:49], s[48:49], 15
	v_cvt_pk_bf16_f32 v174, v168, v169
	v_cvt_pk_bf16_f32 v175, v178, v179
	v_cvt_pk_bf16_f32 v176, v176, v177
	v_cvt_pk_bf16_f32 v177, v180, v181
	v_lshl_add_u64 v[168:169], v[208:209], 0, s[48:49]
	s_mov_b64 s[48:49], 0
	global_store_dwordx4 v[168:169], v[174:177], off nt

; __device__ __forceinline__ unsigned pk2(float lo, float hi) { f32x2_t v = {lo, hi}; bf16x2_t b = __builtin_convertvector(v, bf16x2_t); return __builtin_bit_cast(unsigned, b); }
; __device__ __forceinline__ float bflo(unsigned w) { return __uint_as_float(w << 16); }
; __device__ __forceinline__ float bfhi(unsigned w) { return __uint_as_float(w & 0xffff0000u); }
;     __device__ __forceinline__ void operator()(Acc& acc, const Unit& u, int wr, int wc, int fr, int fq) const {
;     ...
;                     const u32x4 s = gq[ai][m][bj];
;                     const float gv[8] = {bflo(s.x), bfhi(s.x), bflo(s.y), bfhi(s.y), bflo(s.z), bfhi(s.z), bflo(s.w), bfhi(s.w)};
;                     if (u.sub == 0) {
; #pragma unroll
;                         for (int j = 0; j < 4; ++j) { acc[ai][bj][m][0][j] *= gv[j]; acc[ai][bj][m][1][j] *= gv[4 + j]; }
;                     } else {
;                         float o[8];
; #pragma unroll
;                         for (int j = 0; j < 4; ++j) { o[j] = acc[ai][bj][m][0][j] * gv[j]; o[4 + j] = acc[ai][bj][m][1][j] * gv[4 + j]; }
;                         u32x4 w; w.x = pk2(o[0], o[1]); w.y = pk2(o[2], o[3]); w.z = pk2(o[4], o[5]); w.w = pk2(o[6], o[7]);
;                         *(u32x4*)((char*)O + xb_piece(u.pm, u.pn, wr, wc, ai, m, bj) + xlo) = w;
.LBB0_2140:
	s_waitcnt vmcnt(7)
	v_lshlrev_b32_e32 v168, 16, v162
	v_and_b32_e32 v169, 0xffff0000, v162
	v_lshlrev_b32_e32 v166, 16, v163
	v_and_b32_e32 v167, 0xffff0000, v163
	v_lshlrev_b32_e32 v162, 16, v164
	v_and_b32_e32 v163, 0xffff0000, v164
	v_lshlrev_b32_e32 v4, 16, v165
	v_and_b32_e32 v5, 0xffff0000, v165
	s_and_b64 vcc, exec, s[6:7]
	s_mov_b64 s[48:49], -1
	s_cbranch_vccnz .LBB0_2142
	s_lshl_b32 s41, s36, 4
	s_lshl_b32 s43, s38, 2
	s_add_i32 s41, s41, s43
	s_or_b32 s48, s41, s61
	s_ashr_i32 s49, s48, 31
	v_pk_mul_f32 v[164:165], v[66:67], v[168:169]
	v_pk_mul_f32 v[172:173], v[62:63], v[162:163]
	v_pk_mul_f32 v[174:175], v[68:69], v[166:167]
	v_pk_mul_f32 v[176:177], v[64:65], v[4:5]
	s_lshl_b64 s[48:49], s[48:49], 15
	v_cvt_pk_bf16_f32 v170, v164, v165
	v_cvt_pk_bf16_f32 v171, v174, v175
	v_cvt_pk_bf16_f32 v172, v172, v173
	v_cvt_pk_bf16_f32 v173, v176, v177
	v_lshl_add_u64 v[164:165], v[210:211], 0, s[48:49]
	s_mov_b64 s[48:49], 0
	global_store_dwordx4 v[164:165], v[170:173], off nt

; __device__ __forceinline__ unsigned pk2(float lo, float hi) { f32x2_t v = {lo, hi}; bf16x2_t b = __builtin_convertvector(v, bf16x2_t); return __builtin_bit_cast(unsigned, b); }
; __device__ __forceinline__ float bflo(unsigned w) { return __uint_as_float(w << 16); }
; __device__ __forceinline__ float bfhi(unsigned w) { return __uint_as_float(w & 0xffff0000u); }
;     __device__ __forceinline__ void operator()(Acc& acc, const Unit& u, int wr, int wc, int fr, int fq) const {
;     ...
;                     const u32x4 s = gq[ai][m][bj];
;                     const float gv[8] = {bflo(s.x), bfhi(s.x), bflo(s.y), bfhi(s.y), bflo(s.z), bfhi(s.z), bflo(s.w), bfhi(s.w)};
;                     if (u.sub == 0) {
; #pragma unroll
;                         for (int j = 0; j < 4; ++j) { acc[ai][bj][m][0][j] *= gv[j]; acc[ai][bj][m][1][j] *= gv[4 + j]; }
;                     } else {
;                         float o[8];
; #pragma unroll
;                         for (int j = 0; j < 4; ++j) { o[j] = acc[ai][bj][m][0][j] * gv[j]; o[4 + j] = acc[ai][bj][m][1][j] * gv[4 + j]; }
;                         u32x4 w; w.x = pk2(o[0], o[1]); w.y = pk2(o[2], o[3]); w.z = pk2(o[4], o[5]); w.w = pk2(o[6], o[7]);
;                         *(u32x4*)((char*)O + xb_piece(u.pm, u.pn, wr, wc, ai, m, bj) + xlo) = w;
.LBB0_2144:
	s_waitcnt vmcnt(6)
	v_lshlrev_b32_e32 v164, 16, v158
	v_and_b32_e32 v165, 0xffff0000, v158
	v_lshlrev_b32_e32 v162, 16, v159
	v_and_b32_e32 v163, 0xffff0000, v159
	v_lshlrev_b32_e32 v158, 16, v160
	v_and_b32_e32 v159, 0xffff0000, v160
	v_lshlrev_b32_e32 v4, 16, v161
	v_and_b32_e32 v5, 0xffff0000, v161
	s_and_b64 vcc, exec, s[6:7]
	s_mov_b64 s[48:49], -1
	s_cbranch_vccnz .LBB0_2146
	s_lshl_b32 s41, s36, 4
	s_lshl_b32 s43, s38, 2
	s_add_i32 s41, s41, s43
	s_or_b32 s48, s41, s62
	s_ashr_i32 s49, s48, 31
	v_pk_mul_f32 v[160:161], v[34:35], v[164:165]
	v_pk_mul_f32 v[168:169], v[30:31], v[158:159]
	v_pk_mul_f32 v[170:171], v[36:37], v[162:163]
	v_pk_mul_f32 v[172:173], v[32:33], v[4:5]
	s_lshl_b64 s[48:49], s[48:49], 15
	v_cvt_pk_bf16_f32 v166, v160, v161
	v_cvt_pk_bf16_f32 v167, v170, v171
	v_cvt_pk_bf16_f32 v168, v168, v169
	v_cvt_pk_bf16_f32 v169, v172, v173
	v_lshl_add_u64 v[160:161], v[210:211], 0, s[48:49]
	s_mov_b64 s[48:49], 0
	global_store_dwordx4 v[160:161], v[166:169], off nt

; __device__ __forceinline__ unsigned pk2(float lo, float hi) { f32x2_t v = {lo, hi}; bf16x2_t b = __builtin_convertvector(v, bf16x2_t); return __builtin_bit_cast(unsigned, b); }
; __device__ __forceinline__ float bflo(unsigned w) { return __uint_as_float(w << 16); }
; __device__ __forceinline__ float bfhi(unsigned w) { return __uint_as_float(w & 0xffff0000u); }
;     __device__ __forceinline__ void operator()(Acc& acc, const Unit& u, int wr, int wc, int fr, int fq) const {
;     ...
;                     const u32x4 s = gq[ai][m][bj];
;                     const float gv[8] = {bflo(s.x), bfhi(s.x), bflo(s.y), bfhi(s.y), bflo(s.z), bfhi(s.z), bflo(s.w), bfhi(s.w)};
;                     if (u.sub == 0) {
; #pragma unroll
;                         for (int j = 0; j < 4; ++j) { acc[ai][bj][m][0][j] *= gv[j]; acc[ai][bj][m][1][j] *= gv[4 + j]; }
;                     } else {
;                         float o[8];
; #pragma unroll
;                         for (int j = 0; j < 4; ++j) { o[j] = acc[ai][bj][m][0][j] * gv[j]; o[4 + j] = acc[ai][bj][m][1][j] * gv[4 + j]; }
;                         u32x4 w; w.x = pk2(o[0], o[1]); w.y = pk2(o[2], o[3]); w.z = pk2(o[4], o[5]); w.w = pk2(o[6], o[7]);
;                         *(u32x4*)((char*)O + xb_piece(u.pm, u.pn, wr, wc, ai, m, bj) + xlo) = w;
.LBB0_2148:
	s_waitcnt vmcnt(5)
	v_lshlrev_b32_e32 v160, 16, v154
	v_and_b32_e32 v161, 0xffff0000, v154
	v_lshlrev_b32_e32 v158, 16, v155
	v_and_b32_e32 v159, 0xffff0000, v155
	v_lshlrev_b32_e32 v154, 16, v156
	v_and_b32_e32 v155, 0xffff0000, v156
	v_lshlrev_b32_e32 v4, 16, v157
	v_and_b32_e32 v5, 0xffff0000, v157
	s_and_b64 vcc, exec, s[6:7]
	s_mov_b64 s[48:49], -1
	s_cbranch_vccnz .LBB0_2150
	s_lshl_b32 s41, s36, 4
	s_lshl_b32 s43, s38, 2
	s_add_i32 s41, s41, s43
	s_or_b32 s48, s41, s61
	s_ashr_i32 s49, s48, 31
	v_pk_mul_f32 v[156:157], v[58:59], v[160:161]
	v_pk_mul_f32 v[164:165], v[54:55], v[154:155]
	v_pk_mul_f32 v[166:167], v[60:61], v[158:159]
	v_pk_mul_f32 v[168:169], v[56:57], v[4:5]
	s_lshl_b64 s[48:49], s[48:49], 15
	v_cvt_pk_bf16_f32 v162, v156, v157
	v_cvt_pk_bf16_f32 v163, v166, v167
	v_cvt_pk_bf16_f32 v164, v164, v165
	v_cvt_pk_bf16_f32 v165, v168, v169
	v_lshl_add_u64 v[156:157], v[212:213], 0, s[48:49]
	s_mov_b64 s[48:49], 0
	global_store_dwordx4 v[156:157], v[162:165], off nt

; __device__ __forceinline__ unsigned pk2(float lo, float hi) { f32x2_t v = {lo, hi}; bf16x2_t b = __builtin_convertvector(v, bf16x2_t); return __builtin_bit_cast(unsigned, b); }
; __device__ __forceinline__ float bflo(unsigned w) { return __uint_as_float(w << 16); }
; __device__ __forceinline__ float bfhi(unsigned w) { return __uint_as_float(w & 0xffff0000u); }
;     __device__ __forceinline__ void operator()(Acc& acc, const Unit& u, int wr, int wc, int fr, int fq) const {
;     ...
;                     const u32x4 s = gq[ai][m][bj];
;                     const float gv[8] = {bflo(s.x), bfhi(s.x), bflo(s.y), bfhi(s.y), bflo(s.z), bfhi(s.z), bflo(s.w), bfhi(s.w)};
;                     if (u.sub == 0) {
; #pragma unroll
;                         for (int j = 0; j < 4; ++j) { acc[ai][bj][m][0][j] *= gv[j]; acc[ai][bj][m][1][j] *= gv[4 + j]; }
;                     } else {
;                         float o[8];
; #pragma unroll
;                         for (int j = 0; j < 4; ++j) { o[j] = acc[ai][bj][m][0][j] * gv[j]; o[4 + j] = acc[ai][bj][m][1][j] * gv[4 + j]; }
;                         u32x4 w; w.x = pk2(o[0], o[1]); w.y = pk2(o[2], o[3]); w.z = pk2(o[4], o[5]); w.w = pk2(o[6], o[7]);
;                         *(u32x4*)((char*)O + xb_piece(u.pm, u.pn, wr, wc, ai, m, bj) + xlo) = w;
.LBB0_2152:
	s_waitcnt vmcnt(4)
	v_lshlrev_b32_e32 v156, 16, v150
	v_and_b32_e32 v157, 0xffff0000, v150
	v_lshlrev_b32_e32 v154, 16, v151
	v_and_b32_e32 v155, 0xffff0000, v151
	v_lshlrev_b32_e32 v150, 16, v152
	v_and_b32_e32 v151, 0xffff0000, v152
	v_lshlrev_b32_e32 v4, 16, v153
	v_and_b32_e32 v5, 0xffff0000, v153
	s_and_b64 vcc, exec, s[6:7]
	s_mov_b64 s[48:49], -1
	s_cbranch_vccnz .LBB0_2154
	s_lshl_b32 s41, s36, 4
	s_lshl_b32 s43, s38, 2
	s_add_i32 s41, s41, s43
	s_or_b32 s48, s41, s62
	s_ashr_i32 s49, s48, 31
	v_pk_mul_f32 v[152:153], v[26:27], v[156:157]
	v_pk_mul_f32 v[160:161], v[22:23], v[150:151]
	v_pk_mul_f32 v[162:163], v[28:29], v[154:155]
	v_pk_mul_f32 v[164:165], v[24:25], v[4:5]
	s_lshl_b64 s[48:49], s[48:49], 15
	v_cvt_pk_bf16_f32 v158, v152, v153
	v_cvt_pk_bf16_f32 v159, v162, v163
	v_cvt_pk_bf16_f32 v160, v160, v161
	v_cvt_pk_bf16_f32 v161, v164, v165
	v_lshl_add_u64 v[152:153], v[212:213], 0, s[48:49]
	s_mov_b64 s[48:49], 0
	global_store_dwordx4 v[152:153], v[158:161], off nt

; __device__ __forceinline__ unsigned pk2(float lo, float hi) { f32x2_t v = {lo, hi}; bf16x2_t b = __builtin_convertvector(v, bf16x2_t); return __builtin_bit_cast(unsigned, b); }
; __device__ __forceinline__ float bflo(unsigned w) { return __uint_as_float(w << 16); }
; __device__ __forceinline__ float bfhi(unsigned w) { return __uint_as_float(w & 0xffff0000u); }
;     __device__ __forceinline__ void operator()(Acc& acc, const Unit& u, int wr, int wc, int fr, int fq) const {
;     ...
;                     const u32x4 s = gq[ai][m][bj];
;                     const float gv[8] = {bflo(s.x), bfhi(s.x), bflo(s.y), bfhi(s.y), bflo(s.z), bfhi(s.z), bflo(s.w), bfhi(s.w)};
;                     if (u.sub == 0) {
; #pragma unroll
;                         for (int j = 0; j < 4; ++j) { acc[ai][bj][m][0][j] *= gv[j]; acc[ai][bj][m][1][j] *= gv[4 + j]; }
;                     } else {
;                         float o[8];
; #pragma unroll
;                         for (int j = 0; j < 4; ++j) { o[j] = acc[ai][bj][m][0][j] * gv[j]; o[4 + j] = acc[ai][bj][m][1][j] * gv[4 + j]; }
;                         u32x4 w; w.x = pk2(o[0], o[1]); w.y = pk2(o[2], o[3]); w.z = pk2(o[4], o[5]); w.w = pk2(o[6], o[7]);
;                         *(u32x4*)((char*)O + xb_piece(u.pm, u.pn, wr, wc, ai, m, bj) + xlo) = w;
.LBB0_2156:
	s_waitcnt vmcnt(3)
	v_lshlrev_b32_e32 v152, 16, v146
	v_and_b32_e32 v153, 0xffff0000, v146
	v_lshlrev_b32_e32 v150, 16, v147
	v_and_b32_e32 v151, 0xffff0000, v147
	v_lshlrev_b32_e32 v146, 16, v148
	v_and_b32_e32 v147, 0xffff0000, v148
	v_lshlrev_b32_e32 v4, 16, v149
	v_and_b32_e32 v5, 0xffff0000, v149
	s_and_b64 vcc, exec, s[6:7]
	s_mov_b64 s[48:49], -1
	s_cbranch_vccnz .LBB0_2158
	s_lshl_b32 s41, s36, 4
	s_lshl_b32 s43, s38, 2
	s_add_i32 s41, s41, s43
	s_or_b32 s48, s41, s61
	s_ashr_i32 s49, s48, 31
	v_pk_mul_f32 v[148:149], v[50:51], v[152:153]
	v_pk_mul_f32 v[156:157], v[46:47], v[146:147]
	v_pk_mul_f32 v[158:159], v[52:53], v[150:151]
	v_pk_mul_f32 v[160:161], v[48:49], v[4:5]
	s_lshl_b64 s[48:49], s[48:49], 15
	v_cvt_pk_bf16_f32 v154, v148, v149
	v_cvt_pk_bf16_f32 v155, v158, v159
	v_cvt_pk_bf16_f32 v156, v156, v157
	v_cvt_pk_bf16_f32 v157, v160, v161
	v_lshl_add_u64 v[148:149], v[214:215], 0, s[48:49]
	s_mov_b64 s[48:49], 0
	global_store_dwordx4 v[148:149], v[154:157], off nt

; __device__ __forceinline__ unsigned pk2(float lo, float hi) { f32x2_t v = {lo, hi}; bf16x2_t b = __builtin_convertvector(v, bf16x2_t); return __builtin_bit_cast(unsigned, b); }
; __device__ __forceinline__ float bflo(unsigned w) { return __uint_as_float(w << 16); }
; __device__ __forceinline__ float bfhi(unsigned w) { return __uint_as_float(w & 0xffff0000u); }
;     __device__ __forceinline__ void operator()(Acc& acc, const Unit& u, int wr, int wc, int fr, int fq) const {
;     ...
;                     const u32x4 s = gq[ai][m][bj];
;                     const float gv[8] = {bflo(s.x), bfhi(s.x), bflo(s.y), bfhi(s.y), bflo(s.z), bfhi(s.z), bflo(s.w), bfhi(s.w)};
;                     if (u.sub == 0) {
; #pragma unroll
;                         for (int j = 0; j < 4; ++j) { acc[ai][bj][m][0][j] *= gv[j]; acc[ai][bj][m][1][j] *= gv[4 + j]; }
;                     } else {
;                         float o[8];
; #pragma unroll
;                         for (int j = 0; j < 4; ++j) { o[j] = acc[ai][bj][m][0][j] * gv[j]; o[4 + j] = acc[ai][bj][m][1][j] * gv[4 + j]; }
;                         u32x4 w; w.x = pk2(o[0], o[1]); w.y = pk2(o[2], o[3]); w.z = pk2(o[4], o[5]); w.w = pk2(o[6], o[7]);
;                         *(u32x4*)((char*)O + xb_piece(u.pm, u.pn, wr, wc, ai, m, bj) + xlo) = w;
.LBB0_2160:
	s_waitcnt vmcnt(2)
	v_lshlrev_b32_e32 v148, 16, v142
	v_and_b32_e32 v149, 0xffff0000, v142
	v_lshlrev_b32_e32 v146, 16, v143
	v_and_b32_e32 v147, 0xffff0000, v143
	v_lshlrev_b32_e32 v142, 16, v144
	v_and_b32_e32 v143, 0xffff0000, v144
	v_lshlrev_b32_e32 v4, 16, v145
	v_and_b32_e32 v5, 0xffff0000, v145
	s_and_b64 vcc, exec, s[6:7]
	s_mov_b64 s[48:49], -1
	s_cbranch_vccnz .LBB0_2162
	s_lshl_b32 s41, s36, 4
	s_lshl_b32 s43, s38, 2
	s_add_i32 s41, s41, s43
	s_or_b32 s48, s41, s62
	s_ashr_i32 s49, s48, 31
	v_pk_mul_f32 v[144:145], v[18:19], v[148:149]
	v_pk_mul_f32 v[152:153], v[14:15], v[142:143]
	v_pk_mul_f32 v[154:155], v[20:21], v[146:147]
	v_pk_mul_f32 v[156:157], v[16:17], v[4:5]
	s_lshl_b64 s[48:49], s[48:49], 15
	v_cvt_pk_bf16_f32 v150, v144, v145
	v_cvt_pk_bf16_f32 v151, v154, v155
	v_cvt_pk_bf16_f32 v152, v152, v153
	v_cvt_pk_bf16_f32 v153, v156, v157
	v_lshl_add_u64 v[144:145], v[214:215], 0, s[48:49]
	s_mov_b64 s[48:49], 0
	global_store_dwordx4 v[144:145], v[150:153], off nt

; __device__ __forceinline__ unsigned pk2(float lo, float hi) { f32x2_t v = {lo, hi}; bf16x2_t b = __builtin_convertvector(v, bf16x2_t); return __builtin_bit_cast(unsigned, b); }
; __device__ __forceinline__ float bflo(unsigned w) { return __uint_as_float(w << 16); }
; __device__ __forceinline__ float bfhi(unsigned w) { return __uint_as_float(w & 0xffff0000u); }
;     __device__ __forceinline__ void operator()(Acc& acc, const Unit& u, int wr, int wc, int fr, int fq) const {
;     ...
;                     const u32x4 s = gq[ai][m][bj];
;                     const float gv[8] = {bflo(s.x), bfhi(s.x), bflo(s.y), bfhi(s.y), bflo(s.z), bfhi(s.z), bflo(s.w), bfhi(s.w)};
;                     if (u.sub == 0) {
; #pragma unroll
;                         for (int j = 0; j < 4; ++j) { acc[ai][bj][m][0][j] *= gv[j]; acc[ai][bj][m][1][j] *= gv[4 + j]; }
;                     } else {
;                         float o[8];
; #pragma unroll
;                         for (int j = 0; j < 4; ++j) { o[j] = acc[ai][bj][m][0][j] * gv[j]; o[4 + j] = acc[ai][bj][m][1][j] * gv[4 + j]; }
;                         u32x4 w; w.x = pk2(o[0], o[1]); w.y = pk2(o[2], o[3]); w.z = pk2(o[4], o[5]); w.w = pk2(o[6], o[7]);
;                         *(u32x4*)((char*)O + xb_piece(u.pm, u.pn, wr, wc, ai, m, bj) + xlo) = w;
.LBB0_2164:
	s_waitcnt vmcnt(1)
	v_lshlrev_b32_e32 v144, 16, v138
	v_and_b32_e32 v145, 0xffff0000, v138
	v_lshlrev_b32_e32 v142, 16, v139
	v_and_b32_e32 v143, 0xffff0000, v139
	v_lshlrev_b32_e32 v138, 16, v140
	v_and_b32_e32 v139, 0xffff0000, v140
	v_lshlrev_b32_e32 v4, 16, v141
	v_and_b32_e32 v5, 0xffff0000, v141
	s_and_b64 vcc, exec, s[6:7]
	s_mov_b64 s[48:49], -1
	s_cbranch_vccnz .LBB0_2166
	s_lshl_b32 s41, s36, 4
	s_lshl_b32 s43, s38, 2
	s_add_i32 s41, s41, s43
	s_or_b32 s48, s41, s61
	s_ashr_i32 s49, s48, 31
	v_pk_mul_f32 v[140:141], v[42:43], v[144:145]
	v_pk_mul_f32 v[148:149], v[38:39], v[138:139]
	v_pk_mul_f32 v[150:151], v[44:45], v[142:143]
	v_pk_mul_f32 v[152:153], v[40:41], v[4:5]
	s_lshl_b64 s[48:49], s[48:49], 15
	v_cvt_pk_bf16_f32 v146, v140, v141
	v_cvt_pk_bf16_f32 v147, v150, v151
	v_cvt_pk_bf16_f32 v148, v148, v149
	v_cvt_pk_bf16_f32 v149, v152, v153
	v_lshl_add_u64 v[140:141], v[216:217], 0, s[48:49]
	s_mov_b64 s[48:49], 0
	global_store_dwordx4 v[140:141], v[146:149], off nt

; __device__ __forceinline__ unsigned pk2(float lo, float hi) { f32x2_t v = {lo, hi}; bf16x2_t b = __builtin_convertvector(v, bf16x2_t); return __builtin_bit_cast(unsigned, b); }
; __device__ __forceinline__ float bflo(unsigned w) { return __uint_as_float(w << 16); }
; __device__ __forceinline__ float bfhi(unsigned w) { return __uint_as_float(w & 0xffff0000u); }
;     __device__ __forceinline__ void operator()(Acc& acc, const Unit& u, int wr, int wc, int fr, int fq) const {
;     ...
;                     const u32x4 s = gq[ai][m][bj];
;                     const float gv[8] = {bflo(s.x), bfhi(s.x), bflo(s.y), bfhi(s.y), bflo(s.z), bfhi(s.z), bflo(s.w), bfhi(s.w)};
;                     if (u.sub == 0) {
; #pragma unroll
;                         for (int j = 0; j < 4; ++j) { acc[ai][bj][m][0][j] *= gv[j]; acc[ai][bj][m][1][j] *= gv[4 + j]; }
;                     } else {
;                         float o[8];
; #pragma unroll
;                         for (int j = 0; j < 4; ++j) { o[j] = acc[ai][bj][m][0][j] * gv[j]; o[4 + j] = acc[ai][bj][m][1][j] * gv[4 + j]; }
;                         u32x4 w; w.x = pk2(o[0], o[1]); w.y = pk2(o[2], o[3]); w.z = pk2(o[4], o[5]); w.w = pk2(o[6], o[7]);
;                         *(u32x4*)((char*)O + xb_piece(u.pm, u.pn, wr, wc, ai, m, bj) + xlo) = w;
.LBB0_2168:
	s_waitcnt vmcnt(0)
	v_lshlrev_b32_e32 v140, 16, v134
	v_and_b32_e32 v141, 0xffff0000, v134
	v_lshlrev_b32_e32 v138, 16, v135
	v_and_b32_e32 v139, 0xffff0000, v135
	v_lshlrev_b32_e32 v134, 16, v136
	v_and_b32_e32 v135, 0xffff0000, v136
	v_lshlrev_b32_e32 v4, 16, v137
	v_and_b32_e32 v5, 0xffff0000, v137
	s_and_b64 vcc, exec, s[6:7]
	s_mov_b64 s[48:49], -1
	s_cbranch_vccnz .LBB0_2171
	s_lshl_b32 s36, s36, 4
	s_lshl_b32 s38, s38, 2
	s_add_i32 s36, s36, s38
	s_or_b32 s48, s36, s62
	s_ashr_i32 s49, s48, 31
	v_pk_mul_f32 v[136:137], v[10:11], v[140:141]
	v_pk_mul_f32 v[144:145], v[6:7], v[134:135]
	v_pk_mul_f32 v[146:147], v[12:13], v[138:139]
	v_pk_mul_f32 v[148:149], v[8:9], v[4:5]
	s_lshl_b64 s[48:49], s[48:49], 15
	v_cvt_pk_bf16_f32 v142, v136, v137
	v_cvt_pk_bf16_f32 v143, v146, v147
	v_cvt_pk_bf16_f32 v144, v144, v145
	v_cvt_pk_bf16_f32 v145, v148, v149
	v_lshl_add_u64 v[136:137], v[216:217], 0, s[48:49]
	global_store_dwordx4 v[136:137], v[142:145], off nt
	s_cbranch_execz .LBB0_2172

; __device__ __forceinline__ unsigned pk2(float lo, float hi) { f32x2_t v = {lo, hi}; bf16x2_t b = __builtin_convertvector(v, bf16x2_t); return __builtin_bit_cast(unsigned, b); }
; __device__ __forceinline__ float bflo(unsigned w) { return __uint_as_float(w << 16); }
; __device__ __forceinline__ float bfhi(unsigned w) { return __uint_as_float(w & 0xffff0000u); }
;     __device__ __forceinline__ void operator()(Acc& acc, const Unit& u, int wr, int wc, int fr, int fq) const {
;         const int col0 = u.pn * BM + wc * 32 + 8 * fq;
;         const unsigned xlo = (unsigned)lds_byte(fr, 8 * fq);
;         u32x4 rb[2][4][2];
;         if (RES_BF16) {
; #pragma unroll
;             for (int ai = 0; ai < 2; ++ai)
; #pragma unroll
;                 for (int m = 0; m < 4; ++m)
; #pragma unroll
;                     for (int bj = 0; bj < 2; ++bj) rb[ai][m][bj] = *(const u32x4*)((const char*)XBo + xb_piece(u.pm, u.pn, wr, wc, ai, m, bj) + xlo);
;         }
; #pragma unroll
;         for (int ai = 0; ai < 2; ++ai)
; #pragma unroll
;             for (int m = 0; m < 4; ++m) {
;                 const int row = u.pm * BM + ai * HALF + wr * 64 + m * 16 + fr;
;                 float ss = 0.f;
; #pragma unroll
;                 for (int bj = 0; bj < 2; ++bj) {
;                     const size_t off = (size_t)row * D + col0 + bj * HALF;
;                     f32x4 r0, r1;
;                     if (RES_BF16) { const u32x4 q = rb[ai][m][bj]; r0 = (f32x4){bflo(q.x), bfhi(q.x), bflo(q.y), bfhi(q.y)}; r1 = (f32x4){bflo(q.z), bfhi(q.z), bflo(q.w), bfhi(q.w)}; }
;                     else { r0 = *(const f32x4*)(res_f32 + off); r1 = *(const f32x4*)(res_f32 + off + 4); }
;                     const f32x4 v0 = r0 + acc[ai][bj][m][0] * alpha, v1 = r1 + acc[ai][bj][m][1] * alpha;
;                     u32x4 w; w.x = pk2(v0[0], v0[1]); w.y = pk2(v0[2], v0[3]); w.z = pk2(v1[0], v1[1]); w.w = pk2(v1[2], v1[3]);
;                     *(u32x4*)((char*)XBo + xb_piece(u.pm, u.pn, wr, wc, ai, m, bj) + xlo) = w;
;                     ss += (v0[0] * v0[0] + v0[1] * v0[1]) + (v0[2] * v0[2] + v0[3] * v0[3]) + (v1[0] * v1[0] + v1[1] * v1[1]) + (v1[2] * v1[2] + v1[3] * v1[3]);
;                 }
;                 ss += __shfl_xor(ss, 16); ss += __shfl_xor(ss, 32);
;                 if (ssqp && fq == 0) ssqp[(size_t)row * 16 + u.pn * 4 + wc] = ss;
.LBB0_2292:
	s_lshl_b32 s49, s8, 4
	s_lshl_b32 s56, s26, 2
	s_add_i32 s49, s49, s56
	s_or_b32 s58, s49, s73
	s_ashr_i32 s59, s58, 31
	s_lshl_b64 s[60:61], s[58:59], 15
	s_or_b32 s58, s58, 2
	s_ashr_i32 s59, s58, 31
	v_lshl_add_u64 v[102:103], v[194:195], 0, s[60:61]
	s_lshl_b64 s[58:59], s[58:59], 15
	global_load_dwordx4 v[238:241], v[102:103], off
	global_load_dwordx4 v[182:185], v[102:103], off offset:2048
	v_lshl_add_u64 v[104:105], v[194:195], 0, s[58:59]
	global_load_dwordx4 v[242:245], v[104:105], off
	v_lshl_add_u64 v[110:111], v[196:197], 0, s[60:61]
	v_lshl_add_u64 v[112:113], v[198:199], 0, s[60:61]
	v_lshl_add_u64 v[122:123], v[200:201], 0, s[60:61]
	v_lshl_add_u64 v[124:125], v[202:203], 0, s[60:61]
	v_lshl_add_u64 v[134:135], v[204:205], 0, s[60:61]
	v_lshl_add_u64 v[102:103], v[196:197], 0, s[58:59]
	v_lshl_add_u64 v[136:137], v[198:199], 0, s[58:59]
	v_lshl_add_u64 v[146:147], v[200:201], 0, s[58:59]
	v_lshl_add_u64 v[148:149], v[202:203], 0, s[58:59]
	v_lshl_add_u64 v[212:213], v[206:207], 0, s[60:61]
	v_lshl_add_u64 v[236:237], v[204:205], 0, s[58:59]
	v_lshl_add_u64 v[246:247], v[206:207], 0, s[58:59]
	global_load_dwordx4 v[178:181], v[104:105], off offset:2048
	global_load_dwordx4 v[174:177], v[110:111], off
	global_load_dwordx4 v[170:173], v[102:103], off
	global_load_dwordx4 v[166:169], v[112:113], off
	global_load_dwordx4 v[162:165], v[136:137], off
	global_load_dwordx4 v[158:161], v[122:123], off
	global_load_dwordx4 v[154:157], v[146:147], off
	global_load_dwordx4 v[150:153], v[124:125], off
	s_nop 0
	global_load_dwordx4 v[146:149], v[148:149], off
	s_nop 0
	global_load_dwordx4 v[134:137], v[134:135], off
	s_nop 0
	global_load_dwordx4 v[122:125], v[236:237], off
	global_load_dwordx4 v[110:113], v[212:213], off
	global_load_dwordx4 v[102:105], v[246:247], off
	v_and_b32_e32 v212, 64, v235
	v_xor_b32_e32 v248, 16, v235
	v_add_u32_e32 v212, 64, v212
	s_add_u32 s49, s14, s60
	v_xor_b32_e32 v213, 32, v235
	v_cmp_lt_i32_e32 vcc, v248, v212
	s_addc_u32 s51, s15, s61
	s_add_u32 s60, s49, s42
	v_cndmask_b32_e32 v236, v235, v248, vcc
	v_cmp_lt_i32_e32 vcc, v213, v212
	s_addc_u32 s61, s51, s43
	v_lshlrev_b32_e32 v237, 2, v236
	v_cndmask_b32_e32 v212, v235, v213, vcc
	v_lshlrev_b32_e32 v236, 2, v212
	v_lshl_add_u64 v[212:213], s[60:61], 0, v[192:193]
	s_add_u32 s60, s14, s58
	s_addc_u32 s61, s15, s59
	s_add_u32 s58, s60, s42
	s_addc_u32 s59, s61, s43
	s_waitcnt vmcnt(15)
	v_lshlrev_b32_e32 v246, 16, v238
	v_and_b32_e32 v247, 0xffff0000, v238
	v_lshlrev_b32_e32 v238, 16, v239
	v_and_b32_e32 v239, 0xffff0000, v239
	v_lshlrev_b32_e32 v248, 16, v240
	v_and_b32_e32 v249, 0xffff0000, v240
	v_lshlrev_b32_e32 v240, 16, v241
	v_and_b32_e32 v241, 0xffff0000, v241
	v_pk_add_f32 v[144:145], v[144:145], v[238:239]
	v_pk_add_f32 v[142:143], v[142:143], v[246:247]
	v_pk_add_f32 v[238:239], v[140:141], v[240:241]
	v_pk_add_f32 v[240:241], v[138:139], v[248:249]
	s_waitcnt vmcnt(13)
	v_lshlrev_b32_e32 v246, 16, v242
	v_and_b32_e32 v247, 0xffff0000, v242
	v_lshlrev_b32_e32 v242, 16, v243
	v_and_b32_e32 v243, 0xffff0000, v243
	v_cvt_pk_bf16_f32 v138, v142, v143
	v_cvt_pk_bf16_f32 v139, v144, v145
	v_cvt_pk_bf16_f32 v140, v240, v241
	v_cvt_pk_bf16_f32 v141, v238, v239
	v_pk_add_f32 v[132:133], v[132:133], v[242:243]
	v_pk_add_f32 v[242:243], v[130:131], v[246:247]
	v_lshlrev_b32_e32 v248, 16, v244
	v_and_b32_e32 v249, 0xffff0000, v244
	global_store_dwordx4 v[212:213], v[138:141], off nt
	v_cvt_pk_bf16_f32 v131, v132, v133
	v_mul_f32_e32 v133, v133, v133
	v_mul_f32_e32 v139, v243, v243
	v_pk_add_f32 v[126:127], v[126:127], v[248:249]
	v_fmac_f32_e32 v139, v242, v242
	v_fmac_f32_e32 v133, v132, v132
	v_lshlrev_b32_e32 v244, 16, v245
	v_and_b32_e32 v245, 0xffff0000, v245
	v_mul_f32_e32 v143, v143, v143
	v_mul_f32_e32 v145, v145, v145
	v_add_f32_e32 v132, v139, v133
	v_mul_f32_e32 v133, v127, v127
	v_mul_f32_e32 v241, v241, v241
	v_pk_add_f32 v[128:129], v[128:129], v[244:245]
	v_fmac_f32_e32 v143, v142, v142
	v_fmac_f32_e32 v145, v144, v144
	v_fmac_f32_e32 v133, v126, v126
	v_mul_f32_e32 v239, v239, v239
	v_fmac_f32_e32 v241, v240, v240
	v_add_f32_e32 v130, v143, v145
	v_add_f32_e32 v132, v133, v132
	v_mul_f32_e32 v133, v129, v129
	v_fmac_f32_e32 v239, v238, v238
	v_add_f32_e32 v130, v241, v130
	v_fmac_f32_e32 v133, v128, v128
	v_add_f32_e32 v138, v239, v130
	v_add_f32_e32 v132, v133, v132
	v_add_f32_e32 v138, v138, v132
	ds_bpermute_b32 v139, v237, v138
	v_cvt_pk_bf16_f32 v133, v128, v129
	v_cvt_pk_bf16_f32 v130, v242, v243
	v_cvt_pk_bf16_f32 v132, v126, v127
	v_lshl_add_u64 v[126:127], s[58:59], 0, v[192:193]
	s_waitcnt lgkmcnt(0)
	v_add_f32_e32 v128, v138, v139
	ds_bpermute_b32 v129, v236, v128
	global_store_dwordx4 v[126:127], v[130:133], off nt
	s_and_saveexec_b64 s[58:59], s[4:5]
	s_cbranch_execz .LBB0_2294
	v_lshl_add_u32 v130, s8, 8, v223
	v_ashrrev_i32_e32 v131, 31, v130
	s_waitcnt lgkmcnt(0)
	v_add_f32_e32 v132, v128, v129
	v_lshlrev_b64 v[128:129], 6, v[130:131]
	s_ashr_i32 s57, s56, 31
	v_lshl_add_u64 v[128:129], s[30:31], 0, v[128:129]
	v_lshl_add_u64 v[128:129], s[56:57], 2, v[128:129]
	s_lshl_b32 s26, s70, 2
	v_lshl_add_u64 v[128:129], v[128:129], 0, s[26:27]
	global_store_dword v[128:129], v132, off
; __device__ __forceinline__ unsigned pk2(float lo, float hi) { f32x2_t v = {lo, hi}; bf16x2_t b = __builtin_convertvector(v, bf16x2_t); return __builtin_bit_cast(unsigned, b); }
; __device__ __forceinline__ float bflo(unsigned w) { return __uint_as_float(w << 16); }
; __device__ __forceinline__ float bfhi(unsigned w) { return __uint_as_float(w & 0xffff0000u); }
;     __device__ __forceinline__ void operator()(Acc& acc, const Unit& u, int wr, int wc, int fr, int fq) const {
;     ...
;         for (int ai = 0; ai < 2; ++ai)
; #pragma unroll
;             for (int m = 0; m < 4; ++m) {
;                 const int row = u.pm * BM + ai * HALF + wr * 64 + m * 16 + fr;
;                 float ss = 0.f;
; #pragma unroll
;                 for (int bj = 0; bj < 2; ++bj) {
;                     const size_t off = (size_t)row * D + col0 + bj * HALF;
;                     f32x4 r0, r1;
;                     if (RES_BF16) { const u32x4 q = rb[ai][m][bj]; r0 = (f32x4){bflo(q.x), bfhi(q.x), bflo(q.y), bfhi(q.y)}; r1 = (f32x4){bflo(q.z), bfhi(q.z), bflo(q.w), bfhi(q.w)}; }
;                     else { r0 = *(const f32x4*)(res_f32 + off); r1 = *(const f32x4*)(res_f32 + off + 4); }
;                     const f32x4 v0 = r0 + acc[ai][bj][m][0] * alpha, v1 = r1 + acc[ai][bj][m][1] * alpha;
;                     u32x4 w; w.x = pk2(v0[0], v0[1]); w.y = pk2(v0[2], v0[3]); w.z = pk2(v1[0], v1[1]); w.w = pk2(v1[2], v1[3]);
;                     *(u32x4*)((char*)XBo + xb_piece(u.pm, u.pn, wr, wc, ai, m, bj) + xlo) = w;
;                     ss += (v0[0] * v0[0] + v0[1] * v0[1]) + (v0[2] * v0[2] + v0[3] * v0[3]) + (v1[0] * v1[0] + v1[1] * v1[1]) + (v1[2] * v1[2] + v1[3] * v1[3]);
;                 }
;                 ss += __shfl_xor(ss, 16); ss += __shfl_xor(ss, 32);
;                 if (ssqp && fq == 0) ssqp[(size_t)row * 16 + u.pn * 4 + wc] = ss;
.LBB0_2294:
	s_or_b64 exec, exec, s[58:59]
	v_lshlrev_b32_e32 v128, 16, v182
	s_waitcnt lgkmcnt(0)
	v_and_b32_e32 v129, 0xffff0000, v182
	v_lshlrev_b32_e32 v130, 16, v183
	v_and_b32_e32 v131, 0xffff0000, v183
	v_lshlrev_b32_e32 v132, 16, v184
	v_and_b32_e32 v133, 0xffff0000, v184
	v_lshlrev_b32_e32 v138, 16, v185
	v_and_b32_e32 v139, 0xffff0000, v185
	v_pk_add_f32 v[118:119], v[118:119], v[128:129]
	v_pk_add_f32 v[120:121], v[120:121], v[130:131]
	v_pk_add_f32 v[128:129], v[116:117], v[138:139]
	v_pk_add_f32 v[116:117], v[114:115], v[132:133]
	v_cvt_pk_bf16_f32 v114, v118, v119
	v_mul_f32_e32 v119, v119, v119
	v_fmac_f32_e32 v119, v118, v118
	v_mul_f32_e32 v118, v121, v121
	v_fmac_f32_e32 v118, v120, v120
	v_add_f32_e32 v118, v119, v118
	v_mul_f32_e32 v119, v117, v117
	v_fmac_f32_e32 v119, v116, v116
	v_add_f32_e32 v118, v119, v118
	v_mul_f32_e32 v119, v129, v129
	v_fmac_f32_e32 v119, v128, v128
	v_cvt_pk_bf16_f32 v115, v120, v121
	v_add_f32_e32 v138, v119, v118
	s_waitcnt vmcnt(14)
	v_lshlrev_b32_e32 v118, 16, v178
	v_and_b32_e32 v119, 0xffff0000, v178
	v_lshlrev_b32_e32 v120, 16, v179
	v_and_b32_e32 v121, 0xffff0000, v179
	v_lshlrev_b32_e32 v130, 16, v180
	v_and_b32_e32 v131, 0xffff0000, v180
	v_pk_add_f32 v[108:109], v[108:109], v[120:121]
	v_pk_add_f32 v[106:107], v[106:107], v[118:119]
	v_pk_add_f32 v[118:119], v[98:99], v[130:131]
	v_mul_f32_e32 v98, v107, v107
	v_mul_f32_e32 v99, v109, v109
	v_fmac_f32_e32 v98, v106, v106
	v_fmac_f32_e32 v99, v108, v108
	v_lshlrev_b32_e32 v132, 16, v181
	v_and_b32_e32 v133, 0xffff0000, v181
	v_add_f32_e32 v98, v98, v99
	v_mul_f32_e32 v99, v119, v119
	v_pk_add_f32 v[100:101], v[100:101], v[132:133]
	v_fmac_f32_e32 v99, v118, v118
	v_add_f32_e32 v98, v99, v98
	v_mul_f32_e32 v99, v101, v101
	v_fmac_f32_e32 v99, v100, v100
	v_add_f32_e32 v98, v99, v98
	v_add_f32_e32 v98, v138, v98
	ds_bpermute_b32 v99, v237, v98
	v_cvt_pk_bf16_f32 v116, v116, v117
	v_cvt_pk_bf16_f32 v117, v128, v129
	v_cvt_pk_bf16_f32 v106, v106, v107
	v_cvt_pk_bf16_f32 v107, v108, v109
	s_waitcnt lgkmcnt(0)
	v_add_f32_e32 v98, v98, v99
	ds_bpermute_b32 v99, v236, v98
	v_cvt_pk_bf16_f32 v108, v118, v119
	v_cvt_pk_bf16_f32 v109, v100, v101
	global_store_dwordx4 v[212:213], v[114:117], off offset:2048 nt
	global_store_dwordx4 v[126:127], v[106:109], off offset:2048 nt
	s_and_saveexec_b64 s[58:59], s[4:5]
	s_cbranch_execz .LBB0_2296
	v_lshl_add_u32 v100, s8, 8, v225
	v_ashrrev_i32_e32 v101, 31, v100
	s_waitcnt lgkmcnt(0)
	v_add_f32_e32 v106, v98, v99
	v_lshlrev_b64 v[98:99], 6, v[100:101]
	s_ashr_i32 s57, s56, 31
	v_lshl_add_u64 v[98:99], s[30:31], 0, v[98:99]
	v_lshl_add_u64 v[98:99], s[56:57], 2, v[98:99]
	s_lshl_b32 s26, s70, 2
	v_lshl_add_u64 v[98:99], v[98:99], 0, s[26:27]
	global_store_dword v[98:99], v106, off
.LBB0_2296:
	s_or_b64 exec, exec, s[58:59]
	s_waitcnt vmcnt(15)
	v_lshlrev_b32_e32 v98, 16, v174
	s_waitcnt lgkmcnt(0)
	v_and_b32_e32 v99, 0xffff0000, v174
	v_lshlrev_b32_e32 v100, 16, v175
	v_and_b32_e32 v101, 0xffff0000, v175
	v_lshlrev_b32_e32 v106, 16, v176
	v_and_b32_e32 v107, 0xffff0000, v176
	v_lshlrev_b32_e32 v108, 16, v177
	v_and_b32_e32 v109, 0xffff0000, v177
	s_add_u32 s58, s49, s46
	v_pk_add_f32 v[96:97], v[96:97], v[100:101]
	v_pk_add_f32 v[94:95], v[94:95], v[98:99]
	v_pk_add_f32 v[98:99], v[92:93], v[108:109]
	v_pk_add_f32 v[100:101], v[90:91], v[106:107]
	s_addc_u32 s59, s51, s47
	v_cvt_pk_bf16_f32 v90, v94, v95
	v_cvt_pk_bf16_f32 v91, v96, v97
	v_cvt_pk_bf16_f32 v92, v100, v101
	v_cvt_pk_bf16_f32 v93, v98, v99
	v_lshl_add_u64 v[106:107], s[58:59], 0, v[192:193]
	global_store_dwordx4 v[106:107], v[90:93], off nt
	s_add_u32 s58, s60, s46
	s_addc_u32 s59, s61, s47
	v_mul_f32_e32 v90, v95, v95
	v_mul_f32_e32 v91, v97, v97
	v_fmac_f32_e32 v90, v94, v94
	v_fmac_f32_e32 v91, v96, v96
	v_add_f32_e32 v90, v90, v91
	v_mul_f32_e32 v91, v101, v101
	v_fmac_f32_e32 v91, v100, v100
	v_add_f32_e32 v90, v91, v90
	v_mul_f32_e32 v91, v99, v99
	v_fmac_f32_e32 v91, v98, v98
	v_add_f32_e32 v98, v91, v90
	s_waitcnt vmcnt(15)
	v_lshlrev_b32_e32 v90, 16, v170
	v_and_b32_e32 v91, 0xffff0000, v170
	v_lshlrev_b32_e32 v92, 16, v171
	v_and_b32_e32 v93, 0xffff0000, v171
	v_lshlrev_b32_e32 v96, 16, v173
	v_and_b32_e32 v97, 0xffff0000, v173
	v_pk_add_f32 v[88:89], v[88:89], v[92:93]
	v_pk_add_f32 v[86:87], v[86:87], v[90:91]
	v_lshlrev_b32_e32 v94, 16, v172
	v_and_b32_e32 v95, 0xffff0000, v172
	v_pk_add_f32 v[90:91], v[84:85], v[96:97]
	v_mul_f32_e32 v84, v87, v87
	v_mul_f32_e32 v85, v89, v89
	v_pk_add_f32 v[82:83], v[82:83], v[94:95]
	v_fmac_f32_e32 v84, v86, v86
	v_fmac_f32_e32 v85, v88, v88
	v_add_f32_e32 v84, v84, v85
	v_mul_f32_e32 v85, v83, v83
	v_fmac_f32_e32 v85, v82, v82
	v_add_f32_e32 v84, v85, v84
	v_mul_f32_e32 v85, v91, v91
	v_fmac_f32_e32 v85, v90, v90
	v_add_f32_e32 v84, v85, v84
	v_add_f32_e32 v92, v98, v84
	ds_bpermute_b32 v93, v237, v92
	v_cvt_pk_bf16_f32 v84, v86, v87
	v_cvt_pk_bf16_f32 v86, v82, v83
	v_cvt_pk_bf16_f32 v85, v88, v89
	v_cvt_pk_bf16_f32 v87, v90, v91
	s_waitcnt lgkmcnt(0)
	v_add_f32_e32 v82, v92, v93
	ds_bpermute_b32 v83, v236, v82
	v_lshl_add_u64 v[88:89], s[58:59], 0, v[192:193]
	global_store_dwordx4 v[88:89], v[84:87], off nt
	s_and_saveexec_b64 s[58:59], s[4:5]
	s_cbranch_execz .LBB0_2298
	v_lshl_add_u32 v84, s8, 8, v226
	v_ashrrev_i32_e32 v85, 31, v84
	s_waitcnt lgkmcnt(0)
	v_add_f32_e32 v86, v82, v83
	v_lshlrev_b64 v[82:83], 6, v[84:85]
	s_ashr_i32 s57, s56, 31
	v_lshl_add_u64 v[82:83], s[30:31], 0, v[82:83]
	v_lshl_add_u64 v[82:83], s[56:57], 2, v[82:83]
	s_lshl_b32 s26, s70, 2
	v_lshl_add_u64 v[82:83], v[82:83], 0, s[26:27]
	global_store_dword v[82:83], v86, off
; __device__ __forceinline__ unsigned pk2(float lo, float hi) { f32x2_t v = {lo, hi}; bf16x2_t b = __builtin_convertvector(v, bf16x2_t); return __builtin_bit_cast(unsigned, b); }
; __device__ __forceinline__ float bflo(unsigned w) { return __uint_as_float(w << 16); }
; __device__ __forceinline__ float bfhi(unsigned w) { return __uint_as_float(w & 0xffff0000u); }
;     __device__ __forceinline__ void operator()(Acc& acc, const Unit& u, int wr, int wc, int fr, int fq) const {
;     ...
;         for (int ai = 0; ai < 2; ++ai)
; #pragma unroll
;             for (int m = 0; m < 4; ++m) {
;                 const int row = u.pm * BM + ai * HALF + wr * 64 + m * 16 + fr;
;                 float ss = 0.f;
; #pragma unroll
;                 for (int bj = 0; bj < 2; ++bj) {
;                     const size_t off = (size_t)row * D + col0 + bj * HALF;
;                     f32x4 r0, r1;
;                     if (RES_BF16) { const u32x4 q = rb[ai][m][bj]; r0 = (f32x4){bflo(q.x), bfhi(q.x), bflo(q.y), bfhi(q.y)}; r1 = (f32x4){bflo(q.z), bfhi(q.z), bflo(q.w), bfhi(q.w)}; }
;                     else { r0 = *(const f32x4*)(res_f32 + off); r1 = *(const f32x4*)(res_f32 + off + 4); }
;                     const f32x4 v0 = r0 + acc[ai][bj][m][0] * alpha, v1 = r1 + acc[ai][bj][m][1] * alpha;
;                     u32x4 w; w.x = pk2(v0[0], v0[1]); w.y = pk2(v0[2], v0[3]); w.z = pk2(v1[0], v1[1]); w.w = pk2(v1[2], v1[3]);
;                     *(u32x4*)((char*)XBo + xb_piece(u.pm, u.pn, wr, wc, ai, m, bj) + xlo) = w;
;                     ss += (v0[0] * v0[0] + v0[1] * v0[1]) + (v0[2] * v0[2] + v0[3] * v0[3]) + (v1[0] * v1[0] + v1[1] * v1[1]) + (v1[2] * v1[2] + v1[3] * v1[3]);
;                 }
;                 ss += __shfl_xor(ss, 16); ss += __shfl_xor(ss, 32);
;                 if (ssqp && fq == 0) ssqp[(size_t)row * 16 + u.pn * 4 + wc] = ss;
.LBB0_2298:
	s_or_b64 exec, exec, s[58:59]
	s_waitcnt vmcnt(15)
	v_lshlrev_b32_e32 v82, 16, v166
	s_waitcnt lgkmcnt(0)
	v_and_b32_e32 v83, 0xffff0000, v166
	v_lshlrev_b32_e32 v84, 16, v167
	v_and_b32_e32 v85, 0xffff0000, v167
	v_lshlrev_b32_e32 v86, 16, v168
	v_and_b32_e32 v87, 0xffff0000, v168
	v_lshlrev_b32_e32 v88, 16, v169
	v_and_b32_e32 v89, 0xffff0000, v169
	s_add_u32 s58, s49, s44
	v_pk_add_f32 v[80:81], v[80:81], v[84:85]
	v_pk_add_f32 v[78:79], v[78:79], v[82:83]
	v_pk_add_f32 v[82:83], v[76:77], v[88:89]
	v_pk_add_f32 v[84:85], v[74:75], v[86:87]
	s_addc_u32 s59, s51, s45
	v_cvt_pk_bf16_f32 v74, v78, v79
	v_cvt_pk_bf16_f32 v75, v80, v81
	v_cvt_pk_bf16_f32 v76, v84, v85
	v_cvt_pk_bf16_f32 v77, v82, v83
	v_lshl_add_u64 v[86:87], s[58:59], 0, v[192:193]
	global_store_dwordx4 v[86:87], v[74:77], off nt
	s_add_u32 s58, s60, s44
	s_addc_u32 s59, s61, s45
	v_mul_f32_e32 v74, v79, v79
	v_mul_f32_e32 v75, v81, v81
	v_fmac_f32_e32 v74, v78, v78
	v_fmac_f32_e32 v75, v80, v80
	v_add_f32_e32 v74, v74, v75
	v_mul_f32_e32 v75, v85, v85
	v_fmac_f32_e32 v75, v84, v84
	v_add_f32_e32 v74, v75, v74
	v_mul_f32_e32 v75, v83, v83
	v_fmac_f32_e32 v75, v82, v82
	v_add_f32_e32 v82, v75, v74
	s_waitcnt vmcnt(15)
	v_lshlrev_b32_e32 v74, 16, v162
	v_and_b32_e32 v75, 0xffff0000, v162
	v_lshlrev_b32_e32 v76, 16, v163
	v_and_b32_e32 v77, 0xffff0000, v163
	v_lshlrev_b32_e32 v80, 16, v165
	v_and_b32_e32 v81, 0xffff0000, v165
	v_pk_add_f32 v[72:73], v[72:73], v[76:77]
	v_pk_add_f32 v[70:71], v[70:71], v[74:75]
	v_lshlrev_b32_e32 v78, 16, v164
	v_and_b32_e32 v79, 0xffff0000, v164
	v_pk_add_f32 v[74:75], v[68:69], v[80:81]
	v_mul_f32_e32 v68, v71, v71
	v_mul_f32_e32 v69, v73, v73
	v_pk_add_f32 v[66:67], v[66:67], v[78:79]
	v_fmac_f32_e32 v68, v70, v70
	v_fmac_f32_e32 v69, v72, v72
	v_add_f32_e32 v68, v68, v69
	v_mul_f32_e32 v69, v67, v67
	v_fmac_f32_e32 v69, v66, v66
	v_add_f32_e32 v68, v69, v68
	v_mul_f32_e32 v69, v75, v75
	v_fmac_f32_e32 v69, v74, v74
	v_add_f32_e32 v68, v69, v68
	v_add_f32_e32 v76, v82, v68
	ds_bpermute_b32 v77, v237, v76
	v_cvt_pk_bf16_f32 v68, v70, v71
	v_cvt_pk_bf16_f32 v70, v66, v67
	v_cvt_pk_bf16_f32 v69, v72, v73
	v_cvt_pk_bf16_f32 v71, v74, v75
	s_waitcnt lgkmcnt(0)
	v_add_f32_e32 v66, v76, v77
	ds_bpermute_b32 v67, v236, v66
	v_lshl_add_u64 v[72:73], s[58:59], 0, v[192:193]
	global_store_dwordx4 v[72:73], v[68:71], off nt
	s_and_saveexec_b64 s[58:59], s[4:5]
	s_cbranch_execz .LBB0_2300
	v_lshl_add_u32 v68, s8, 8, v227
	v_ashrrev_i32_e32 v69, 31, v68
	s_waitcnt lgkmcnt(0)
	v_add_f32_e32 v70, v66, v67
	v_lshlrev_b64 v[66:67], 6, v[68:69]
	s_ashr_i32 s57, s56, 31
	v_lshl_add_u64 v[66:67], s[30:31], 0, v[66:67]
	v_lshl_add_u64 v[66:67], s[56:57], 2, v[66:67]
	s_lshl_b32 s26, s70, 2
	v_lshl_add_u64 v[66:67], v[66:67], 0, s[26:27]
	global_store_dword v[66:67], v70, off
.LBB0_2300:
	s_or_b64 exec, exec, s[58:59]
	s_waitcnt vmcnt(15)
	v_lshlrev_b32_e32 v66, 16, v158
	s_waitcnt lgkmcnt(0)
	v_and_b32_e32 v67, 0xffff0000, v158
	v_lshlrev_b32_e32 v68, 16, v159
	v_and_b32_e32 v69, 0xffff0000, v159
	v_lshlrev_b32_e32 v70, 16, v160
	v_and_b32_e32 v71, 0xffff0000, v160
	v_lshlrev_b32_e32 v72, 16, v161
	v_and_b32_e32 v73, 0xffff0000, v161
	v_pk_add_f32 v[64:65], v[64:65], v[68:69]
	v_pk_add_f32 v[66:67], v[62:63], v[66:67]
	v_pk_add_f32 v[68:69], v[60:61], v[72:73]
	v_pk_add_f32 v[70:71], v[58:59], v[70:71]
	v_add_co_u32_e32 v58, vcc, s69, v212
	v_cvt_pk_bf16_f32 v60, v66, v67
	v_cvt_pk_bf16_f32 v61, v64, v65
	v_cvt_pk_bf16_f32 v62, v70, v71
	v_cvt_pk_bf16_f32 v63, v68, v69
	v_addc_co_u32_e32 v59, vcc, 0, v213, vcc
	global_store_dwordx4 v[58:59], v[60:63], off nt
	s_nop 1
	v_mul_f32_e32 v60, v67, v67
	v_mul_f32_e32 v61, v65, v65
	v_fmac_f32_e32 v60, v66, v66
	v_fmac_f32_e32 v61, v64, v64
	v_add_f32_e32 v60, v60, v61
	v_mul_f32_e32 v61, v71, v71
	v_fmac_f32_e32 v61, v70, v70
	v_add_f32_e32 v60, v61, v60
	v_mul_f32_e32 v61, v69, v69
	v_fmac_f32_e32 v61, v68, v68
	v_add_f32_e32 v68, v61, v60
	s_waitcnt vmcnt(15)
	v_lshlrev_b32_e32 v60, 16, v154
	v_and_b32_e32 v61, 0xffff0000, v154
	v_lshlrev_b32_e32 v62, 16, v155
	v_and_b32_e32 v63, 0xffff0000, v155
	v_pk_add_f32 v[56:57], v[56:57], v[62:63]
	v_pk_add_f32 v[54:55], v[54:55], v[60:61]
	v_lshlrev_b32_e32 v64, 16, v156
	v_and_b32_e32 v65, 0xffff0000, v156
	v_mul_f32_e32 v60, v55, v55
	v_mul_f32_e32 v61, v57, v57
	v_pk_add_f32 v[50:51], v[50:51], v[64:65]
	v_fmac_f32_e32 v60, v54, v54
	v_fmac_f32_e32 v61, v56, v56
	v_lshlrev_b32_e32 v66, 16, v157
	v_and_b32_e32 v67, 0xffff0000, v157
	v_add_f32_e32 v60, v60, v61
	v_mul_f32_e32 v61, v51, v51
	v_pk_add_f32 v[52:53], v[52:53], v[66:67]
	v_fmac_f32_e32 v61, v50, v50
	v_add_f32_e32 v60, v61, v60
	v_mul_f32_e32 v61, v53, v53
	v_fmac_f32_e32 v61, v52, v52
	v_add_f32_e32 v60, v61, v60
	v_add_f32_e32 v60, v68, v60
	ds_bpermute_b32 v61, v237, v60
	v_cvt_pk_bf16_f32 v54, v54, v55
	v_cvt_pk_bf16_f32 v55, v56, v57
	v_cvt_pk_bf16_f32 v57, v52, v53
	v_cvt_pk_bf16_f32 v56, v50, v51
	s_waitcnt lgkmcnt(0)
	v_add_f32_e32 v52, v60, v61
	ds_bpermute_b32 v53, v236, v52
	v_add_co_u32_e32 v50, vcc, s69, v126
	s_nop 1
	v_addc_co_u32_e32 v51, vcc, 0, v127, vcc
	global_store_dwordx4 v[50:51], v[54:57], off nt
	s_and_saveexec_b64 s[58:59], s[4:5]
	s_cbranch_execz .LBB0_2302
	v_lshl_add_u32 v54, s8, 8, v228
	v_ashrrev_i32_e32 v55, 31, v54
	s_waitcnt lgkmcnt(0)
	v_add_f32_e32 v56, v52, v53
	v_lshlrev_b64 v[52:53], 6, v[54:55]
	s_ashr_i32 s57, s56, 31
	v_lshl_add_u64 v[52:53], s[30:31], 0, v[52:53]
	v_lshl_add_u64 v[52:53], s[56:57], 2, v[52:53]
	s_lshl_b32 s26, s70, 2
	v_lshl_add_u64 v[52:53], v[52:53], 0, s[26:27]
	global_store_dword v[52:53], v56, off
; __device__ __forceinline__ unsigned pk2(float lo, float hi) { f32x2_t v = {lo, hi}; bf16x2_t b = __builtin_convertvector(v, bf16x2_t); return __builtin_bit_cast(unsigned, b); }
; __device__ __forceinline__ float bflo(unsigned w) { return __uint_as_float(w << 16); }
; __device__ __forceinline__ float bfhi(unsigned w) { return __uint_as_float(w & 0xffff0000u); }
;     __device__ __forceinline__ void operator()(Acc& acc, const Unit& u, int wr, int wc, int fr, int fq) const {
;     ...
;         for (int ai = 0; ai < 2; ++ai)
; #pragma unroll
;             for (int m = 0; m < 4; ++m) {
;                 const int row = u.pm * BM + ai * HALF + wr * 64 + m * 16 + fr;
;                 float ss = 0.f;
; #pragma unroll
;                 for (int bj = 0; bj < 2; ++bj) {
;                     const size_t off = (size_t)row * D + col0 + bj * HALF;
;                     f32x4 r0, r1;
;                     if (RES_BF16) { const u32x4 q = rb[ai][m][bj]; r0 = (f32x4){bflo(q.x), bfhi(q.x), bflo(q.y), bfhi(q.y)}; r1 = (f32x4){bflo(q.z), bfhi(q.z), bflo(q.w), bfhi(q.w)}; }
;                     else { r0 = *(const f32x4*)(res_f32 + off); r1 = *(const f32x4*)(res_f32 + off + 4); }
;                     const f32x4 v0 = r0 + acc[ai][bj][m][0] * alpha, v1 = r1 + acc[ai][bj][m][1] * alpha;
;                     u32x4 w; w.x = pk2(v0[0], v0[1]); w.y = pk2(v0[2], v0[3]); w.z = pk2(v1[0], v1[1]); w.w = pk2(v1[2], v1[3]);
;                     *(u32x4*)((char*)XBo + xb_piece(u.pm, u.pn, wr, wc, ai, m, bj) + xlo) = w;
;                     ss += (v0[0] * v0[0] + v0[1] * v0[1]) + (v0[2] * v0[2] + v0[3] * v0[3]) + (v1[0] * v1[0] + v1[1] * v1[1]) + (v1[2] * v1[2] + v1[3] * v1[3]);
;                 }
;                 ss += __shfl_xor(ss, 16); ss += __shfl_xor(ss, 32);
;                 if (ssqp && fq == 0) ssqp[(size_t)row * 16 + u.pn * 4 + wc] = ss;
.LBB0_2302:
	s_or_b64 exec, exec, s[58:59]
	s_waitcnt vmcnt(15)
	v_lshlrev_b32_e32 v52, 16, v150
	s_waitcnt lgkmcnt(0)
	v_and_b32_e32 v53, 0xffff0000, v150
	v_lshlrev_b32_e32 v54, 16, v151
	v_and_b32_e32 v55, 0xffff0000, v151
	v_lshlrev_b32_e32 v56, 16, v152
	v_and_b32_e32 v57, 0xffff0000, v152
	v_lshlrev_b32_e32 v60, 16, v153
	v_and_b32_e32 v61, 0xffff0000, v153
	v_pk_add_f32 v[46:47], v[46:47], v[52:53]
	v_pk_add_f32 v[48:49], v[48:49], v[54:55]
	v_pk_add_f32 v[52:53], v[44:45], v[60:61]
	v_pk_add_f32 v[44:45], v[42:43], v[56:57]
	v_cvt_pk_bf16_f32 v42, v46, v47
	v_mul_f32_e32 v47, v47, v47
	v_fmac_f32_e32 v47, v46, v46
	v_mul_f32_e32 v46, v49, v49
	v_fmac_f32_e32 v46, v48, v48
	v_add_f32_e32 v46, v47, v46
	v_mul_f32_e32 v47, v45, v45
	v_fmac_f32_e32 v47, v44, v44
	v_add_f32_e32 v46, v47, v46
	v_mul_f32_e32 v47, v53, v53
	v_fmac_f32_e32 v47, v52, v52
	v_cvt_pk_bf16_f32 v43, v48, v49
	v_add_f32_e32 v60, v47, v46
	s_waitcnt vmcnt(14)
	v_lshlrev_b32_e32 v46, 16, v146
	v_and_b32_e32 v47, 0xffff0000, v146
	v_lshlrev_b32_e32 v48, 16, v147
	v_and_b32_e32 v49, 0xffff0000, v147
	v_lshlrev_b32_e32 v54, 16, v148
	v_and_b32_e32 v55, 0xffff0000, v148
	v_pk_add_f32 v[40:41], v[40:41], v[48:49]
	v_pk_add_f32 v[38:39], v[38:39], v[46:47]
	v_pk_add_f32 v[48:49], v[34:35], v[54:55]
	v_mul_f32_e32 v34, v39, v39
	v_mul_f32_e32 v35, v41, v41
	v_fmac_f32_e32 v34, v38, v38
	v_fmac_f32_e32 v35, v40, v40
	v_lshlrev_b32_e32 v56, 16, v149
	v_and_b32_e32 v57, 0xffff0000, v149
	v_add_f32_e32 v34, v34, v35
	v_mul_f32_e32 v35, v49, v49
	v_pk_add_f32 v[46:47], v[36:37], v[56:57]
	v_fmac_f32_e32 v35, v48, v48
	v_add_f32_e32 v34, v35, v34
	v_mul_f32_e32 v35, v47, v47
	v_fmac_f32_e32 v35, v46, v46
	v_add_f32_e32 v34, v35, v34
	v_add_f32_e32 v34, v60, v34
	ds_bpermute_b32 v35, v237, v34
	v_cvt_pk_bf16_f32 v44, v44, v45
	v_cvt_pk_bf16_f32 v45, v52, v53
	v_cvt_pk_bf16_f32 v36, v38, v39
	v_cvt_pk_bf16_f32 v37, v40, v41
	s_waitcnt lgkmcnt(0)
	v_add_f32_e32 v34, v34, v35
	ds_bpermute_b32 v35, v236, v34
	v_cvt_pk_bf16_f32 v38, v48, v49
	v_cvt_pk_bf16_f32 v39, v46, v47
	global_store_dwordx4 v[58:59], v[42:45], off offset:2048 nt
	global_store_dwordx4 v[50:51], v[36:39], off offset:2048 nt
	s_and_saveexec_b64 s[58:59], s[4:5]
	s_cbranch_execz .LBB0_2304
	v_lshl_add_u32 v36, s8, 8, v229
	v_ashrrev_i32_e32 v37, 31, v36
	s_waitcnt lgkmcnt(0)
	v_add_f32_e32 v38, v34, v35
	v_lshlrev_b64 v[34:35], 6, v[36:37]
	s_ashr_i32 s57, s56, 31
	v_lshl_add_u64 v[34:35], s[30:31], 0, v[34:35]
	v_lshl_add_u64 v[34:35], s[56:57], 2, v[34:35]
	s_lshl_b32 s26, s70, 2
	v_lshl_add_u64 v[34:35], v[34:35], 0, s[26:27]
	global_store_dword v[34:35], v38, off
; __device__ __forceinline__ unsigned pk2(float lo, float hi) { f32x2_t v = {lo, hi}; bf16x2_t b = __builtin_convertvector(v, bf16x2_t); return __builtin_bit_cast(unsigned, b); }
; __device__ __forceinline__ float bflo(unsigned w) { return __uint_as_float(w << 16); }
; __device__ __forceinline__ float bfhi(unsigned w) { return __uint_as_float(w & 0xffff0000u); }
;     __device__ __forceinline__ void operator()(Acc& acc, const Unit& u, int wr, int wc, int fr, int fq) const {
;     ...
;         for (int ai = 0; ai < 2; ++ai)
; #pragma unroll
;             for (int m = 0; m < 4; ++m) {
;                 const int row = u.pm * BM + ai * HALF + wr * 64 + m * 16 + fr;
;                 float ss = 0.f;
; #pragma unroll
;                 for (int bj = 0; bj < 2; ++bj) {
;                     const size_t off = (size_t)row * D + col0 + bj * HALF;
;                     f32x4 r0, r1;
;                     if (RES_BF16) { const u32x4 q = rb[ai][m][bj]; r0 = (f32x4){bflo(q.x), bfhi(q.x), bflo(q.y), bfhi(q.y)}; r1 = (f32x4){bflo(q.z), bfhi(q.z), bflo(q.w), bfhi(q.w)}; }
;                     else { r0 = *(const f32x4*)(res_f32 + off); r1 = *(const f32x4*)(res_f32 + off + 4); }
;                     const f32x4 v0 = r0 + acc[ai][bj][m][0] * alpha, v1 = r1 + acc[ai][bj][m][1] * alpha;
;                     u32x4 w; w.x = pk2(v0[0], v0[1]); w.y = pk2(v0[2], v0[3]); w.z = pk2(v1[0], v1[1]); w.w = pk2(v1[2], v1[3]);
;                     *(u32x4*)((char*)XBo + xb_piece(u.pm, u.pn, wr, wc, ai, m, bj) + xlo) = w;
;                     ss += (v0[0] * v0[0] + v0[1] * v0[1]) + (v0[2] * v0[2] + v0[3] * v0[3]) + (v1[0] * v1[0] + v1[1] * v1[1]) + (v1[2] * v1[2] + v1[3] * v1[3]);
;                 }
;                 ss += __shfl_xor(ss, 16); ss += __shfl_xor(ss, 32);
;                 if (ssqp && fq == 0) ssqp[(size_t)row * 16 + u.pn * 4 + wc] = ss;
.LBB0_2304:
	s_or_b64 exec, exec, s[58:59]
	s_waitcnt vmcnt(15)
	v_lshlrev_b32_e32 v34, 16, v134
	s_waitcnt lgkmcnt(0)
	v_and_b32_e32 v35, 0xffff0000, v134
	v_lshlrev_b32_e32 v36, 16, v135
	v_and_b32_e32 v37, 0xffff0000, v135
	v_lshlrev_b32_e32 v38, 16, v136
	v_and_b32_e32 v39, 0xffff0000, v136
	v_lshlrev_b32_e32 v40, 16, v137
	v_and_b32_e32 v41, 0xffff0000, v137
	v_pk_add_f32 v[32:33], v[32:33], v[36:37]
	v_pk_add_f32 v[34:35], v[30:31], v[34:35]
	v_pk_add_f32 v[36:37], v[28:29], v[40:41]
	v_pk_add_f32 v[38:39], v[26:27], v[38:39]
	v_add_co_u32_e32 v26, vcc, s74, v212
	v_cvt_pk_bf16_f32 v28, v34, v35
	v_cvt_pk_bf16_f32 v29, v32, v33
	v_cvt_pk_bf16_f32 v30, v38, v39
	v_cvt_pk_bf16_f32 v31, v36, v37
	v_addc_co_u32_e32 v27, vcc, 0, v213, vcc
	global_store_dwordx4 v[26:27], v[28:31], off nt
	s_nop 1
	v_mul_f32_e32 v28, v35, v35
	v_mul_f32_e32 v29, v33, v33
	v_fmac_f32_e32 v28, v34, v34
	v_fmac_f32_e32 v29, v32, v32
	v_add_f32_e32 v28, v28, v29
	v_mul_f32_e32 v29, v39, v39
	v_fmac_f32_e32 v29, v38, v38
	v_add_f32_e32 v28, v29, v28
	v_mul_f32_e32 v29, v37, v37
	v_fmac_f32_e32 v29, v36, v36
	v_add_f32_e32 v36, v29, v28
	s_waitcnt vmcnt(15)
	v_lshlrev_b32_e32 v28, 16, v122
	v_and_b32_e32 v29, 0xffff0000, v122
	v_lshlrev_b32_e32 v30, 16, v123
	v_and_b32_e32 v31, 0xffff0000, v123
	v_pk_add_f32 v[24:25], v[24:25], v[30:31]
	v_pk_add_f32 v[22:23], v[22:23], v[28:29]
	v_lshlrev_b32_e32 v32, 16, v124
	v_and_b32_e32 v33, 0xffff0000, v124
	v_mul_f32_e32 v28, v23, v23
	v_mul_f32_e32 v29, v25, v25
	v_pk_add_f32 v[18:19], v[18:19], v[32:33]
	v_fmac_f32_e32 v28, v22, v22
	v_fmac_f32_e32 v29, v24, v24
	v_lshlrev_b32_e32 v34, 16, v125
	v_and_b32_e32 v35, 0xffff0000, v125
	v_add_f32_e32 v28, v28, v29
	v_mul_f32_e32 v29, v19, v19
	v_pk_add_f32 v[20:21], v[20:21], v[34:35]
	v_fmac_f32_e32 v29, v18, v18
	v_add_f32_e32 v28, v29, v28
	v_mul_f32_e32 v29, v21, v21
	v_fmac_f32_e32 v29, v20, v20
	v_add_f32_e32 v28, v29, v28
	v_add_f32_e32 v28, v36, v28
	ds_bpermute_b32 v29, v237, v28
	v_cvt_pk_bf16_f32 v22, v22, v23
	v_cvt_pk_bf16_f32 v23, v24, v25
	v_cvt_pk_bf16_f32 v25, v20, v21
	v_cvt_pk_bf16_f32 v24, v18, v19
	s_waitcnt lgkmcnt(0)
	v_add_f32_e32 v20, v28, v29
	ds_bpermute_b32 v21, v236, v20
	v_add_co_u32_e32 v18, vcc, s74, v126
	s_nop 1
	v_addc_co_u32_e32 v19, vcc, 0, v127, vcc
	global_store_dwordx4 v[18:19], v[22:25], off nt
	s_and_saveexec_b64 s[58:59], s[4:5]
	s_cbranch_execz .LBB0_2306
	v_lshl_add_u32 v22, s8, 8, v230
	v_ashrrev_i32_e32 v23, 31, v22
	s_waitcnt lgkmcnt(0)
	v_add_f32_e32 v24, v20, v21
	v_lshlrev_b64 v[20:21], 6, v[22:23]
	s_ashr_i32 s57, s56, 31
	v_lshl_add_u64 v[20:21], s[30:31], 0, v[20:21]
	v_lshl_add_u64 v[20:21], s[56:57], 2, v[20:21]
	s_lshl_b32 s26, s70, 2
	v_lshl_add_u64 v[20:21], v[20:21], 0, s[26:27]
	global_store_dword v[20:21], v24, off
.LBB0_2306:
	s_or_b64 exec, exec, s[58:59]
	s_waitcnt vmcnt(15)
	v_lshlrev_b32_e32 v20, 16, v110
	s_waitcnt lgkmcnt(0)
	v_and_b32_e32 v21, 0xffff0000, v110
	v_lshlrev_b32_e32 v22, 16, v111
	v_and_b32_e32 v23, 0xffff0000, v111
	v_lshlrev_b32_e32 v24, 16, v112
	v_and_b32_e32 v25, 0xffff0000, v112
	v_lshlrev_b32_e32 v28, 16, v113
	v_and_b32_e32 v29, 0xffff0000, v113
	v_pk_add_f32 v[14:15], v[14:15], v[20:21]
	v_pk_add_f32 v[16:17], v[16:17], v[22:23]
	v_pk_add_f32 v[20:21], v[12:13], v[28:29]
	v_pk_add_f32 v[12:13], v[10:11], v[24:25]
	v_cvt_pk_bf16_f32 v10, v14, v15
	v_mul_f32_e32 v15, v15, v15
	v_fmac_f32_e32 v15, v14, v14
	v_mul_f32_e32 v14, v17, v17
	v_fmac_f32_e32 v14, v16, v16
	v_add_f32_e32 v14, v15, v14
	v_mul_f32_e32 v15, v13, v13
	v_fmac_f32_e32 v15, v12, v12
	v_add_f32_e32 v14, v15, v14
	v_mul_f32_e32 v15, v21, v21
	v_fmac_f32_e32 v15, v20, v20
	v_cvt_pk_bf16_f32 v11, v16, v17
	v_add_f32_e32 v28, v15, v14
	s_waitcnt vmcnt(14)
	v_lshlrev_b32_e32 v14, 16, v102
	v_and_b32_e32 v15, 0xffff0000, v102
	v_lshlrev_b32_e32 v16, 16, v103
	v_and_b32_e32 v17, 0xffff0000, v103
	v_lshlrev_b32_e32 v22, 16, v104
	v_and_b32_e32 v23, 0xffff0000, v104
	v_pk_add_f32 v[8:9], v[8:9], v[16:17]
	v_pk_add_f32 v[6:7], v[6:7], v[14:15]
	v_pk_add_f32 v[16:17], v[2:3], v[22:23]
	v_mul_f32_e32 v2, v7, v7
	v_mul_f32_e32 v3, v9, v9
	v_fmac_f32_e32 v2, v6, v6
	v_fmac_f32_e32 v3, v8, v8
	v_lshlrev_b32_e32 v24, 16, v105
	v_and_b32_e32 v25, 0xffff0000, v105
	v_add_f32_e32 v2, v2, v3
	v_mul_f32_e32 v3, v17, v17
	v_pk_add_f32 v[14:15], v[4:5], v[24:25]
	v_fmac_f32_e32 v3, v16, v16
	v_add_f32_e32 v2, v3, v2
	v_mul_f32_e32 v3, v15, v15
	v_fmac_f32_e32 v3, v14, v14
	v_add_f32_e32 v2, v3, v2
	v_add_f32_e32 v2, v28, v2
	ds_bpermute_b32 v3, v237, v2
	v_cvt_pk_bf16_f32 v12, v12, v13
	v_cvt_pk_bf16_f32 v13, v20, v21
	v_cvt_pk_bf16_f32 v4, v6, v7
	v_cvt_pk_bf16_f32 v5, v8, v9
	s_waitcnt lgkmcnt(0)
	v_add_f32_e32 v2, v2, v3
	ds_bpermute_b32 v3, v236, v2
	v_cvt_pk_bf16_f32 v6, v16, v17
	v_cvt_pk_bf16_f32 v7, v14, v15
	global_store_dwordx4 v[26:27], v[10:13], off offset:2048 nt
	global_store_dwordx4 v[18:19], v[4:7], off offset:2048 nt
	s_and_saveexec_b64 s[58:59], s[4:5]
	s_cbranch_execz .LBB0_2308
	v_lshl_add_u32 v4, s8, 8, v231
	v_ashrrev_i32_e32 v5, 31, v4
	s_waitcnt lgkmcnt(0)
	v_add_f32_e32 v6, v2, v3
	v_lshlrev_b64 v[2:3], 6, v[4:5]
	s_ashr_i32 s57, s56, 31
	v_lshl_add_u64 v[2:3], s[30:31], 0, v[2:3]
	v_lshl_add_u64 v[2:3], s[56:57], 2, v[2:3]
	s_lshl_b32 s26, s70, 2
	v_lshl_add_u64 v[2:3], v[2:3], 0, s[26:27]
	global_store_dword v[2:3], v6, off

; __device__ __forceinline__ unsigned pk2(float lo, float hi) { f32x2_t v = {lo, hi}; bf16x2_t b = __builtin_convertvector(v, bf16x2_t); return __builtin_bit_cast(unsigned, b); }
; __device__ __forceinline__ float siluf_(float x) { return x * sigmoidf_(x); }
;     __device__ __forceinline__ void operator()(Acc& acc, const Unit& u, int wr, int wc, int fr, int fq, const float (&rsa)[2][4]) const {
;         const int row0 = u.pm * BM + wr * 64 + fr, col0 = u.pn * HALF + wc * 32 + 8 * fq;
; #pragma unroll
;         for (int ai = 0; ai < 2; ++ai)
; #pragma unroll
;             for (int m = 0; m < 4; ++m) {
;                 const int row = row0 + ai * HALF + m * 16; const float rs = rsa[ai][m];
;                 float o[8];
; #pragma unroll
;                 for (int n = 0; n < 2; ++n)
; #pragma unroll
;                     for (int j = 0; j < 4; ++j) { const float g = acc[ai][0][m][n][j] * rs, up = acc[ai][1][m][n][j] * rs; o[n * 4 + j] = siluf_(g) * up; }
;                 u32x4 w; w.x = pk2(o[0], o[1]); w.y = pk2(o[2], o[3]); w.z = pk2(o[4], o[5]); w.w = pk2(o[6], o[7]);
;                 const int rr = row & (BM - 1);
;                 *(u32x4*)((char*)O + ((size_t)(u.pm * (FF / BK) + (col0 >> 6))) * (2 * HTB) + (rr >> 7) * HTB + lds_byte(rr & 127, col0 & 63)) = w;
.LBB0_2502:
	v_pk_mul_f32 v[178:179], v[126:127], v[134:135] op_sel_hi:[1,0]
	v_mov_b64_e32 v[126:127], 0
	v_pk_mul_f32 v[184:185], v[128:129], v[134:135] op_sel_hi:[1,0]
	v_mov_b64_e32 v[128:129], 0
	v_mul_f32_e32 v131, 0xbfb8aa3b, v178
	v_exp_f32_e32 v131, v131
	v_mul_f32_e32 v133, 0xbfb8aa3b, v179
	v_exp_f32_e32 v133, v133
	v_pk_mul_f32 v[182:183], v[94:95], v[134:135] op_sel_hi:[1,0]
	v_mov_b64_e32 v[94:95], 0
	v_add_f32_e32 v131, 1.0, v131
	v_rcp_f32_e32 v180, v131
	v_add_f32_e32 v131, 1.0, v133
	v_mul_f32_e32 v133, 0xbfb8aa3b, v184
	v_exp_f32_e32 v133, v133
	v_mul_f32_e32 v135, 0xbfb8aa3b, v185
	v_exp_f32_e32 v135, v135
	v_rcp_f32_e32 v181, v131
	v_add_f32_e32 v131, 1.0, v133
	v_rcp_f32_e32 v186, v131
	v_add_f32_e32 v131, 1.0, v135
	v_rcp_f32_e32 v187, v131
	v_pk_mul_f32 v[178:179], v[178:179], v[180:181]
	v_pk_mul_f32 v[180:181], v[96:97], v[134:135] op_sel_hi:[1,0]
	v_mov_b64_e32 v[96:97], 0
	v_pk_mul_f32 v[178:179], v[182:183], v[178:179]
	v_pk_mul_f32 v[182:183], v[184:185], v[186:187]
	v_pk_mul_f32 v[184:185], v[122:123], v[134:135] op_sel_hi:[1,0]
	v_mov_b64_e32 v[122:123], 0
	v_pk_mul_f32 v[188:189], v[124:125], v[134:135] op_sel_hi:[1,0]
	v_mov_b64_e32 v[124:125], 0
	v_mul_f32_e32 v131, 0xbfb8aa3b, v184
	v_exp_f32_e32 v131, v131
	v_mul_f32_e32 v133, 0xbfb8aa3b, v185
	v_exp_f32_e32 v133, v133
	v_pk_mul_f32 v[180:181], v[180:181], v[182:183]
	v_add_f32_e32 v131, 1.0, v131
	v_rcp_f32_e32 v182, v131
	v_add_f32_e32 v131, 1.0, v133
	v_mul_f32_e32 v133, 0xbfb8aa3b, v188
	v_pk_mul_f32 v[186:187], v[90:91], v[134:135] op_sel_hi:[1,0]
	v_mov_b64_e32 v[90:91], 0
	v_exp_f32_e32 v133, v133
	v_mul_f32_e32 v135, 0xbfb8aa3b, v189
	v_exp_f32_e32 v135, v135
	v_rcp_f32_e32 v183, v131
	s_lshl_b32 s51, s10, 7
	s_or_b32 s51, s51, s17
	s_ashr_i32 s51, s51, 6
	v_add_f32_e32 v131, 1.0, v133
	s_mul_i32 s53, s8, 44
	v_rcp_f32_e32 v190, v131
	v_add_f32_e32 v131, 1.0, v135
	v_pk_mul_f32 v[182:183], v[184:185], v[182:183]
	s_add_i32 s58, s51, s53
	v_rcp_f32_e32 v191, v131
	v_pk_mul_f32 v[182:183], v[186:187], v[182:183]
	s_ashr_i32 s59, s58, 31
	v_cvt_pk_bf16_f32 v178, v178, v179
	v_cvt_pk_bf16_f32 v179, v180, v181
	v_cvt_pk_bf16_f32 v180, v182, v183
	s_lshl_b64 s[58:59], s[58:59], 15
	v_pk_mul_f32 v[182:183], v[118:119], v[164:165] op_sel_hi:[1,0]
	v_mov_b64_e32 v[118:119], 0
	s_add_u32 s51, s14, s58
	v_mul_f32_e32 v131, 0xbfb8aa3b, v182
	s_addc_u32 s53, s15, s59
	v_exp_f32_e32 v131, v131
	v_mul_f32_e32 v133, 0xbfb8aa3b, v183
	v_pk_mul_f32 v[134:135], v[92:93], v[134:135] op_sel_hi:[1,0]
	v_mov_b64_e32 v[92:93], 0
	v_pk_mul_f32 v[184:185], v[188:189], v[190:191]
	s_add_u32 s58, s51, s73
	v_exp_f32_e32 v133, v133
	v_pk_mul_f32 v[134:135], v[134:135], v[184:185]
	s_addc_u32 s59, s53, 0
	v_cvt_pk_bf16_f32 v181, v134, v135
	v_lshl_add_u64 v[134:135], s[58:59], 0, v[144:145]
	global_store_dwordx4 v[134:135], v[178:181], off nt
	v_add_f32_e32 v131, 1.0, v131
	v_rcp_f32_e32 v134, v131
	v_pk_mul_f32 v[180:181], v[120:121], v[164:165] op_sel_hi:[1,0]
	v_mov_b64_e32 v[120:121], 0
	v_add_f32_e32 v131, 1.0, v133
	v_mul_f32_e32 v133, 0xbfb8aa3b, v180
	v_exp_f32_e32 v133, v133
	v_mul_f32_e32 v135, 0xbfb8aa3b, v181
	v_exp_f32_e32 v137, v135
	v_rcp_f32_e32 v135, v131
	v_add_f32_e32 v131, 1.0, v133
	v_rcp_f32_e32 v184, v131
	v_add_f32_e32 v131, 1.0, v137
	v_pk_mul_f32 v[134:135], v[182:183], v[134:135]
	v_pk_mul_f32 v[182:183], v[114:115], v[164:165] op_sel_hi:[1,0]
	v_mov_b64_e32 v[114:115], 0
	v_rcp_f32_e32 v185, v131
	v_mul_f32_e32 v131, 0xbfb8aa3b, v182
	v_exp_f32_e32 v131, v131
	v_mul_f32_e32 v133, 0xbfb8aa3b, v183
	v_exp_f32_e32 v133, v133
	v_pk_mul_f32 v[178:179], v[86:87], v[164:165] op_sel_hi:[1,0]
	v_mov_b64_e32 v[86:87], 0
	v_pk_mul_f32 v[180:181], v[180:181], v[184:185]
	v_pk_mul_f32 v[134:135], v[178:179], v[134:135]
	v_pk_mul_f32 v[178:179], v[88:89], v[164:165] op_sel_hi:[1,0]
	v_mov_b64_e32 v[88:89], 0
	v_add_f32_e32 v131, 1.0, v131
	v_pk_mul_f32 v[186:187], v[116:117], v[164:165] op_sel_hi:[1,0]
	v_mov_b64_e32 v[116:117], 0
	v_pk_mul_f32 v[180:181], v[178:179], v[180:181]
	v_rcp_f32_e32 v178, v131
	v_add_f32_e32 v131, 1.0, v133
	v_mul_f32_e32 v133, 0xbfb8aa3b, v186
	v_exp_f32_e32 v133, v133
	v_mul_f32_e32 v137, 0xbfb8aa3b, v187
	v_exp_f32_e32 v137, v137
	v_rcp_f32_e32 v179, v131
	v_add_f32_e32 v131, 1.0, v133
	v_rcp_f32_e32 v188, v131
	v_add_f32_e32 v131, 1.0, v137
	v_rcp_f32_e32 v189, v131
	v_pk_mul_f32 v[184:185], v[82:83], v[164:165] op_sel_hi:[1,0]
	v_mov_b64_e32 v[82:83], 0
	v_pk_mul_f32 v[178:179], v[182:183], v[178:179]
	s_nop 0
	v_pk_mul_f32 v[182:183], v[184:185], v[178:179]
	v_pk_mul_f32 v[178:179], v[84:85], v[164:165] op_sel_hi:[1,0]
	v_mov_b64_e32 v[84:85], 0
	v_pk_mul_f32 v[184:185], v[186:187], v[188:189]
	s_nop 0
	v_pk_mul_f32 v[184:185], v[178:179], v[184:185]
	v_cvt_pk_bf16_f32 v179, v180, v181
	v_cvt_pk_bf16_f32 v180, v182, v183
	v_pk_mul_f32 v[182:183], v[110:111], v[136:137] op_sel_hi:[1,0]
	v_mov_b64_e32 v[110:111], 0
	v_cvt_pk_bf16_f32 v178, v134, v135
	v_mul_f32_e32 v131, 0xbfb8aa3b, v182
	v_exp_f32_e32 v131, v131
	v_mul_f32_e32 v133, 0xbfb8aa3b, v183
	v_exp_f32_e32 v133, v133
	v_cvt_pk_bf16_f32 v181, v184, v185
	v_lshl_add_u64 v[134:135], s[58:59], 0, v[148:149]
	global_store_dwordx4 v[134:135], v[178:181], off nt
	v_add_f32_e32 v131, 1.0, v131
	v_rcp_f32_e32 v134, v131
	v_pk_mul_f32 v[180:181], v[112:113], v[136:137] op_sel_hi:[1,0]
	v_mov_b64_e32 v[112:113], 0
	v_add_f32_e32 v131, 1.0, v133
	v_mul_f32_e32 v133, 0xbfb8aa3b, v180
	v_exp_f32_e32 v133, v133
	v_mul_f32_e32 v135, 0xbfb8aa3b, v181
	v_pk_mul_f32 v[178:179], v[78:79], v[136:137] op_sel_hi:[1,0]
	v_mov_b64_e32 v[78:79], 0
	v_exp_f32_e32 v137, v135
	v_rcp_f32_e32 v135, v131
; __device__ __forceinline__ unsigned pk2(float lo, float hi) { f32x2_t v = {lo, hi}; bf16x2_t b = __builtin_convertvector(v, bf16x2_t); return __builtin_bit_cast(unsigned, b); }
; __device__ __forceinline__ float siluf_(float x) { return x * sigmoidf_(x); }
;     __device__ __forceinline__ void operator()(Acc& acc, const Unit& u, int wr, int wc, int fr, int fq, const float (&rsa)[2][4]) const {
;         const int row0 = u.pm * BM + wr * 64 + fr, col0 = u.pn * HALF + wc * 32 + 8 * fq;
; #pragma unroll
;         for (int ai = 0; ai < 2; ++ai)
; #pragma unroll
;             for (int m = 0; m < 4; ++m) {
;                 const int row = row0 + ai * HALF + m * 16; const float rs = rsa[ai][m];
;                 float o[8];
; #pragma unroll
;                 for (int n = 0; n < 2; ++n)
; #pragma unroll
;                     for (int j = 0; j < 4; ++j) { const float g = acc[ai][0][m][n][j] * rs, up = acc[ai][1][m][n][j] * rs; o[n * 4 + j] = siluf_(g) * up; }
;                 u32x4 w; w.x = pk2(o[0], o[1]); w.y = pk2(o[2], o[3]); w.z = pk2(o[4], o[5]); w.w = pk2(o[6], o[7]);
;                 const int rr = row & (BM - 1);
;                 *(u32x4*)((char*)O + ((size_t)(u.pm * (FF / BK) + (col0 >> 6))) * (2 * HTB) + (rr >> 7) * HTB + lds_byte(rr & 127, col0 & 63)) = w;
	v_add_f32_e32 v131, 1.0, v133
	v_rcp_f32_e32 v184, v131
	v_add_f32_e32 v131, 1.0, v137
	v_pk_mul_f32 v[134:135], v[182:183], v[134:135]
	v_pk_mul_f32 v[182:183], v[106:107], v[136:137] op_sel_hi:[1,0]
	v_mov_b64_e32 v[106:107], 0
	v_rcp_f32_e32 v185, v131
	v_mul_f32_e32 v131, 0xbfb8aa3b, v182
	v_exp_f32_e32 v131, v131
	v_mul_f32_e32 v133, 0xbfb8aa3b, v183
	v_exp_f32_e32 v133, v133
	v_pk_mul_f32 v[134:135], v[178:179], v[134:135]
	v_pk_mul_f32 v[178:179], v[80:81], v[136:137] op_sel_hi:[1,0]
	v_mov_b64_e32 v[80:81], 0
	v_pk_mul_f32 v[180:181], v[180:181], v[184:185]
	v_add_f32_e32 v131, 1.0, v131
	v_pk_mul_f32 v[186:187], v[108:109], v[136:137] op_sel_hi:[1,0]
	v_mov_b64_e32 v[108:109], 0
	v_pk_mul_f32 v[178:179], v[178:179], v[180:181]
	v_rcp_f32_e32 v180, v131
	v_add_f32_e32 v131, 1.0, v133
	v_mul_f32_e32 v133, 0xbfb8aa3b, v186
	v_pk_mul_f32 v[184:185], v[74:75], v[136:137] op_sel_hi:[1,0]
	v_mov_b64_e32 v[74:75], 0
	v_exp_f32_e32 v133, v133
	v_mul_f32_e32 v137, 0xbfb8aa3b, v187
	v_exp_f32_e32 v137, v137
	v_rcp_f32_e32 v181, v131
	v_add_f32_e32 v131, 1.0, v133
	v_rcp_f32_e32 v188, v131
	v_add_f32_e32 v131, 1.0, v137
	v_rcp_f32_e32 v189, v131
	v_pk_mul_f32 v[180:181], v[182:183], v[180:181]
	v_pk_mul_f32 v[136:137], v[76:77], v[136:137] op_sel_hi:[1,0]
	v_mov_b64_e32 v[76:77], 0
	v_pk_mul_f32 v[180:181], v[184:185], v[180:181]
	v_pk_mul_f32 v[182:183], v[186:187], v[188:189]
	v_cvt_pk_bf16_f32 v134, v134, v135
	v_pk_mul_f32 v[182:183], v[136:137], v[182:183]
	v_cvt_pk_bf16_f32 v136, v180, v181
	v_pk_mul_f32 v[180:181], v[102:103], v[162:163] op_sel_hi:[1,0]
	v_mov_b64_e32 v[102:103], 0
	v_cvt_pk_bf16_f32 v135, v178, v179
	v_mul_f32_e32 v131, 0xbfb8aa3b, v180
	v_exp_f32_e32 v131, v131
	v_mul_f32_e32 v133, 0xbfb8aa3b, v181
	v_exp_f32_e32 v133, v133
	v_cvt_pk_bf16_f32 v137, v182, v183
	v_lshl_add_u64 v[178:179], s[58:59], 0, v[150:151]
	global_store_dwordx4 v[178:179], v[134:137], off nt
	v_add_f32_e32 v131, 1.0, v131
	v_pk_mul_f32 v[178:179], v[104:105], v[162:163] op_sel_hi:[1,0]
	v_mov_b64_e32 v[104:105], 0
	v_rcp_f32_e32 v134, v131
	v_add_f32_e32 v131, 1.0, v133
	v_mul_f32_e32 v133, 0xbfb8aa3b, v178
	v_exp_f32_e32 v133, v133
	v_mul_f32_e32 v135, 0xbfb8aa3b, v179
	v_exp_f32_e32 v164, v135
	v_rcp_f32_e32 v135, v131
	v_add_f32_e32 v131, 1.0, v133
	v_rcp_f32_e32 v182, v131
	v_add_f32_e32 v131, 1.0, v164
	v_pk_mul_f32 v[134:135], v[180:181], v[134:135]
	v_pk_mul_f32 v[180:181], v[98:99], v[162:163] op_sel_hi:[1,0]
	v_mov_b64_e32 v[98:99], 0
	v_rcp_f32_e32 v183, v131
	v_mul_f32_e32 v131, 0xbfb8aa3b, v180
	v_exp_f32_e32 v131, v131
	v_mul_f32_e32 v133, 0xbfb8aa3b, v181
	v_exp_f32_e32 v133, v133
	v_pk_mul_f32 v[136:137], v[70:71], v[162:163] op_sel_hi:[1,0]
	v_mov_b64_e32 v[70:71], 0
	v_pk_mul_f32 v[178:179], v[178:179], v[182:183]
	v_pk_mul_f32 v[134:135], v[136:137], v[134:135]
	v_pk_mul_f32 v[136:137], v[72:73], v[162:163] op_sel_hi:[1,0]
	v_mov_b64_e32 v[72:73], 0
	v_add_f32_e32 v131, 1.0, v131
	v_pk_mul_f32 v[184:185], v[100:101], v[162:163] op_sel_hi:[1,0]
	v_mov_b64_e32 v[100:101], 0
	v_pk_mul_f32 v[136:137], v[136:137], v[178:179]
	v_rcp_f32_e32 v178, v131
	v_add_f32_e32 v131, 1.0, v133
	v_mul_f32_e32 v133, 0xbfb8aa3b, v184
	v_exp_f32_e32 v133, v133
	v_mul_f32_e32 v164, 0xbfb8aa3b, v185
	v_exp_f32_e32 v164, v164
	v_rcp_f32_e32 v179, v131
	v_add_f32_e32 v131, 1.0, v133
	v_rcp_f32_e32 v186, v131
	v_add_f32_e32 v131, 1.0, v164
	v_rcp_f32_e32 v187, v131
	v_pk_mul_f32 v[182:183], v[66:67], v[162:163] op_sel_hi:[1,0]
	v_mov_b64_e32 v[66:67], 0
	v_pk_mul_f32 v[178:179], v[180:181], v[178:179]
	v_pk_mul_f32 v[180:181], v[68:69], v[162:163] op_sel_hi:[1,0]
	v_mov_b64_e32 v[68:69], 0
	v_pk_mul_f32 v[178:179], v[182:183], v[178:179]
	v_pk_mul_f32 v[182:183], v[184:185], v[186:187]
	v_cvt_pk_bf16_f32 v134, v134, v135
	v_pk_mul_f32 v[180:181], v[180:181], v[182:183]
	v_cvt_pk_bf16_f32 v135, v136, v137
	v_cvt_pk_bf16_f32 v137, v180, v181
	v_pk_mul_f32 v[180:181], v[62:63], v[130:131] op_sel_hi:[1,0]
	v_mov_b64_e32 v[62:63], 0
	v_cvt_pk_bf16_f32 v136, v178, v179
	v_mul_f32_e32 v131, 0xbfb8aa3b, v180
	v_exp_f32_e32 v131, v131
	v_mul_f32_e32 v133, 0xbfb8aa3b, v181
	v_exp_f32_e32 v133, v133
	v_lshl_add_u64 v[178:179], s[58:59], 0, v[152:153]
	v_add_f32_e32 v131, 1.0, v131
	global_store_dwordx4 v[178:179], v[134:137], off nt
	s_add_u32 s58, s51, s74
	s_addc_u32 s59, s53, 0
	v_rcp_f32_e32 v134, v131
	v_pk_mul_f32 v[136:137], v[30:31], v[130:131] op_sel_hi:[1,0]
	v_mov_b64_e32 v[30:31], 0
	v_add_f32_e32 v131, 1.0, v133
	v_pk_mul_f32 v[178:179], v[64:65], v[130:131] op_sel_hi:[1,0]
	v_mov_b64_e32 v[64:65], 0
	s_andn2_b64 vcc, exec, s[6:7]
	v_mul_f32_e32 v133, 0xbfb8aa3b, v178
	v_exp_f32_e32 v133, v133
	v_mul_f32_e32 v135, 0xbfb8aa3b, v179
	v_exp_f32_e32 v162, v135
	v_rcp_f32_e32 v135, v131
	v_add_f32_e32 v131, 1.0, v133
	v_rcp_f32_e32 v182, v131
	v_add_f32_e32 v131, 1.0, v162
	v_pk_mul_f32 v[134:135], v[180:181], v[134:135]
	v_pk_mul_f32 v[180:181], v[58:59], v[130:131] op_sel_hi:[1,0]
	v_mov_b64_e32 v[58:59], 0
	v_rcp_f32_e32 v183, v131
	v_pk_mul_f32 v[134:135], v[136:137], v[134:135]
	v_pk_mul_f32 v[136:137], v[32:33], v[130:131] op_sel_hi:[1,0]
	v_mov_b64_e32 v[32:33], 0
	v_mul_f32_e32 v131, 0xbfb8aa3b, v180
	v_exp_f32_e32 v131, v131
	v_mul_f32_e32 v133, 0xbfb8aa3b, v181
	v_exp_f32_e32 v133, v133
	v_pk_mul_f32 v[178:179], v[178:179], v[182:183]
	v_add_f32_e32 v131, 1.0, v131
	v_pk_mul_f32 v[136:137], v[136:137], v[178:179]
	v_rcp_f32_e32 v178, v131
	v_pk_mul_f32 v[182:183], v[26:27], v[130:131] op_sel_hi:[1,0]
	v_mov_b64_e32 v[26:27], 0
	v_add_f32_e32 v131, 1.0, v133
	v_pk_mul_f32 v[184:185], v[60:61], v[130:131] op_sel_hi:[1,0]
	v_mov_b64_e32 v[60:61], 0
; __device__ __forceinline__ unsigned pk2(float lo, float hi) { f32x2_t v = {lo, hi}; bf16x2_t b = __builtin_convertvector(v, bf16x2_t); return __builtin_bit_cast(unsigned, b); }
; __device__ __forceinline__ float siluf_(float x) { return x * sigmoidf_(x); }
;     __device__ __forceinline__ void operator()(Acc& acc, const Unit& u, int wr, int wc, int fr, int fq, const float (&rsa)[2][4]) const {
;         const int row0 = u.pm * BM + wr * 64 + fr, col0 = u.pn * HALF + wc * 32 + 8 * fq;
; #pragma unroll
;         for (int ai = 0; ai < 2; ++ai)
; #pragma unroll
;             for (int m = 0; m < 4; ++m) {
;                 const int row = row0 + ai * HALF + m * 16; const float rs = rsa[ai][m];
;                 float o[8];
; #pragma unroll
;                 for (int n = 0; n < 2; ++n)
; #pragma unroll
;                     for (int j = 0; j < 4; ++j) { const float g = acc[ai][0][m][n][j] * rs, up = acc[ai][1][m][n][j] * rs; o[n * 4 + j] = siluf_(g) * up; }
;                 u32x4 w; w.x = pk2(o[0], o[1]); w.y = pk2(o[2], o[3]); w.z = pk2(o[4], o[5]); w.w = pk2(o[6], o[7]);
;                 const int rr = row & (BM - 1);
;                 *(u32x4*)((char*)O + ((size_t)(u.pm * (FF / BK) + (col0 >> 6))) * (2 * HTB) + (rr >> 7) * HTB + lds_byte(rr & 127, col0 & 63)) = w;
;             }
	v_rcp_f32_e32 v179, v131
	v_mul_f32_e32 v133, 0xbfb8aa3b, v184
	v_exp_f32_e32 v133, v133
	v_mul_f32_e32 v162, 0xbfb8aa3b, v185
	v_exp_f32_e32 v162, v162
	v_pk_mul_f32 v[178:179], v[180:181], v[178:179]
	v_add_f32_e32 v131, 1.0, v133
	v_rcp_f32_e32 v186, v131
	v_add_f32_e32 v131, 1.0, v162
	v_rcp_f32_e32 v187, v131
	v_pk_mul_f32 v[178:179], v[182:183], v[178:179]
	v_cvt_pk_bf16_f32 v134, v134, v135
	v_cvt_pk_bf16_f32 v135, v136, v137
	v_cvt_pk_bf16_f32 v136, v178, v179
	v_pk_mul_f32 v[178:179], v[54:55], v[160:161] op_sel_hi:[1,0]
	v_mov_b64_e32 v[54:55], 0
	v_pk_mul_f32 v[130:131], v[28:29], v[130:131] op_sel_hi:[1,0]
	v_mov_b64_e32 v[28:29], 0
	v_mul_f32_e32 v133, 0xbfb8aa3b, v178
	v_pk_mul_f32 v[180:181], v[184:185], v[186:187]
	v_exp_f32_e32 v133, v133
	v_pk_mul_f32 v[130:131], v[130:131], v[180:181]
	v_pk_mul_f32 v[182:183], v[52:53], v[160:161] op_sel_hi:[1,0]
	v_mov_b64_e32 v[52:53], 0
	v_cvt_pk_bf16_f32 v137, v130, v131
	v_lshl_add_u64 v[130:131], s[58:59], 0, v[144:145]
	global_store_dwordx4 v[130:131], v[134:137], off nt
	v_mul_f32_e32 v130, 0xbfb8aa3b, v179
	v_exp_f32_e32 v131, v130
	v_pk_mul_f32 v[136:137], v[56:57], v[160:161] op_sel_hi:[1,0]
	v_mov_b64_e32 v[56:57], 0
	v_add_f32_e32 v130, 1.0, v133
	v_mul_f32_e32 v133, 0xbfb8aa3b, v136
	v_exp_f32_e32 v133, v133
	v_mul_f32_e32 v162, 0xbfb8aa3b, v137
	v_exp_f32_e32 v162, v162
	v_add_f32_e32 v131, 1.0, v131
	v_add_f32_e32 v133, 1.0, v133
	v_rcp_f32_e32 v130, v130
	v_rcp_f32_e32 v131, v131
	v_rcp_f32_e32 v180, v133
	v_add_f32_e32 v133, 1.0, v162
	v_rcp_f32_e32 v181, v133
	v_pk_mul_f32 v[134:135], v[22:23], v[160:161] op_sel_hi:[1,0]
	v_mov_b64_e32 v[22:23], 0
	v_pk_mul_f32 v[130:131], v[178:179], v[130:131]
	v_pk_mul_f32 v[178:179], v[50:51], v[160:161] op_sel_hi:[1,0]
	v_mov_b64_e32 v[50:51], 0
	v_pk_mul_f32 v[130:131], v[134:135], v[130:131]
	v_pk_mul_f32 v[134:135], v[24:25], v[160:161] op_sel_hi:[1,0]
	v_mov_b64_e32 v[24:25], 0
	v_pk_mul_f32 v[136:137], v[136:137], v[180:181]
	v_mul_f32_e32 v133, 0xbfb8aa3b, v178
	v_exp_f32_e32 v133, v133
	v_pk_mul_f32 v[136:137], v[134:135], v[136:137]
	v_mul_f32_e32 v134, 0xbfb8aa3b, v179
	v_exp_f32_e32 v135, v134
	v_add_f32_e32 v133, 1.0, v133
	v_rcp_f32_e32 v134, v133
	v_pk_mul_f32 v[180:181], v[18:19], v[160:161] op_sel_hi:[1,0]
	v_mov_b64_e32 v[18:19], 0
	v_add_f32_e32 v133, 1.0, v135
	v_mul_f32_e32 v135, 0xbfb8aa3b, v182
	v_exp_f32_e32 v162, v135
	v_mul_f32_e32 v135, 0xbfb8aa3b, v183
	v_exp_f32_e32 v164, v135
	v_rcp_f32_e32 v135, v133
	v_add_f32_e32 v133, 1.0, v162
	v_rcp_f32_e32 v184, v133
	v_add_f32_e32 v133, 1.0, v164
	v_rcp_f32_e32 v185, v133
	v_pk_mul_f32 v[134:135], v[178:179], v[134:135]
	s_nop 0
	v_pk_mul_f32 v[178:179], v[180:181], v[134:135]
	v_pk_mul_f32 v[134:135], v[20:21], v[160:161] op_sel_hi:[1,0]
	v_mov_b64_e32 v[20:21], 0
	v_pk_mul_f32 v[180:181], v[182:183], v[184:185]
	s_nop 0
	v_pk_mul_f32 v[180:181], v[134:135], v[180:181]
	v_cvt_pk_bf16_f32 v135, v136, v137
	v_cvt_pk_bf16_f32 v136, v178, v179
	v_pk_mul_f32 v[178:179], v[46:47], v[132:133] op_sel_hi:[1,0]
	v_mov_b64_e32 v[46:47], 0
	v_cvt_pk_bf16_f32 v134, v130, v131
	v_mul_f32_e32 v133, 0xbfb8aa3b, v178
	v_exp_f32_e32 v133, v133
	v_cvt_pk_bf16_f32 v137, v180, v181
	v_lshl_add_u64 v[130:131], s[58:59], 0, v[148:149]
	global_store_dwordx4 v[130:131], v[134:137], off nt
	v_mul_f32_e32 v130, 0xbfb8aa3b, v179
	v_exp_f32_e32 v131, v130
	v_pk_mul_f32 v[136:137], v[48:49], v[132:133] op_sel_hi:[1,0]
	v_mov_b64_e32 v[48:49], 0
	v_add_f32_e32 v130, 1.0, v133
	v_pk_mul_f32 v[134:135], v[14:15], v[132:133] op_sel_hi:[1,0]
	v_mov_b64_e32 v[14:15], 0
	v_mul_f32_e32 v133, 0xbfb8aa3b, v136
	v_exp_f32_e32 v133, v133
	v_mul_f32_e32 v160, 0xbfb8aa3b, v137
	v_exp_f32_e32 v160, v160
	v_add_f32_e32 v131, 1.0, v131
	v_add_f32_e32 v133, 1.0, v133
	v_rcp_f32_e32 v130, v130
	v_rcp_f32_e32 v131, v131
	v_rcp_f32_e32 v180, v133
	v_add_f32_e32 v133, 1.0, v160
	v_rcp_f32_e32 v181, v133
	v_pk_mul_f32 v[130:131], v[178:179], v[130:131]
; __device__ __forceinline__ unsigned pk2(float lo, float hi) { f32x2_t v = {lo, hi}; bf16x2_t b = __builtin_convertvector(v, bf16x2_t); return __builtin_bit_cast(unsigned, b); }
; __device__ __forceinline__ float siluf_(float x) { return x * sigmoidf_(x); }
;     __device__ __forceinline__ void operator()(Acc& acc, const Unit& u, int wr, int wc, int fr, int fq, const float (&rsa)[2][4]) const {
;     ...
;             for (int m = 0; m < 4; ++m) {
;                 const int row = row0 + ai * HALF + m * 16; const float rs = rsa[ai][m];
;                 float o[8];
; #pragma unroll
;                 for (int n = 0; n < 2; ++n)
; #pragma unroll
;                     for (int j = 0; j < 4; ++j) { const float g = acc[ai][0][m][n][j] * rs, up = acc[ai][1][m][n][j] * rs; o[n * 4 + j] = siluf_(g) * up; }
;                 u32x4 w; w.x = pk2(o[0], o[1]); w.y = pk2(o[2], o[3]); w.z = pk2(o[4], o[5]); w.w = pk2(o[6], o[7]);
;                 const int rr = row & (BM - 1);
;                 *(u32x4*)((char*)O + ((size_t)(u.pm * (FF / BK) + (col0 >> 6))) * (2 * HTB) + (rr >> 7) * HTB + lds_byte(rr & 127, col0 & 63)) = w;
;             }
	v_pk_mul_f32 v[178:179], v[42:43], v[132:133] op_sel_hi:[1,0]
	v_mov_b64_e32 v[42:43], 0
	v_pk_mul_f32 v[130:131], v[134:135], v[130:131]
	v_pk_mul_f32 v[134:135], v[16:17], v[132:133] op_sel_hi:[1,0]
	v_mov_b64_e32 v[16:17], 0
	v_pk_mul_f32 v[136:137], v[136:137], v[180:181]
	v_mul_f32_e32 v133, 0xbfb8aa3b, v178
	v_exp_f32_e32 v133, v133
	v_pk_mul_f32 v[134:135], v[134:135], v[136:137]
	v_mul_f32_e32 v136, 0xbfb8aa3b, v179
	v_exp_f32_e32 v137, v136
	v_add_f32_e32 v133, 1.0, v133
	v_rcp_f32_e32 v136, v133
	v_pk_mul_f32 v[180:181], v[10:11], v[132:133] op_sel_hi:[1,0]
	v_mov_b64_e32 v[10:11], 0
	v_add_f32_e32 v133, 1.0, v137
	v_pk_mul_f32 v[182:183], v[44:45], v[132:133] op_sel_hi:[1,0]
	v_mov_b64_e32 v[44:45], 0
	v_cvt_pk_bf16_f32 v130, v130, v131
	v_mul_f32_e32 v137, 0xbfb8aa3b, v182
	v_exp_f32_e32 v160, v137
	v_mul_f32_e32 v137, 0xbfb8aa3b, v183
	v_exp_f32_e32 v162, v137
	v_rcp_f32_e32 v137, v133
	v_add_f32_e32 v133, 1.0, v160
	v_rcp_f32_e32 v184, v133
	v_add_f32_e32 v133, 1.0, v162
	v_rcp_f32_e32 v185, v133
	v_pk_mul_f32 v[136:137], v[178:179], v[136:137]
	v_pk_mul_f32 v[132:133], v[12:13], v[132:133] op_sel_hi:[1,0]
	v_mov_b64_e32 v[12:13], 0
	v_pk_mul_f32 v[136:137], v[180:181], v[136:137]
	v_pk_mul_f32 v[178:179], v[182:183], v[184:185]
	v_cvt_pk_bf16_f32 v131, v134, v135
	v_pk_mul_f32 v[178:179], v[132:133], v[178:179]
	v_cvt_pk_bf16_f32 v132, v136, v137
	v_pk_mul_f32 v[136:137], v[38:39], v[158:159] op_sel_hi:[1,0]
	v_mov_b64_e32 v[38:39], 0
	v_cvt_pk_bf16_f32 v133, v178, v179
	v_mul_f32_e32 v160, 0xbfb8aa3b, v136
	v_lshl_add_u64 v[134:135], s[58:59], 0, v[150:151]
	v_exp_f32_e32 v160, v160
	global_store_dwordx4 v[134:135], v[130:133], off nt
	v_pk_mul_f32 v[134:135], v[40:41], v[158:159] op_sel_hi:[1,0]
	v_mov_b64_e32 v[40:41], 0
	v_pk_mul_f32 v[180:181], v[36:37], v[158:159] op_sel_hi:[1,0]
	v_mov_b64_e32 v[36:37], 0
	v_mul_f32_e32 v130, 0xbfb8aa3b, v137
	v_exp_f32_e32 v131, v130
	v_add_f32_e32 v130, 1.0, v160
	v_mul_f32_e32 v160, 0xbfb8aa3b, v134
	v_exp_f32_e32 v160, v160
	v_mul_f32_e32 v162, 0xbfb8aa3b, v135
	v_add_f32_e32 v131, 1.0, v131
	v_exp_f32_e32 v162, v162
	v_rcp_f32_e32 v130, v130
	v_rcp_f32_e32 v131, v131
	v_add_f32_e32 v160, 1.0, v160
	v_rcp_f32_e32 v178, v160
	v_add_f32_e32 v160, 1.0, v162
	v_rcp_f32_e32 v179, v160
	v_pk_mul_f32 v[130:131], v[136:137], v[130:131]
	v_pk_mul_f32 v[136:137], v[34:35], v[158:159] op_sel_hi:[1,0]
	v_mov_b64_e32 v[34:35], 0
	v_pk_mul_f32 v[132:133], v[6:7], v[158:159] op_sel_hi:[1,0]
	v_mov_b64_e32 v[6:7], 0
	v_mul_f32_e32 v160, 0xbfb8aa3b, v136
	v_exp_f32_e32 v160, v160
	v_pk_mul_f32 v[130:131], v[132:133], v[130:131]
	v_pk_mul_f32 v[132:133], v[8:9], v[158:159] op_sel_hi:[1,0]
	v_mov_b64_e32 v[8:9], 0
	v_pk_mul_f32 v[134:135], v[134:135], v[178:179]
	v_mul_f32_e32 v162, 0xbfb8aa3b, v181
	v_pk_mul_f32 v[132:133], v[132:133], v[134:135]
	v_mul_f32_e32 v134, 0xbfb8aa3b, v137
	v_exp_f32_e32 v135, v134
	v_add_f32_e32 v134, 1.0, v160
	v_mul_f32_e32 v160, 0xbfb8aa3b, v180
	v_exp_f32_e32 v160, v160
	v_exp_f32_e32 v162, v162
	v_add_f32_e32 v135, 1.0, v135
	v_rcp_f32_e32 v134, v134
	v_add_f32_e32 v160, 1.0, v160
	v_rcp_f32_e32 v135, v135
	v_rcp_f32_e32 v182, v160
	v_add_f32_e32 v160, 1.0, v162
	v_rcp_f32_e32 v183, v160
	v_pk_mul_f32 v[178:179], v[2:3], v[158:159] op_sel_hi:[1,0]
	v_mov_b64_e32 v[2:3], 0
	v_pk_mul_f32 v[134:135], v[136:137], v[134:135]
	v_pk_mul_f32 v[136:137], v[4:5], v[158:159] op_sel_hi:[1,0]
	v_mov_b64_e32 v[4:5], 0
	v_pk_mul_f32 v[134:135], v[178:179], v[134:135]
	v_pk_mul_f32 v[178:179], v[180:181], v[182:183]
	v_cvt_pk_bf16_f32 v130, v130, v131
	v_pk_mul_f32 v[136:137], v[136:137], v[178:179]
	v_cvt_pk_bf16_f32 v131, v132, v133
	v_cvt_pk_bf16_f32 v132, v134, v135
	v_cvt_pk_bf16_f32 v133, v136, v137
	v_lshl_add_u64 v[134:135], s[58:59], 0, v[152:153]
	global_store_dwordx4 v[134:135], v[130:133], off nt
	s_cbranch_vccnz .LBB0_2491
	s_andn2_b64 vcc, exec, s[26:27]
	s_cbranch_vccnz .Lp9_nz
	s_barrier

;     __device__ __forceinline__ void fused(Acc& acc, const Unit& u, int wr, int wc, int fr, int fq, PG8_LAS unsigned char* lds, int wid, int lane) const {
;     ...
;         f32x4 gv[2][2];
; #pragma unroll
;         for (int bj = 0; bj < 2; ++bj) { gv[bj][0] = *(const f32x4*)(gfin + col0 + bj * HALF); gv[bj][1] = *(const f32x4*)(gfin + col0 + bj * HALF + 4); }
; #pragma unroll
;         for (int ai = 0; ai < 2; ++ai)
; #pragma unroll
;             for (int m = 0; m < 4; ++m) {
;                 const int lr = ai * HALF + wr * 64 + m * 16 + fr; const size_t grow = (size_t)(u.pm * BM + lr) * D; const float rs = Sx[lr];
.LBB0_2663:
	s_or_b64 exec, exec, s[52:53]
	v_lshl_or_b32 v2, s50, 8, v216
	s_waitcnt lgkmcnt(0)
	v_ashrrev_i32_e32 v3, 31, v2
	v_lshlrev_b64 v[146:147], 2, v[2:3]
	s_waitcnt lgkmcnt(0)
	s_barrier
	v_lshl_add_u64 v[2:3], s[92:93], 0, v[146:147]
	global_load_dwordx4 v[14:17], v[2:3], off
	global_load_dwordx4 v[10:13], v[2:3], off offset:16
	global_load_dwordx4 v[6:9], v[2:3], off offset:512
	s_nop 0
	global_load_dwordx4 v[2:5], v[2:3], off offset:528
	v_add_u32_e32 v148, s51, v214
	v_add_u32_e32 v160, s51, v222
	v_add_u32_e32 v152, s51, v220
	v_ashrrev_i32_e32 v149, 31, v148
	v_ashrrev_i32_e32 v161, 31, v160
	v_ashrrev_i32_e32 v153, 31, v152
	v_lshlrev_b64 v[148:149], 12, v[148:149]
	v_lshlrev_b64 v[160:161], 12, v[160:161]
	ds_read_b32 v158, v219
	ds_read_b32 v156, v221
	ds_read_b32 v150, v223
	ds_read_b32 v154, v225
	ds_read_b32 v162, v227
	ds_read_b32 v164, v229
	ds_read_b32 v166, v231
	ds_read_b32 v168, v233
	v_lshlrev_b64 v[152:153], 12, v[152:153]
	v_lshl_add_u64 v[148:149], s[94:95], 0, v[148:149]
	v_lshl_add_u64 v[160:161], s[94:95], 0, v[160:161]
	s_waitcnt lgkmcnt(7)
	v_pk_mul_f32 v[128:129], v[128:129], v[158:159] op_sel_hi:[1,0]
	v_pk_mul_f32 v[126:127], v[126:127], v[158:159] op_sel_hi:[1,0]
	s_waitcnt lgkmcnt(5)
	v_pk_mul_f32 v[84:85], v[84:85], v[150:151] op_sel_hi:[1,0]
	v_pk_mul_f32 v[82:83], v[82:83], v[150:151] op_sel_hi:[1,0]
	v_lshl_add_u64 v[152:153], s[94:95], 0, v[152:153]
	v_lshl_add_u64 v[148:149], v[148:149], 0, v[146:147]
	v_lshl_add_u64 v[160:161], v[160:161], 0, v[146:147]
	v_pk_mul_f32 v[124:125], v[124:125], v[158:159] op_sel_hi:[1,0]
	v_pk_mul_f32 v[122:123], v[122:123], v[158:159] op_sel_hi:[1,0]
	v_pk_mul_f32 v[120:121], v[120:121], v[158:159] op_sel_hi:[1,0]
	v_pk_mul_f32 v[118:119], v[118:119], v[158:159] op_sel_hi:[1,0]
	v_pk_mul_f32 v[116:117], v[116:117], v[158:159] op_sel_hi:[1,0]
	v_pk_mul_f32 v[114:115], v[114:115], v[158:159] op_sel_hi:[1,0]
	v_pk_mul_f32 v[112:113], v[112:113], v[156:157] op_sel_hi:[1,0]
	v_pk_mul_f32 v[110:111], v[110:111], v[156:157] op_sel_hi:[1,0]
	v_pk_mul_f32 v[108:109], v[108:109], v[156:157] op_sel_hi:[1,0]
	v_pk_mul_f32 v[106:107], v[106:107], v[156:157] op_sel_hi:[1,0]
	v_pk_mul_f32 v[158:159], v[104:105], v[156:157] op_sel_hi:[1,0]
	v_pk_mul_f32 v[170:171], v[102:103], v[156:157] op_sel_hi:[1,0]
	v_pk_mul_f32 v[172:173], v[100:101], v[156:157] op_sel_hi:[1,0]
	v_pk_mul_f32 v[156:157], v[98:99], v[156:157] op_sel_hi:[1,0]
	v_pk_mul_f32 v[174:175], v[96:97], v[150:151] op_sel_hi:[1,0]
	v_pk_mul_f32 v[176:177], v[94:95], v[150:151] op_sel_hi:[1,0]
	v_pk_mul_f32 v[178:179], v[92:93], v[150:151] op_sel_hi:[1,0]
	v_pk_mul_f32 v[180:181], v[90:91], v[150:151] op_sel_hi:[1,0]
	v_pk_mul_f32 v[182:183], v[88:89], v[150:151] op_sel_hi:[1,0]
	v_pk_mul_f32 v[184:185], v[86:87], v[150:151] op_sel_hi:[1,0]
	v_lshl_add_u64 v[152:153], v[152:153], 0, v[146:147]
	s_waitcnt lgkmcnt(4)
	v_pk_mul_f32 v[68:69], v[68:69], v[154:155] op_sel_hi:[1,0]
	v_pk_mul_f32 v[66:67], v[66:67], v[154:155] op_sel_hi:[1,0]
	s_waitcnt lgkmcnt(3)
	v_pk_mul_f32 v[52:53], v[52:53], v[162:163] op_sel_hi:[1,0]
	v_pk_mul_f32 v[50:51], v[50:51], v[162:163] op_sel_hi:[1,0]
	s_waitcnt lgkmcnt(2)
	v_pk_mul_f32 v[36:37], v[36:37], v[164:165] op_sel_hi:[1,0]
	v_pk_mul_f32 v[34:35], v[34:35], v[164:165] op_sel_hi:[1,0]
	s_waitcnt lgkmcnt(1)
	v_pk_mul_f32 v[20:21], v[20:21], v[166:167] op_sel_hi:[1,0]
	v_pk_mul_f32 v[18:19], v[18:19], v[166:167] op_sel_hi:[1,0]
	v_pk_mul_f32 v[24:25], v[24:25], v[166:167] op_sel_hi:[1,0]
	v_pk_mul_f32 v[22:23], v[22:23], v[166:167] op_sel_hi:[1,0]
	v_pk_mul_f32 v[80:81], v[80:81], v[154:155] op_sel_hi:[1,0]
	v_pk_mul_f32 v[78:79], v[78:79], v[154:155] op_sel_hi:[1,0]
	v_pk_mul_f32 v[64:65], v[64:65], v[162:163] op_sel_hi:[1,0]
	v_pk_mul_f32 v[62:63], v[62:63], v[162:163] op_sel_hi:[1,0]
	v_pk_mul_f32 v[48:49], v[48:49], v[164:165] op_sel_hi:[1,0]
	v_pk_mul_f32 v[46:47], v[46:47], v[164:165] op_sel_hi:[1,0]
	v_pk_mul_f32 v[32:33], v[32:33], v[166:167] op_sel_hi:[1,0]
	v_pk_mul_f32 v[30:31], v[30:31], v[166:167] op_sel_hi:[1,0]
	v_pk_mul_f32 v[76:77], v[76:77], v[154:155] op_sel_hi:[1,0]
	v_pk_mul_f32 v[74:75], v[74:75], v[154:155] op_sel_hi:[1,0]
	v_pk_mul_f32 v[60:61], v[60:61], v[162:163] op_sel_hi:[1,0]
	v_pk_mul_f32 v[58:59], v[58:59], v[162:163] op_sel_hi:[1,0]
	v_pk_mul_f32 v[44:45], v[44:45], v[164:165] op_sel_hi:[1,0]
	v_pk_mul_f32 v[42:43], v[42:43], v[164:165] op_sel_hi:[1,0]
	v_pk_mul_f32 v[28:29], v[28:29], v[166:167] op_sel_hi:[1,0]
	v_pk_mul_f32 v[26:27], v[26:27], v[166:167] op_sel_hi:[1,0]
	v_pk_mul_f32 v[72:73], v[72:73], v[154:155] op_sel_hi:[1,0]
	v_pk_mul_f32 v[70:71], v[70:71], v[154:155] op_sel_hi:[1,0]
	v_pk_mul_f32 v[56:57], v[56:57], v[162:163] op_sel_hi:[1,0]
	v_pk_mul_f32 v[54:55], v[54:55], v[162:163] op_sel_hi:[1,0]
	v_pk_mul_f32 v[40:41], v[40:41], v[164:165] op_sel_hi:[1,0]
	v_pk_mul_f32 v[38:39], v[38:39], v[164:165] op_sel_hi:[1,0]
	s_and_b64 vcc, exec, s[10:11]
	s_mov_b64 s[10:11], -1
	s_waitcnt vmcnt(3)
	v_pk_mul_f32 v[88:89], v[16:17], v[128:129]
	v_pk_mul_f32 v[86:87], v[14:15], v[126:127]
	s_waitcnt vmcnt(2)
	v_pk_mul_f32 v[92:93], v[12:13], v[124:125]
	s_waitcnt vmcnt(0)
;     __device__ __forceinline__ void fused(Acc& acc, const Unit& u, int wr, int wc, int fr, int fq, PG8_LAS unsigned char* lds, int wid, int lane) const {
;     ...
; #pragma unroll
;         for (int ai = 0; ai < 2; ++ai)
; #pragma unroll
;             for (int m = 0; m < 4; ++m) {
;                 const int lr = ai * HALF + wr * 64 + m * 16 + fr; const size_t grow = (size_t)(u.pm * BM + lr) * D; const float rs = Sx[lr];
; #pragma unroll
;                 for (int bj = 0; bj < 2; ++bj) {
;                     *(f32x4*)(Y + grow + col0 + bj * HALF) = acc[ai][bj][m][0] * rs * gv[bj][0];
;                     *(f32x4*)(Y + grow + col0 + bj * HALF + 4) = acc[ai][bj][m][1] * rs * gv[bj][1];
;                 }
;             }
	v_pk_mul_f32 v[84:85], v[4:5], v[84:85]
	v_pk_mul_f32 v[82:83], v[2:3], v[82:83]
	v_pk_mul_f32 v[90:91], v[10:11], v[122:123]
	v_pk_mul_f32 v[96:97], v[8:9], v[120:121]
	v_pk_mul_f32 v[94:95], v[6:7], v[118:119]
	v_pk_mul_f32 v[100:101], v[4:5], v[116:117]
	v_pk_mul_f32 v[98:99], v[2:3], v[114:115]
	v_pk_mul_f32 v[104:105], v[16:17], v[112:113]
	v_pk_mul_f32 v[102:103], v[14:15], v[110:111]
	v_pk_mul_f32 v[108:109], v[12:13], v[108:109]
	v_pk_mul_f32 v[106:107], v[10:11], v[106:107]
	v_pk_mul_f32 v[112:113], v[8:9], v[158:159]
	v_pk_mul_f32 v[110:111], v[6:7], v[170:171]
	v_pk_mul_f32 v[116:117], v[4:5], v[172:173]
	v_pk_mul_f32 v[114:115], v[2:3], v[156:157]
	v_pk_mul_f32 v[120:121], v[16:17], v[174:175]
	v_pk_mul_f32 v[118:119], v[14:15], v[176:177]
	v_pk_mul_f32 v[124:125], v[12:13], v[178:179]
	v_pk_mul_f32 v[122:123], v[10:11], v[180:181]
	global_store_dwordx4 v[148:149], v[86:89], off nt
	global_store_dwordx4 v[148:149], v[90:93], off offset:16 nt
	global_store_dwordx4 v[148:149], v[94:97], off offset:512 nt
	global_store_dwordx4 v[148:149], v[98:101], off offset:528 nt
	global_store_dwordx4 v[152:153], v[102:105], off nt
	global_store_dwordx4 v[152:153], v[106:109], off offset:16 nt
	global_store_dwordx4 v[152:153], v[110:113], off offset:512 nt
	global_store_dwordx4 v[152:153], v[114:117], off offset:528 nt
	global_store_dwordx4 v[160:161], v[118:121], off nt
	global_store_dwordx4 v[160:161], v[122:125], off offset:16 nt
	global_store_dwordx4 v[160:161], v[82:85], off offset:528 nt
	v_pk_mul_f32 v[68:69], v[4:5], v[68:69]
	v_pk_mul_f32 v[66:67], v[2:3], v[66:67]
	v_add_u32_e32 v82, s51, v224
	v_ashrrev_i32_e32 v83, 31, v82
	v_lshlrev_b64 v[82:83], 12, v[82:83]
	v_lshl_add_u64 v[82:83], s[94:95], 0, v[82:83]
	v_lshl_add_u64 v[82:83], v[82:83], 0, v[146:147]
	global_store_dwordx4 v[82:83], v[66:69], off offset:528 nt
	v_pk_mul_f32 v[52:53], v[4:5], v[52:53]
	v_pk_mul_f32 v[50:51], v[2:3], v[50:51]
	v_add_u32_e32 v66, s51, v226
	v_ashrrev_i32_e32 v67, 31, v66
	v_lshlrev_b64 v[66:67], 12, v[66:67]
	v_lshl_add_u64 v[66:67], s[94:95], 0, v[66:67]
	v_lshl_add_u64 v[66:67], v[66:67], 0, v[146:147]
	global_store_dwordx4 v[66:67], v[50:53], off offset:528 nt
	v_pk_mul_f32 v[36:37], v[4:5], v[36:37]
	v_pk_mul_f32 v[34:35], v[2:3], v[34:35]
	v_add_u32_e32 v50, s51, v228
	v_ashrrev_i32_e32 v51, 31, v50
	v_lshlrev_b64 v[50:51], 12, v[50:51]
	v_lshl_add_u64 v[50:51], s[94:95], 0, v[50:51]
	v_lshl_add_u64 v[50:51], v[50:51], 0, v[146:147]
	global_store_dwordx4 v[50:51], v[34:37], off offset:528 nt
	v_pk_mul_f32 v[20:21], v[4:5], v[20:21]
	v_pk_mul_f32 v[18:19], v[2:3], v[18:19]
	v_add_u32_e32 v34, s51, v230
	v_ashrrev_i32_e32 v35, 31, v34
	v_lshlrev_b64 v[34:35], 12, v[34:35]
	v_lshl_add_u64 v[34:35], s[94:95], 0, v[34:35]
	v_lshl_add_u64 v[34:35], v[34:35], 0, v[146:147]
	global_store_dwordx4 v[34:35], v[18:21], off offset:528 nt
	v_pk_mul_f32 v[88:89], v[8:9], v[182:183]
	v_pk_mul_f32 v[86:87], v[6:7], v[184:185]
	v_add_u32_e32 v18, s51, v232
	v_ashrrev_i32_e32 v19, 31, v18
	v_pk_mul_f32 v[24:25], v[8:9], v[24:25]
	v_pk_mul_f32 v[22:23], v[6:7], v[22:23]
	v_lshlrev_b64 v[18:19], 12, v[18:19]
	global_store_dwordx4 v[160:161], v[86:89], off offset:512 nt
	global_store_dwordx4 v[34:35], v[22:25], off offset:512 nt
	s_waitcnt lgkmcnt(0)
	v_pk_mul_f32 v[20:21], v[138:139], v[168:169] op_sel_hi:[1,0]
	v_lshl_add_u64 v[18:19], s[94:95], 0, v[18:19]
	v_pk_mul_f32 v[22:23], v[140:141], v[168:169] op_sel_hi:[1,0]
	v_pk_mul_f32 v[80:81], v[16:17], v[80:81]
	v_pk_mul_f32 v[78:79], v[14:15], v[78:79]
	v_pk_mul_f32 v[64:65], v[16:17], v[64:65]
	v_pk_mul_f32 v[62:63], v[14:15], v[62:63]
	v_pk_mul_f32 v[48:49], v[16:17], v[48:49]
	v_pk_mul_f32 v[46:47], v[14:15], v[46:47]
	v_pk_mul_f32 v[32:33], v[16:17], v[32:33]
	v_pk_mul_f32 v[30:31], v[14:15], v[30:31]
	v_pk_mul_f32 v[16:17], v[16:17], v[20:21]
	v_pk_mul_f32 v[14:15], v[14:15], v[22:23]
	v_lshl_add_u64 v[18:19], v[18:19], 0, v[146:147]
	global_store_dwordx4 v[82:83], v[78:81], off nt
	global_store_dwordx4 v[18:19], v[14:17], off nt
	v_pk_mul_f32 v[76:77], v[12:13], v[76:77]
	v_pk_mul_f32 v[74:75], v[10:11], v[74:75]
	v_pk_mul_f32 v[14:15], v[134:135], v[168:169] op_sel_hi:[1,0]
	v_pk_mul_f32 v[16:17], v[136:137], v[168:169] op_sel_hi:[1,0]
	v_pk_mul_f32 v[60:61], v[12:13], v[60:61]
	v_pk_mul_f32 v[58:59], v[10:11], v[58:59]
	v_pk_mul_f32 v[44:45], v[12:13], v[44:45]
	v_pk_mul_f32 v[42:43], v[10:11], v[42:43]
	v_pk_mul_f32 v[28:29], v[12:13], v[28:29]
	v_pk_mul_f32 v[26:27], v[10:11], v[26:27]
	v_pk_mul_f32 v[12:13], v[12:13], v[14:15]
	v_pk_mul_f32 v[10:11], v[10:11], v[16:17]
	global_store_dwordx4 v[82:83], v[74:77], off offset:16 nt
	global_store_dwordx4 v[18:19], v[10:13], off offset:16 nt
	v_pk_mul_f32 v[72:73], v[8:9], v[72:73]
	v_pk_mul_f32 v[70:71], v[6:7], v[70:71]
	v_pk_mul_f32 v[10:11], v[142:143], v[168:169] op_sel_hi:[1,0]
	v_pk_mul_f32 v[12:13], v[144:145], v[168:169] op_sel_hi:[1,0]
	v_pk_mul_f32 v[56:57], v[8:9], v[56:57]
	v_pk_mul_f32 v[54:55], v[6:7], v[54:55]
	v_pk_mul_f32 v[40:41], v[8:9], v[40:41]
	v_pk_mul_f32 v[38:39], v[6:7], v[38:39]
	v_pk_mul_f32 v[8:9], v[8:9], v[10:11]
	v_pk_mul_f32 v[6:7], v[6:7], v[12:13]
	global_store_dwordx4 v[82:83], v[70:73], off offset:512 nt
	global_store_dwordx4 v[18:19], v[6:9], off offset:512 nt
	global_store_dwordx4 v[66:67], v[62:65], off nt
	global_store_dwordx4 v[66:67], v[58:61], off offset:16 nt
	v_pk_mul_f32 v[6:7], v[130:131], v[168:169] op_sel_hi:[1,0]
	v_pk_mul_f32 v[8:9], v[132:133], v[168:169] op_sel_hi:[1,0]
	v_pk_mul_f32 v[4:5], v[4:5], v[6:7]
	v_pk_mul_f32 v[2:3], v[2:3], v[8:9]
	global_store_dwordx4 v[66:67], v[54:57], off offset:512 nt
	global_store_dwordx4 v[50:51], v[46:49], off nt
	global_store_dwordx4 v[50:51], v[42:45], off offset:16 nt
	global_store_dwordx4 v[50:51], v[38:41], off offset:512 nt
	global_store_dwordx4 v[34:35], v[30:33], off nt
	global_store_dwordx4 v[34:35], v[26:29], off offset:16 nt
	global_store_dwordx4 v[18:19], v[2:5], off offset:528 nt
	s_cbranch_vccnz .LBB0_2619
	s_andn2_b64 vcc, exec, s[28:29]
	s_cbranch_vccnz .LBB0_2618
	s_barrier
	s_branch .LBB0_2618
